# fast group barrier + row-sum conversion chain shortened + next-phase weight K-tiles touched into L2 by idle waves during seams
# baseline (speedup 1.0000x reference)
; __device__ __forceinline__ unsigned cvt_pk_bf16(float lo, float hi) { unsigned r; asm volatile("v_cvt_pk_bf16_f32 %0, %1, %2" : "=v"(r) : "v"(lo), "v"(hi)); return r; }
; __device__ __forceinline__ float ss_val(u64 v) { return (float)v * (1.0f / 1099511627776.0f); }
;     __device__ __forceinline__ void operator()(const f32x4 (&acc)[2][2][4][2], const Unit& u, const Unit& nxt, bool has_next, int wr, int wc, int fr, int fq) const {
;     ...
; #pragma unroll
;         for (int g = 0; g < 8; ++g) {
;             const int ai = g >> 2, m = g & 3;
;             const float rs = __builtin_amdgcn_rsqf(ss_val(cur[g]) * inv_k + eps), rsn = rs * -1.44269504089f, rs2 = rs * rs;
;             float h[8];
; #pragma unroll
;             for (int n = 0; n < 2; ++n)
; #pragma unroll
;                 for (int jp = 0; jp < 2; ++jp) {
;                     const f32x2v av = {acc[ai][0][m][n][2 * jp], acc[ai][0][m][n][2 * jp + 1]}, gv = {acc[ai][1][m][n][2 * jp], acc[ai][1][m][n][2 * jp + 1]};
;                     const f32x2v t = (av * gv) * rs2, y = gv * rsn;
;                     f32x2v ex; ex.x = __builtin_amdgcn_exp2f(y.x); ex.y = __builtin_amdgcn_exp2f(y.y);
;                     const f32x2v d = ex + 1.0f;
;                     f32x2v r; r.x = __builtin_amdgcn_rcpf(d.x); r.y = __builtin_amdgcn_rcpf(d.y);
;                     const f32x2v o = t * r;
;                     h[4 * n + 2 * jp] = o.x; h[4 * n + 2 * jp + 1] = o.y;
;                 }
;             u32x4 w; w.x = cvt_pk_bf16(h[0], h[1]); w.y = cvt_pk_bf16(h[2], h[3]); w.z = cvt_pk_bf16(h[4], h[5]); w.w = cvt_pk_bf16(h[6], h[7]);
;             *(u32x4*)(O + (size_t)(row0 + ai * HALF + m * 16) * ldc + col0) = w;
;         }
.LBB0_180:
	s_waitcnt vmcnt(0)
	v_or_b32_e32 v185, 16, v168
	v_pk_mul_f32 v[124:125], v[124:125], v[116:117]
	v_cvt_f32_u32_e32 v172, v172
	v_cvt_f32_u32_e32 v173, v173
	v_fmamk_f32 v172, v173, 0x4f800000, v172
	v_fmamk_f32 v169, v172, 0x26800000, v180
	v_rsq_f32_e32 v186, v169
	v_pk_mul_f32 v[120:121], v[120:121], v[112:113]
	v_pk_mul_f32 v[126:127], v[126:127], v[118:119]
	v_pk_mul_f32 v[122:123], v[122:123], v[114:115]
	v_mul_f32_e32 v184, 0xbfb8aa3b, v186
	v_pk_mul_f32 v[116:117], v[116:117], v[184:185] op_sel_hi:[1,0]
	v_pk_mul_f32 v[112:113], v[112:113], v[184:185] op_sel_hi:[1,0]
	v_exp_f32_e32 v116, v116
	v_exp_f32_e32 v117, v117
	v_pk_mul_f32 v[118:119], v[118:119], v[184:185] op_sel_hi:[1,0]
	v_exp_f32_e32 v112, v112
	v_exp_f32_e32 v113, v113
	v_pk_mul_f32 v[114:115], v[114:115], v[184:185] op_sel_hi:[1,0]
	v_exp_f32_e32 v118, v118
	v_exp_f32_e32 v119, v119
	v_exp_f32_e32 v114, v114
	v_exp_f32_e32 v115, v115
	v_pk_add_f32 v[116:117], v[116:117], 1.0 op_sel_hi:[1,0]
	v_pk_add_f32 v[112:113], v[112:113], 1.0 op_sel_hi:[1,0]
	v_rcp_f32_e32 v116, v116
	v_rcp_f32_e32 v117, v117
	v_pk_add_f32 v[118:119], v[118:119], 1.0 op_sel_hi:[1,0]
	v_rcp_f32_e32 v112, v112
	v_rcp_f32_e32 v113, v113
	v_pk_add_f32 v[114:115], v[114:115], 1.0 op_sel_hi:[1,0]
	v_rcp_f32_e32 v118, v118
	v_rcp_f32_e32 v119, v119
	v_rcp_f32_e32 v114, v114
	v_rcp_f32_e32 v115, v115
	v_or_b32_e32 v187, 32, v168
	v_mul_f32_e32 v186, v186, v186
	v_pk_mul_f32 v[124:125], v[124:125], v[186:187] op_sel_hi:[1,0]
	v_pk_mul_f32 v[120:121], v[120:121], v[186:187] op_sel_hi:[1,0]
	v_pk_mul_f32 v[116:117], v[124:125], v[116:117]
	v_pk_mul_f32 v[124:125], v[126:127], v[186:187] op_sel_hi:[1,0]
	v_pk_mul_f32 v[112:113], v[120:121], v[112:113]
	v_pk_mul_f32 v[120:121], v[122:123], v[186:187] op_sel_hi:[1,0]
	v_pk_mul_f32 v[118:119], v[124:125], v[118:119]
	v_pk_mul_f32 v[114:115], v[120:121], v[114:115]
	v_cvt_pk_bf16_f32 v116, v116, v117
	v_cvt_pk_bf16_f32 v117, v118, v119
	v_cvt_pk_bf16_f32 v118, v112, v113
	v_lshl_or_b32 v182, s70, 7, v176
	v_cvt_pk_bf16_f32 v119, v114, v115
	v_ashrrev_i32_e32 v183, 31, v182
	v_mov_b64_e32 v[112:113], s[24:25]
	v_cvt_f32_u32_e32 v170, v170
	v_cvt_f32_u32_e32 v171, v171
	v_fmamk_f32 v170, v171, 0x4f800000, v170
	v_fmamk_f32 v114, v170, 0x26800000, v180
	v_rsq_f32_e32 v122, v114
	v_mad_i64_i32 v[120:121], s[56:57], v168, s69, v[112:113]
	v_lshlrev_b64 v[114:115], 1, v[182:183]
	v_lshl_add_u64 v[120:121], v[120:121], 0, v[114:115]
	global_store_dwordx4 v[120:121], v[116:119], off
	v_pk_mul_f32 v[104:105], v[104:105], v[96:97]
	v_pk_mul_f32 v[108:109], v[108:109], v[100:101]
	v_mul_f32_e32 v116, 0xbfb8aa3b, v122
	v_pk_mul_f32 v[96:97], v[96:97], v[116:117] op_sel_hi:[1,0]
	v_pk_mul_f32 v[100:101], v[100:101], v[116:117] op_sel_hi:[1,0]
	v_pk_mul_f32 v[106:107], v[106:107], v[98:99]
	v_exp_f32_e32 v96, v96
	v_exp_f32_e32 v97, v97
	v_pk_mul_f32 v[98:99], v[98:99], v[116:117] op_sel_hi:[1,0]
	v_exp_f32_e32 v100, v100
	v_exp_f32_e32 v101, v101
	v_exp_f32_e32 v98, v98
	v_exp_f32_e32 v99, v99
	v_pk_add_f32 v[96:97], v[96:97], 1.0 op_sel_hi:[1,0]
	v_pk_add_f32 v[100:101], v[100:101], 1.0 op_sel_hi:[1,0]
	v_rcp_f32_e32 v96, v96
	v_rcp_f32_e32 v97, v97
	v_pk_add_f32 v[98:99], v[98:99], 1.0 op_sel_hi:[1,0]
	v_rcp_f32_e32 v100, v100
	v_rcp_f32_e32 v101, v101
	v_rcp_f32_e32 v98, v98
	v_rcp_f32_e32 v99, v99
	v_mul_f32_e32 v118, v122, v122
	v_pk_mul_f32 v[104:105], v[104:105], v[118:119] op_sel_hi:[1,0]
	v_pk_mul_f32 v[108:109], v[108:109], v[118:119] op_sel_hi:[1,0]
	v_pk_mul_f32 v[104:105], v[104:105], v[96:97]
	v_pk_mul_f32 v[96:97], v[106:107], v[118:119] op_sel_hi:[1,0]
	v_pk_mul_f32 v[100:101], v[108:109], v[100:101]
	v_pk_mul_f32 v[106:107], v[96:97], v[98:99]
	v_pk_mul_f32 v[110:111], v[110:111], v[102:103]
	v_pk_mul_f32 v[102:103], v[102:103], v[116:117] op_sel_hi:[1,0]
	v_cvt_pk_bf16_f32 v96, v100, v101
	v_exp_f32_e32 v102, v102
	v_exp_f32_e32 v103, v103
	s_nop 0
	v_pk_add_f32 v[102:103], v[102:103], 1.0 op_sel_hi:[1,0]
	v_rcp_f32_e32 v102, v102
	v_rcp_f32_e32 v103, v103
	v_pk_mul_f32 v[108:109], v[110:111], v[118:119] op_sel_hi:[1,0]
	v_pk_mul_f32 v[102:103], v[108:109], v[102:103]
	v_cvt_f32_u32_e32 v166, v166
	v_cvt_f32_u32_e32 v167, v167
	v_fmamk_f32 v166, v167, 0x4f800000, v166
	v_fmamk_f32 v100, v166, 0x26800000, v180
	v_cvt_pk_bf16_f32 v97, v102, v103
	v_rsq_f32_e32 v102, v100
	v_mad_i64_i32 v[100:101], s[56:57], v185, s69, v[112:113]
	v_lshl_add_u64 v[100:101], v[100:101], 0, v[114:115]
	v_cvt_pk_bf16_f32 v98, v104, v105
	v_cvt_pk_bf16_f32 v99, v106, v107
	global_store_dwordx4 v[100:101], v[96:99], off
	v_pk_mul_f32 v[88:89], v[88:89], v[80:81]
	v_pk_mul_f32 v[92:93], v[92:93], v[84:85]
	v_mul_f32_e32 v96, 0xbfb8aa3b, v102
	v_pk_mul_f32 v[80:81], v[80:81], v[96:97] op_sel_hi:[1,0]
	v_pk_mul_f32 v[84:85], v[84:85], v[96:97] op_sel_hi:[1,0]
	v_pk_mul_f32 v[90:91], v[90:91], v[82:83]
	v_exp_f32_e32 v80, v80
	v_exp_f32_e32 v81, v81
	v_pk_mul_f32 v[82:83], v[82:83], v[96:97] op_sel_hi:[1,0]
	v_exp_f32_e32 v84, v84
	v_exp_f32_e32 v85, v85
	v_exp_f32_e32 v82, v82
	v_exp_f32_e32 v83, v83
	v_pk_add_f32 v[80:81], v[80:81], 1.0 op_sel_hi:[1,0]
	v_pk_add_f32 v[84:85], v[84:85], 1.0 op_sel_hi:[1,0]
	v_rcp_f32_e32 v80, v80
	v_rcp_f32_e32 v81, v81
	v_pk_add_f32 v[82:83], v[82:83], 1.0 op_sel_hi:[1,0]
	v_rcp_f32_e32 v84, v84
	v_rcp_f32_e32 v85, v85
	v_rcp_f32_e32 v82, v82
	v_rcp_f32_e32 v83, v83
	v_mul_f32_e32 v98, v102, v102
	v_pk_mul_f32 v[88:89], v[88:89], v[98:99] op_sel_hi:[1,0]
	v_pk_mul_f32 v[92:93], v[92:93], v[98:99] op_sel_hi:[1,0]
	v_pk_mul_f32 v[88:89], v[88:89], v[80:81]
	v_pk_mul_f32 v[80:81], v[90:91], v[98:99] op_sel_hi:[1,0]
; __device__ __forceinline__ unsigned cvt_pk_bf16(float lo, float hi) { unsigned r; asm volatile("v_cvt_pk_bf16_f32 %0, %1, %2" : "=v"(r) : "v"(lo), "v"(hi)); return r; }
; __device__ __forceinline__ float ss_val(u64 v) { return (float)v * (1.0f / 1099511627776.0f); }
;     __device__ __forceinline__ void operator()(const f32x4 (&acc)[2][2][4][2], const Unit& u, const Unit& nxt, bool has_next, int wr, int wc, int fr, int fq) const {
;     ...
; #pragma unroll
;         for (int g = 0; g < 8; ++g) {
;             const int ai = g >> 2, m = g & 3;
;             const float rs = __builtin_amdgcn_rsqf(ss_val(cur[g]) * inv_k + eps), rsn = rs * -1.44269504089f, rs2 = rs * rs;
;             float h[8];
; #pragma unroll
;             for (int n = 0; n < 2; ++n)
; #pragma unroll
;                 for (int jp = 0; jp < 2; ++jp) {
;                     const f32x2v av = {acc[ai][0][m][n][2 * jp], acc[ai][0][m][n][2 * jp + 1]}, gv = {acc[ai][1][m][n][2 * jp], acc[ai][1][m][n][2 * jp + 1]};
;                     const f32x2v t = (av * gv) * rs2, y = gv * rsn;
;                     f32x2v ex; ex.x = __builtin_amdgcn_exp2f(y.x); ex.y = __builtin_amdgcn_exp2f(y.y);
;                     const f32x2v d = ex + 1.0f;
;                     f32x2v r; r.x = __builtin_amdgcn_rcpf(d.x); r.y = __builtin_amdgcn_rcpf(d.y);
;                     const f32x2v o = t * r;
;                     h[4 * n + 2 * jp] = o.x; h[4 * n + 2 * jp + 1] = o.y;
;                 }
;             u32x4 w; w.x = cvt_pk_bf16(h[0], h[1]); w.y = cvt_pk_bf16(h[2], h[3]); w.z = cvt_pk_bf16(h[4], h[5]); w.w = cvt_pk_bf16(h[6], h[7]);
;             *(u32x4*)(O + (size_t)(row0 + ai * HALF + m * 16) * ldc + col0) = w;
;         }
	v_pk_mul_f32 v[84:85], v[92:93], v[84:85]
	v_pk_mul_f32 v[90:91], v[80:81], v[82:83]
	v_pk_mul_f32 v[94:95], v[94:95], v[86:87]
	v_pk_mul_f32 v[86:87], v[86:87], v[96:97] op_sel_hi:[1,0]
	v_cvt_pk_bf16_f32 v80, v84, v85
	v_exp_f32_e32 v86, v86
	v_exp_f32_e32 v87, v87
	s_nop 0
	v_pk_add_f32 v[86:87], v[86:87], 1.0 op_sel_hi:[1,0]
	v_rcp_f32_e32 v86, v86
	v_rcp_f32_e32 v87, v87
	v_pk_mul_f32 v[92:93], v[94:95], v[98:99] op_sel_hi:[1,0]
	v_pk_mul_f32 v[86:87], v[92:93], v[86:87]
	v_cvt_f32_u32_e32 v164, v164
	v_cvt_f32_u32_e32 v165, v165
	v_fmamk_f32 v164, v165, 0x4f800000, v164
	v_fmamk_f32 v84, v164, 0x26800000, v180
	v_cvt_pk_bf16_f32 v81, v86, v87
	v_rsq_f32_e32 v86, v84
	v_mad_i64_i32 v[84:85], s[56:57], v187, s69, v[112:113]
	v_lshl_add_u64 v[84:85], v[84:85], 0, v[114:115]
	v_cvt_pk_bf16_f32 v82, v88, v89
	v_cvt_pk_bf16_f32 v83, v90, v91
	global_store_dwordx4 v[84:85], v[80:83], off
	v_pk_mul_f32 v[72:73], v[72:73], v[64:65]
	v_pk_mul_f32 v[76:77], v[76:77], v[68:69]
	v_mul_f32_e32 v80, 0xbfb8aa3b, v86
	v_pk_mul_f32 v[64:65], v[64:65], v[80:81] op_sel_hi:[1,0]
	v_pk_mul_f32 v[68:69], v[68:69], v[80:81] op_sel_hi:[1,0]
	v_pk_mul_f32 v[74:75], v[74:75], v[66:67]
	v_exp_f32_e32 v64, v64
	v_exp_f32_e32 v65, v65
	v_pk_mul_f32 v[66:67], v[66:67], v[80:81] op_sel_hi:[1,0]
	v_exp_f32_e32 v68, v68
	v_exp_f32_e32 v69, v69
	v_exp_f32_e32 v66, v66
	v_exp_f32_e32 v67, v67
	v_pk_add_f32 v[64:65], v[64:65], 1.0 op_sel_hi:[1,0]
	v_pk_add_f32 v[68:69], v[68:69], 1.0 op_sel_hi:[1,0]
	v_rcp_f32_e32 v64, v64
	v_rcp_f32_e32 v65, v65
	v_pk_add_f32 v[66:67], v[66:67], 1.0 op_sel_hi:[1,0]
	v_rcp_f32_e32 v68, v68
	v_rcp_f32_e32 v69, v69
	v_rcp_f32_e32 v66, v66
	v_rcp_f32_e32 v67, v67
	v_mul_f32_e32 v82, v86, v86
	v_pk_mul_f32 v[72:73], v[72:73], v[82:83] op_sel_hi:[1,0]
	v_pk_mul_f32 v[76:77], v[76:77], v[82:83] op_sel_hi:[1,0]
	v_pk_mul_f32 v[72:73], v[72:73], v[64:65]
	v_pk_mul_f32 v[64:65], v[74:75], v[82:83] op_sel_hi:[1,0]
	v_pk_mul_f32 v[68:69], v[76:77], v[68:69]
	v_pk_mul_f32 v[74:75], v[64:65], v[66:67]
	v_pk_mul_f32 v[78:79], v[78:79], v[70:71]
	v_pk_mul_f32 v[70:71], v[70:71], v[80:81] op_sel_hi:[1,0]
	v_cvt_pk_bf16_f32 v64, v68, v69
	v_exp_f32_e32 v70, v70
	v_exp_f32_e32 v71, v71
	s_nop 0
	v_pk_add_f32 v[70:71], v[70:71], 1.0 op_sel_hi:[1,0]
	v_rcp_f32_e32 v70, v70
	v_rcp_f32_e32 v71, v71
	v_pk_mul_f32 v[76:77], v[78:79], v[82:83] op_sel_hi:[1,0]
	v_pk_mul_f32 v[70:71], v[76:77], v[70:71]
	v_cvt_f32_u32_e32 v162, v162
	v_cvt_f32_u32_e32 v163, v163
	v_fmamk_f32 v162, v163, 0x4f800000, v162
	v_fmamk_f32 v68, v162, 0x26800000, v180
	v_cvt_pk_bf16_f32 v65, v70, v71
	v_rsq_f32_e32 v70, v68
	v_or_b32_e32 v188, 48, v168
	v_mad_i64_i32 v[68:69], s[56:57], v188, s69, v[112:113]
	v_lshl_add_u64 v[68:69], v[68:69], 0, v[114:115]
	v_cvt_pk_bf16_f32 v66, v72, v73
	v_cvt_pk_bf16_f32 v67, v74, v75
	global_store_dwordx4 v[68:69], v[64:67], off
	v_pk_mul_f32 v[56:57], v[56:57], v[48:49]
	v_pk_mul_f32 v[60:61], v[60:61], v[52:53]
	v_mul_f32_e32 v64, 0xbfb8aa3b, v70
	v_pk_mul_f32 v[48:49], v[48:49], v[64:65] op_sel_hi:[1,0]
	v_pk_mul_f32 v[52:53], v[52:53], v[64:65] op_sel_hi:[1,0]
	v_pk_mul_f32 v[58:59], v[58:59], v[50:51]
	v_exp_f32_e32 v48, v48
	v_exp_f32_e32 v49, v49
	v_pk_mul_f32 v[50:51], v[50:51], v[64:65] op_sel_hi:[1,0]
	v_exp_f32_e32 v52, v52
	v_exp_f32_e32 v53, v53
	v_exp_f32_e32 v50, v50
	v_exp_f32_e32 v51, v51
	v_pk_add_f32 v[48:49], v[48:49], 1.0 op_sel_hi:[1,0]
	v_pk_add_f32 v[52:53], v[52:53], 1.0 op_sel_hi:[1,0]
	v_rcp_f32_e32 v48, v48
	v_rcp_f32_e32 v49, v49
	v_pk_add_f32 v[50:51], v[50:51], 1.0 op_sel_hi:[1,0]
	v_rcp_f32_e32 v52, v52
	v_rcp_f32_e32 v53, v53
	v_rcp_f32_e32 v50, v50
	v_rcp_f32_e32 v51, v51
	v_mul_f32_e32 v66, v70, v70
	v_pk_mul_f32 v[56:57], v[56:57], v[66:67] op_sel_hi:[1,0]
	v_pk_mul_f32 v[60:61], v[60:61], v[66:67] op_sel_hi:[1,0]
	v_pk_mul_f32 v[56:57], v[56:57], v[48:49]
	v_pk_mul_f32 v[48:49], v[58:59], v[66:67] op_sel_hi:[1,0]
	v_pk_mul_f32 v[52:53], v[60:61], v[52:53]
	v_pk_mul_f32 v[58:59], v[48:49], v[50:51]
	v_pk_mul_f32 v[62:63], v[62:63], v[54:55]
	v_pk_mul_f32 v[54:55], v[54:55], v[64:65] op_sel_hi:[1,0]
	v_cvt_pk_bf16_f32 v48, v52, v53
	v_exp_f32_e32 v54, v54
	v_exp_f32_e32 v55, v55
	s_nop 0
	v_pk_add_f32 v[54:55], v[54:55], 1.0 op_sel_hi:[1,0]
	v_rcp_f32_e32 v54, v54
	v_rcp_f32_e32 v55, v55
	v_pk_mul_f32 v[60:61], v[62:63], v[66:67] op_sel_hi:[1,0]
	v_pk_mul_f32 v[54:55], v[60:61], v[54:55]
	v_cvt_f32_u32_e32 v160, v160
	v_cvt_f32_u32_e32 v161, v161
	v_fmamk_f32 v160, v161, 0x4f800000, v160
	v_fmamk_f32 v52, v160, 0x26800000, v180
	v_cvt_pk_bf16_f32 v49, v54, v55
	v_rsq_f32_e32 v54, v52
	v_add_u32_e32 v181, 0x80, v168
	v_mad_i64_i32 v[52:53], s[56:57], v181, s69, v[112:113]
	v_lshl_add_u64 v[52:53], v[52:53], 0, v[114:115]
	v_cvt_pk_bf16_f32 v50, v56, v57
	v_cvt_pk_bf16_f32 v51, v58, v59
	global_store_dwordx4 v[52:53], v[48:51], off
	v_pk_mul_f32 v[40:41], v[40:41], v[32:33]
	v_pk_mul_f32 v[44:45], v[44:45], v[36:37]
	v_mul_f32_e32 v48, 0xbfb8aa3b, v54
	v_pk_mul_f32 v[32:33], v[32:33], v[48:49] op_sel_hi:[1,0]
	v_pk_mul_f32 v[36:37], v[36:37], v[48:49] op_sel_hi:[1,0]
	v_pk_mul_f32 v[42:43], v[42:43], v[34:35]
	v_exp_f32_e32 v32, v32
	v_exp_f32_e32 v33, v33
	v_pk_mul_f32 v[34:35], v[34:35], v[48:49] op_sel_hi:[1,0]
	v_exp_f32_e32 v36, v36
	v_exp_f32_e32 v37, v37
	v_exp_f32_e32 v34, v34
	v_exp_f32_e32 v35, v35
	v_pk_add_f32 v[32:33], v[32:33], 1.0 op_sel_hi:[1,0]
	v_pk_add_f32 v[36:37], v[36:37], 1.0 op_sel_hi:[1,0]
; __device__ __forceinline__ unsigned cvt_pk_bf16(float lo, float hi) { unsigned r; asm volatile("v_cvt_pk_bf16_f32 %0, %1, %2" : "=v"(r) : "v"(lo), "v"(hi)); return r; }
; __device__ __forceinline__ float ss_val(u64 v) { return (float)v * (1.0f / 1099511627776.0f); }
;     __device__ __forceinline__ void operator()(const f32x4 (&acc)[2][2][4][2], const Unit& u, const Unit& nxt, bool has_next, int wr, int wc, int fr, int fq) const {
;     ...
; #pragma unroll
;         for (int g = 0; g < 8; ++g) {
;             const int ai = g >> 2, m = g & 3;
;             const float rs = __builtin_amdgcn_rsqf(ss_val(cur[g]) * inv_k + eps), rsn = rs * -1.44269504089f, rs2 = rs * rs;
;             float h[8];
; #pragma unroll
;             for (int n = 0; n < 2; ++n)
; #pragma unroll
;                 for (int jp = 0; jp < 2; ++jp) {
;                     const f32x2v av = {acc[ai][0][m][n][2 * jp], acc[ai][0][m][n][2 * jp + 1]}, gv = {acc[ai][1][m][n][2 * jp], acc[ai][1][m][n][2 * jp + 1]};
;                     const f32x2v t = (av * gv) * rs2, y = gv * rsn;
;                     f32x2v ex; ex.x = __builtin_amdgcn_exp2f(y.x); ex.y = __builtin_amdgcn_exp2f(y.y);
;                     const f32x2v d = ex + 1.0f;
;                     f32x2v r; r.x = __builtin_amdgcn_rcpf(d.x); r.y = __builtin_amdgcn_rcpf(d.y);
;                     const f32x2v o = t * r;
;                     h[4 * n + 2 * jp] = o.x; h[4 * n + 2 * jp + 1] = o.y;
;                 }
;             u32x4 w; w.x = cvt_pk_bf16(h[0], h[1]); w.y = cvt_pk_bf16(h[2], h[3]); w.z = cvt_pk_bf16(h[4], h[5]); w.w = cvt_pk_bf16(h[6], h[7]);
;             *(u32x4*)(O + (size_t)(row0 + ai * HALF + m * 16) * ldc + col0) = w;
;         }
	v_rcp_f32_e32 v32, v32
	v_rcp_f32_e32 v33, v33
	v_pk_add_f32 v[34:35], v[34:35], 1.0 op_sel_hi:[1,0]
	v_rcp_f32_e32 v36, v36
	v_rcp_f32_e32 v37, v37
	v_rcp_f32_e32 v34, v34
	v_rcp_f32_e32 v35, v35
	v_mul_f32_e32 v50, v54, v54
	v_pk_mul_f32 v[40:41], v[40:41], v[50:51] op_sel_hi:[1,0]
	v_pk_mul_f32 v[44:45], v[44:45], v[50:51] op_sel_hi:[1,0]
	v_pk_mul_f32 v[40:41], v[40:41], v[32:33]
	v_pk_mul_f32 v[32:33], v[42:43], v[50:51] op_sel_hi:[1,0]
	v_pk_mul_f32 v[36:37], v[44:45], v[36:37]
	v_pk_mul_f32 v[42:43], v[32:33], v[34:35]
	v_pk_mul_f32 v[46:47], v[46:47], v[38:39]
	v_pk_mul_f32 v[38:39], v[38:39], v[48:49] op_sel_hi:[1,0]
	v_cvt_pk_bf16_f32 v32, v36, v37
	v_exp_f32_e32 v38, v38
	v_exp_f32_e32 v39, v39
	s_nop 0
	v_pk_add_f32 v[38:39], v[38:39], 1.0 op_sel_hi:[1,0]
	v_rcp_f32_e32 v38, v38
	v_rcp_f32_e32 v39, v39
	v_pk_mul_f32 v[44:45], v[46:47], v[50:51] op_sel_hi:[1,0]
	v_pk_mul_f32 v[38:39], v[44:45], v[38:39]
	v_cvt_f32_u32_e32 v158, v158
	v_cvt_f32_u32_e32 v159, v159
	v_fmamk_f32 v158, v159, 0x4f800000, v158
	v_fmamk_f32 v36, v158, 0x26800000, v180
	v_cvt_pk_bf16_f32 v33, v38, v39
	v_rsq_f32_e32 v38, v36
	v_add_u32_e32 v173, 0x90, v168
	v_mad_i64_i32 v[36:37], s[56:57], v173, s69, v[112:113]
	v_lshl_add_u64 v[36:37], v[36:37], 0, v[114:115]
	v_cvt_pk_bf16_f32 v34, v40, v41
	v_cvt_pk_bf16_f32 v35, v42, v43
	global_store_dwordx4 v[36:37], v[32:35], off
	v_pk_mul_f32 v[24:25], v[24:25], v[16:17]
	v_pk_mul_f32 v[28:29], v[28:29], v[20:21]
	v_mul_f32_e32 v32, 0xbfb8aa3b, v38
	v_pk_mul_f32 v[16:17], v[16:17], v[32:33] op_sel_hi:[1,0]
	v_pk_mul_f32 v[20:21], v[20:21], v[32:33] op_sel_hi:[1,0]
	v_pk_mul_f32 v[26:27], v[26:27], v[18:19]
	v_exp_f32_e32 v16, v16
	v_exp_f32_e32 v17, v17
	v_pk_mul_f32 v[18:19], v[18:19], v[32:33] op_sel_hi:[1,0]
	v_exp_f32_e32 v20, v20
	v_exp_f32_e32 v21, v21
	v_exp_f32_e32 v18, v18
	v_exp_f32_e32 v19, v19
	v_pk_add_f32 v[16:17], v[16:17], 1.0 op_sel_hi:[1,0]
	v_pk_add_f32 v[20:21], v[20:21], 1.0 op_sel_hi:[1,0]
	v_rcp_f32_e32 v16, v16
	v_rcp_f32_e32 v17, v17
	v_pk_add_f32 v[18:19], v[18:19], 1.0 op_sel_hi:[1,0]
	v_rcp_f32_e32 v20, v20
	v_rcp_f32_e32 v21, v21
	v_rcp_f32_e32 v18, v18
	v_rcp_f32_e32 v19, v19
	v_mul_f32_e32 v34, v38, v38
	v_pk_mul_f32 v[24:25], v[24:25], v[34:35] op_sel_hi:[1,0]
	v_pk_mul_f32 v[28:29], v[28:29], v[34:35] op_sel_hi:[1,0]
	v_pk_mul_f32 v[24:25], v[24:25], v[16:17]
	v_pk_mul_f32 v[16:17], v[26:27], v[34:35] op_sel_hi:[1,0]
	v_pk_mul_f32 v[20:21], v[28:29], v[20:21]
	v_pk_mul_f32 v[26:27], v[16:17], v[18:19]
	v_pk_mul_f32 v[30:31], v[30:31], v[22:23]
	v_pk_mul_f32 v[22:23], v[22:23], v[32:33] op_sel_hi:[1,0]
	v_cvt_pk_bf16_f32 v16, v20, v21
	v_exp_f32_e32 v22, v22
	v_exp_f32_e32 v23, v23
	s_nop 0
	v_pk_add_f32 v[22:23], v[22:23], 1.0 op_sel_hi:[1,0]
	v_rcp_f32_e32 v22, v22
	v_rcp_f32_e32 v23, v23
	v_pk_mul_f32 v[28:29], v[30:31], v[34:35] op_sel_hi:[1,0]
	v_pk_mul_f32 v[22:23], v[28:29], v[22:23]
	v_cvt_f32_u32_e32 v156, v156
	v_cvt_f32_u32_e32 v157, v157
	v_fmamk_f32 v156, v157, 0x4f800000, v156
	v_fmamk_f32 v20, v156, 0x26800000, v180
	v_cvt_pk_bf16_f32 v17, v22, v23
	v_rsq_f32_e32 v22, v20
	v_add_u32_e32 v172, 0xa0, v168
	v_mad_i64_i32 v[20:21], s[56:57], v172, s69, v[112:113]
	v_lshl_add_u64 v[20:21], v[20:21], 0, v[114:115]
	v_cvt_pk_bf16_f32 v18, v24, v25
	v_cvt_pk_bf16_f32 v19, v26, v27
	global_store_dwordx4 v[20:21], v[16:19], off
	v_pk_mul_f32 v[12:13], v[12:13], v[4:5]
	v_pk_mul_f32 v[8:9], v[8:9], v[0:1]
	v_mul_f32_e32 v16, 0xbfb8aa3b, v22
	v_pk_mul_f32 v[4:5], v[4:5], v[16:17] op_sel_hi:[1,0]
	v_pk_mul_f32 v[0:1], v[0:1], v[16:17] op_sel_hi:[1,0]
	v_exp_f32_e32 v4, v4
	v_exp_f32_e32 v5, v5
	v_pk_mul_f32 v[10:11], v[10:11], v[2:3]
	v_exp_f32_e32 v0, v0
	v_exp_f32_e32 v1, v1
	v_pk_mul_f32 v[2:3], v[2:3], v[16:17] op_sel_hi:[1,0]
	v_pk_mul_f32 v[14:15], v[14:15], v[6:7]
	v_exp_f32_e32 v2, v2
	v_exp_f32_e32 v3, v3
	v_pk_mul_f32 v[6:7], v[6:7], v[16:17] op_sel_hi:[1,0]
	v_pk_add_f32 v[4:5], v[4:5], 1.0 op_sel_hi:[1,0]
	v_exp_f32_e32 v6, v6
	v_exp_f32_e32 v7, v7
	v_pk_add_f32 v[0:1], v[0:1], 1.0 op_sel_hi:[1,0]
	v_rcp_f32_e32 v4, v4
	v_rcp_f32_e32 v5, v5
	v_rcp_f32_e32 v0, v0
	v_rcp_f32_e32 v1, v1
	v_pk_add_f32 v[2:3], v[2:3], 1.0 op_sel_hi:[1,0]
	v_mul_f32_e32 v18, v22, v22
	v_rcp_f32_e32 v2, v2
	v_rcp_f32_e32 v3, v3
	v_pk_add_f32 v[6:7], v[6:7], 1.0 op_sel_hi:[1,0]
	v_pk_mul_f32 v[12:13], v[12:13], v[18:19] op_sel_hi:[1,0]
	v_rcp_f32_e32 v6, v6
	v_rcp_f32_e32 v7, v7
	v_pk_mul_f32 v[8:9], v[8:9], v[18:19] op_sel_hi:[1,0]
	v_add_u32_e32 v169, 0xb0, v168
	v_pk_mul_f32 v[4:5], v[12:13], v[4:5]
	v_pk_mul_f32 v[8:9], v[8:9], v[0:1]
	v_pk_mul_f32 v[0:1], v[10:11], v[18:19] op_sel_hi:[1,0]
	v_pk_mul_f32 v[12:13], v[14:15], v[18:19] op_sel_hi:[1,0]
	v_pk_mul_f32 v[10:11], v[0:1], v[2:3]
	v_cvt_pk_bf16_f32 v0, v4, v5
	v_mad_i64_i32 v[4:5], s[56:57], v169, s69, v[112:113]
	v_lshl_add_u64 v[4:5], v[4:5], 0, v[114:115]
	s_and_b64 vcc, exec, s[2:3]
	s_mov_b64 s[2:3], -1
	v_pk_mul_f32 v[6:7], v[12:13], v[6:7]
	s_nop 0
	v_cvt_pk_bf16_f32 v1, v6, v7
	v_cvt_pk_bf16_f32 v2, v8, v9
	v_cvt_pk_bf16_f32 v3, v10, v11
	global_store_dwordx4 v[4:5], v[0:3], off
	s_cbranch_vccnz .LBB0_171
	s_nop 0
	v_or_b32_e32 v0, v155, v153
	v_or_b32_e32 v1, v154, v152
	v_or3_b32 v0, v0, v149, v151
	v_or3_b32 v1, v1, v148, v150
	v_or3_b32 v0, v0, v145, v147
	v_or3_b32 v1, v1, v144, v146
	s_andn2_b64 vcc, exec, s[4:5]
	v_or3_b32 v0, v0, v141, v143
	v_or3_b32 v1, v1, v140, v142
	s_cbranch_vccnz .LBB0_170
	s_barrier
	s_branch .LBB0_170

; #define SEAM(k) do { if (IN(k) && IN((k) + 1)) xcd_barrier(bar); } while (0)
; template <int L>
; __device__ __forceinline__ void layer(const Args& a, LAS unsigned char* lds, const XcdBarrier& bar, int lo, int hi, int wave, int lane, int b, int r, int GS) {
;     ...
;     SEAM(P + 0);
;     if (IN(P + 1)) {
;         pg8::Gemm g{HB, (const bf16*)(wl + W2_OFF), SEQ, D, DFF}; pg8::GroupOrder S; S.init(SEQ, D, GS, r);
;         pg8::EpiResid E{nullptr, XN, rowss + (size_t)(3 * L + 1) * M, 0.5f, D};
;         pg8::gemm_phase<pg8::EpiResid, pg8::GroupOrder, true, true>(lds, g, S, E);
.LBB0_184:
	s_cmp_gt_i32 s53, 2
	s_cselect_b64 s[2:3], -1, 0
	s_and_b64 s[0:1], s[0:1], s[2:3]
	s_andn2_b64 vcc, exec, s[0:1]
	s_cbranch_vccnz .LBB0_229
	s_waitcnt vmcnt(0)
	s_barrier
	s_cmp_eq_u32 s97, 0
	s_cbranch_scc1 .Lbpf_skip_0
	v_mov_b32_e32 v232, s95
	v_mul_u32_u24_e32 v232, 7, v232
	v_add_u32_e32 v232, s97, v232
	v_add_u32_e32 v232, -1, v232
	v_lshl_add_u32 v232, v232, 6, v200
	v_lshrrev_b32_e32 v231, 1, v232
	v_min_u32_e32 v231, 0x3ff, v231
	v_mul_u32_u24_e32 v231, 0x1600, v231
	v_and_b32_e32 v232, 1, v232
	v_lshlrev_b32_e32 v232, 7, v232
	v_add_u32_e32 v232, v231, v232
	v_add_u32_e32 v232, 0x1300000, v232
	global_load_dword v231, v232, s[34:35]
.Lbpf_skip_0:
	s_and_saveexec_b64 s[0:1], s[8:9]
	s_cbranch_execz .LBB0_228
	v_mov_b32_e32 v0, s92
	s_waitcnt vmcnt(0) expcnt(0) lgkmcnt(0)
	ds_read_b32 v2, v0
	ds_read_b32 v0, v0 offset:4
	s_waitcnt lgkmcnt(1)
	v_cmp_ne_u32_e32 vcc, 0, v2
	s_cbranch_vccnz .LBB0_199
	s_add_u32 s4, s54, 0x1000
	s_addc_u32 s5, s55, 0
	s_add_u32 s36, s54, 0x1100
	s_addc_u32 s37, s55, 0
	s_add_u32 s38, s54, 0x1200
	s_addc_u32 s39, s55, 0
	s_add_u32 s40, s54, 0x1300
	s_addc_u32 s41, s55, 0
	s_mov_b32 s11, 1
	v_mov_b32_e32 v16, 0
	s_branch .LBB0_189

; #define SEAM(k) do { if (IN(k) && IN((k) + 1)) xcd_barrier(bar); } while (0)
; template <int L>
; __device__ __forceinline__ void layer(const Args& a, LAS unsigned char* lds, const XcdBarrier& bar, int lo, int hi, int wave, int lane, int b, int r, int GS) {
;     ...
;     SEAM(P + 1);
;     if (IN(P + 2)) {
;         pg8::Gemm g{XN, (const bf16*)(wl + WIN_OFF), SEQ, 2560, D}; pg8::GroupOrder S; S.init(SEQ, 2560, GS, r);
;         pg8::EpiProj E{HB, NPROJ, rowss + (size_t)(3 * L + 1) * M, rowss + (size_t)(7 + L) * M, RB, 1.f / D, EPS};
;         pg8::gemm_phase<pg8::EpiProj, pg8::GroupOrder, true, true>(lds, g, S, E);
.LBB0_268:
	s_cmp_gt_i32 s53, 3
	s_cselect_b64 s[2:3], -1, 0
	s_and_b64 s[0:1], s[0:1], s[2:3]
	s_andn2_b64 vcc, exec, s[0:1]
	s_cbranch_vccnz .LBB0_313
	s_waitcnt vmcnt(0)
	s_waitcnt lgkmcnt(0)
	s_barrier
	s_cmp_eq_u32 s97, 0
	s_cbranch_scc1 .Lbpf_skip_1
	v_mov_b32_e32 v232, s95
	v_mul_u32_u24_e32 v232, 7, v232
	v_add_u32_e32 v232, s97, v232
	v_add_u32_e32 v232, -1, v232
	v_lshl_add_u32 v232, v232, 6, v200
	v_lshrrev_b32_e32 v231, 1, v232
	v_min_u32_e32 v231, 0x9ff, v231
	v_mul_u32_u24_e32 v231, 0x800, v231
	v_and_b32_e32 v232, 1, v232
	v_lshlrev_b32_e32 v232, 7, v232
	v_add_u32_e32 v232, v231, v232
	v_add_u32_e32 v232, 0x1880000, v232
	global_load_dword v231, v232, s[34:35]

; __device__ __forceinline__ unsigned cvt_pk_bf16(float lo, float hi) { unsigned r; asm volatile("v_cvt_pk_bf16_f32 %0, %1, %2" : "=v"(r) : "v"(lo), "v"(hi)); return r; }
; __device__ __forceinline__ u64 ss_fix(float s) { return (u64)(s * 1099511627776.0f); }
; __device__ __forceinline__ float ss_val(u64 v) { return (float)v * (1.0f / 1099511627776.0f); }
;     __device__ __forceinline__ void operator()(const f32x4 (&acc)[2][2][4][2], const Unit& u, const Unit&, bool, int wr, int wc, int fr, int fq) const {
;     ...
;         for (int ai = 0; ai < 2; ++ai)
; #pragma unroll
;             for (int m = 0; m < 4; ++m) {
;                 const int row = row0 + ai * HALF + m * 16;
;                 const float rs = __builtin_amdgcn_rsqf(ss_val(cur[ai * 4 + m]) * inv_k + eps);
;                 float ss = 0.f;
; #pragma unroll
;                 for (int bj = 0; bj < 2; ++bj) {
;                     const f32x4 v0 = acc[ai][bj][m][0] * rs, v1 = acc[ai][bj][m][1] * rs;
;                     ss += (v0[0] * v0[0] + v0[1] * v0[1]) + (v0[2] * v0[2] + v0[3] * v0[3]) + (v1[0] * v1[0] + v1[1] * v1[1]) + (v1[2] * v1[2] + v1[3] * v1[3]);
;                     u32x4 w; w.x = cvt_pk_bf16(v0[0], v0[1]); w.y = cvt_pk_bf16(v0[2], v0[3]); w.z = cvt_pk_bf16(v1[0], v1[1]); w.w = cvt_pk_bf16(v1[2], v1[3]);
;                     *(u32x4*)(O + (size_t)row * ldc + col0 + bj * HALF) = w;
;                 }
;                 if (is_va) { ss += __shfl_xor(ss, 16); ss += __shfl_xor(ss, 32); if (fq == 0) atomicAdd(rowss_v + row, ss_fix(ss)); }
.LBB0_332:
	s_waitcnt lgkmcnt(0)
	v_mov_b64_e32 v[120:121], s[24:25]
	s_andn2_b64 vcc, exec, s[70:71]
	v_cvt_f32_u32_e32 v156, v156
	v_cvt_f32_u32_e32 v157, v157
	v_fmamk_f32 v156, v157, 0x4f800000, v156
	v_fmamk_f32 v112, v156, 0x26800000, v165
	v_rsq_f32_e32 v118, v112
	v_or_b32_e32 v112, 16, v142
	v_mad_i64_i32 v[120:121], s[4:5], v112, s81, v[120:121]
	v_cndmask_b32_e64 v113, 0, 1, s[70:71]
	v_pk_mul_f32 v[110:111], v[110:111], v[118:119] op_sel_hi:[1,0]
	v_pk_mul_f32 v[108:109], v[108:109], v[118:119] op_sel_hi:[1,0]
	v_pk_mul_f32 v[106:107], v[106:107], v[118:119] op_sel_hi:[1,0]
	v_pk_mul_f32 v[104:105], v[104:105], v[118:119] op_sel_hi:[1,0]
	v_cvt_pk_bf16_f32 v114, v108, v109
	v_cvt_pk_bf16_f32 v115, v110, v111
	v_lshl_add_u64 v[120:121], v[140:141], 1, v[120:121]
	v_cvt_pk_bf16_f32 v116, v104, v105
	v_cvt_pk_bf16_f32 v117, v106, v107
	v_pk_mul_f32 v[102:103], v[102:103], v[118:119] op_sel_hi:[1,0]
	v_pk_mul_f32 v[100:101], v[100:101], v[118:119] op_sel_hi:[1,0]
	v_pk_mul_f32 v[98:99], v[98:99], v[118:119] op_sel_hi:[1,0]
	v_pk_mul_f32 v[96:97], v[96:97], v[118:119] op_sel_hi:[1,0]
	v_cmp_ne_u32_e64 s[4:5], 1, v113
	global_store_dwordx4 v[120:121], v[114:117], off
	s_nop 1
	v_cvt_pk_bf16_f32 v114, v100, v101
	v_cvt_pk_bf16_f32 v115, v102, v103
	v_cvt_pk_bf16_f32 v116, v96, v97
	v_cvt_pk_bf16_f32 v117, v98, v99
	global_store_dwordx4 v[120:121], v[114:117], off offset:256
	s_cbranch_vccnz .LBB0_336
	v_mul_f32_e32 v99, v99, v99
	v_fmac_f32_e32 v99, v98, v98
	v_mul_f32_e32 v98, v101, v101
	v_mul_f32_e32 v107, v107, v107
	v_fmac_f32_e32 v98, v100, v100
	v_mul_f32_e32 v100, v103, v103
	v_fmac_f32_e32 v107, v106, v106
	v_mul_f32_e32 v106, v109, v109
	v_fmac_f32_e32 v100, v102, v102
	v_mul_f32_e32 v97, v97, v97
	v_fmac_f32_e32 v106, v108, v108
	v_mul_f32_e32 v108, v111, v111
	v_add_f32_e32 v98, v98, v100
	v_fmac_f32_e32 v97, v96, v96
	v_fmac_f32_e32 v108, v110, v110
	v_mul_f32_e32 v105, v105, v105
	v_add_f32_e32 v96, v97, v98
	v_and_b32_e32 v98, 64, v166
	v_add_f32_e32 v106, v106, v108
	v_fmac_f32_e32 v105, v104, v104
	v_xor_b32_e32 v97, 16, v166
	v_add_u32_e32 v98, 64, v98
	v_add_f32_e32 v104, v105, v106
	v_cmp_lt_i32_e32 vcc, v97, v98
	v_add_f32_e32 v104, v107, v104
	v_add_f32_e32 v96, v99, v96
	v_cndmask_b32_e32 v97, v166, v97, vcc
	v_add_f32_e32 v96, v104, v96
	v_lshlrev_b32_e32 v97, 2, v97
	ds_bpermute_b32 v97, v97, v96
	s_waitcnt lgkmcnt(0)
	v_add_f32_e32 v96, v96, v97
	v_xor_b32_e32 v97, 32, v166
	v_cmp_lt_i32_e32 vcc, v97, v98
	s_nop 1
	v_cndmask_b32_e32 v97, v166, v97, vcc
	v_lshlrev_b32_e32 v97, 2, v97
	ds_bpermute_b32 v97, v97, v96
	s_and_saveexec_b64 s[70:71], s[2:3]
	s_cbranch_execz .LBB0_335
	s_waitcnt lgkmcnt(0)
	v_add_f32_e32 v96, v96, v97
	v_mul_f32_e32 v96, 0x53800000, v96
	v_trunc_f32_e32 v96, v96
	v_mul_f32_e32 v97, 0x2f800000, v96
	v_floor_f32_e32 v97, v97
	v_fmac_f32_e32 v96, 0xcf800000, v97
	v_cvt_u32_f32_e32 v96, v96
	v_cvt_u32_f32_e32 v97, v97
	v_ashrrev_i32_e32 v113, 31, v112
	v_lshl_add_u64 v[98:99], v[112:113], 3, s[50:51]
	global_atomic_add_x2 v[98:99], v[96:97], off

; __device__ __forceinline__ unsigned cvt_pk_bf16(float lo, float hi) { unsigned r; asm volatile("v_cvt_pk_bf16_f32 %0, %1, %2" : "=v"(r) : "v"(lo), "v"(hi)); return r; }
; __device__ __forceinline__ u64 ss_fix(float s) { return (u64)(s * 1099511627776.0f); }
; __device__ __forceinline__ float ss_val(u64 v) { return (float)v * (1.0f / 1099511627776.0f); }
;     __device__ __forceinline__ void operator()(const f32x4 (&acc)[2][2][4][2], const Unit& u, const Unit&, bool, int wr, int wc, int fr, int fq) const {
;     ...
;         for (int ai = 0; ai < 2; ++ai)
; #pragma unroll
;             for (int m = 0; m < 4; ++m) {
;                 const int row = row0 + ai * HALF + m * 16;
;                 const float rs = __builtin_amdgcn_rsqf(ss_val(cur[ai * 4 + m]) * inv_k + eps);
;                 float ss = 0.f;
; #pragma unroll
;                 for (int bj = 0; bj < 2; ++bj) {
;                     const f32x4 v0 = acc[ai][bj][m][0] * rs, v1 = acc[ai][bj][m][1] * rs;
;                     ss += (v0[0] * v0[0] + v0[1] * v0[1]) + (v0[2] * v0[2] + v0[3] * v0[3]) + (v1[0] * v1[0] + v1[1] * v1[1]) + (v1[2] * v1[2] + v1[3] * v1[3]);
;                     u32x4 w; w.x = cvt_pk_bf16(v0[0], v0[1]); w.y = cvt_pk_bf16(v0[2], v0[3]); w.z = cvt_pk_bf16(v1[0], v1[1]); w.w = cvt_pk_bf16(v1[2], v1[3]);
;                     *(u32x4*)(O + (size_t)row * ldc + col0 + bj * HALF) = w;
;                 }
;                 if (is_va) { ss += __shfl_xor(ss, 16); ss += __shfl_xor(ss, 32); if (fq == 0) atomicAdd(rowss_v + row, ss_fix(ss)); }
.LBB0_336:
	s_waitcnt lgkmcnt(0)
	v_mov_b64_e32 v[104:105], s[24:25]
	s_and_b64 vcc, exec, s[4:5]
	v_cvt_f32_u32_e32 v154, v154
	v_cvt_f32_u32_e32 v155, v155
	v_fmamk_f32 v154, v155, 0x4f800000, v154
	v_fmamk_f32 v96, v154, 0x26800000, v165
	v_rsq_f32_e32 v102, v96
	v_or_b32_e32 v96, 32, v142
	v_mad_i64_i32 v[104:105], s[70:71], v96, s81, v[104:105]
	v_pk_mul_f32 v[94:95], v[94:95], v[102:103] op_sel_hi:[1,0]
	v_pk_mul_f32 v[92:93], v[92:93], v[102:103] op_sel_hi:[1,0]
	v_pk_mul_f32 v[90:91], v[90:91], v[102:103] op_sel_hi:[1,0]
	v_pk_mul_f32 v[88:89], v[88:89], v[102:103] op_sel_hi:[1,0]
	v_cvt_pk_bf16_f32 v98, v92, v93
	v_cvt_pk_bf16_f32 v99, v94, v95
	v_lshl_add_u64 v[104:105], v[140:141], 1, v[104:105]
	v_cvt_pk_bf16_f32 v100, v88, v89
	v_cvt_pk_bf16_f32 v101, v90, v91
	v_pk_mul_f32 v[86:87], v[86:87], v[102:103] op_sel_hi:[1,0]
	v_pk_mul_f32 v[84:85], v[84:85], v[102:103] op_sel_hi:[1,0]
	v_pk_mul_f32 v[82:83], v[82:83], v[102:103] op_sel_hi:[1,0]
	v_pk_mul_f32 v[80:81], v[80:81], v[102:103] op_sel_hi:[1,0]
	global_store_dwordx4 v[104:105], v[98:101], off
	s_nop 1
	v_cvt_pk_bf16_f32 v98, v84, v85
	v_cvt_pk_bf16_f32 v99, v86, v87
	v_cvt_pk_bf16_f32 v100, v80, v81
	v_cvt_pk_bf16_f32 v101, v82, v83
	global_store_dwordx4 v[104:105], v[98:101], off offset:256
	s_cbranch_vccnz .LBB0_340
	v_mul_f32_e32 v83, v83, v83
	v_fmac_f32_e32 v83, v82, v82
	v_mul_f32_e32 v82, v85, v85
	v_mul_f32_e32 v91, v91, v91
	v_fmac_f32_e32 v82, v84, v84
	v_mul_f32_e32 v84, v87, v87
	v_fmac_f32_e32 v91, v90, v90
	v_mul_f32_e32 v90, v93, v93
	v_fmac_f32_e32 v84, v86, v86
	v_mul_f32_e32 v81, v81, v81
	v_fmac_f32_e32 v90, v92, v92
	v_mul_f32_e32 v92, v95, v95
	v_add_f32_e32 v82, v82, v84
	v_fmac_f32_e32 v81, v80, v80
	v_fmac_f32_e32 v92, v94, v94
	v_mul_f32_e32 v89, v89, v89
	v_add_f32_e32 v80, v81, v82
	v_and_b32_e32 v82, 64, v166
	v_add_f32_e32 v90, v90, v92
	v_fmac_f32_e32 v89, v88, v88
	v_xor_b32_e32 v81, 16, v166
	v_add_u32_e32 v82, 64, v82
	v_add_f32_e32 v88, v89, v90
	v_cmp_lt_i32_e32 vcc, v81, v82
	v_add_f32_e32 v88, v91, v88
	v_add_f32_e32 v80, v83, v80
	v_cndmask_b32_e32 v81, v166, v81, vcc
	v_add_f32_e32 v80, v88, v80
	v_lshlrev_b32_e32 v81, 2, v81
	ds_bpermute_b32 v81, v81, v80
	s_waitcnt lgkmcnt(0)
	v_add_f32_e32 v80, v80, v81
	v_xor_b32_e32 v81, 32, v166
	v_cmp_lt_i32_e32 vcc, v81, v82
	s_nop 1
	v_cndmask_b32_e32 v81, v166, v81, vcc
	v_lshlrev_b32_e32 v81, 2, v81
	ds_bpermute_b32 v81, v81, v80
	s_and_saveexec_b64 s[70:71], s[2:3]
	s_cbranch_execz .LBB0_339
	s_waitcnt lgkmcnt(0)
	v_add_f32_e32 v80, v80, v81
	v_mul_f32_e32 v80, 0x53800000, v80
	v_trunc_f32_e32 v80, v80
	v_mul_f32_e32 v81, 0x2f800000, v80
	v_floor_f32_e32 v81, v81
	v_fmac_f32_e32 v80, 0xcf800000, v81
	v_cvt_u32_f32_e32 v80, v80
	v_cvt_u32_f32_e32 v81, v81
	v_ashrrev_i32_e32 v97, 31, v96
	v_lshl_add_u64 v[82:83], v[96:97], 3, s[50:51]
	global_atomic_add_x2 v[82:83], v[80:81], off

; __device__ __forceinline__ unsigned cvt_pk_bf16(float lo, float hi) { unsigned r; asm volatile("v_cvt_pk_bf16_f32 %0, %1, %2" : "=v"(r) : "v"(lo), "v"(hi)); return r; }
; __device__ __forceinline__ u64 ss_fix(float s) { return (u64)(s * 1099511627776.0f); }
; __device__ __forceinline__ float ss_val(u64 v) { return (float)v * (1.0f / 1099511627776.0f); }
;     __device__ __forceinline__ void operator()(const f32x4 (&acc)[2][2][4][2], const Unit& u, const Unit&, bool, int wr, int wc, int fr, int fq) const {
;     ...
;         for (int ai = 0; ai < 2; ++ai)
; #pragma unroll
;             for (int m = 0; m < 4; ++m) {
;                 const int row = row0 + ai * HALF + m * 16;
;                 const float rs = __builtin_amdgcn_rsqf(ss_val(cur[ai * 4 + m]) * inv_k + eps);
;                 float ss = 0.f;
; #pragma unroll
;                 for (int bj = 0; bj < 2; ++bj) {
;                     const f32x4 v0 = acc[ai][bj][m][0] * rs, v1 = acc[ai][bj][m][1] * rs;
;                     ss += (v0[0] * v0[0] + v0[1] * v0[1]) + (v0[2] * v0[2] + v0[3] * v0[3]) + (v1[0] * v1[0] + v1[1] * v1[1]) + (v1[2] * v1[2] + v1[3] * v1[3]);
;                     u32x4 w; w.x = cvt_pk_bf16(v0[0], v0[1]); w.y = cvt_pk_bf16(v0[2], v0[3]); w.z = cvt_pk_bf16(v1[0], v1[1]); w.w = cvt_pk_bf16(v1[2], v1[3]);
;                     *(u32x4*)(O + (size_t)row * ldc + col0 + bj * HALF) = w;
;                 }
;                 if (is_va) { ss += __shfl_xor(ss, 16); ss += __shfl_xor(ss, 32); if (fq == 0) atomicAdd(rowss_v + row, ss_fix(ss)); }
.LBB0_340:
	s_waitcnt lgkmcnt(0)
	v_mov_b64_e32 v[88:89], s[24:25]
	s_and_b64 vcc, exec, s[4:5]
	v_cvt_f32_u32_e32 v152, v152
	v_cvt_f32_u32_e32 v153, v153
	v_fmamk_f32 v152, v153, 0x4f800000, v152
	v_fmamk_f32 v80, v152, 0x26800000, v165
	v_rsq_f32_e32 v86, v80
	v_or_b32_e32 v80, 48, v142
	v_mad_i64_i32 v[88:89], s[70:71], v80, s81, v[88:89]
	v_pk_mul_f32 v[78:79], v[78:79], v[86:87] op_sel_hi:[1,0]
	v_pk_mul_f32 v[76:77], v[76:77], v[86:87] op_sel_hi:[1,0]
	v_pk_mul_f32 v[74:75], v[74:75], v[86:87] op_sel_hi:[1,0]
	v_pk_mul_f32 v[72:73], v[72:73], v[86:87] op_sel_hi:[1,0]
	v_cvt_pk_bf16_f32 v82, v76, v77
	v_cvt_pk_bf16_f32 v83, v78, v79
	v_lshl_add_u64 v[88:89], v[140:141], 1, v[88:89]
	v_cvt_pk_bf16_f32 v84, v72, v73
	v_cvt_pk_bf16_f32 v85, v74, v75
	v_pk_mul_f32 v[70:71], v[70:71], v[86:87] op_sel_hi:[1,0]
	v_pk_mul_f32 v[68:69], v[68:69], v[86:87] op_sel_hi:[1,0]
	v_pk_mul_f32 v[66:67], v[66:67], v[86:87] op_sel_hi:[1,0]
	v_pk_mul_f32 v[64:65], v[64:65], v[86:87] op_sel_hi:[1,0]
	global_store_dwordx4 v[88:89], v[82:85], off
	s_nop 1
	v_cvt_pk_bf16_f32 v82, v68, v69
	v_cvt_pk_bf16_f32 v83, v70, v71
	v_cvt_pk_bf16_f32 v84, v64, v65
	v_cvt_pk_bf16_f32 v85, v66, v67
	global_store_dwordx4 v[88:89], v[82:85], off offset:256
	s_cbranch_vccnz .LBB0_344
	v_mul_f32_e32 v67, v67, v67
	v_fmac_f32_e32 v67, v66, v66
	v_mul_f32_e32 v66, v69, v69
	v_mul_f32_e32 v75, v75, v75
	v_fmac_f32_e32 v66, v68, v68
	v_mul_f32_e32 v68, v71, v71
	v_fmac_f32_e32 v75, v74, v74
	v_mul_f32_e32 v74, v77, v77
	v_fmac_f32_e32 v68, v70, v70
	v_mul_f32_e32 v65, v65, v65
	v_fmac_f32_e32 v74, v76, v76
	v_mul_f32_e32 v76, v79, v79
	v_add_f32_e32 v66, v66, v68
	v_fmac_f32_e32 v65, v64, v64
	v_fmac_f32_e32 v76, v78, v78
	v_mul_f32_e32 v73, v73, v73
	v_add_f32_e32 v64, v65, v66
	v_and_b32_e32 v66, 64, v166
	v_add_f32_e32 v74, v74, v76
	v_fmac_f32_e32 v73, v72, v72
	v_xor_b32_e32 v65, 16, v166
	v_add_u32_e32 v66, 64, v66
	v_add_f32_e32 v72, v73, v74
	v_cmp_lt_i32_e32 vcc, v65, v66
	v_add_f32_e32 v72, v75, v72
	v_add_f32_e32 v64, v67, v64
	v_cndmask_b32_e32 v65, v166, v65, vcc
	v_add_f32_e32 v64, v72, v64
	v_lshlrev_b32_e32 v65, 2, v65
	ds_bpermute_b32 v65, v65, v64
	s_waitcnt lgkmcnt(0)
	v_add_f32_e32 v64, v64, v65
	v_xor_b32_e32 v65, 32, v166
	v_cmp_lt_i32_e32 vcc, v65, v66
	s_nop 1
	v_cndmask_b32_e32 v65, v166, v65, vcc
	v_lshlrev_b32_e32 v65, 2, v65
	ds_bpermute_b32 v65, v65, v64
	s_and_saveexec_b64 s[70:71], s[2:3]
	s_cbranch_execz .LBB0_343
	s_waitcnt lgkmcnt(0)
	v_add_f32_e32 v64, v64, v65
	v_mul_f32_e32 v64, 0x53800000, v64
	v_trunc_f32_e32 v64, v64
	v_mul_f32_e32 v65, 0x2f800000, v64
	v_floor_f32_e32 v65, v65
	v_fmac_f32_e32 v64, 0xcf800000, v65
	v_cvt_u32_f32_e32 v64, v64
	v_cvt_u32_f32_e32 v65, v65
	v_ashrrev_i32_e32 v81, 31, v80
	v_lshl_add_u64 v[66:67], v[80:81], 3, s[50:51]
	global_atomic_add_x2 v[66:67], v[64:65], off

; __device__ __forceinline__ unsigned cvt_pk_bf16(float lo, float hi) { unsigned r; asm volatile("v_cvt_pk_bf16_f32 %0, %1, %2" : "=v"(r) : "v"(lo), "v"(hi)); return r; }
; __device__ __forceinline__ u64 ss_fix(float s) { return (u64)(s * 1099511627776.0f); }
; __device__ __forceinline__ float ss_val(u64 v) { return (float)v * (1.0f / 1099511627776.0f); }
;     __device__ __forceinline__ void operator()(const f32x4 (&acc)[2][2][4][2], const Unit& u, const Unit&, bool, int wr, int wc, int fr, int fq) const {
;     ...
;         for (int ai = 0; ai < 2; ++ai)
; #pragma unroll
;             for (int m = 0; m < 4; ++m) {
;                 const int row = row0 + ai * HALF + m * 16;
;                 const float rs = __builtin_amdgcn_rsqf(ss_val(cur[ai * 4 + m]) * inv_k + eps);
;                 float ss = 0.f;
; #pragma unroll
;                 for (int bj = 0; bj < 2; ++bj) {
;                     const f32x4 v0 = acc[ai][bj][m][0] * rs, v1 = acc[ai][bj][m][1] * rs;
;                     ss += (v0[0] * v0[0] + v0[1] * v0[1]) + (v0[2] * v0[2] + v0[3] * v0[3]) + (v1[0] * v1[0] + v1[1] * v1[1]) + (v1[2] * v1[2] + v1[3] * v1[3]);
;                     u32x4 w; w.x = cvt_pk_bf16(v0[0], v0[1]); w.y = cvt_pk_bf16(v0[2], v0[3]); w.z = cvt_pk_bf16(v1[0], v1[1]); w.w = cvt_pk_bf16(v1[2], v1[3]);
;                     *(u32x4*)(O + (size_t)row * ldc + col0 + bj * HALF) = w;
;                 }
;                 if (is_va) { ss += __shfl_xor(ss, 16); ss += __shfl_xor(ss, 32); if (fq == 0) atomicAdd(rowss_v + row, ss_fix(ss)); }
.LBB0_344:
	s_waitcnt lgkmcnt(0)
	v_mov_b64_e32 v[72:73], s[24:25]
	s_and_b64 vcc, exec, s[4:5]
	v_cvt_f32_u32_e32 v150, v150
	v_cvt_f32_u32_e32 v151, v151
	v_fmamk_f32 v150, v151, 0x4f800000, v150
	v_fmamk_f32 v64, v150, 0x26800000, v165
	v_rsq_f32_e32 v70, v64
	v_add_u32_e32 v64, 0x80, v142
	v_mad_i64_i32 v[72:73], s[70:71], v64, s81, v[72:73]
	v_pk_mul_f32 v[62:63], v[62:63], v[70:71] op_sel_hi:[1,0]
	v_pk_mul_f32 v[60:61], v[60:61], v[70:71] op_sel_hi:[1,0]
	v_pk_mul_f32 v[58:59], v[58:59], v[70:71] op_sel_hi:[1,0]
	v_pk_mul_f32 v[56:57], v[56:57], v[70:71] op_sel_hi:[1,0]
	v_cvt_pk_bf16_f32 v66, v60, v61
	v_cvt_pk_bf16_f32 v67, v62, v63
	v_lshl_add_u64 v[72:73], v[140:141], 1, v[72:73]
	v_cvt_pk_bf16_f32 v68, v56, v57
	v_cvt_pk_bf16_f32 v69, v58, v59
	v_pk_mul_f32 v[54:55], v[54:55], v[70:71] op_sel_hi:[1,0]
	v_pk_mul_f32 v[52:53], v[52:53], v[70:71] op_sel_hi:[1,0]
	v_pk_mul_f32 v[50:51], v[50:51], v[70:71] op_sel_hi:[1,0]
	v_pk_mul_f32 v[48:49], v[48:49], v[70:71] op_sel_hi:[1,0]
	global_store_dwordx4 v[72:73], v[66:69], off
	s_nop 1
	v_cvt_pk_bf16_f32 v66, v52, v53
	v_cvt_pk_bf16_f32 v67, v54, v55
	v_cvt_pk_bf16_f32 v68, v48, v49
	v_cvt_pk_bf16_f32 v69, v50, v51
	global_store_dwordx4 v[72:73], v[66:69], off offset:256
	s_cbranch_vccnz .LBB0_348
	v_mul_f32_e32 v51, v51, v51
	v_fmac_f32_e32 v51, v50, v50
	v_mul_f32_e32 v50, v53, v53
	v_mul_f32_e32 v59, v59, v59
	v_fmac_f32_e32 v50, v52, v52
	v_mul_f32_e32 v52, v55, v55
	v_fmac_f32_e32 v59, v58, v58
	v_mul_f32_e32 v58, v61, v61
	v_fmac_f32_e32 v52, v54, v54
	v_mul_f32_e32 v49, v49, v49
	v_fmac_f32_e32 v58, v60, v60
	v_mul_f32_e32 v60, v63, v63
	v_add_f32_e32 v50, v50, v52
	v_fmac_f32_e32 v49, v48, v48
	v_fmac_f32_e32 v60, v62, v62
	v_mul_f32_e32 v57, v57, v57
	v_add_f32_e32 v48, v49, v50
	v_and_b32_e32 v50, 64, v166
	v_add_f32_e32 v58, v58, v60
	v_fmac_f32_e32 v57, v56, v56
	v_xor_b32_e32 v49, 16, v166
	v_add_u32_e32 v50, 64, v50
	v_add_f32_e32 v56, v57, v58
	v_cmp_lt_i32_e32 vcc, v49, v50
	v_add_f32_e32 v56, v59, v56
	v_add_f32_e32 v48, v51, v48
	v_cndmask_b32_e32 v49, v166, v49, vcc
	v_add_f32_e32 v48, v56, v48
	v_lshlrev_b32_e32 v49, 2, v49
	ds_bpermute_b32 v49, v49, v48
	s_waitcnt lgkmcnt(0)
	v_add_f32_e32 v48, v48, v49
	v_xor_b32_e32 v49, 32, v166
	v_cmp_lt_i32_e32 vcc, v49, v50
	s_nop 1
	v_cndmask_b32_e32 v49, v166, v49, vcc
	v_lshlrev_b32_e32 v49, 2, v49
	ds_bpermute_b32 v49, v49, v48
	s_and_saveexec_b64 s[70:71], s[2:3]
	s_cbranch_execz .LBB0_347
	s_waitcnt lgkmcnt(0)
	v_add_f32_e32 v48, v48, v49
	v_mul_f32_e32 v48, 0x53800000, v48
	v_trunc_f32_e32 v48, v48
	v_mul_f32_e32 v49, 0x2f800000, v48
	v_floor_f32_e32 v49, v49
	v_fmac_f32_e32 v48, 0xcf800000, v49
	v_cvt_u32_f32_e32 v48, v48
	v_cvt_u32_f32_e32 v49, v49
	v_ashrrev_i32_e32 v65, 31, v64
	v_lshl_add_u64 v[50:51], v[64:65], 3, s[50:51]
	global_atomic_add_x2 v[50:51], v[48:49], off

; __device__ __forceinline__ unsigned cvt_pk_bf16(float lo, float hi) { unsigned r; asm volatile("v_cvt_pk_bf16_f32 %0, %1, %2" : "=v"(r) : "v"(lo), "v"(hi)); return r; }
; __device__ __forceinline__ u64 ss_fix(float s) { return (u64)(s * 1099511627776.0f); }
; __device__ __forceinline__ float ss_val(u64 v) { return (float)v * (1.0f / 1099511627776.0f); }
;     __device__ __forceinline__ void operator()(const f32x4 (&acc)[2][2][4][2], const Unit& u, const Unit&, bool, int wr, int wc, int fr, int fq) const {
;     ...
;         for (int ai = 0; ai < 2; ++ai)
; #pragma unroll
;             for (int m = 0; m < 4; ++m) {
;                 const int row = row0 + ai * HALF + m * 16;
;                 const float rs = __builtin_amdgcn_rsqf(ss_val(cur[ai * 4 + m]) * inv_k + eps);
;                 float ss = 0.f;
; #pragma unroll
;                 for (int bj = 0; bj < 2; ++bj) {
;                     const f32x4 v0 = acc[ai][bj][m][0] * rs, v1 = acc[ai][bj][m][1] * rs;
;                     ss += (v0[0] * v0[0] + v0[1] * v0[1]) + (v0[2] * v0[2] + v0[3] * v0[3]) + (v1[0] * v1[0] + v1[1] * v1[1]) + (v1[2] * v1[2] + v1[3] * v1[3]);
;                     u32x4 w; w.x = cvt_pk_bf16(v0[0], v0[1]); w.y = cvt_pk_bf16(v0[2], v0[3]); w.z = cvt_pk_bf16(v1[0], v1[1]); w.w = cvt_pk_bf16(v1[2], v1[3]);
;                     *(u32x4*)(O + (size_t)row * ldc + col0 + bj * HALF) = w;
;                 }
;                 if (is_va) { ss += __shfl_xor(ss, 16); ss += __shfl_xor(ss, 32); if (fq == 0) atomicAdd(rowss_v + row, ss_fix(ss)); }
.LBB0_348:
	s_waitcnt lgkmcnt(0)
	v_mov_b64_e32 v[56:57], s[24:25]
	s_and_b64 vcc, exec, s[4:5]
	v_cvt_f32_u32_e32 v148, v148
	v_cvt_f32_u32_e32 v149, v149
	v_fmamk_f32 v148, v149, 0x4f800000, v148
	v_fmamk_f32 v48, v148, 0x26800000, v165
	v_rsq_f32_e32 v54, v48
	v_add_u32_e32 v48, 0x90, v142
	v_mad_i64_i32 v[56:57], s[70:71], v48, s81, v[56:57]
	v_pk_mul_f32 v[46:47], v[46:47], v[54:55] op_sel_hi:[1,0]
	v_pk_mul_f32 v[44:45], v[44:45], v[54:55] op_sel_hi:[1,0]
	v_pk_mul_f32 v[42:43], v[42:43], v[54:55] op_sel_hi:[1,0]
	v_pk_mul_f32 v[40:41], v[40:41], v[54:55] op_sel_hi:[1,0]
	v_cvt_pk_bf16_f32 v50, v44, v45
	v_cvt_pk_bf16_f32 v51, v46, v47
	v_lshl_add_u64 v[56:57], v[140:141], 1, v[56:57]
	v_cvt_pk_bf16_f32 v52, v40, v41
	v_cvt_pk_bf16_f32 v53, v42, v43
	v_pk_mul_f32 v[38:39], v[38:39], v[54:55] op_sel_hi:[1,0]
	v_pk_mul_f32 v[36:37], v[36:37], v[54:55] op_sel_hi:[1,0]
	v_pk_mul_f32 v[34:35], v[34:35], v[54:55] op_sel_hi:[1,0]
	v_pk_mul_f32 v[32:33], v[32:33], v[54:55] op_sel_hi:[1,0]
	global_store_dwordx4 v[56:57], v[50:53], off
	s_nop 1
	v_cvt_pk_bf16_f32 v50, v36, v37
	v_cvt_pk_bf16_f32 v51, v38, v39
	v_cvt_pk_bf16_f32 v52, v32, v33
	v_cvt_pk_bf16_f32 v53, v34, v35
	global_store_dwordx4 v[56:57], v[50:53], off offset:256
	s_cbranch_vccnz .LBB0_352
	v_mul_f32_e32 v35, v35, v35
	v_fmac_f32_e32 v35, v34, v34
	v_mul_f32_e32 v34, v37, v37
	v_mul_f32_e32 v43, v43, v43
	v_fmac_f32_e32 v34, v36, v36
	v_mul_f32_e32 v36, v39, v39
	v_fmac_f32_e32 v43, v42, v42
	v_mul_f32_e32 v42, v45, v45
	v_fmac_f32_e32 v36, v38, v38
	v_mul_f32_e32 v33, v33, v33
	v_fmac_f32_e32 v42, v44, v44
	v_mul_f32_e32 v44, v47, v47
	v_add_f32_e32 v34, v34, v36
	v_fmac_f32_e32 v33, v32, v32
	v_fmac_f32_e32 v44, v46, v46
	v_mul_f32_e32 v41, v41, v41
	v_add_f32_e32 v32, v33, v34
	v_and_b32_e32 v34, 64, v166
	v_add_f32_e32 v42, v42, v44
	v_fmac_f32_e32 v41, v40, v40
	v_xor_b32_e32 v33, 16, v166
	v_add_u32_e32 v34, 64, v34
	v_add_f32_e32 v40, v41, v42
	v_cmp_lt_i32_e32 vcc, v33, v34
	v_add_f32_e32 v40, v43, v40
	v_add_f32_e32 v32, v35, v32
	v_cndmask_b32_e32 v33, v166, v33, vcc
	v_add_f32_e32 v32, v40, v32
	v_lshlrev_b32_e32 v33, 2, v33
	ds_bpermute_b32 v33, v33, v32
	s_waitcnt lgkmcnt(0)
	v_add_f32_e32 v32, v32, v33
	v_xor_b32_e32 v33, 32, v166
	v_cmp_lt_i32_e32 vcc, v33, v34
	s_nop 1
	v_cndmask_b32_e32 v33, v166, v33, vcc
	v_lshlrev_b32_e32 v33, 2, v33
	ds_bpermute_b32 v33, v33, v32
	s_and_saveexec_b64 s[70:71], s[2:3]
	s_cbranch_execz .LBB0_351
	s_waitcnt lgkmcnt(0)
	v_add_f32_e32 v32, v32, v33
	v_mul_f32_e32 v32, 0x53800000, v32
	v_trunc_f32_e32 v32, v32
	v_mul_f32_e32 v33, 0x2f800000, v32
	v_floor_f32_e32 v33, v33
	v_fmac_f32_e32 v32, 0xcf800000, v33
	v_cvt_u32_f32_e32 v32, v32
	v_cvt_u32_f32_e32 v33, v33
	v_ashrrev_i32_e32 v49, 31, v48
	v_lshl_add_u64 v[34:35], v[48:49], 3, s[50:51]
	global_atomic_add_x2 v[34:35], v[32:33], off

; __device__ __forceinline__ unsigned cvt_pk_bf16(float lo, float hi) { unsigned r; asm volatile("v_cvt_pk_bf16_f32 %0, %1, %2" : "=v"(r) : "v"(lo), "v"(hi)); return r; }
; __device__ __forceinline__ u64 ss_fix(float s) { return (u64)(s * 1099511627776.0f); }
; __device__ __forceinline__ float ss_val(u64 v) { return (float)v * (1.0f / 1099511627776.0f); }
;     __device__ __forceinline__ void operator()(const f32x4 (&acc)[2][2][4][2], const Unit& u, const Unit&, bool, int wr, int wc, int fr, int fq) const {
;     ...
;         for (int ai = 0; ai < 2; ++ai)
; #pragma unroll
;             for (int m = 0; m < 4; ++m) {
;                 const int row = row0 + ai * HALF + m * 16;
;                 const float rs = __builtin_amdgcn_rsqf(ss_val(cur[ai * 4 + m]) * inv_k + eps);
;                 float ss = 0.f;
; #pragma unroll
;                 for (int bj = 0; bj < 2; ++bj) {
;                     const f32x4 v0 = acc[ai][bj][m][0] * rs, v1 = acc[ai][bj][m][1] * rs;
;                     ss += (v0[0] * v0[0] + v0[1] * v0[1]) + (v0[2] * v0[2] + v0[3] * v0[3]) + (v1[0] * v1[0] + v1[1] * v1[1]) + (v1[2] * v1[2] + v1[3] * v1[3]);
;                     u32x4 w; w.x = cvt_pk_bf16(v0[0], v0[1]); w.y = cvt_pk_bf16(v0[2], v0[3]); w.z = cvt_pk_bf16(v1[0], v1[1]); w.w = cvt_pk_bf16(v1[2], v1[3]);
;                     *(u32x4*)(O + (size_t)row * ldc + col0 + bj * HALF) = w;
;                 }
;                 if (is_va) { ss += __shfl_xor(ss, 16); ss += __shfl_xor(ss, 32); if (fq == 0) atomicAdd(rowss_v + row, ss_fix(ss)); }
.LBB0_352:
	s_waitcnt lgkmcnt(0)
	v_mov_b64_e32 v[40:41], s[24:25]
	s_and_b64 vcc, exec, s[4:5]
	v_cvt_f32_u32_e32 v146, v146
	v_cvt_f32_u32_e32 v147, v147
	v_fmamk_f32 v146, v147, 0x4f800000, v146
	v_fmamk_f32 v32, v146, 0x26800000, v165
	v_rsq_f32_e32 v38, v32
	v_add_u32_e32 v32, 0xa0, v142
	v_mad_i64_i32 v[40:41], s[70:71], v32, s81, v[40:41]
	v_pk_mul_f32 v[30:31], v[30:31], v[38:39] op_sel_hi:[1,0]
	v_pk_mul_f32 v[28:29], v[28:29], v[38:39] op_sel_hi:[1,0]
	v_pk_mul_f32 v[26:27], v[26:27], v[38:39] op_sel_hi:[1,0]
	v_pk_mul_f32 v[24:25], v[24:25], v[38:39] op_sel_hi:[1,0]
	v_cvt_pk_bf16_f32 v34, v28, v29
	v_cvt_pk_bf16_f32 v35, v30, v31
	v_lshl_add_u64 v[40:41], v[140:141], 1, v[40:41]
	v_cvt_pk_bf16_f32 v36, v24, v25
	v_cvt_pk_bf16_f32 v37, v26, v27
	v_pk_mul_f32 v[22:23], v[22:23], v[38:39] op_sel_hi:[1,0]
	v_pk_mul_f32 v[20:21], v[20:21], v[38:39] op_sel_hi:[1,0]
	v_pk_mul_f32 v[18:19], v[18:19], v[38:39] op_sel_hi:[1,0]
	v_pk_mul_f32 v[16:17], v[16:17], v[38:39] op_sel_hi:[1,0]
	global_store_dwordx4 v[40:41], v[34:37], off
	s_nop 1
	v_cvt_pk_bf16_f32 v34, v20, v21
	v_cvt_pk_bf16_f32 v35, v22, v23
	v_cvt_pk_bf16_f32 v36, v16, v17
	v_cvt_pk_bf16_f32 v37, v18, v19
	global_store_dwordx4 v[40:41], v[34:37], off offset:256
	s_cbranch_vccnz .LBB0_356
	v_mul_f32_e32 v19, v19, v19
	v_fmac_f32_e32 v19, v18, v18
	v_mul_f32_e32 v18, v21, v21
	v_mul_f32_e32 v27, v27, v27
	v_fmac_f32_e32 v18, v20, v20
	v_mul_f32_e32 v20, v23, v23
	v_fmac_f32_e32 v27, v26, v26
	v_mul_f32_e32 v26, v29, v29
	v_fmac_f32_e32 v20, v22, v22
	v_mul_f32_e32 v17, v17, v17
	v_fmac_f32_e32 v26, v28, v28
	v_mul_f32_e32 v28, v31, v31
	v_add_f32_e32 v18, v18, v20
	v_fmac_f32_e32 v17, v16, v16
	v_fmac_f32_e32 v28, v30, v30
	v_mul_f32_e32 v25, v25, v25
	v_add_f32_e32 v16, v17, v18
	v_and_b32_e32 v18, 64, v166
	v_add_f32_e32 v26, v26, v28
	v_fmac_f32_e32 v25, v24, v24
	v_xor_b32_e32 v17, 16, v166
	v_add_u32_e32 v18, 64, v18
	v_add_f32_e32 v24, v25, v26
	v_cmp_lt_i32_e32 vcc, v17, v18
	v_add_f32_e32 v24, v27, v24
	v_add_f32_e32 v16, v19, v16
	v_cndmask_b32_e32 v17, v166, v17, vcc
	v_add_f32_e32 v16, v24, v16
	v_lshlrev_b32_e32 v17, 2, v17
	ds_bpermute_b32 v17, v17, v16
	s_waitcnt lgkmcnt(0)
	v_add_f32_e32 v16, v16, v17
	v_xor_b32_e32 v17, 32, v166
	v_cmp_lt_i32_e32 vcc, v17, v18
	s_nop 1
	v_cndmask_b32_e32 v17, v166, v17, vcc
	v_lshlrev_b32_e32 v17, 2, v17
	ds_bpermute_b32 v17, v17, v16
	s_and_saveexec_b64 s[70:71], s[2:3]
	s_cbranch_execz .LBB0_355
	s_waitcnt lgkmcnt(0)
	v_add_f32_e32 v16, v16, v17
	v_mul_f32_e32 v16, 0x53800000, v16
	v_trunc_f32_e32 v16, v16
	v_mul_f32_e32 v17, 0x2f800000, v16
	v_floor_f32_e32 v17, v17
	v_fmac_f32_e32 v16, 0xcf800000, v17
	v_cvt_u32_f32_e32 v16, v16
	v_cvt_u32_f32_e32 v17, v17
	v_ashrrev_i32_e32 v33, 31, v32
	v_lshl_add_u64 v[18:19], v[32:33], 3, s[50:51]
	global_atomic_add_x2 v[18:19], v[16:17], off

; __device__ __forceinline__ unsigned cvt_pk_bf16(float lo, float hi) { unsigned r; asm volatile("v_cvt_pk_bf16_f32 %0, %1, %2" : "=v"(r) : "v"(lo), "v"(hi)); return r; }
; __device__ __forceinline__ u64 ss_fix(float s) { return (u64)(s * 1099511627776.0f); }
; __device__ __forceinline__ float ss_val(u64 v) { return (float)v * (1.0f / 1099511627776.0f); }
;     __device__ __forceinline__ void operator()(const f32x4 (&acc)[2][2][4][2], const Unit& u, const Unit&, bool, int wr, int wc, int fr, int fq) const {
;     ...
;         for (int ai = 0; ai < 2; ++ai)
; #pragma unroll
;             for (int m = 0; m < 4; ++m) {
;                 const int row = row0 + ai * HALF + m * 16;
;                 const float rs = __builtin_amdgcn_rsqf(ss_val(cur[ai * 4 + m]) * inv_k + eps);
;                 float ss = 0.f;
; #pragma unroll
;                 for (int bj = 0; bj < 2; ++bj) {
;                     const f32x4 v0 = acc[ai][bj][m][0] * rs, v1 = acc[ai][bj][m][1] * rs;
;                     ss += (v0[0] * v0[0] + v0[1] * v0[1]) + (v0[2] * v0[2] + v0[3] * v0[3]) + (v1[0] * v1[0] + v1[1] * v1[1]) + (v1[2] * v1[2] + v1[3] * v1[3]);
;                     u32x4 w; w.x = cvt_pk_bf16(v0[0], v0[1]); w.y = cvt_pk_bf16(v0[2], v0[3]); w.z = cvt_pk_bf16(v1[0], v1[1]); w.w = cvt_pk_bf16(v1[2], v1[3]);
;                     *(u32x4*)(O + (size_t)row * ldc + col0 + bj * HALF) = w;
;                 }
;                 if (is_va) { ss += __shfl_xor(ss, 16); ss += __shfl_xor(ss, 32); if (fq == 0) atomicAdd(rowss_v + row, ss_fix(ss)); }
.LBB0_356:
	s_waitcnt lgkmcnt(0)
	v_mov_b64_e32 v[24:25], s[24:25]
	s_and_b64 vcc, exec, s[4:5]
	v_cvt_f32_u32_e32 v144, v144
	v_cvt_f32_u32_e32 v145, v145
	v_fmamk_f32 v144, v145, 0x4f800000, v144
	v_fmamk_f32 v16, v144, 0x26800000, v165
	v_rsq_f32_e32 v22, v16
	v_add_u32_e32 v16, 0xb0, v142
	v_mad_i64_i32 v[24:25], s[70:71], v16, s81, v[24:25]
	v_pk_mul_f32 v[14:15], v[14:15], v[22:23] op_sel_hi:[1,0]
	v_pk_mul_f32 v[12:13], v[12:13], v[22:23] op_sel_hi:[1,0]
	v_pk_mul_f32 v[10:11], v[10:11], v[22:23] op_sel_hi:[1,0]
	v_pk_mul_f32 v[8:9], v[8:9], v[22:23] op_sel_hi:[1,0]
	v_cvt_pk_bf16_f32 v18, v12, v13
	v_cvt_pk_bf16_f32 v19, v14, v15
	v_lshl_add_u64 v[24:25], v[140:141], 1, v[24:25]
	v_cvt_pk_bf16_f32 v20, v8, v9
	v_cvt_pk_bf16_f32 v21, v10, v11
	v_pk_mul_f32 v[6:7], v[6:7], v[22:23] op_sel_hi:[1,0]
	v_pk_mul_f32 v[4:5], v[4:5], v[22:23] op_sel_hi:[1,0]
	v_pk_mul_f32 v[2:3], v[2:3], v[22:23] op_sel_hi:[1,0]
	v_pk_mul_f32 v[0:1], v[0:1], v[22:23] op_sel_hi:[1,0]
	global_store_dwordx4 v[24:25], v[18:21], off
	s_nop 1
	v_cvt_pk_bf16_f32 v18, v4, v5
	v_cvt_pk_bf16_f32 v19, v6, v7
	v_cvt_pk_bf16_f32 v20, v0, v1
	v_cvt_pk_bf16_f32 v21, v2, v3
	global_store_dwordx4 v[24:25], v[18:21], off offset:256
	s_cbranch_vccnz .LBB0_360
	v_mul_f32_e32 v3, v3, v3
	v_fmac_f32_e32 v3, v2, v2
	v_mul_f32_e32 v2, v5, v5
	v_mul_f32_e32 v11, v11, v11
	v_fmac_f32_e32 v2, v4, v4
	v_mul_f32_e32 v4, v7, v7
	v_fmac_f32_e32 v11, v10, v10
	v_mul_f32_e32 v10, v13, v13
	v_fmac_f32_e32 v4, v6, v6
	v_mul_f32_e32 v1, v1, v1
	v_fmac_f32_e32 v10, v12, v12
	v_mul_f32_e32 v12, v15, v15
	v_add_f32_e32 v2, v2, v4
	v_fmac_f32_e32 v1, v0, v0
	v_fmac_f32_e32 v12, v14, v14
	v_mul_f32_e32 v9, v9, v9
	v_add_f32_e32 v0, v1, v2
	v_and_b32_e32 v2, 64, v166
	v_add_f32_e32 v10, v10, v12
	v_fmac_f32_e32 v9, v8, v8
	v_xor_b32_e32 v1, 16, v166
	v_add_u32_e32 v2, 64, v2
	v_add_f32_e32 v8, v9, v10
	v_cmp_lt_i32_e32 vcc, v1, v2
	v_add_f32_e32 v8, v11, v8
	v_add_f32_e32 v0, v3, v0
	v_cndmask_b32_e32 v1, v166, v1, vcc
	v_add_f32_e32 v0, v8, v0
	v_lshlrev_b32_e32 v1, 2, v1
	ds_bpermute_b32 v1, v1, v0
	s_waitcnt lgkmcnt(0)
	v_add_f32_e32 v0, v0, v1
	v_xor_b32_e32 v1, 32, v166
	v_cmp_lt_i32_e32 vcc, v1, v2
	s_nop 1
	v_cndmask_b32_e32 v1, v166, v1, vcc
	v_lshlrev_b32_e32 v1, 2, v1
	ds_bpermute_b32 v1, v1, v0
	s_and_saveexec_b64 s[4:5], s[2:3]
	s_cbranch_execz .LBB0_359
	s_waitcnt lgkmcnt(0)
	v_add_f32_e32 v0, v0, v1
	v_mul_f32_e32 v0, 0x53800000, v0
	v_trunc_f32_e32 v0, v0
	v_mul_f32_e32 v1, 0x2f800000, v0
	v_floor_f32_e32 v1, v1
	v_fmac_f32_e32 v0, 0xcf800000, v1
	v_cvt_u32_f32_e32 v0, v0
	v_cvt_u32_f32_e32 v1, v1
	v_ashrrev_i32_e32 v17, 31, v16
	v_lshl_add_u64 v[2:3], v[16:17], 3, s[50:51]
	global_atomic_add_x2 v[2:3], v[0:1], off

; __device__ __forceinline__ float ss_val(u64 v) { return (float)v * (1.0f / 1099511627776.0f); }
; __device__ __forceinline__ void rank_unit(const bf16* XN, const bf16* WrT, const u64* rowss, float* R, int m0, int lane) {
;     const int fr = lane & 15, fq = lane >> 4;
;     const bf16* ap = XN + (size_t)(m0 + fr) * D + 8 * fq; const bf16* bp = WrT + (size_t)fr * D + 8 * fq;
;     f32x4 acc0 = (f32x4){0.f, 0.f, 0.f, 0.f}, acc1 = (f32x4){0.f, 0.f, 0.f, 0.f};
; #pragma unroll 8
;     for (int ki = 0; ki < 32; ki += 2) {
;         const bf16x8 a0 = *(const bf16x8*)(ap + 32 * ki), b0 = *(const bf16x8*)(bp + 32 * ki), a1 = *(const bf16x8*)(ap + 32 * ki + 32), b1 = *(const bf16x8*)(bp + 32 * ki + 32);
;         acc0 = __builtin_amdgcn_mfma_f32_16x16x32_bf16(b0, a0, acc0, 0, 0, 0);
;         acc1 = __builtin_amdgcn_mfma_f32_16x16x32_bf16(b1, a1, acc1, 0, 0, 0);
;     }
;     { const int row = m0 + fr; const float rs = __builtin_amdgcn_rsqf(ss_val(rowss[row]) * (1.f / D) + EPS); *(f32x4*)(R + (size_t)row * 16 + 4 * fq) = (acc0 + acc1) * rs; }
; }
.LBB0_367:
	v_lshl_add_u64 v[78:79], v[18:19], 0, v[8:9]
	v_add_co_u32_e32 v92, vcc, s20, v78
	v_lshl_add_u64 v[90:91], v[16:17], 0, v[8:9]
	s_nop 0
	v_addc_co_u32_e32 v93, vcc, 0, v79, vcc
	global_load_dwordx4 v[22:25], v[90:91], off offset:-512
	global_load_dwordx4 v[26:29], v[90:91], off offset:-448
	global_load_dwordx4 v[30:33], v[90:91], off offset:-384
	global_load_dwordx4 v[34:37], v[90:91], off offset:-320
	global_load_dwordx4 v[38:41], v[90:91], off offset:-256
	global_load_dwordx4 v[42:45], v[90:91], off offset:-192
	global_load_dwordx4 v[46:49], v[90:91], off offset:-128
	global_load_dwordx4 v[50:53], v[90:91], off offset:-64
	global_load_dwordx4 v[54:57], v[90:91], off
	global_load_dwordx4 v[58:61], v[90:91], off offset:64
	global_load_dwordx4 v[62:65], v[90:91], off offset:128
	global_load_dwordx4 v[66:69], v[90:91], off offset:192
	global_load_dwordx4 v[70:73], v[90:91], off offset:256
	global_load_dwordx4 v[74:77], v[90:91], off offset:320
	global_load_dwordx4 v[78:81], v[92:93], off
	global_load_dwordx4 v[82:85], v[92:93], off offset:64
	global_load_dwordx4 v[86:89], v[92:93], off offset:128
	s_add_i32 s28, s28, 16
	v_lshl_add_u64 v[18:19], v[18:19], 0, s[4:5]
	s_cmp_lt_u32 s28, 30
	v_lshl_add_u64 v[16:17], v[16:17], 0, s[4:5]
	s_waitcnt vmcnt(2)
	v_mfma_f32_16x16x32_bf16 v[0:3], v[78:81], v[22:25], v[0:3]
	global_load_dwordx4 v[22:25], v[92:93], off offset:192
	s_waitcnt vmcnt(2)
	v_mfma_f32_16x16x32_bf16 v[4:7], v[82:85], v[26:29], v[4:7]
	global_load_dwordx4 v[26:29], v[92:93], off offset:256
	s_waitcnt vmcnt(2)
	v_mfma_f32_16x16x32_bf16 v[0:3], v[86:89], v[30:33], v[0:3]
	global_load_dwordx4 v[30:33], v[92:93], off offset:320
	s_waitcnt vmcnt(2)
	v_mfma_f32_16x16x32_bf16 v[4:7], v[22:25], v[34:37], v[4:7]
	global_load_dwordx4 v[22:25], v[92:93], off offset:384
	s_waitcnt vmcnt(2)
	v_mfma_f32_16x16x32_bf16 v[0:3], v[26:29], v[38:41], v[0:3]
	global_load_dwordx4 v[26:29], v[92:93], off offset:448
	s_waitcnt vmcnt(2)
	v_mfma_f32_16x16x32_bf16 v[4:7], v[30:33], v[42:45], v[4:7]
	global_load_dwordx4 v[30:33], v[92:93], off offset:512
	s_waitcnt vmcnt(2)
	v_mfma_f32_16x16x32_bf16 v[0:3], v[22:25], v[46:49], v[0:3]
	global_load_dwordx4 v[22:25], v[92:93], off offset:576
	s_waitcnt vmcnt(2)
	v_mfma_f32_16x16x32_bf16 v[4:7], v[26:29], v[50:53], v[4:7]
	global_load_dwordx4 v[26:29], v[92:93], off offset:640
	s_waitcnt vmcnt(2)
	v_mfma_f32_16x16x32_bf16 v[0:3], v[30:33], v[54:57], v[0:3]
	global_load_dwordx4 v[30:33], v[92:93], off offset:704
	s_waitcnt vmcnt(2)
	v_mfma_f32_16x16x32_bf16 v[4:7], v[22:25], v[58:61], v[4:7]
	global_load_dwordx4 v[22:25], v[92:93], off offset:768
	s_waitcnt vmcnt(2)
	v_mfma_f32_16x16x32_bf16 v[0:3], v[26:29], v[62:65], v[0:3]
	global_load_dwordx4 v[26:29], v[92:93], off offset:832
	s_waitcnt vmcnt(2)
	v_mfma_f32_16x16x32_bf16 v[4:7], v[30:33], v[66:69], v[4:7]
	global_load_dwordx4 v[30:33], v[92:93], off offset:896
	global_load_dwordx4 v[34:37], v[92:93], off offset:960
	s_waitcnt vmcnt(3)
	v_mfma_f32_16x16x32_bf16 v[0:3], v[22:25], v[70:73], v[0:3]
	global_load_dwordx4 v[22:25], v[90:91], off offset:384
	s_waitcnt vmcnt(3)
	v_mfma_f32_16x16x32_bf16 v[4:7], v[26:29], v[74:77], v[4:7]
	global_load_dwordx4 v[26:29], v[90:91], off offset:448
	s_waitcnt vmcnt(1)
	v_mfma_f32_16x16x32_bf16 v[0:3], v[30:33], v[22:25], v[0:3]
	s_waitcnt vmcnt(0)
	v_mfma_f32_16x16x32_bf16 v[4:7], v[34:37], v[26:29], v[4:7]
	s_cbranch_scc1 .LBB0_367
	v_lshl_or_b32 v16, s21, 4, v158
	v_ashrrev_i32_e32 v17, 31, v16
	v_lshl_add_u64 v[18:19], v[16:17], 3, s[40:41]
	global_load_dwordx2 v[18:19], v[18:19], off
	s_nop 2
	v_pk_add_f32 v[2:3], v[2:3], v[6:7]
	v_pk_add_f32 v[0:1], v[0:1], v[4:5]
	s_add_i32 s21, s21, s36
	s_cmpk_lt_i32 s21, 0x100
	v_add_u32_e32 v14, s11, v14
	s_waitcnt vmcnt(0)
	v_cvt_f32_u32_e32 v18, v18
	v_cvt_f32_u32_e32 v19, v19
	v_fmamk_f32 v18, v19, 0x4f800000, v18
	v_fmamk_f32 v4, v18, 0x26800000, v20
	v_rsq_f32_e32 v4, v4
	v_lshlrev_b64 v[6:7], 6, v[16:17]
	v_lshl_add_u64 v[6:7], v[10:11], 0, v[6:7]
	v_pk_mul_f32 v[2:3], v[2:3], v[4:5] op_sel_hi:[1,0]
	v_pk_mul_f32 v[0:1], v[0:1], v[4:5] op_sel_hi:[1,0]
	global_store_dwordx4 v[6:7], v[0:3], off
	s_cbranch_scc1 .LBB0_366

; __device__ __forceinline__ float ss_val(u64 v) { return (float)v * (1.0f / 1099511627776.0f); }
; __device__ __forceinline__ unsigned pk2(float lo, float hi) { return f2bf(lo) | (f2bf(hi) << 16); }
; __device__ __forceinline__ void gmlp_unit(LAS unsigned char* wl, const bf16* PROJ, const u64* rowss_v, const bf16* wsb, const float* norm_v, const float* b_s, bf16* Y, int nb, int g, int lane) {
;     ...
;     const int tok0 = nb * 128, sp = lane >> 3, cc = lane & 7;
; #pragma unroll 4
;     for (int it = 0; it < 8; ++it) {
;         const int s0 = it * 16 + 2 * sp;
;         const float r0 = __builtin_amdgcn_rsqf(ss_val(rowss_v[tok0 + s0]) * (1.f / 512.f) + EPS), r1 = __builtin_amdgcn_rsqf(ss_val(rowss_v[tok0 + s0 + 1]) * (1.f / 512.f) + EPS);
;         const u32x4 va = *(const u32x4*)(PROJ + (size_t)(tok0 + s0) * NPROJ + 512 + g * 64 + 8 * cc);
;         const u32x4 vb = *(const u32x4*)(PROJ + (size_t)(tok0 + s0 + 1) * NPROJ + 512 + g * 64 + 8 * cc);
; #pragma unroll
;         for (int i = 0; i < 4; ++i) {
;             VT32[(8 * cc + 2 * i) * (VS / 2) + (s0 >> 1)] = pk2(bf_lo(va[i]) * r0, bf_lo(vb[i]) * r1);
;             VT32[(8 * cc + 2 * i + 1) * (VS / 2) + (s0 >> 1)] = pk2(bf_hi(va[i]) * r0, bf_hi(vb[i]) * r1);
;         }
.LBB0_418:
	v_add_u32_e32 v0, s21, v2
	v_ashrrev_i32_e32 v1, 31, v0
	v_add_u32_e32 v8, 1, v0
	v_add_u32_e32 v40, 16, v0
	v_add_u32_e32 v9, 17, v0
	v_add_u32_e32 v42, 32, v0
	v_add_u32_e32 v10, 33, v0
	v_add_u32_e32 v44, 48, v0
	v_add_u32_e32 v11, 49, v0
	v_mad_i64_i32 v[12:13], s[28:29], v0, s4, v[126:127]
	v_lshl_add_u64 v[0:1], v[0:1], 3, s[0:1]
	v_mad_i64_i32 v[16:17], s[28:29], v8, s4, v[126:127]
	v_ashrrev_i32_e32 v41, 31, v40
	v_mad_i64_i32 v[20:21], s[28:29], v40, s4, v[126:127]
	v_mad_i64_i32 v[24:25], s[28:29], v9, s4, v[126:127]
	v_ashrrev_i32_e32 v43, 31, v42
	v_mad_i64_i32 v[28:29], s[28:29], v10, s4, v[126:127]
	v_ashrrev_i32_e32 v45, 31, v44
	v_mad_i64_i32 v[32:33], s[28:29], v44, s4, v[126:127]
	v_mad_i64_i32 v[36:37], s[28:29], v11, s4, v[126:127]
	v_mad_i64_i32 v[48:49], s[28:29], v42, s4, v[126:127]
	global_load_dwordx4 v[8:11], v[0:1], off
	s_nop 0
	global_load_dwordx4 v[12:15], v[12:13], off offset:1024
	s_nop 0
	global_load_dwordx4 v[16:19], v[16:17], off offset:1024
	s_nop 0
	global_load_dwordx4 v[20:23], v[20:21], off offset:1024
	s_nop 0
	global_load_dwordx4 v[24:27], v[24:25], off offset:1024
	s_nop 0
	global_load_dwordx4 v[28:31], v[28:29], off offset:1024
	s_nop 0
	global_load_dwordx4 v[32:35], v[32:33], off offset:1024
	s_nop 0
	global_load_dwordx4 v[36:39], v[36:37], off offset:1024
	v_lshl_add_u64 v[0:1], v[40:41], 3, s[0:1]
	v_lshl_add_u64 v[46:47], v[42:43], 3, s[0:1]
	v_lshl_add_u64 v[52:53], v[44:45], 3, s[0:1]
	global_load_dwordx4 v[40:43], v[0:1], off
	s_nop 0
	global_load_dwordx4 v[44:47], v[46:47], off
	s_nop 0
	global_load_dwordx4 v[48:51], v[48:49], off offset:1024
	s_nop 0
	global_load_dwordx4 v[52:55], v[52:53], off
	v_add_u32_e32 v4, v3, v142
	s_add_i32 s21, s21, 64
	v_add_u32_e32 v5, v3, v141
	v_add_u32_e32 v6, v3, v140
	v_add_u32_e32 v7, v3, v139
	v_add_u32_e32 v3, 0x80, v3
	v_add_u32_e32 v56, 0x400, v4
	s_cmpk_lg_i32 s21, 0x80
	v_add_u32_e32 v57, 0x400, v5
	v_add_u32_e32 v58, 0x400, v6
	v_add_u32_e32 v59, 0x400, v7
	s_waitcnt vmcnt(11)
	v_ffbh_u32_e32 v0, v9
	v_ffbh_u32_e32 v1, v11
	s_waitcnt vmcnt(10)
	v_lshlrev_b32_e32 v60, 16, v12
	v_and_b32_e32 v62, 0xffff0000, v12
	v_lshlrev_b32_e32 v145, 16, v13
	v_and_b32_e32 v147, 0xffff0000, v13
	v_lshlrev_b32_e32 v149, 16, v14
	v_and_b32_e32 v151, 0xffff0000, v14
	v_min_u32_e32 v12, 32, v0
	v_min_u32_e32 v13, 32, v1
	s_waitcnt vmcnt(3)
	v_ffbh_u32_e32 v14, v41
	v_lshlrev_b32_e32 v61, 16, v16
	v_and_b32_e32 v63, 0xffff0000, v16
	v_lshlrev_b32_e32 v146, 16, v17
	v_and_b32_e32 v148, 0xffff0000, v17
	v_lshlrev_b32_e32 v150, 16, v18
	v_and_b32_e32 v152, 0xffff0000, v18
	v_lshlrev_b32_e32 v153, 16, v15
	v_and_b32_e32 v155, 0xffff0000, v15
	v_ffbh_u32_e32 v15, v43
	s_waitcnt vmcnt(2)
	v_ffbh_u32_e32 v16, v45
	v_ffbh_u32_e32 v17, v47
	s_waitcnt vmcnt(0)
	v_ffbh_u32_e32 v18, v53
	v_lshlrev_b64 v[0:1], v12, v[8:9]
	v_sub_u32_e32 v183, 32, v12
	v_lshlrev_b64 v[8:9], v13, v[10:11]
	v_min_u32_e32 v12, 32, v14
	v_lshlrev_b32_e32 v154, 16, v19
	v_and_b32_e32 v156, 0xffff0000, v19
	v_lshlrev_b32_e32 v157, 16, v20
	v_and_b32_e32 v159, 0xffff0000, v20
	v_lshlrev_b32_e32 v160, 16, v21
	v_and_b32_e32 v162, 0xffff0000, v21
	v_min_u32_e32 v14, 32, v15
	v_min_u32_e32 v16, 32, v16
	v_min_u32_e32 v20, 32, v17
	v_min_u32_e32 v21, 32, v18
	v_min_u32_e32 v0, 1, v0
	v_min_u32_e32 v8, 1, v8
	v_lshlrev_b64 v[10:11], v12, v[40:41]
	v_sub_u32_e32 v184, 32, v13
	v_sub_u32_e32 v40, 32, v12
	v_lshlrev_b64 v[12:13], v14, v[42:43]
	v_sub_u32_e32 v41, 32, v14
	v_lshlrev_b64 v[14:15], v16, v[44:45]
	v_sub_u32_e32 v42, 32, v16
	v_lshlrev_b64 v[16:17], v20, v[46:47]
	v_lshlrev_b64 v[18:19], v21, v[52:53]
	v_or_b32_e32 v0, v1, v0
	v_or_b32_e32 v1, v9, v8
	v_min_u32_e32 v8, 1, v10
	v_sub_u32_e32 v43, 32, v20
	v_sub_u32_e32 v44, 32, v21
	v_min_u32_e32 v9, 1, v12
	v_min_u32_e32 v10, 1, v14
	v_min_u32_e32 v12, 1, v16
	v_min_u32_e32 v14, 1, v18
	v_cvt_f32_u32_e32 v0, v0
	v_or_b32_e32 v8, v11, v8
	v_cvt_f32_u32_e32 v1, v1
	v_or_b32_e32 v9, v13, v9
	v_or_b32_e32 v10, v15, v10
	v_or_b32_e32 v11, v17, v12
	v_or_b32_e32 v12, v19, v14
	v_cvt_f32_u32_e32 v8, v8
	v_cvt_f32_u32_e32 v9, v9
	v_cvt_f32_u32_e32 v10, v10
	v_cvt_f32_u32_e32 v11, v11
	v_cvt_f32_u32_e32 v12, v12
	v_ldexp_f32 v0, v0, v183
	v_ldexp_f32 v1, v1, v184
	v_mul_f32_e32 v0, 0x2b800000, v0
	v_ldexp_f32 v8, v8, v40
	v_mul_f32_e32 v1, 0x2b800000, v1
	v_ldexp_f32 v9, v9, v41
	v_ldexp_f32 v10, v10, v42
	v_ldexp_f32 v11, v11, v43
	v_ldexp_f32 v12, v12, v44
	v_fmamk_f32 v0, v0, 0x3b000000, v143
	v_mul_f32_e32 v8, 0x2b800000, v8
	v_fmamk_f32 v1, v1, 0x3b000000, v143
	v_mul_f32_e32 v9, 0x2b800000, v9
	v_mul_f32_e32 v10, 0x2b800000, v10
	v_mul_f32_e32 v11, 0x2b800000, v11
	v_mul_f32_e32 v12, 0x2b800000, v12
	v_rsq_f32_e32 v0, v0
	v_fmamk_f32 v8, v8, 0x3b000000, v143
	v_rsq_f32_e32 v1, v1
	v_fmamk_f32 v9, v9, 0x3b000000, v143
	v_fmamk_f32 v10, v10, 0x3b000000, v143
	v_fmamk_f32 v11, v11, 0x3b000000, v143
	v_fmamk_f32 v12, v12, 0x3b000000, v143
	v_rsq_f32_e32 v8, v8
	v_cvt_f32_u32_e32 v54, v54
	v_cvt_f32_u32_e32 v55, v55
	v_fmamk_f32 v54, v55, 0x4f800000, v54
	v_fmamk_f32 v13, v54, 0x27000000, v143
	v_rsq_f32_e32 v9, v9
	v_rsq_f32_e32 v10, v10
	v_rsq_f32_e32 v11, v11
	v_rsq_f32_e32 v12, v12
	v_rsq_f32_e32 v13, v13
	v_mul_f32_e32 v14, v0, v60
	v_mul_f32_e32 v16, v0, v62
	v_mul_f32_e32 v18, v0, v145
	v_mul_f32_e32 v20, v0, v147
	v_mul_f32_e32 v40, v0, v149
	v_mul_f32_e32 v42, v0, v151
	v_mul_f32_e32 v44, v0, v153
	v_mul_f32_e32 v0, v0, v155
	v_lshlrev_b32_e32 v158, 16, v24
	v_and_b32_e32 v24, 0xffff0000, v24
	v_lshlrev_b32_e32 v161, 16, v25
	v_and_b32_e32 v25, 0xffff0000, v25
	v_lshlrev_b32_e32 v163, 16, v22
	v_lshlrev_b32_e32 v164, 16, v26
; __device__ __forceinline__ float ss_val(u64 v) { return (float)v * (1.0f / 1099511627776.0f); }
; __device__ __forceinline__ unsigned pk2(float lo, float hi) { return f2bf(lo) | (f2bf(hi) << 16); }
; __device__ __forceinline__ void gmlp_unit(LAS unsigned char* wl, const bf16* PROJ, const u64* rowss_v, const bf16* wsb, const float* norm_v, const float* b_s, bf16* Y, int nb, int g, int lane) {
;     ...
;         const int s0 = it * 16 + 2 * sp;
;         const float r0 = __builtin_amdgcn_rsqf(ss_val(rowss_v[tok0 + s0]) * (1.f / 512.f) + EPS), r1 = __builtin_amdgcn_rsqf(ss_val(rowss_v[tok0 + s0 + 1]) * (1.f / 512.f) + EPS);
;         const u32x4 va = *(const u32x4*)(PROJ + (size_t)(tok0 + s0) * NPROJ + 512 + g * 64 + 8 * cc);
;         const u32x4 vb = *(const u32x4*)(PROJ + (size_t)(tok0 + s0 + 1) * NPROJ + 512 + g * 64 + 8 * cc);
; #pragma unroll
;         for (int i = 0; i < 4; ++i) {
;             VT32[(8 * cc + 2 * i) * (VS / 2) + (s0 >> 1)] = pk2(bf_lo(va[i]) * r0, bf_lo(vb[i]) * r1);
;             VT32[(8 * cc + 2 * i + 1) * (VS / 2) + (s0 >> 1)] = pk2(bf_hi(va[i]) * r0, bf_hi(vb[i]) * r1);
;         }
	v_and_b32_e32 v22, 0xffff0000, v22
	v_and_b32_e32 v26, 0xffff0000, v26
	v_lshlrev_b32_e32 v165, 16, v23
	v_lshlrev_b32_e32 v166, 16, v27
	v_and_b32_e32 v23, 0xffff0000, v23
	v_and_b32_e32 v27, 0xffff0000, v27
	v_lshlrev_b32_e32 v167, 16, v28
	v_and_b32_e32 v28, 0xffff0000, v28
	v_lshlrev_b32_e32 v168, 16, v29
	v_and_b32_e32 v29, 0xffff0000, v29
	v_lshlrev_b32_e32 v169, 16, v30
	v_and_b32_e32 v30, 0xffff0000, v30
	v_lshlrev_b32_e32 v170, 16, v31
	v_and_b32_e32 v31, 0xffff0000, v31
	v_lshlrev_b32_e32 v171, 16, v32
	v_and_b32_e32 v32, 0xffff0000, v32
	v_lshlrev_b32_e32 v173, 16, v33
	v_and_b32_e32 v33, 0xffff0000, v33
	v_lshlrev_b32_e32 v175, 16, v34
	v_and_b32_e32 v34, 0xffff0000, v34
	v_lshlrev_b32_e32 v177, 16, v35
	v_and_b32_e32 v35, 0xffff0000, v35
	v_lshlrev_b32_e32 v179, 16, v48
	v_and_b32_e32 v48, 0xffff0000, v48
	v_lshlrev_b32_e32 v180, 16, v49
	v_and_b32_e32 v49, 0xffff0000, v49
	v_lshlrev_b32_e32 v181, 16, v50
	v_and_b32_e32 v50, 0xffff0000, v50
	v_lshlrev_b32_e32 v182, 16, v51
	v_and_b32_e32 v51, 0xffff0000, v51
	v_mul_f32_e32 v15, v1, v61
	v_mul_f32_e32 v17, v1, v63
	v_mul_f32_e32 v19, v1, v146
	v_mul_f32_e32 v21, v1, v148
	v_mul_f32_e32 v41, v1, v150
	v_mul_f32_e32 v43, v1, v152
	v_mul_f32_e32 v45, v1, v154
	v_mul_f32_e32 v1, v1, v156
	v_bfe_u32 v46, v14, 16, 1
	v_bfe_u32 v52, v16, 16, 1
	v_bfe_u32 v60, v20, 16, 1
	v_bfe_u32 v62, v40, 16, 1
	v_bfe_u32 v145, v42, 16, 1
	v_bfe_u32 v147, v44, 16, 1
	v_bfe_u32 v149, v0, 16, 1
	v_mul_f32_e32 v151, v8, v157
	v_mul_f32_e32 v153, v8, v159
	v_lshlrev_b32_e32 v172, 16, v36
	v_and_b32_e32 v36, 0xffff0000, v36
	v_lshlrev_b32_e32 v174, 16, v37
	v_and_b32_e32 v37, 0xffff0000, v37
	v_lshlrev_b32_e32 v176, 16, v38
	v_and_b32_e32 v38, 0xffff0000, v38
	v_lshlrev_b32_e32 v178, 16, v39
	v_and_b32_e32 v39, 0xffff0000, v39
	v_bfe_u32 v47, v15, 16, 1
	v_bfe_u32 v53, v17, 16, 1
	v_bfe_u32 v54, v18, 16, 1
	v_bfe_u32 v61, v21, 16, 1
	v_bfe_u32 v63, v41, 16, 1
	v_bfe_u32 v146, v43, 16, 1
	v_bfe_u32 v148, v45, 16, 1
	v_bfe_u32 v150, v1, 16, 1
	v_mul_f32_e32 v152, v9, v158
	v_mul_f32_e32 v24, v9, v24
	v_mul_f32_e32 v154, v8, v160
	v_mul_f32_e32 v155, v9, v161
	v_mul_f32_e32 v156, v8, v162
	v_mul_f32_e32 v25, v9, v25
	v_mul_f32_e32 v157, v8, v163
	v_mul_f32_e32 v158, v9, v164
	v_mul_f32_e32 v22, v8, v22
	v_mul_f32_e32 v26, v9, v26
	v_mul_f32_e32 v159, v8, v165
	v_mul_f32_e32 v160, v9, v166
	v_mul_f32_e32 v8, v8, v23
	v_mul_f32_e32 v9, v9, v27
	v_mul_f32_e32 v23, v10, v179
	v_mul_f32_e32 v27, v11, v167
	v_mul_f32_e32 v48, v10, v48
	v_mul_f32_e32 v28, v11, v28
	v_mul_f32_e32 v161, v10, v180
	v_mul_f32_e32 v162, v11, v168
	v_mul_f32_e32 v49, v10, v49
	v_mul_f32_e32 v29, v11, v29
	v_mul_f32_e32 v163, v10, v181
	v_mul_f32_e32 v164, v11, v169
	v_mul_f32_e32 v50, v10, v50
	v_mul_f32_e32 v30, v11, v30
	v_mul_f32_e32 v165, v10, v182
	v_mul_f32_e32 v166, v11, v170
	v_mul_f32_e32 v10, v10, v51
	v_mul_f32_e32 v11, v11, v31
	v_mul_f32_e32 v31, v12, v171
	v_mul_f32_e32 v32, v12, v32
	v_mul_f32_e32 v167, v12, v173
	v_mul_f32_e32 v33, v12, v33
	v_mul_f32_e32 v169, v12, v175
	v_mul_f32_e32 v34, v12, v34
	v_mul_f32_e32 v171, v12, v177
	v_mul_f32_e32 v12, v12, v35
	v_add3_u32 v14, v14, v46, s5
	v_add3_u32 v16, v16, v52, s5
	v_add3_u32 v20, v20, v60, s5
	v_add3_u32 v35, v40, v62, s5
	v_add3_u32 v40, v42, v145, s5
	v_add3_u32 v42, v44, v147, s5
	v_add3_u32 v0, v0, v149, s5
	v_bfe_u32 v44, v151, 16, 1
	v_bfe_u32 v46, v153, 16, 1
	v_bfe_u32 v55, v19, 16, 1
	v_mul_f32_e32 v51, v13, v172
	v_mul_f32_e32 v36, v13, v36
	v_mul_f32_e32 v168, v13, v174
	v_mul_f32_e32 v37, v13, v37
	v_mul_f32_e32 v170, v13, v176
	v_mul_f32_e32 v38, v13, v38
	v_mul_f32_e32 v172, v13, v178
	v_mul_f32_e32 v13, v13, v39
	v_add3_u32 v15, v15, v47, s5
	v_add3_u32 v17, v17, v53, s5
	v_add3_u32 v18, v18, v54, s5
	v_add3_u32 v21, v21, v61, s5
	v_add3_u32 v39, v41, v63, s5
	v_add3_u32 v41, v43, v146, s5
	v_add3_u32 v43, v45, v148, s5
	v_add3_u32 v1, v1, v150, s5
	v_bfe_u32 v45, v152, 16, 1
	v_bfe_u32 v47, v24, 16, 1
	v_bfe_u32 v52, v154, 16, 1
	v_bfe_u32 v53, v155, 16, 1
	v_bfe_u32 v54, v156, 16, 1
	v_bfe_u32 v60, v157, 16, 1
	v_bfe_u32 v62, v22, 16, 1
	v_bfe_u32 v145, v159, 16, 1
	v_bfe_u32 v147, v8, 16, 1
	v_bfe_u32 v149, v23, 16, 1
	v_bfe_u32 v173, v48, 16, 1
	v_bfe_u32 v175, v161, 16, 1
	v_bfe_u32 v177, v49, 16, 1
	v_bfe_u32 v179, v163, 16, 1
	v_bfe_u32 v181, v50, 16, 1
	v_bfe_u32 v183, v165, 16, 1
	v_bfe_u32 v185, v10, 16, 1
	v_bfe_u32 v187, v31, 16, 1
	v_bfe_u32 v189, v32, 16, 1
	v_bfe_u32 v191, v167, 16, 1
	v_bfe_u32 v193, v33, 16, 1
	v_bfe_u32 v195, v169, 16, 1
	v_bfe_u32 v197, v34, 16, 1
	v_bfe_u32 v199, v171, 16, 1
	v_bfe_u32 v203, v12, 16, 1
	v_lshrrev_b32_e32 v14, 16, v14
	v_lshrrev_b32_e32 v16, 16, v16
	v_lshrrev_b32_e32 v20, 16, v20
	v_lshrrev_b32_e32 v0, 16, v0
	v_add3_u32 v44, v151, v44, s5
	v_add3_u32 v46, v153, v46, s5
	v_add3_u32 v19, v19, v55, s5
	v_bfe_u32 v55, v25, 16, 1
	v_bfe_u32 v61, v158, 16, 1
	v_bfe_u32 v63, v26, 16, 1
	v_bfe_u32 v146, v160, 16, 1
	v_bfe_u32 v148, v9, 16, 1
	v_bfe_u32 v150, v27, 16, 1
	v_bfe_u32 v174, v28, 16, 1
	v_bfe_u32 v176, v162, 16, 1
	v_bfe_u32 v178, v29, 16, 1
	v_bfe_u32 v180, v164, 16, 1
	v_bfe_u32 v182, v30, 16, 1
	v_bfe_u32 v184, v166, 16, 1
	v_bfe_u32 v186, v11, 16, 1
	v_bfe_u32 v188, v51, 16, 1
	v_bfe_u32 v190, v36, 16, 1
	v_bfe_u32 v192, v168, 16, 1
	v_bfe_u32 v194, v37, 16, 1
	v_bfe_u32 v196, v170, 16, 1
	v_bfe_u32 v198, v38, 16, 1
	v_bfe_u32 v202, v172, 16, 1
	v_bfe_u32 v204, v13, 16, 1
	v_lshrrev_b32_e32 v18, 16, v18
	v_lshrrev_b32_e32 v35, 16, v35
	v_lshrrev_b32_e32 v40, 16, v40
	v_lshrrev_b32_e32 v42, 16, v42
	v_add3_u32 v45, v152, v45, s5
	v_add3_u32 v24, v24, v47, s5
	v_add3_u32 v47, v154, v52, s5
; #define LAS __attribute__((address_space(3)))
; #define LDS_WAIT() asm volatile("s_waitcnt lgkmcnt(0)" ::: "memory")
; __device__ __forceinline__ unsigned pk2(float lo, float hi) { return f2bf(lo) | (f2bf(hi) << 16); }
; template <int HF>
; __device__ __forceinline__ void gmlp_half(LAS unsigned char* wl, const bf16* PROJ, const bf16* wsg, const float* norm_v, const float* b_s, bf16* Y, int tok0, int g, int fr, int fq) {
;     ...
;     bf16x8 bw[NK][4];
; #pragma unroll
;     for (int ki = 0; ki < NK; ++ki)
; #pragma unroll
;         for (int nt = 0; nt < 4; ++nt) bw[ki][nt] = *(const bf16x8*)(wsg + (size_t)(64 * HF + 16 * nt + fr) * 128 + 32 * ki + 8 * fq);
;     f32x4 acc[4][4];
; #pragma unroll
;     for (int i = 0; i < 4; ++i)
; #pragma unroll
;         for (int j = 0; j < 4; ++j) acc[i][j] = (f32x4){0.f, 0.f, 0.f, 0.f};
; #pragma unroll
;     for (int ki = 0; ki < NK; ++ki) {
;         bf16x8 av[4];
; #pragma unroll
;         for (int mi = 0; mi < 4; ++mi) av[mi] = *(const LAS bf16x8*)(wl + ((32 * (mi >> 1) + 8 * (fr >> 2) + 4 * (mi & 1) + (fr & 3)) * VS + 32 * ki + 8 * fq) * 2);
; #pragma unroll
;         for (int nt = 0; nt < 4; ++nt)
; #pragma unroll
;             for (int mi = 0; mi < 4; ++mi) acc[mi][nt] = __builtin_amdgcn_mfma_f32_16x16x32_bf16(av[mi], bw[ki][nt], acc[mi][nt], 0, 0, 0);
;     }
; __device__ __forceinline__ void gmlp_unit(LAS unsigned char* wl, const bf16* PROJ, const u64* rowss_v, const bf16* wsb, const float* norm_v, const float* b_s, bf16* Y, int nb, int g, int lane) {
;     ...
;         for (int i = 0; i < 4; ++i) {
;             VT32[(8 * cc + 2 * i) * (VS / 2) + (s0 >> 1)] = pk2(bf_lo(va[i]) * r0, bf_lo(vb[i]) * r1);
;             VT32[(8 * cc + 2 * i + 1) * (VS / 2) + (s0 >> 1)] = pk2(bf_hi(va[i]) * r0, bf_hi(vb[i]) * r1);
;         }
;     }
;     LDS_WAIT(); asm volatile("" ::: "memory");
	v_add3_u32 v52, v155, v53, s5
	v_add3_u32 v53, v156, v54, s5
	v_add3_u32 v54, v157, v60, s5
	v_add3_u32 v22, v22, v62, s5
	v_add3_u32 v60, v159, v145, s5
	v_add3_u32 v8, v8, v147, s5
	v_add3_u32 v23, v23, v149, s5
	v_add3_u32 v48, v48, v173, s5
	v_add3_u32 v62, v161, v175, s5
	v_add3_u32 v49, v49, v177, s5
	v_add3_u32 v145, v163, v179, s5
	v_add3_u32 v50, v50, v181, s5
	v_add3_u32 v147, v165, v183, s5
	v_add3_u32 v10, v10, v185, s5
	v_add3_u32 v31, v31, v187, s5
	v_add3_u32 v32, v32, v189, s5
	v_add3_u32 v149, v167, v191, s5
	v_add3_u32 v33, v33, v193, s5
	v_add3_u32 v151, v169, v195, s5
	v_add3_u32 v34, v34, v197, s5
	v_add3_u32 v153, v171, v199, s5
	v_add3_u32 v12, v12, v203, s5
	v_and_or_b32 v14, v15, s11, v14
	v_and_or_b32 v15, v17, s11, v16
	v_and_or_b32 v17, v21, s11, v20
	v_and_or_b32 v0, v1, s11, v0
	v_lshrrev_b32_e32 v1, 16, v44
	v_lshrrev_b32_e32 v21, 16, v46
	v_add3_u32 v25, v25, v55, s5
	v_add3_u32 v55, v158, v61, s5
	v_add3_u32 v26, v26, v63, s5
	v_add3_u32 v61, v160, v146, s5
	v_add3_u32 v9, v9, v148, s5
	v_add3_u32 v27, v27, v150, s5
	v_add3_u32 v28, v28, v174, s5
	v_add3_u32 v63, v162, v176, s5
	v_add3_u32 v29, v29, v178, s5
	v_add3_u32 v146, v164, v180, s5
	v_add3_u32 v30, v30, v182, s5
	v_add3_u32 v148, v166, v184, s5
	v_add3_u32 v11, v11, v186, s5
	v_add3_u32 v51, v51, v188, s5
	v_add3_u32 v36, v36, v190, s5
	v_add3_u32 v150, v168, v192, s5
	v_add3_u32 v37, v37, v194, s5
	v_add3_u32 v152, v170, v196, s5
	v_add3_u32 v38, v38, v198, s5
	v_add3_u32 v154, v172, v202, s5
	v_add3_u32 v13, v13, v204, s5
	v_and_or_b32 v16, v19, s11, v18
	v_and_or_b32 v18, v39, s11, v35
	v_and_or_b32 v19, v41, s11, v40
	v_and_or_b32 v20, v43, s11, v42
	v_lshrrev_b32_e32 v35, 16, v47
	v_lshrrev_b32_e32 v39, 16, v53
	v_lshrrev_b32_e32 v40, 16, v54
	v_lshrrev_b32_e32 v22, 16, v22
	v_lshrrev_b32_e32 v41, 16, v60
	v_lshrrev_b32_e32 v8, 16, v8
	v_lshrrev_b32_e32 v23, 16, v23
	v_lshrrev_b32_e32 v42, 16, v48
	v_lshrrev_b32_e32 v43, 16, v62
	v_lshrrev_b32_e32 v44, 16, v49
	v_lshrrev_b32_e32 v46, 16, v145
	v_lshrrev_b32_e32 v47, 16, v50
	v_lshrrev_b32_e32 v48, 16, v147
	v_lshrrev_b32_e32 v10, 16, v10
	v_lshrrev_b32_e32 v31, 16, v31
	v_lshrrev_b32_e32 v32, 16, v32
	v_lshrrev_b32_e32 v49, 16, v149
	v_lshrrev_b32_e32 v33, 16, v33
	v_lshrrev_b32_e32 v50, 16, v151
	v_lshrrev_b32_e32 v34, 16, v34
	v_lshrrev_b32_e32 v53, 16, v153
	v_lshrrev_b32_e32 v12, 16, v12
	ds_write2_b32 v4, v14, v15 offset1:68
	ds_write2_b32 v4, v16, v17 offset0:136 offset1:204
	ds_write2_b32 v56, v18, v19 offset0:16 offset1:84
	ds_write2_b32 v56, v20, v0 offset0:152 offset1:220
	v_and_or_b32 v0, v45, s11, v1
	v_and_or_b32 v1, v24, s11, v21
	v_and_or_b32 v4, v52, s11, v35
	v_and_or_b32 v14, v25, s11, v39
	v_and_or_b32 v15, v55, s11, v40
	v_and_or_b32 v16, v26, s11, v22
	v_and_or_b32 v17, v61, s11, v41
	v_and_or_b32 v8, v9, s11, v8
	v_and_or_b32 v9, v27, s11, v23
	v_and_or_b32 v18, v28, s11, v42
	v_and_or_b32 v19, v63, s11, v43
	v_and_or_b32 v20, v29, s11, v44
	v_and_or_b32 v21, v146, s11, v46
	v_and_or_b32 v22, v30, s11, v47
	v_and_or_b32 v23, v148, s11, v48
	v_and_or_b32 v10, v11, s11, v10
	v_and_or_b32 v11, v51, s11, v31
	v_and_or_b32 v24, v36, s11, v32
	v_and_or_b32 v25, v150, s11, v49
	v_and_or_b32 v26, v37, s11, v33
	v_and_or_b32 v27, v152, s11, v50
	v_and_or_b32 v28, v38, s11, v34
	v_and_or_b32 v29, v154, s11, v53
	v_and_or_b32 v12, v13, s11, v12
	ds_write2_b32 v5, v0, v1 offset1:68
	ds_write2_b32 v5, v4, v14 offset0:136 offset1:204
	ds_write2_b32 v57, v15, v16 offset0:16 offset1:84
	ds_write2_b32 v57, v17, v8 offset0:152 offset1:220
	ds_write2_b32 v6, v9, v18 offset1:68
	ds_write2_b32 v6, v19, v20 offset0:136 offset1:204
	ds_write2_b32 v58, v21, v22 offset0:16 offset1:84
	ds_write2_b32 v58, v23, v10 offset0:152 offset1:220
	ds_write2_b32 v7, v11, v24 offset1:68
	ds_write2_b32 v7, v25, v26 offset0:136 offset1:204
	ds_write2_b32 v59, v27, v28 offset0:16 offset1:84
	ds_write2_b32 v59, v29, v12 offset0:152 offset1:220
	s_cbranch_scc1 .LBB0_418
	s_waitcnt lgkmcnt(0)
	global_load_dwordx4 v[4:7], v[68:69], off
	ds_read_b128 v[20:23], v144
	ds_read_b128 v[28:31], v144 offset:1088
	global_load_dwordx4 v[146:149], v[68:69], off offset:64
	ds_read_b128 v[48:51], v144 offset:64
	ds_read_b128 v[12:15], v144 offset:8704
	ds_read_b128 v[32:35], v144 offset:1152
	global_load_dwordx4 v[24:27], v[70:71], off
	ds_read_b128 v[8:11], v144 offset:8768
	ds_read_b128 v[16:19], v144 offset:9792
	ds_read_b128 v[0:3], v144 offset:9856
	s_lshl_b32 s21, s20, 4
	s_and_b32 s28, s21, 0xffffff80
	v_or_b32_e32 v198, s28, v129
	global_load_dwordx4 v[190:193], v[76:77], off
	v_ashrrev_i32_e32 v199, 31, v198
	s_add_i32 s20, s20, s36
	s_add_i32 s2, s2, s3
	s_cmpk_gt_i32 s20, 0xff
	s_waitcnt vmcnt(3) lgkmcnt(7)
	v_mfma_f32_16x16x32_bf16 v[36:39], v[20:23], v[4:7], 0
	s_waitcnt lgkmcnt(6)
	v_mfma_f32_16x16x32_bf16 v[150:153], v[28:31], v[4:7], 0
	s_waitcnt lgkmcnt(4)
	v_mfma_f32_16x16x32_bf16 v[154:157], v[12:15], v[4:7], 0
	s_waitcnt lgkmcnt(1)
	v_mfma_f32_16x16x32_bf16 v[158:161], v[16:19], v[4:7], 0
	global_load_dwordx4 v[4:7], v[72:73], off
	s_waitcnt vmcnt(2)
	v_mfma_f32_16x16x32_bf16 v[162:165], v[20:23], v[24:27], 0
	v_mfma_f32_16x16x32_bf16 v[166:169], v[28:31], v[24:27], 0
	v_mfma_f32_16x16x32_bf16 v[170:173], v[12:15], v[24:27], 0
	v_mfma_f32_16x16x32_bf16 v[174:177], v[16:19], v[24:27], 0
	global_load_dwordx4 v[24:27], v[74:75], off
	v_mfma_f32_16x16x32_bf16 v[194:197], v[48:51], v[146:149], v[36:39]
	v_mfma_f32_16x16x32_bf16 v[150:153], v[32:35], v[146:149], v[150:153]
	v_mfma_f32_16x16x32_bf16 v[154:157], v[8:11], v[146:149], v[154:157]
	s_waitcnt lgkmcnt(0)
	v_mfma_f32_16x16x32_bf16 v[146:149], v[0:3], v[146:149], v[158:161]
	s_waitcnt vmcnt(2)
; __device__ __forceinline__ unsigned pk2(float lo, float hi) { return f2bf(lo) | (f2bf(hi) << 16); }
; template <int HF>
; __device__ __forceinline__ void gmlp_half(LAS unsigned char* wl, const bf16* PROJ, const bf16* wsg, const float* norm_v, const float* b_s, bf16* Y, int tok0, int g, int fr, int fq) {
;     ...
;         for (int nt = 0; nt < 4; ++nt)
; #pragma unroll
;             for (int mi = 0; mi < 4; ++mi) acc[mi][nt] = __builtin_amdgcn_mfma_f32_16x16x32_bf16(av[mi], bw[ki][nt], acc[mi][nt], 0, 0, 0);
;     }
;     asm volatile("" ::: "memory");
;     f32x4 nv[2][2];
; #pragma unroll
;     for (int p = 0; p < 2; ++p) { nv[p][0] = *(const f32x4*)(norm_v + g * 64 + 32 * p + 8 * fq); nv[p][1] = *(const f32x4*)(norm_v + g * 64 + 32 * p + 8 * fq + 4); }
; #pragma unroll
;     for (int nt = 0; nt < 4; ++nt) {
;         const int t = 64 * HF + 16 * nt + fr; const size_t tok = (size_t)(tok0 + t); const float bs = b_s[g * 128 + t];
;         u32x4 uu[2];
; #pragma unroll
;         for (int p = 0; p < 2; ++p) uu[p] = *(const u32x4*)(PROJ + tok * NPROJ + g * 64 + 32 * p + 8 * fq);
; #pragma unroll
;         for (int p = 0; p < 2; ++p) {
;             u32x4 w;
; #pragma unroll
;             for (int e2 = 0; e2 < 2; ++e2) {
;                 const f32x4 z = nv[p][e2] * acc[2 * p + e2][nt] + bs;
;                 const unsigned u0 = uu[p][2 * e2], u1 = uu[p][2 * e2 + 1];
;                 w[2 * e2] = pk2(bf_lo(u0) * z[0], bf_hi(u0) * z[1]); w[2 * e2 + 1] = pk2(bf_lo(u1) * z[2], bf_hi(u1) * z[3]);
;             }
;             *(u32x4*)(Y + tok * D + g * 64 + 32 * p + 8 * fq) = w;
;         }
;     }
	v_mfma_f32_16x16x32_bf16 v[158:161], v[48:51], v[190:193], v[162:165]
	v_mfma_f32_16x16x32_bf16 v[162:165], v[32:35], v[190:193], v[166:169]
	v_mfma_f32_16x16x32_bf16 v[166:169], v[8:11], v[190:193], v[170:173]
	v_mfma_f32_16x16x32_bf16 v[170:173], v[0:3], v[190:193], v[174:177]
	s_waitcnt vmcnt(1)
	v_mfma_f32_16x16x32_bf16 v[178:181], v[20:23], v[4:7], 0
	v_mfma_f32_16x16x32_bf16 v[182:185], v[28:31], v[4:7], 0
	v_mfma_f32_16x16x32_bf16 v[186:189], v[12:15], v[4:7], 0
	v_mfma_f32_16x16x32_bf16 v[52:55], v[16:19], v[4:7], 0
	global_load_dwordx4 v[60:63], v[78:79], off
	global_load_dwordx4 v[4:7], v[80:81], off
	s_waitcnt vmcnt(2)
	v_mfma_f32_16x16x32_bf16 v[56:59], v[20:23], v[24:27], 0
	v_mad_i64_i32 v[20:21], s[30:31], v198, s4, v[82:83]
	global_load_dwordx4 v[202:205], v[20:21], off
	global_load_dwordx4 v[44:47], v[118:119], off
	global_load_dword v210, v[120:121], off
	v_mfma_f32_16x16x32_bf16 v[40:43], v[28:31], v[24:27], 0
	global_load_dwordx4 v[36:39], v[118:119], off offset:16
	global_load_dwordx4 v[28:31], v[118:119], off offset:128
	global_load_dwordx4 v[206:209], v[20:21], off offset:64
	v_lshlrev_b64 v[198:199], 11, v[198:199]
	global_load_dwordx4 v[20:23], v[118:119], off offset:144
	v_lshl_add_u64 v[198:199], v[84:85], 0, v[198:199]
	v_mfma_f32_16x16x32_bf16 v[12:15], v[12:15], v[24:27], 0
	s_waitcnt vmcnt(6)
	v_lshlrev_b32_e32 v213, 16, v203
	v_lshlrev_b32_e32 v212, 16, v202
	s_waitcnt vmcnt(4)
	v_pk_fma_f32 v[174:175], v[196:197], v[46:47], v[210:211] op_sel_hi:[1,1,0]
	v_pk_fma_f32 v[176:177], v[194:195], v[44:45], v[210:211] op_sel_hi:[1,1,0]
	s_waitcnt vmcnt(3)
	v_pk_fma_f32 v[152:153], v[152:153], v[38:39], v[210:211] op_sel_hi:[1,1,0]
	v_pk_fma_f32 v[150:151], v[150:151], v[36:37], v[210:211] op_sel_hi:[1,1,0]
	v_lshlrev_b32_e32 v215, 16, v205
	v_lshlrev_b32_e32 v214, 16, v204
	v_and_b32_e32 v205, 0xffff0000, v205
	v_and_b32_e32 v204, 0xffff0000, v204
	v_mov_b32_e32 v190, v176
	v_mov_b32_e32 v191, v174
	v_mov_b32_e32 v174, v177
	v_mov_b32_e32 v176, v150
	v_mov_b32_e32 v177, v152
	v_mov_b32_e32 v152, v151
	v_and_b32_e32 v203, 0xffff0000, v203
	v_and_b32_e32 v202, 0xffff0000, v202
	v_pk_mul_f32 v[150:151], v[190:191], v[212:213]
	v_pk_mul_f32 v[176:177], v[176:177], v[214:215]
	v_pk_mul_f32 v[152:153], v[152:153], v[204:205]
	v_pk_mul_f32 v[174:175], v[174:175], v[202:203]
	v_bfe_u32 v145, v153, 16, 1
	v_bfe_u32 v193, v150, 16, 1
	v_bfe_u32 v194, v151, 16, 1
	v_bfe_u32 v195, v176, 16, 1
	v_bfe_u32 v196, v177, 16, 1
	v_bfe_u32 v190, v152, 16, 1
	v_bfe_u32 v191, v175, 16, 1
	v_bfe_u32 v192, v174, 16, 1
	v_add3_u32 v145, v153, v145, s5
	v_add3_u32 v153, v177, v196, s5
	v_add3_u32 v176, v176, v195, s5
	v_add3_u32 v151, v151, v194, s5
	v_add3_u32 v150, v150, v193, s5
	v_add3_u32 v174, v174, v192, s5
	v_add3_u32 v175, v175, v191, s5
	v_add3_u32 v152, v152, v190, s5
	v_lshrrev_b32_e32 v150, 16, v150
	v_lshrrev_b32_e32 v151, 16, v151
	v_lshrrev_b32_e32 v176, 16, v176
	v_lshrrev_b32_e32 v153, 16, v153
	v_and_or_b32 v153, v145, s11, v153
	v_and_or_b32 v152, v152, s11, v176
	v_and_or_b32 v151, v175, s11, v151
	v_and_or_b32 v150, v174, s11, v150
	global_store_dwordx4 v[198:199], v[150:153], off
	s_waitcnt vmcnt(1)
	v_pk_fma_f32 v[148:149], v[148:149], v[22:23], v[210:211] op_sel_hi:[1,1,0]
	v_pk_fma_f32 v[146:147], v[146:147], v[20:21], v[210:211] op_sel_hi:[1,1,0]
	v_pk_fma_f32 v[150:151], v[156:157], v[30:31], v[210:211] op_sel_hi:[1,1,0]
	v_pk_fma_f32 v[152:153], v[154:155], v[28:29], v[210:211] op_sel_hi:[1,1,0]
	v_lshlrev_b32_e32 v155, 16, v207
	v_lshlrev_b32_e32 v154, 16, v206
	v_mov_b32_e32 v156, v152
	v_mov_b32_e32 v157, v150
	v_pk_mul_f32 v[154:155], v[156:157], v[154:155]
	v_and_b32_e32 v157, 0xffff0000, v207
	v_and_b32_e32 v156, 0xffff0000, v206
	v_mov_b32_e32 v150, v153
	v_pk_mul_f32 v[150:151], v[150:151], v[156:157]
	v_lshlrev_b32_e32 v153, 16, v209
	v_lshlrev_b32_e32 v152, 16, v208
	v_mov_b32_e32 v156, v146
	v_mov_b32_e32 v157, v148
	v_pk_mul_f32 v[152:153], v[156:157], v[152:153]
	v_and_b32_e32 v157, 0xffff0000, v209
	v_and_b32_e32 v156, 0xffff0000, v208
	v_mov_b32_e32 v148, v147
	v_pk_mul_f32 v[146:147], v[148:149], v[156:157]
	v_bfe_u32 v149, v151, 16, 1
	v_bfe_u32 v145, v147, 16, 1
	v_bfe_u32 v148, v146, 16, 1
	v_bfe_u32 v156, v150, 16, 1
	v_add3_u32 v150, v150, v156, s5
	v_add3_u32 v151, v151, v149, s5
	v_add3_u32 v146, v146, v148, s5
	v_add3_u32 v145, v147, v145, s5
	v_bfe_u32 v147, v154, 16, 1
	v_bfe_u32 v148, v155, 16, 1
	v_bfe_u32 v149, v152, 16, 1
	v_bfe_u32 v156, v153, 16, 1
	v_add3_u32 v153, v153, v156, s5
	v_add3_u32 v149, v152, v149, s5
	v_add3_u32 v148, v155, v148, s5
	v_add3_u32 v147, v154, v147, s5
	v_lshrrev_b32_e32 v152, 16, v147
	v_lshrrev_b32_e32 v147, 16, v148
	v_lshrrev_b32_e32 v148, 16, v149
	v_lshrrev_b32_e32 v149, 16, v153
	v_and_or_b32 v149, v145, s11, v149
	v_and_or_b32 v148, v146, s11, v148
	v_and_or_b32 v147, v151, s11, v147
	v_and_or_b32 v146, v150, s11, v152
	global_store_dwordx4 v[198:199], v[146:149], off offset:64
	v_or_b32_e32 v190, s28, v133
	global_load_dword v192, v[120:121], off offset:64
	v_mad_i64_i32 v[154:155], s[30:31], v190, s4, v[82:83]
	global_load_dwordx4 v[146:149], v[154:155], off
	v_ashrrev_i32_e32 v191, 31, v190
	global_load_dwordx4 v[154:157], v[154:155], off offset:64
	v_mfma_f32_16x16x32_bf16 v[150:153], v[48:51], v[60:63], v[178:181]
	v_or_b32_e32 v198, s28, v135
	v_ashrrev_i32_e32 v199, 31, v198
	s_waitcnt vmcnt(2)
; __device__ __forceinline__ unsigned pk2(float lo, float hi) { return f2bf(lo) | (f2bf(hi) << 16); }
; template <int HF>
; __device__ __forceinline__ void gmlp_half(LAS unsigned char* wl, const bf16* PROJ, const bf16* wsg, const float* norm_v, const float* b_s, bf16* Y, int tok0, int g, int fr, int fq) {
;     ...
;     for (int nt = 0; nt < 4; ++nt) {
;         const int t = 64 * HF + 16 * nt + fr; const size_t tok = (size_t)(tok0 + t); const float bs = b_s[g * 128 + t];
;         u32x4 uu[2];
; #pragma unroll
;         for (int p = 0; p < 2; ++p) uu[p] = *(const u32x4*)(PROJ + tok * NPROJ + g * 64 + 32 * p + 8 * fq);
; #pragma unroll
;         for (int p = 0; p < 2; ++p) {
;             u32x4 w;
; #pragma unroll
;             for (int e2 = 0; e2 < 2; ++e2) {
;                 const f32x4 z = nv[p][e2] * acc[2 * p + e2][nt] + bs;
;                 const unsigned u0 = uu[p][2 * e2], u1 = uu[p][2 * e2 + 1];
;                 w[2 * e2] = pk2(bf_lo(u0) * z[0], bf_hi(u0) * z[1]); w[2 * e2 + 1] = pk2(bf_lo(u1) * z[2], bf_hi(u1) * z[3]);
;             }
;             *(u32x4*)(Y + tok * D + g * 64 + 32 * p + 8 * fq) = w;
;         }
;     }
	v_pk_fma_f32 v[160:161], v[160:161], v[46:47], v[192:193] op_sel_hi:[1,1,0]
	v_lshlrev_b64 v[178:179], 11, v[190:191]
	v_pk_fma_f32 v[158:159], v[158:159], v[44:45], v[192:193] op_sel_hi:[1,1,0]
	v_pk_fma_f32 v[164:165], v[164:165], v[38:39], v[192:193] op_sel_hi:[1,1,0]
	v_pk_fma_f32 v[162:163], v[162:163], v[36:37], v[192:193] op_sel_hi:[1,1,0]
	v_mfma_f32_16x16x32_bf16 v[174:177], v[32:35], v[60:63], v[182:185]
	s_nop 2
	v_lshl_add_u64 v[182:183], v[84:85], 0, v[178:179]
	v_mfma_f32_16x16x32_bf16 v[178:181], v[8:11], v[60:63], v[186:189]
	s_waitcnt vmcnt(1)
	v_lshlrev_b32_e32 v185, 16, v147
	v_lshlrev_b32_e32 v184, 16, v146
	v_and_b32_e32 v147, 0xffff0000, v147
	v_and_b32_e32 v146, 0xffff0000, v146
	v_lshlrev_b32_e32 v187, 16, v149
	v_lshlrev_b32_e32 v186, 16, v148
	v_and_b32_e32 v149, 0xffff0000, v149
	v_mov_b32_e32 v189, v160
	v_mov_b32_e32 v160, v159
	v_mov_b32_e32 v159, v164
	v_and_b32_e32 v148, 0xffff0000, v148
	v_mov_b32_e32 v164, v163
	v_mov_b32_e32 v188, v158
	v_mov_b32_e32 v158, v162
	v_pk_mul_f32 v[146:147], v[160:161], v[146:147]
	v_pk_mul_f32 v[148:149], v[164:165], v[148:149]
	v_pk_mul_f32 v[184:185], v[188:189], v[184:185]
	v_pk_mul_f32 v[158:159], v[158:159], v[186:187]
	v_bfe_u32 v145, v149, 16, 1
	v_bfe_u32 v160, v148, 16, 1
	v_bfe_u32 v161, v147, 16, 1
	v_bfe_u32 v162, v146, 16, 1
	v_add3_u32 v146, v146, v162, s5
	v_add3_u32 v147, v147, v161, s5
	v_add3_u32 v148, v148, v160, s5
	v_add3_u32 v145, v149, v145, s5
	v_bfe_u32 v149, v184, 16, 1
	v_bfe_u32 v160, v185, 16, 1
	v_bfe_u32 v161, v158, 16, 1
	v_bfe_u32 v162, v159, 16, 1
	v_add3_u32 v159, v159, v162, s5
	v_add3_u32 v158, v158, v161, s5
	v_add3_u32 v160, v185, v160, s5
	v_add3_u32 v149, v184, v149, s5
	v_lshrrev_b32_e32 v161, 16, v149
	v_lshrrev_b32_e32 v160, 16, v160
	v_lshrrev_b32_e32 v158, 16, v158
	v_lshrrev_b32_e32 v149, 16, v159
	v_and_or_b32 v149, v145, s11, v149
	v_and_or_b32 v148, v148, s11, v158
	v_and_or_b32 v147, v147, s11, v160
	v_and_or_b32 v146, v146, s11, v161
	global_store_dwordx4 v[182:183], v[146:149], off
	s_waitcnt vmcnt(1)
	v_lshlrev_b32_e32 v159, 16, v155
	v_lshlrev_b32_e32 v158, 16, v154
	v_pk_fma_f32 v[146:147], v[168:169], v[30:31], v[192:193] op_sel_hi:[1,1,0]
	v_pk_fma_f32 v[148:149], v[166:167], v[28:29], v[192:193] op_sel_hi:[1,1,0]
	v_mov_b32_e32 v161, v146
	v_and_b32_e32 v155, 0xffff0000, v155
	v_and_b32_e32 v154, 0xffff0000, v154
	v_mov_b32_e32 v146, v149
	v_mov_b32_e32 v160, v148
	v_pk_mul_f32 v[146:147], v[146:147], v[154:155]
	v_pk_fma_f32 v[148:149], v[172:173], v[22:23], v[192:193] op_sel_hi:[1,1,0]
	v_pk_fma_f32 v[154:155], v[170:171], v[20:21], v[192:193] op_sel_hi:[1,1,0]
	v_pk_mul_f32 v[158:159], v[160:161], v[158:159]
	v_lshlrev_b32_e32 v161, 16, v157
	v_lshlrev_b32_e32 v160, 16, v156
	v_mov_b32_e32 v163, v148
	v_and_b32_e32 v157, 0xffff0000, v157
	v_and_b32_e32 v156, 0xffff0000, v156
	v_mov_b32_e32 v148, v155
	v_mov_b32_e32 v162, v154
	v_pk_mul_f32 v[148:149], v[148:149], v[156:157]
	v_pk_mul_f32 v[160:161], v[162:163], v[160:161]
	v_bfe_u32 v145, v149, 16, 1
	v_bfe_u32 v154, v148, 16, 1
	v_bfe_u32 v155, v147, 16, 1
	v_bfe_u32 v156, v146, 16, 1
	v_add3_u32 v146, v146, v156, s5
	v_add3_u32 v147, v147, v155, s5
	v_add3_u32 v148, v148, v154, s5
	v_add3_u32 v145, v149, v145, s5
	v_bfe_u32 v149, v158, 16, 1
	v_bfe_u32 v154, v159, 16, 1
	v_bfe_u32 v155, v160, 16, 1
	v_bfe_u32 v156, v161, 16, 1
	v_add3_u32 v156, v161, v156, s5
	v_add3_u32 v155, v160, v155, s5
	v_add3_u32 v154, v159, v154, s5
	v_add3_u32 v149, v158, v149, s5
	v_lshrrev_b32_e32 v157, 16, v149
	v_lshrrev_b32_e32 v154, 16, v154
	v_lshrrev_b32_e32 v155, 16, v155
	v_lshrrev_b32_e32 v149, 16, v156
	v_and_or_b32 v149, v145, s11, v149
	v_and_or_b32 v148, v148, s11, v155
	v_and_or_b32 v147, v147, s11, v154
	v_and_or_b32 v146, v146, s11, v157
	global_store_dwordx4 v[182:183], v[146:149], off offset:64
	v_or_b32_e32 v154, s28, v134
	global_load_dword v156, v[120:121], off offset:128
	v_mad_i64_i32 v[158:159], s[30:31], v154, s4, v[82:83]
	global_load_dwordx4 v[146:149], v[158:159], off
	v_mfma_f32_16x16x32_bf16 v[52:55], v[0:3], v[60:63], v[52:55]
	global_load_dwordx4 v[60:63], v[158:159], off offset:64
	v_ashrrev_i32_e32 v155, 31, v154
	v_mfma_f32_16x16x32_bf16 v[48:51], v[48:51], v[4:7], v[56:59]
	s_nop 2
	v_lshlrev_b64 v[56:57], 11, v[154:155]
	v_lshl_add_u64 v[154:155], v[84:85], 0, v[56:57]
	v_mfma_f32_16x16x32_bf16 v[32:35], v[32:35], v[4:7], v[40:43]
	s_waitcnt vmcnt(2)
	v_pk_fma_f32 v[56:57], v[152:153], v[46:47], v[156:157] op_sel_hi:[1,1,0]
	v_pk_fma_f32 v[58:59], v[150:151], v[44:45], v[156:157] op_sel_hi:[1,1,0]
	v_mov_b32_e32 v153, v56
	s_waitcnt vmcnt(1)
	v_lshlrev_b32_e32 v151, 16, v147
	v_lshlrev_b32_e32 v150, 16, v146
	v_and_b32_e32 v147, 0xffff0000, v147
	v_and_b32_e32 v146, 0xffff0000, v146
	v_mov_b32_e32 v56, v59
	v_mov_b32_e32 v152, v58
	v_pk_mul_f32 v[56:57], v[56:57], v[146:147]
	v_pk_fma_f32 v[58:59], v[176:177], v[38:39], v[156:157] op_sel_hi:[1,1,0]
	v_pk_fma_f32 v[146:147], v[174:175], v[36:37], v[156:157] op_sel_hi:[1,1,0]
	v_pk_mul_f32 v[150:151], v[152:153], v[150:151]
	v_lshlrev_b32_e32 v153, 16, v149
	v_lshlrev_b32_e32 v152, 16, v148
	v_mov_b32_e32 v159, v58
	v_and_b32_e32 v149, 0xffff0000, v149
	v_and_b32_e32 v148, 0xffff0000, v148
	v_mov_b32_e32 v58, v147
	v_mov_b32_e32 v158, v146
	v_pk_mul_f32 v[58:59], v[58:59], v[148:149]
	v_pk_mul_f32 v[152:153], v[158:159], v[152:153]
	v_bfe_u32 v145, v59, 16, 1
	v_bfe_u32 v146, v58, 16, 1
	v_bfe_u32 v147, v57, 16, 1
	v_bfe_u32 v148, v56, 16, 1
	v_add3_u32 v56, v56, v148, s5
	v_add3_u32 v57, v57, v147, s5
	v_add3_u32 v58, v58, v146, s5
	v_add3_u32 v59, v59, v145, s5
	v_bfe_u32 v145, v150, 16, 1
	v_bfe_u32 v146, v151, 16, 1
	v_bfe_u32 v147, v152, 16, 1
	v_bfe_u32 v148, v153, 16, 1
	v_add3_u32 v148, v153, v148, s5
	v_add3_u32 v147, v152, v147, s5
	v_add3_u32 v146, v151, v146, s5
	v_add3_u32 v145, v150, v145, s5
	v_lshrrev_b32_e32 v145, 16, v145
	v_lshrrev_b32_e32 v146, 16, v146
	v_lshrrev_b32_e32 v147, 16, v147
	v_lshrrev_b32_e32 v148, 16, v148
	v_and_or_b32 v59, v59, s11, v148
	v_and_or_b32 v58, v58, s11, v147
	v_and_or_b32 v57, v57, s11, v146
	v_and_or_b32 v56, v56, s11, v145
	global_store_dwordx4 v[154:155], v[56:59], off
	s_waitcnt vmcnt(1)
; __device__ __forceinline__ unsigned pk2(float lo, float hi) { return f2bf(lo) | (f2bf(hi) << 16); }
; template <int HF>
; __device__ __forceinline__ void gmlp_half(LAS unsigned char* wl, const bf16* PROJ, const bf16* wsg, const float* norm_v, const float* b_s, bf16* Y, int tok0, int g, int fr, int fq) {
;     ...
;     for (int nt = 0; nt < 4; ++nt) {
;         const int t = 64 * HF + 16 * nt + fr; const size_t tok = (size_t)(tok0 + t); const float bs = b_s[g * 128 + t];
;         u32x4 uu[2];
; #pragma unroll
;         for (int p = 0; p < 2; ++p) uu[p] = *(const u32x4*)(PROJ + tok * NPROJ + g * 64 + 32 * p + 8 * fq);
; #pragma unroll
;         for (int p = 0; p < 2; ++p) {
;             u32x4 w;
; #pragma unroll
;             for (int e2 = 0; e2 < 2; ++e2) {
;                 const f32x4 z = nv[p][e2] * acc[2 * p + e2][nt] + bs;
;                 const unsigned u0 = uu[p][2 * e2], u1 = uu[p][2 * e2 + 1];
;                 w[2 * e2] = pk2(bf_lo(u0) * z[0], bf_hi(u0) * z[1]); w[2 * e2 + 1] = pk2(bf_lo(u1) * z[2], bf_hi(u1) * z[3]);
;             }
;             *(u32x4*)(Y + tok * D + g * 64 + 32 * p + 8 * fq) = w;
;         }
	v_lshlrev_b32_e32 v147, 16, v61
	v_lshlrev_b32_e32 v146, 16, v60
	v_pk_fma_f32 v[56:57], v[180:181], v[30:31], v[156:157] op_sel_hi:[1,1,0]
	v_pk_fma_f32 v[58:59], v[178:179], v[28:29], v[156:157] op_sel_hi:[1,1,0]
	v_mov_b32_e32 v149, v56
	v_and_b32_e32 v61, 0xffff0000, v61
	v_and_b32_e32 v60, 0xffff0000, v60
	v_mov_b32_e32 v56, v59
	v_pk_fma_f32 v[54:55], v[54:55], v[22:23], v[156:157] op_sel_hi:[1,1,0]
	v_pk_fma_f32 v[52:53], v[52:53], v[20:21], v[156:157] op_sel_hi:[1,1,0]
	v_mov_b32_e32 v148, v58
	v_pk_mul_f32 v[56:57], v[56:57], v[60:61]
	v_lshlrev_b32_e32 v59, 16, v63
	v_lshlrev_b32_e32 v58, 16, v62
	v_mov_b32_e32 v60, v52
	v_mov_b32_e32 v61, v54
	v_pk_mul_f32 v[58:59], v[60:61], v[58:59]
	v_and_b32_e32 v61, 0xffff0000, v63
	v_and_b32_e32 v60, 0xffff0000, v62
	v_mov_b32_e32 v54, v53
	v_pk_mul_f32 v[52:53], v[54:55], v[60:61]
	v_pk_mul_f32 v[146:147], v[148:149], v[146:147]
	v_bfe_u32 v54, v53, 16, 1
	v_bfe_u32 v55, v52, 16, 1
	v_bfe_u32 v60, v57, 16, 1
	v_bfe_u32 v61, v56, 16, 1
	v_add3_u32 v56, v56, v61, s5
	v_add3_u32 v57, v57, v60, s5
	v_add3_u32 v52, v52, v55, s5
	v_add3_u32 v53, v53, v54, s5
	v_bfe_u32 v54, v146, 16, 1
	v_bfe_u32 v55, v147, 16, 1
	v_bfe_u32 v60, v58, 16, 1
	v_bfe_u32 v61, v59, 16, 1
	v_add3_u32 v59, v59, v61, s5
	v_add3_u32 v58, v58, v60, s5
	v_add3_u32 v55, v147, v55, s5
	v_add3_u32 v54, v146, v54, s5
	v_lshrrev_b32_e32 v60, 16, v54
	v_lshrrev_b32_e32 v61, 16, v55
	v_lshrrev_b32_e32 v54, 16, v58
	v_lshrrev_b32_e32 v55, 16, v59
	v_and_or_b32 v55, v53, s11, v55
	v_and_or_b32 v54, v52, s11, v54
	v_and_or_b32 v53, v57, s11, v61
	v_and_or_b32 v52, v56, s11, v60
	global_store_dwordx4 v[154:155], v[52:55], off offset:64
	v_or_b32_e32 v56, s28, v131
	global_load_dword v150, v[122:123], off
	v_mad_i64_i32 v[58:59], s[30:31], v56, s4, v[82:83]
	global_load_dwordx4 v[52:55], v[58:59], off
	global_load_dwordx4 v[40:43], v[58:59], off offset:64
	v_ashrrev_i32_e32 v57, 31, v56
	v_lshlrev_b64 v[56:57], 11, v[56:57]
	v_lshl_add_u64 v[170:171], v[84:85], 0, v[56:57]
	v_mfma_f32_16x16x32_bf16 v[16:19], v[16:19], v[24:27], 0
	s_waitcnt vmcnt(2)
	v_pk_fma_f32 v[46:47], v[50:51], v[46:47], v[150:151] op_sel_hi:[1,1,0]
	v_pk_fma_f32 v[44:45], v[48:49], v[44:45], v[150:151] op_sel_hi:[1,1,0]
	v_pk_fma_f32 v[34:35], v[34:35], v[38:39], v[150:151] op_sel_hi:[1,1,0]
	v_pk_fma_f32 v[32:33], v[32:33], v[36:37], v[150:151] op_sel_hi:[1,1,0]
	s_waitcnt vmcnt(1)
	v_lshlrev_b32_e32 v49, 16, v53
	v_lshlrev_b32_e32 v48, 16, v52
	v_mov_b32_e32 v50, v44
	v_mov_b32_e32 v51, v46
	v_lshlrev_b32_e32 v37, 16, v55
	v_lshlrev_b32_e32 v36, 16, v54
	v_mov_b32_e32 v38, v32
	v_mov_b32_e32 v39, v34
	v_pk_mul_f32 v[48:49], v[50:51], v[48:49]
	v_and_b32_e32 v51, 0xffff0000, v53
	v_and_b32_e32 v50, 0xffff0000, v52
	v_mov_b32_e32 v46, v45
	v_pk_mul_f32 v[36:37], v[38:39], v[36:37]
	v_and_b32_e32 v39, 0xffff0000, v55
	v_and_b32_e32 v38, 0xffff0000, v54
	v_mov_b32_e32 v34, v33
	v_pk_mul_f32 v[44:45], v[46:47], v[50:51]
	v_pk_mul_f32 v[32:33], v[34:35], v[38:39]
	v_bfe_u32 v38, v45, 16, 1
	v_bfe_u32 v34, v33, 16, 1
	v_bfe_u32 v35, v32, 16, 1
	v_bfe_u32 v39, v44, 16, 1
	v_add3_u32 v39, v44, v39, s5
	v_add3_u32 v38, v45, v38, s5
	v_add3_u32 v32, v32, v35, s5
	v_add3_u32 v33, v33, v34, s5
	v_bfe_u32 v34, v48, 16, 1
	v_bfe_u32 v35, v49, 16, 1
	v_bfe_u32 v44, v36, 16, 1
	v_bfe_u32 v45, v37, 16, 1
	v_add3_u32 v37, v37, v45, s5
	v_add3_u32 v36, v36, v44, s5
	v_add3_u32 v35, v49, v35, s5
	v_add3_u32 v34, v48, v34, s5
	v_lshrrev_b32_e32 v44, 16, v34
	v_lshrrev_b32_e32 v45, 16, v35
	v_lshrrev_b32_e32 v34, 16, v36
	v_lshrrev_b32_e32 v35, 16, v37
	v_and_or_b32 v35, v33, s11, v35
	v_and_or_b32 v34, v32, s11, v34
	v_and_or_b32 v33, v38, s11, v45
	v_and_or_b32 v32, v39, s11, v44
	global_store_dwordx4 v[170:171], v[32:35], off
	global_load_dwordx4 v[32:35], v[86:87], off
	s_nop 0
	global_load_dwordx4 v[36:39], v[88:89], off
	global_load_dwordx4 v[44:47], v[90:91], off
	global_load_dwordx4 v[24:27], v[92:93], off
	v_mfma_f32_16x16x32_bf16 v[8:11], v[8:11], v[4:7], v[12:15]
	ds_read_b128 v[48:51], v144 offset:8704
	ds_read_b128 v[52:55], v144 offset:9792
	s_nop 0
	ds_read_b128 v[12:15], v144
	ds_read_b128 v[56:59], v144 offset:64
	ds_read_b128 v[60:63], v144 offset:1088
	ds_read_b128 v[146:149], v144 offset:1152
	s_nop 0
	v_pk_fma_f32 v[8:9], v[8:9], v[28:29], v[150:151] op_sel_hi:[1,1,0]
	v_mfma_f32_16x16x32_bf16 v[0:3], v[0:3], v[4:7], v[16:19]
	v_mov_b32_e32 v28, v8
	s_nop 1
	v_pk_fma_f32 v[16:17], v[10:11], v[30:31], v[150:151] op_sel_hi:[1,1,0]
	s_waitcnt vmcnt(5)
	v_lshlrev_b32_e32 v11, 16, v41
	s_nop 1
	v_pk_fma_f32 v[152:153], v[2:3], v[22:23], v[150:151] op_sel_hi:[1,1,0]
	v_pk_fma_f32 v[150:151], v[0:1], v[20:21], v[150:151] op_sel_hi:[1,1,0]
	v_lshlrev_b32_e32 v10, 16, v40
	v_and_b32_e32 v19, 0xffff0000, v41
	v_and_b32_e32 v18, 0xffff0000, v40
	v_mov_b32_e32 v29, v16
	v_lshlrev_b32_e32 v41, 16, v43
	v_lshlrev_b32_e32 v40, 16, v42
	v_mov_b32_e32 v156, v150
	v_mov_b32_e32 v157, v152
	v_mov_b32_e32 v16, v9
	v_pk_mul_f32 v[166:167], v[28:29], v[10:11]
	v_pk_mul_f32 v[168:169], v[156:157], v[40:41]
	v_and_b32_e32 v157, 0xffff0000, v43
	v_and_b32_e32 v156, 0xffff0000, v42
	v_mov_b32_e32 v152, v151
	v_pk_mul_f32 v[154:155], v[16:17], v[18:19]
	v_pk_mul_f32 v[158:159], v[152:153], v[156:157]
	v_bfe_u32 v175, v166, 16, 1
	v_bfe_u32 v176, v167, 16, 1
	v_bfe_u32 v177, v168, 16, 1
	v_bfe_u32 v162, v169, 16, 1
	v_bfe_u32 v145, v159, 16, 1
	v_bfe_u32 v156, v158, 16, 1
	v_bfe_u32 v157, v155, 16, 1
	v_bfe_u32 v160, v154, 16, 1
	v_add3_u32 v169, v169, v162, s5
	v_add3_u32 v168, v168, v177, s5
	v_add3_u32 v167, v167, v176, s5
	v_add3_u32 v166, v166, v175, s5
	v_add3_u32 v172, v154, v160, s5
	v_add3_u32 v173, v155, v157, s5
	v_add3_u32 v174, v158, v156, s5
	v_add3_u32 v145, v159, v145, s5
	v_lshrrev_b32_e32 v166, 16, v166
	v_lshrrev_b32_e32 v167, 16, v167
	v_lshrrev_b32_e32 v168, 16, v168
	v_lshrrev_b32_e32 v169, 16, v169
	v_and_or_b32 v169, v145, s11, v169
	v_and_or_b32 v168, v174, s11, v168
	v_and_or_b32 v167, v173, s11, v167
	v_and_or_b32 v166, v172, s11, v166
	global_store_dwordx4 v[170:171], v[166:169], off offset:64
	s_waitcnt vmcnt(4) lgkmcnt(3)
; #define LAS __attribute__((address_space(3)))
; template <int HF>
; __device__ __forceinline__ void gmlp_half(LAS unsigned char* wl, const bf16* PROJ, const bf16* wsg, const float* norm_v, const float* b_s, bf16* Y, int tok0, int g, int fr, int fq) {
;     ...
; #pragma unroll
;     for (int ki = 0; ki < NK; ++ki)
; #pragma unroll
;         for (int nt = 0; nt < 4; ++nt) bw[ki][nt] = *(const bf16x8*)(wsg + (size_t)(64 * HF + 16 * nt + fr) * 128 + 32 * ki + 8 * fq);
;     f32x4 acc[4][4];
; #pragma unroll
;     for (int i = 0; i < 4; ++i)
; #pragma unroll
;         for (int j = 0; j < 4; ++j) acc[i][j] = (f32x4){0.f, 0.f, 0.f, 0.f};
; #pragma unroll
;     for (int ki = 0; ki < NK; ++ki) {
;         bf16x8 av[4];
; #pragma unroll
;         for (int mi = 0; mi < 4; ++mi) av[mi] = *(const LAS bf16x8*)(wl + ((32 * (mi >> 1) + 8 * (fr >> 2) + 4 * (mi & 1) + (fr & 3)) * VS + 32 * ki + 8 * fq) * 2);
; #pragma unroll
;         for (int nt = 0; nt < 4; ++nt)
; #pragma unroll
;             for (int mi = 0; mi < 4; ++mi) acc[mi][nt] = __builtin_amdgcn_mfma_f32_16x16x32_bf16(av[mi], bw[ki][nt], acc[mi][nt], 0, 0, 0);
;     }
;     asm volatile("" ::: "memory");
;     f32x4 nv[2][2];
; #pragma unroll
;     for (int p = 0; p < 2; ++p) { nv[p][0] = *(const f32x4*)(norm_v + g * 64 + 32 * p + 8 * fq); nv[p][1] = *(const f32x4*)(norm_v + g * 64 + 32 * p + 8 * fq + 4); }
	v_mfma_f32_16x16x32_bf16 v[4:7], v[12:15], v[32:35], 0
	global_load_dwordx4 v[166:169], v[94:95], off
	ds_read_b128 v[16:19], v144 offset:8768
	ds_read_b128 v[0:3], v144 offset:9856
	s_waitcnt lgkmcnt(3)
	v_mfma_f32_16x16x32_bf16 v[8:11], v[60:63], v[32:35], 0
	v_mfma_f32_16x16x32_bf16 v[28:31], v[48:51], v[32:35], 0
	v_mfma_f32_16x16x32_bf16 v[20:23], v[52:55], v[32:35], 0
	s_waitcnt vmcnt(4)
	v_mfma_f32_16x16x32_bf16 v[32:35], v[12:15], v[36:39], 0
	v_mfma_f32_16x16x32_bf16 v[40:43], v[60:63], v[36:39], 0
	v_mfma_f32_16x16x32_bf16 v[150:153], v[48:51], v[36:39], 0
	v_mfma_f32_16x16x32_bf16 v[36:39], v[52:55], v[36:39], 0
	s_waitcnt vmcnt(3)
	v_mfma_f32_16x16x32_bf16 v[154:157], v[12:15], v[44:47], 0
	v_mfma_f32_16x16x32_bf16 v[158:161], v[60:63], v[44:47], 0
	v_mfma_f32_16x16x32_bf16 v[162:165], v[48:51], v[44:47], 0
	v_mfma_f32_16x16x32_bf16 v[44:47], v[52:55], v[44:47], 0
	s_waitcnt vmcnt(2)
	v_mfma_f32_16x16x32_bf16 v[12:15], v[12:15], v[24:27], 0
	v_mfma_f32_16x16x32_bf16 v[60:63], v[60:63], v[24:27], 0
	v_mfma_f32_16x16x32_bf16 v[48:51], v[48:51], v[24:27], 0
	v_mfma_f32_16x16x32_bf16 v[24:27], v[52:55], v[24:27], 0
	global_load_dwordx4 v[52:55], v[96:97], off
	s_waitcnt vmcnt(1)
	v_mfma_f32_16x16x32_bf16 v[4:7], v[56:59], v[166:169], v[4:7]
	s_waitcnt lgkmcnt(2)
	v_mfma_f32_16x16x32_bf16 v[8:11], v[146:149], v[166:169], v[8:11]
	s_waitcnt lgkmcnt(1)
	v_mfma_f32_16x16x32_bf16 v[28:31], v[16:19], v[166:169], v[28:31]
	s_waitcnt lgkmcnt(0)
	v_mfma_f32_16x16x32_bf16 v[20:23], v[0:3], v[166:169], v[20:23]
	s_waitcnt vmcnt(0)
	v_mfma_f32_16x16x32_bf16 v[32:35], v[56:59], v[52:55], v[32:35]
	v_mfma_f32_16x16x32_bf16 v[166:169], v[146:149], v[52:55], v[40:43]
	v_mfma_f32_16x16x32_bf16 v[150:153], v[16:19], v[52:55], v[150:153]
	s_nop 1
	global_load_dwordx4 v[40:43], v[98:99], off
	v_mfma_f32_16x16x32_bf16 v[52:55], v[0:3], v[52:55], v[36:39]
	s_nop 2
	global_load_dwordx4 v[36:39], v[100:101], off
	s_waitcnt vmcnt(1)
	v_mfma_f32_16x16x32_bf16 v[158:161], v[146:149], v[40:43], v[158:161]
	s_waitcnt vmcnt(0)
	v_mfma_f32_16x16x32_bf16 v[60:63], v[146:149], v[36:39], v[60:63]
	global_load_dwordx4 v[146:149], v[102:103], off
	v_mfma_f32_16x16x32_bf16 v[154:157], v[56:59], v[40:43], v[154:157]
	v_mfma_f32_16x16x32_bf16 v[162:165], v[16:19], v[40:43], v[162:165]
	v_mfma_f32_16x16x32_bf16 v[44:47], v[0:3], v[40:43], v[44:47]
	v_mfma_f32_16x16x32_bf16 v[56:59], v[56:59], v[36:39], v[12:15]
	v_mfma_f32_16x16x32_bf16 v[16:19], v[16:19], v[36:39], v[48:51]
	s_nop 2
	global_load_dwordx4 v[48:51], v[104:105], off
	v_mfma_f32_16x16x32_bf16 v[0:3], v[0:3], v[36:39], v[24:27]
	s_nop 2
	ds_read_b128 v[24:27], v144 offset:128
	ds_read_b128 v[36:39], v144 offset:192
	ds_read_b128 v[170:173], v144 offset:1216
	ds_read_b128 v[40:43], v144 offset:1280
	s_waitcnt vmcnt(1) lgkmcnt(1)
	v_mfma_f32_16x16x32_bf16 v[174:177], v[170:173], v[146:149], v[8:11]
	ds_read_b128 v[178:181], v144 offset:8832
	s_nop 1
	ds_read_b128 v[8:11], v144 offset:8896
	ds_read_b128 v[182:185], v144 offset:9920
	ds_read_b128 v[12:15], v144 offset:9984
	global_load_dwordx4 v[186:189], v[108:109], off
	v_mfma_f32_16x16x32_bf16 v[4:7], v[24:27], v[146:149], v[4:7]
	s_waitcnt lgkmcnt(3)
	v_mfma_f32_16x16x32_bf16 v[28:31], v[178:181], v[146:149], v[28:31]
	s_waitcnt lgkmcnt(1)
	v_mfma_f32_16x16x32_bf16 v[146:149], v[182:185], v[146:149], v[20:23]
	s_nop 2
	global_load_dwordx4 v[20:23], v[106:107], off
	s_waitcnt vmcnt(2)
	v_mfma_f32_16x16x32_bf16 v[32:35], v[24:27], v[48:51], v[32:35]
	v_mfma_f32_16x16x32_bf16 v[166:169], v[170:173], v[48:51], v[166:169]
	v_mfma_f32_16x16x32_bf16 v[150:153], v[178:181], v[48:51], v[150:153]
	v_mfma_f32_16x16x32_bf16 v[52:55], v[182:185], v[48:51], v[52:55]
	s_waitcnt vmcnt(0)
	v_mfma_f32_16x16x32_bf16 v[154:157], v[24:27], v[20:23], v[154:157]
	v_mfma_f32_16x16x32_bf16 v[48:51], v[24:27], v[186:189], v[56:59]
	global_load_dwordx4 v[24:27], v[110:111], off
	v_mfma_f32_16x16x32_bf16 v[158:161], v[170:173], v[20:23], v[158:161]
	s_nop 0
	v_mad_i64_i32 v[56:57], s[30:31], v198, s4, v[82:83]
	v_mfma_f32_16x16x32_bf16 v[162:165], v[178:181], v[20:23], v[162:165]
	v_mfma_f32_16x16x32_bf16 v[190:193], v[182:185], v[20:23], v[44:47]
	v_mfma_f32_16x16x32_bf16 v[20:23], v[182:185], v[186:189], v[0:3]
	s_nop 2
	global_load_dwordx4 v[0:3], v[112:113], off
	v_mfma_f32_16x16x32_bf16 v[44:47], v[170:173], v[186:189], v[60:63]
	v_mfma_f32_16x16x32_bf16 v[16:19], v[178:181], v[186:189], v[16:19]
	s_waitcnt vmcnt(1)
	v_mfma_f32_16x16x32_bf16 v[178:181], v[8:11], v[24:27], v[28:31]
	global_load_dwordx4 v[186:189], v[114:115], off
	s_nop 1
	global_load_dwordx4 v[28:31], v[116:117], off
	global_load_dword v206, v[120:121], off offset:256
	s_waitcnt vmcnt(3)
	v_mfma_f32_16x16x32_bf16 v[182:185], v[36:39], v[0:3], v[32:35]
	s_nop 2
	global_load_dwordx4 v[32:35], v[118:119], off
	global_load_dwordx4 v[194:197], v[56:57], off
	v_mfma_f32_16x16x32_bf16 v[170:173], v[36:39], v[24:27], v[4:7]
	v_mfma_f32_16x16x32_bf16 v[174:177], v[40:43], v[24:27], v[174:177]
	s_waitcnt lgkmcnt(0)
	v_mfma_f32_16x16x32_bf16 v[146:149], v[12:15], v[24:27], v[146:149]
	global_load_dwordx4 v[24:27], v[118:119], off offset:16
	global_load_dwordx4 v[4:7], v[118:119], off offset:128
	global_load_dwordx4 v[202:205], v[56:57], off offset:64
	v_mfma_f32_16x16x32_bf16 v[166:169], v[40:43], v[0:3], v[166:169]
	v_mfma_f32_16x16x32_bf16 v[150:153], v[8:11], v[0:3], v[150:153]
	v_mfma_f32_16x16x32_bf16 v[60:63], v[12:15], v[0:3], v[52:55]
	global_load_dwordx4 v[0:3], v[118:119], off offset:144
	s_waitcnt vmcnt(0)
; __device__ __forceinline__ unsigned pk2(float lo, float hi) { return f2bf(lo) | (f2bf(hi) << 16); }
; template <int HF>
; __device__ __forceinline__ void gmlp_half(LAS unsigned char* wl, const bf16* PROJ, const bf16* wsg, const float* norm_v, const float* b_s, bf16* Y, int tok0, int g, int fr, int fq) {
;     ...
;     for (int nt = 0; nt < 4; ++nt) {
;         const int t = 64 * HF + 16 * nt + fr; const size_t tok = (size_t)(tok0 + t); const float bs = b_s[g * 128 + t];
;         u32x4 uu[2];
; #pragma unroll
;         for (int p = 0; p < 2; ++p) uu[p] = *(const u32x4*)(PROJ + tok * NPROJ + g * 64 + 32 * p + 8 * fq);
; #pragma unroll
;         for (int p = 0; p < 2; ++p) {
;             u32x4 w;
; #pragma unroll
;             for (int e2 = 0; e2 < 2; ++e2) {
;                 const f32x4 z = nv[p][e2] * acc[2 * p + e2][nt] + bs;
;                 const unsigned u0 = uu[p][2 * e2], u1 = uu[p][2 * e2 + 1];
;                 w[2 * e2] = pk2(bf_lo(u0) * z[0], bf_hi(u0) * z[1]); w[2 * e2 + 1] = pk2(bf_lo(u1) * z[2], bf_hi(u1) * z[3]);
;             }
;             *(u32x4*)(Y + tok * D + g * 64 + 32 * p + 8 * fq) = w;
;         }
	v_pk_fma_f32 v[148:149], v[148:149], v[2:3], v[206:207] op_sel_hi:[1,1,0]
	v_mfma_f32_16x16x32_bf16 v[56:59], v[36:39], v[186:189], v[154:157]
	v_fma_f32 v146, v146, v0, v206
	v_fma_f32 v147, v147, v1, v206
	s_nop 0
	v_lshlrev_b64 v[154:155], 11, v[198:199]
	v_mfma_f32_16x16x32_bf16 v[52:55], v[40:43], v[186:189], v[158:161]
	v_fma_f32 v156, v170, v32, v206
	v_fma_f32 v157, v171, v33, v206
	v_mov_b32_e32 v170, v156
	v_lshl_add_u64 v[158:159], v[84:85], 0, v[154:155]
	v_pk_fma_f32 v[154:155], v[172:173], v[34:35], v[206:207] op_sel_hi:[1,1,0]
	v_lshlrev_b32_e32 v161, 16, v195
	v_lshlrev_b32_e32 v160, 16, v194
	v_mov_b32_e32 v171, v154
	v_pk_mul_f32 v[160:161], v[170:171], v[160:161]
	v_and_b32_e32 v171, 0xffff0000, v195
	v_and_b32_e32 v170, 0xffff0000, v194
	v_mov_b32_e32 v154, v157
	v_pk_mul_f32 v[154:155], v[154:155], v[170:171]
	v_pk_fma_f32 v[156:157], v[176:177], v[26:27], v[206:207] op_sel_hi:[1,1,0]
	v_pk_fma_f32 v[170:171], v[174:175], v[24:25], v[206:207] op_sel_hi:[1,1,0]
	v_lshlrev_b32_e32 v173, 16, v197
	v_lshlrev_b32_e32 v172, 16, v196
	v_mov_b32_e32 v174, v170
	v_mov_b32_e32 v175, v156
	v_pk_mul_f32 v[172:173], v[174:175], v[172:173]
	v_and_b32_e32 v175, 0xffff0000, v197
	v_and_b32_e32 v174, 0xffff0000, v196
	v_mov_b32_e32 v156, v171
	v_pk_mul_f32 v[156:157], v[156:157], v[174:175]
	v_bfe_u32 v171, v155, 16, 1
	v_bfe_u32 v145, v157, 16, 1
	v_bfe_u32 v170, v156, 16, 1
	v_bfe_u32 v174, v154, 16, 1
	v_add3_u32 v154, v154, v174, s5
	v_add3_u32 v155, v155, v171, s5
	v_add3_u32 v156, v156, v170, s5
	v_add3_u32 v145, v157, v145, s5
	v_bfe_u32 v157, v160, 16, 1
	v_bfe_u32 v170, v161, 16, 1
	v_bfe_u32 v171, v172, 16, 1
	v_bfe_u32 v174, v173, 16, 1
	v_add3_u32 v173, v173, v174, s5
	v_add3_u32 v171, v172, v171, s5
	v_add3_u32 v161, v161, v170, s5
	v_add3_u32 v157, v160, v157, s5
	v_lshrrev_b32_e32 v160, 16, v157
	v_lshrrev_b32_e32 v161, 16, v161
	v_lshrrev_b32_e32 v170, 16, v171
	v_lshrrev_b32_e32 v157, 16, v173
	v_and_or_b32 v157, v145, s11, v157
	v_and_or_b32 v156, v156, s11, v170
	v_and_or_b32 v155, v155, s11, v161
	v_and_or_b32 v154, v154, s11, v160
	global_store_dwordx4 v[158:159], v[154:157], off
	v_lshlrev_b32_e32 v161, 16, v203
	v_lshlrev_b32_e32 v160, 16, v202
	v_pk_fma_f32 v[154:155], v[180:181], v[6:7], v[206:207] op_sel_hi:[1,1,0]
	v_pk_fma_f32 v[156:157], v[178:179], v[4:5], v[206:207] op_sel_hi:[1,1,0]
	v_mov_b32_e32 v171, v154
	v_mov_b32_e32 v170, v156
	v_pk_mul_f32 v[160:161], v[170:171], v[160:161]
	v_and_b32_e32 v171, 0xffff0000, v203
	v_and_b32_e32 v170, 0xffff0000, v202
	v_mov_b32_e32 v154, v157
	v_pk_mul_f32 v[154:155], v[154:155], v[170:171]
	v_lshlrev_b32_e32 v157, 16, v205
	v_lshlrev_b32_e32 v156, 16, v204
	v_mov_b32_e32 v170, v146
	v_mov_b32_e32 v171, v148
	v_pk_mul_f32 v[156:157], v[170:171], v[156:157]
	v_and_b32_e32 v171, 0xffff0000, v205
	v_and_b32_e32 v170, 0xffff0000, v204
	v_mov_b32_e32 v148, v147
	v_pk_mul_f32 v[146:147], v[148:149], v[170:171]
	v_bfe_u32 v149, v155, 16, 1
	v_bfe_u32 v145, v147, 16, 1
	v_bfe_u32 v148, v146, 16, 1
	v_bfe_u32 v170, v154, 16, 1
	v_add3_u32 v154, v154, v170, s5
	v_add3_u32 v155, v155, v149, s5
	v_add3_u32 v146, v146, v148, s5
	v_add3_u32 v145, v147, v145, s5
	v_bfe_u32 v147, v160, 16, 1
	v_bfe_u32 v148, v161, 16, 1
	v_bfe_u32 v149, v156, 16, 1
	v_bfe_u32 v170, v157, 16, 1
	v_add3_u32 v157, v157, v170, s5
	v_add3_u32 v149, v156, v149, s5
	v_add3_u32 v148, v161, v148, s5
	v_add3_u32 v147, v160, v147, s5
	v_lshrrev_b32_e32 v156, 16, v147
	v_lshrrev_b32_e32 v147, 16, v148
	v_lshrrev_b32_e32 v148, 16, v149
	v_lshrrev_b32_e32 v149, 16, v157
	v_and_or_b32 v149, v145, s11, v149
	v_and_or_b32 v148, v146, s11, v148
	v_and_or_b32 v147, v155, s11, v147
	v_and_or_b32 v146, v154, s11, v156
	global_store_dwordx4 v[158:159], v[146:149], off offset:64
	v_or_b32_e32 v170, s28, v136
	global_load_dword v172, v[120:121], off offset:320
	v_mad_i64_i32 v[158:159], s[30:31], v170, s4, v[82:83]
	global_load_dwordx4 v[146:149], v[158:159], off
	v_ashrrev_i32_e32 v171, 31, v170
	global_load_dwordx4 v[158:161], v[158:159], off offset:64
	v_lshlrev_b64 v[170:171], 11, v[170:171]
	v_lshl_add_u64 v[170:171], v[84:85], 0, v[170:171]
	v_mfma_f32_16x16x32_bf16 v[36:39], v[36:39], v[28:31], v[48:51]
	s_waitcnt vmcnt(2)
	v_pk_fma_f32 v[174:175], v[184:185], v[34:35], v[172:173] op_sel_hi:[1,1,0]
	v_pk_fma_f32 v[176:177], v[182:183], v[32:33], v[172:173] op_sel_hi:[1,1,0]
	v_mov_b32_e32 v181, v174
	s_waitcnt vmcnt(1)
	v_lshlrev_b32_e32 v179, 16, v147
	v_lshlrev_b32_e32 v178, 16, v146
	v_and_b32_e32 v147, 0xffff0000, v147
	v_and_b32_e32 v146, 0xffff0000, v146
	v_mov_b32_e32 v174, v177
	v_pk_fma_f32 v[168:169], v[168:169], v[26:27], v[172:173] op_sel_hi:[1,1,0]
	v_pk_fma_f32 v[166:167], v[166:167], v[24:25], v[172:173] op_sel_hi:[1,1,0]
	v_pk_mul_f32 v[146:147], v[174:175], v[146:147]
	v_lshlrev_b32_e32 v175, 16, v149
	v_lshlrev_b32_e32 v174, 16, v148
	v_mov_b32_e32 v177, v168
	v_and_b32_e32 v149, 0xffff0000, v149
	v_and_b32_e32 v148, 0xffff0000, v148
	v_mov_b32_e32 v168, v167
	v_mov_b32_e32 v180, v176
	v_mov_b32_e32 v176, v166
	v_pk_mul_f32 v[148:149], v[168:169], v[148:149]
	v_pk_mul_f32 v[178:179], v[180:181], v[178:179]
	v_pk_mul_f32 v[174:175], v[176:177], v[174:175]
	v_bfe_u32 v145, v149, 16, 1
	v_bfe_u32 v166, v148, 16, 1
	v_bfe_u32 v167, v147, 16, 1
	v_bfe_u32 v168, v146, 16, 1
	v_add3_u32 v146, v146, v168, s5
	v_add3_u32 v147, v147, v167, s5
	v_add3_u32 v148, v148, v166, s5
	v_add3_u32 v145, v149, v145, s5
	v_bfe_u32 v149, v178, 16, 1
	v_bfe_u32 v166, v179, 16, 1
	v_bfe_u32 v167, v174, 16, 1
	v_bfe_u32 v168, v175, 16, 1
	v_add3_u32 v168, v175, v168, s5
	v_add3_u32 v167, v174, v167, s5
	v_add3_u32 v166, v179, v166, s5
	v_add3_u32 v149, v178, v149, s5
	v_lshrrev_b32_e32 v169, 16, v149
	v_lshrrev_b32_e32 v166, 16, v166
	v_lshrrev_b32_e32 v167, 16, v167
	v_lshrrev_b32_e32 v149, 16, v168
	v_and_or_b32 v149, v145, s11, v149
	v_and_or_b32 v148, v148, s11, v167
	v_and_or_b32 v147, v147, s11, v166
	v_and_or_b32 v146, v146, s11, v169
	global_store_dwordx4 v[170:171], v[146:149], off
	v_pk_fma_f32 v[62:63], v[62:63], v[2:3], v[172:173] op_sel_hi:[1,1,0]
	v_pk_fma_f32 v[60:61], v[60:61], v[0:1], v[172:173] op_sel_hi:[1,1,0]
	v_pk_fma_f32 v[146:147], v[152:153], v[6:7], v[172:173] op_sel_hi:[1,1,0]
	v_pk_fma_f32 v[148:149], v[150:151], v[4:5], v[172:173] op_sel_hi:[1,1,0]
	s_waitcnt vmcnt(1)
; __device__ __forceinline__ unsigned pk2(float lo, float hi) { return f2bf(lo) | (f2bf(hi) << 16); }
; template <int HF>
; __device__ __forceinline__ void gmlp_half(LAS unsigned char* wl, const bf16* PROJ, const bf16* wsg, const float* norm_v, const float* b_s, bf16* Y, int tok0, int g, int fr, int fq) {
;     ...
;     for (int nt = 0; nt < 4; ++nt) {
;         const int t = 64 * HF + 16 * nt + fr; const size_t tok = (size_t)(tok0 + t); const float bs = b_s[g * 128 + t];
;         u32x4 uu[2];
; #pragma unroll
;         for (int p = 0; p < 2; ++p) uu[p] = *(const u32x4*)(PROJ + tok * NPROJ + g * 64 + 32 * p + 8 * fq);
; #pragma unroll
;         for (int p = 0; p < 2; ++p) {
;             u32x4 w;
; #pragma unroll
;             for (int e2 = 0; e2 < 2; ++e2) {
;                 const f32x4 z = nv[p][e2] * acc[2 * p + e2][nt] + bs;
;                 const unsigned u0 = uu[p][2 * e2], u1 = uu[p][2 * e2 + 1];
;                 w[2 * e2] = pk2(bf_lo(u0) * z[0], bf_hi(u0) * z[1]); w[2 * e2 + 1] = pk2(bf_lo(u1) * z[2], bf_hi(u1) * z[3]);
;             }
;             *(u32x4*)(Y + tok * D + g * 64 + 32 * p + 8 * fq) = w;
;         }
	v_lshlrev_b32_e32 v151, 16, v159
	v_lshlrev_b32_e32 v150, 16, v158
	v_mov_b32_e32 v152, v148
	v_mov_b32_e32 v153, v146
	v_pk_mul_f32 v[150:151], v[152:153], v[150:151]
	v_and_b32_e32 v153, 0xffff0000, v159
	v_and_b32_e32 v152, 0xffff0000, v158
	v_mov_b32_e32 v146, v149
	v_pk_mul_f32 v[146:147], v[146:147], v[152:153]
	v_lshlrev_b32_e32 v149, 16, v161
	v_lshlrev_b32_e32 v148, 16, v160
	v_mov_b32_e32 v152, v60
	v_mov_b32_e32 v153, v62
	v_pk_mul_f32 v[148:149], v[152:153], v[148:149]
	v_and_b32_e32 v153, 0xffff0000, v161
	v_and_b32_e32 v152, 0xffff0000, v160
	v_mov_b32_e32 v62, v61
	v_pk_mul_f32 v[60:61], v[62:63], v[152:153]
	v_bfe_u32 v145, v147, 16, 1
	v_bfe_u32 v62, v61, 16, 1
	v_bfe_u32 v63, v60, 16, 1
	v_bfe_u32 v152, v146, 16, 1
	v_add3_u32 v146, v146, v152, s5
	v_add3_u32 v145, v147, v145, s5
	v_add3_u32 v60, v60, v63, s5
	v_add3_u32 v61, v61, v62, s5
	v_bfe_u32 v62, v150, 16, 1
	v_bfe_u32 v63, v151, 16, 1
	v_bfe_u32 v147, v148, 16, 1
	v_bfe_u32 v152, v149, 16, 1
	v_add3_u32 v149, v149, v152, s5
	v_add3_u32 v147, v148, v147, s5
	v_add3_u32 v63, v151, v63, s5
	v_add3_u32 v62, v150, v62, s5
	v_lshrrev_b32_e32 v148, 16, v62
	v_lshrrev_b32_e32 v150, 16, v63
	v_lshrrev_b32_e32 v62, 16, v147
	v_lshrrev_b32_e32 v63, 16, v149
	v_and_or_b32 v63, v61, s11, v63
	v_and_or_b32 v62, v60, s11, v62
	v_and_or_b32 v61, v145, s11, v150
	v_and_or_b32 v60, v146, s11, v148
	global_store_dwordx4 v[170:171], v[60:63], off offset:64
	v_or_b32_e32 v146, s28, v137
	global_load_dword v148, v[120:121], off offset:384
	v_mad_i64_i32 v[150:151], s[28:29], v146, s4, v[82:83]
	global_load_dwordx4 v[60:63], v[150:151], off
	global_load_dwordx4 v[48:51], v[150:151], off offset:64
	v_ashrrev_i32_e32 v147, 31, v146
	v_mfma_f32_16x16x32_bf16 v[40:43], v[40:43], v[28:31], v[44:47]
	s_waitcnt vmcnt(2)
	v_pk_fma_f32 v[52:53], v[52:53], v[24:25], v[148:149] op_sel_hi:[1,1,0]
	s_nop 0
	v_lshlrev_b64 v[44:45], 11, v[146:147]
	v_lshl_add_u64 v[146:147], v[84:85], 0, v[44:45]
	v_pk_fma_f32 v[44:45], v[58:59], v[34:35], v[148:149] op_sel_hi:[1,1,0]
	v_pk_fma_f32 v[46:47], v[56:57], v[32:33], v[148:149] op_sel_hi:[1,1,0]
	s_waitcnt vmcnt(1)
	v_lshlrev_b32_e32 v57, 16, v61
	v_lshlrev_b32_e32 v56, 16, v60
	v_mov_b32_e32 v58, v46
	v_mov_b32_e32 v59, v44
	v_pk_mul_f32 v[56:57], v[58:59], v[56:57]
	v_and_b32_e32 v59, 0xffff0000, v61
	v_and_b32_e32 v58, 0xffff0000, v60
	v_mov_b32_e32 v44, v47
	v_pk_fma_f32 v[46:47], v[54:55], v[26:27], v[148:149] op_sel_hi:[1,1,0]
	v_pk_mul_f32 v[44:45], v[44:45], v[58:59]
	v_lshlrev_b32_e32 v55, 16, v63
	v_lshlrev_b32_e32 v54, 16, v62
	v_mov_b32_e32 v58, v52
	v_mov_b32_e32 v59, v46
	v_pk_mul_f32 v[54:55], v[58:59], v[54:55]
	v_and_b32_e32 v59, 0xffff0000, v63
	v_and_b32_e32 v58, 0xffff0000, v62
	v_mov_b32_e32 v46, v53
	v_pk_mul_f32 v[46:47], v[46:47], v[58:59]
	v_bfe_u32 v58, v45, 16, 1
	v_bfe_u32 v52, v47, 16, 1
	v_bfe_u32 v53, v46, 16, 1
	v_bfe_u32 v59, v44, 16, 1
	v_mfma_f32_16x16x32_bf16 v[154:157], v[8:11], v[186:189], v[162:165]
	v_add3_u32 v44, v44, v59, s5
	v_add3_u32 v45, v45, v58, s5
	v_add3_u32 v46, v46, v53, s5
	v_add3_u32 v47, v47, v52, s5
	v_bfe_u32 v52, v56, 16, 1
	v_bfe_u32 v53, v57, 16, 1
	v_bfe_u32 v58, v54, 16, 1
	v_bfe_u32 v59, v55, 16, 1
	v_add3_u32 v55, v55, v59, s5
	v_add3_u32 v54, v54, v58, s5
	v_add3_u32 v53, v57, v53, s5
	v_add3_u32 v52, v56, v52, s5
	v_mfma_f32_16x16x32_bf16 v[162:165], v[12:15], v[186:189], v[190:193]
	v_lshrrev_b32_e32 v52, 16, v52
	v_lshrrev_b32_e32 v53, 16, v53
	v_lshrrev_b32_e32 v54, 16, v54
	v_lshrrev_b32_e32 v55, 16, v55
	v_and_or_b32 v47, v47, s11, v55
	v_and_or_b32 v46, v46, s11, v54
	v_and_or_b32 v45, v45, s11, v53
	v_and_or_b32 v44, v44, s11, v52
	global_store_dwordx4 v[146:147], v[44:47], off
	s_waitcnt vmcnt(1)
	v_lshlrev_b32_e32 v53, 16, v49
	v_lshlrev_b32_e32 v52, 16, v48
	v_pk_fma_f32 v[44:45], v[156:157], v[6:7], v[148:149] op_sel_hi:[1,1,0]
	v_pk_fma_f32 v[46:47], v[154:155], v[4:5], v[148:149] op_sel_hi:[1,1,0]
	v_mov_b32_e32 v55, v44
	v_and_b32_e32 v49, 0xffff0000, v49
	v_and_b32_e32 v48, 0xffff0000, v48
	v_mov_b32_e32 v44, v47
	v_mov_b32_e32 v54, v46
	v_pk_mul_f32 v[44:45], v[44:45], v[48:49]
	v_pk_fma_f32 v[46:47], v[164:165], v[2:3], v[148:149] op_sel_hi:[1,1,0]
	v_pk_fma_f32 v[48:49], v[162:163], v[0:1], v[148:149] op_sel_hi:[1,1,0]
	v_pk_mul_f32 v[52:53], v[54:55], v[52:53]
	v_lshlrev_b32_e32 v55, 16, v51
	v_lshlrev_b32_e32 v54, 16, v50
	v_mov_b32_e32 v57, v46
	v_and_b32_e32 v51, 0xffff0000, v51
	v_and_b32_e32 v50, 0xffff0000, v50
	v_mov_b32_e32 v46, v49
	v_mov_b32_e32 v56, v48
	v_pk_mul_f32 v[46:47], v[46:47], v[50:51]
	v_pk_mul_f32 v[54:55], v[56:57], v[54:55]
	v_bfe_u32 v48, v47, 16, 1
	v_bfe_u32 v49, v46, 16, 1
	v_bfe_u32 v50, v45, 16, 1
	v_bfe_u32 v51, v44, 16, 1
	v_add3_u32 v44, v44, v51, s5
	v_add3_u32 v45, v45, v50, s5
	v_add3_u32 v46, v46, v49, s5
	v_add3_u32 v47, v47, v48, s5
	v_bfe_u32 v48, v52, 16, 1
	v_bfe_u32 v49, v53, 16, 1
	v_bfe_u32 v50, v54, 16, 1
	v_bfe_u32 v51, v55, 16, 1
	v_add3_u32 v51, v55, v51, s5
	v_add3_u32 v50, v54, v50, s5
	v_add3_u32 v49, v53, v49, s5
	v_add3_u32 v48, v52, v48, s5
	v_lshrrev_b32_e32 v48, 16, v48
	v_lshrrev_b32_e32 v49, 16, v49
	v_lshrrev_b32_e32 v50, 16, v50
	v_lshrrev_b32_e32 v51, 16, v51
	v_and_or_b32 v47, v47, s11, v51
	v_and_or_b32 v46, v46, s11, v50
	v_and_or_b32 v45, v45, s11, v49
	v_and_or_b32 v44, v44, s11, v48
	global_store_dwordx4 v[146:147], v[44:47], off offset:64
	v_or_b32_e32 v48, s21, v138
	global_load_dword v50, v[124:125], off
	v_mad_i64_i32 v[52:53], s[28:29], v48, s4, v[82:83]
	global_load_dwordx4 v[44:47], v[52:53], off
	v_mfma_f32_16x16x32_bf16 v[8:11], v[8:11], v[28:31], v[16:19]
	v_ashrrev_i32_e32 v49, 31, v48
	s_waitcnt vmcnt(1)
; #define LAS __attribute__((address_space(3)))
; __device__ __forceinline__ unsigned pk2(float lo, float hi) { return f2bf(lo) | (f2bf(hi) << 16); }
; template <int HF>
; __device__ __forceinline__ void gmlp_half(LAS unsigned char* wl, const bf16* PROJ, const bf16* wsg, const float* norm_v, const float* b_s, bf16* Y, int tok0, int g, int fr, int fq) {
;     ...
;     for (int nt = 0; nt < 4; ++nt) {
;         const int t = 64 * HF + 16 * nt + fr; const size_t tok = (size_t)(tok0 + t); const float bs = b_s[g * 128 + t];
;         u32x4 uu[2];
; #pragma unroll
;         for (int p = 0; p < 2; ++p) uu[p] = *(const u32x4*)(PROJ + tok * NPROJ + g * 64 + 32 * p + 8 * fq);
; #pragma unroll
;         for (int p = 0; p < 2; ++p) {
;             u32x4 w;
; #pragma unroll
;             for (int e2 = 0; e2 < 2; ++e2) {
;                 const f32x4 z = nv[p][e2] * acc[2 * p + e2][nt] + bs;
;                 const unsigned u0 = uu[p][2 * e2], u1 = uu[p][2 * e2 + 1];
;                 w[2 * e2] = pk2(bf_lo(u0) * z[0], bf_hi(u0) * z[1]); w[2 * e2 + 1] = pk2(bf_lo(u1) * z[2], bf_hi(u1) * z[3]);
;             }
;             *(u32x4*)(Y + tok * D + g * 64 + 32 * p + 8 * fq) = w;
;         }
; __device__ __forceinline__ void gla_upd_unit(LAS unsigned char* wl, const bf16* PROJ, const float* R, const float* w_gk2, const float* b_gk, float* UPD, float* DEC, int unit, int lane) {
;     constexpr int KS = 72;
;     LAS unsigned* KD32 = (LAS unsigned*)wl; LAS unsigned* VB32 = (LAS unsigned*)(wl + 9216);
;     const int h = unit & 3, tok0 = (unit >> 2) * 64, kk = lane;
;     { const f32x4* rp = (const f32x4*)(R + (size_t)(tok0 + lane) * 16); LAS f32x4* rl = (LAS f32x4*)(wl + 9216) + lane * 4;
;       const f32x4 r0 = rp[0], r1 = rp[1], r2 = rp[2], r3 = rp[3]; rl[0] = r0; rl[1] = r1; rl[2] = r2; rl[3] = r3; }
;     const bf16* kp = PROJ + (size_t)tok0 * NPROJ + 1280 + h * 64 + kk;
;     unsigned short kv0[32], kv1[32];
; #pragma unroll
;     for (int t = 0; t < 32; ++t) kv0[t] = kp[(size_t)t * NPROJ];
;     float w[16];
; #pragma unroll
;     for (int j = 0; j < 16; ++j) w[j] = w_gk2[j * 256 + h * 64 + kk];
;     const float bias = b_gk[h * 64 + kk];
	v_pk_fma_f32 v[24:25], v[40:41], v[24:25], v[50:51] op_sel_hi:[1,1,0]
	global_load_dwordx4 v[16:19], v[52:53], off offset:64
	v_mfma_f32_16x16x32_bf16 v[12:15], v[12:15], v[28:31], v[20:23]
	s_nop 2
	v_fma_f32 v6, v10, v6, v50
	v_fma_f32 v7, v11, v7, v50
	v_pk_fma_f32 v[4:5], v[8:9], v[4:5], v[50:51] op_sel_hi:[1,1,0]
	s_waitcnt vmcnt(1)
	v_lshlrev_b32_e32 v31, 16, v45
	v_lshlrev_b64 v[20:21], 11, v[48:49]
	v_lshl_add_u64 v[28:29], v[84:85], 0, v[20:21]
	v_pk_fma_f32 v[20:21], v[38:39], v[34:35], v[50:51] op_sel_hi:[1,1,0]
	v_pk_fma_f32 v[22:23], v[36:37], v[32:33], v[50:51] op_sel_hi:[1,1,0]
	v_lshlrev_b32_e32 v30, 16, v44
	v_mov_b32_e32 v32, v22
	v_mov_b32_e32 v33, v20
	v_mov_b32_e32 v10, v4
	v_mov_b32_e32 v11, v6
	v_pk_mul_f32 v[30:31], v[32:33], v[30:31]
	v_and_b32_e32 v33, 0xffff0000, v45
	v_and_b32_e32 v32, 0xffff0000, v44
	v_mov_b32_e32 v20, v23
	v_pk_fma_f32 v[22:23], v[42:43], v[26:27], v[50:51] op_sel_hi:[1,1,0]
	v_mov_b32_e32 v6, v5
	v_pk_fma_f32 v[2:3], v[14:15], v[2:3], v[50:51] op_sel_hi:[1,1,0]
	v_pk_fma_f32 v[0:1], v[12:13], v[0:1], v[50:51] op_sel_hi:[1,1,0]
	v_pk_mul_f32 v[20:21], v[20:21], v[32:33]
	v_lshlrev_b32_e32 v27, 16, v47
	v_lshlrev_b32_e32 v26, 16, v46
	v_mov_b32_e32 v32, v24
	v_mov_b32_e32 v33, v22
	v_pk_mul_f32 v[26:27], v[32:33], v[26:27]
	v_and_b32_e32 v33, 0xffff0000, v47
	v_and_b32_e32 v32, 0xffff0000, v46
	v_mov_b32_e32 v22, v25
	v_pk_mul_f32 v[22:23], v[22:23], v[32:33]
	v_bfe_u32 v32, v21, 16, 1
	v_bfe_u32 v24, v23, 16, 1
	v_bfe_u32 v25, v22, 16, 1
	v_bfe_u32 v33, v20, 16, 1
	v_add3_u32 v20, v20, v33, s5
	v_add3_u32 v21, v21, v32, s5
	v_add3_u32 v22, v22, v25, s5
	v_add3_u32 v23, v23, v24, s5
	v_bfe_u32 v24, v30, 16, 1
	v_bfe_u32 v25, v31, 16, 1
	v_bfe_u32 v32, v26, 16, 1
	v_bfe_u32 v33, v27, 16, 1
	v_add3_u32 v27, v27, v33, s5
	v_add3_u32 v26, v26, v32, s5
	v_add3_u32 v25, v31, v25, s5
	v_add3_u32 v24, v30, v24, s5
	v_lshrrev_b32_e32 v24, 16, v24
	v_lshrrev_b32_e32 v25, 16, v25
	v_lshrrev_b32_e32 v26, 16, v26
	v_lshrrev_b32_e32 v27, 16, v27
	v_and_or_b32 v23, v23, s11, v27
	v_and_or_b32 v22, v22, s11, v26
	v_and_or_b32 v21, v21, s11, v25
	v_and_or_b32 v20, v20, s11, v24
	global_store_dwordx4 v[28:29], v[20:23], off
	s_waitcnt vmcnt(1)
	v_lshlrev_b32_e32 v9, 16, v17
	v_lshlrev_b32_e32 v8, 16, v16
	v_pk_mul_f32 v[8:9], v[10:11], v[8:9]
	v_and_b32_e32 v11, 0xffff0000, v17
	v_and_b32_e32 v10, 0xffff0000, v16
	v_pk_mul_f32 v[4:5], v[6:7], v[10:11]
	v_lshlrev_b32_e32 v7, 16, v19
	v_lshlrev_b32_e32 v6, 16, v18
	v_mov_b32_e32 v10, v0
	v_mov_b32_e32 v11, v2
	v_pk_mul_f32 v[6:7], v[10:11], v[6:7]
	v_and_b32_e32 v11, 0xffff0000, v19
	v_and_b32_e32 v10, 0xffff0000, v18
	v_mov_b32_e32 v2, v1
	v_pk_mul_f32 v[0:1], v[2:3], v[10:11]
	v_bfe_u32 v10, v5, 16, 1
	v_bfe_u32 v2, v1, 16, 1
	v_bfe_u32 v3, v0, 16, 1
	v_bfe_u32 v11, v4, 16, 1
	v_add3_u32 v4, v4, v11, s5
	v_add3_u32 v5, v5, v10, s5
	v_add3_u32 v0, v0, v3, s5
	v_add3_u32 v1, v1, v2, s5
	v_bfe_u32 v2, v8, 16, 1
	v_bfe_u32 v3, v9, 16, 1
	v_bfe_u32 v10, v6, 16, 1
	v_bfe_u32 v11, v7, 16, 1
	v_add3_u32 v7, v7, v11, s5
	v_add3_u32 v6, v6, v10, s5
	v_add3_u32 v3, v9, v3, s5
	v_add3_u32 v2, v8, v2, s5
	v_lshrrev_b32_e32 v8, 16, v2
	v_lshrrev_b32_e32 v9, 16, v3
	v_lshrrev_b32_e32 v2, 16, v6
	v_lshrrev_b32_e32 v3, 16, v7
	v_and_or_b32 v3, v1, s11, v3
	v_and_or_b32 v2, v0, s11, v2
	v_and_or_b32 v1, v5, s11, v9
	v_and_or_b32 v0, v4, s11, v8
	global_store_dwordx4 v[28:29], v[0:3], off offset:64
	s_waitcnt lgkmcnt(0)
	s_cbranch_scc0 .LBB0_417
	v_readlane_b32 s0, v230, 10
	v_lshlrev_b32_e32 v0, 2, v200
	v_mov_b32_e32 v1, 0
	v_readlane_b32 s1, v230, 11
	v_and_b32_e32 v2, 12, v130
	v_readlane_b32 s2, v230, 8
	v_lshl_add_u64 v[24:25], s[0:1], 0, v[0:1]
	s_movk_i32 s0, 0x90
	v_mov_b32_e32 v6, s37
	v_lshlrev_b32_e32 v2, 2, v2
	v_mov_b32_e32 v3, v1
	v_readlane_b32 s3, v230, 9
	v_mad_u32_u24 v6, v64, s0, v6
	v_readlane_b32 s0, v230, 4
	v_lshl_add_u64 v[2:3], s[2:3], 0, v[2:3]
	s_bfe_u32 s2, s0, 0x20006
	s_lshl_b32 s3, s2, 8
	v_or_b32_e32 v0, s3, v0
	v_lshl_add_u64 v[28:29], s[14:15], 0, v[0:1]
	s_mov_b64 s[0:1], 0x1000
	v_lshl_add_u64 v[30:31], v[28:29], 0, s[0:1]
	s_mov_b64 s[0:1], 0x1400
	v_lshl_add_u64 v[32:33], v[28:29], 0, s[0:1]
	s_mov_b64 s[0:1], 0x1800
	v_lshl_add_u64 v[34:35], v[28:29], 0, s[0:1]
	s_mov_b64 s[0:1], 0x1c00
	v_lshl_add_u64 v[36:37], v[28:29], 0, s[0:1]
	s_mov_b64 s[0:1], 0x2000
	v_lshl_add_u64 v[38:39], v[28:29], 0, s[0:1]
	s_mov_b64 s[0:1], 0x2400
	v_lshl_add_u64 v[40:41], v[28:29], 0, s[0:1]
	s_mov_b64 s[0:1], 0x2800
	v_lshl_add_u64 v[42:43], v[28:29], 0, s[0:1]
	s_mov_b64 s[0:1], 0x2c00
	v_lshl_add_u64 v[44:45], v[28:29], 0, s[0:1]
	s_mov_b64 s[0:1], 0x3000
	v_lshl_add_u64 v[46:47], v[28:29], 0, s[0:1]
	s_mov_b64 s[0:1], 0x3400
	v_lshl_add_u64 v[48:49], v[28:29], 0, s[0:1]
	s_mov_b64 s[0:1], 0x3800
	v_lshl_add_u64 v[50:51], v[28:29], 0, s[0:1]
	s_mov_b64 s[0:1], 0x3c00
	v_lshl_add_u64 v[52:53], v[28:29], 0, s[0:1]
	s_lshl_b32 s0, s2, 7
	s_add_u32 s0, s24, s0
	v_lshl_add_u64 v[54:55], s[16:17], 0, v[0:1]
	s_addc_u32 s1, s25, 0
	v_lshlrev_b32_e32 v0, 1, v200
	v_or_b32_e32 v78, 16, v128
	v_or_b32_e32 v79, 32, v128
	v_or_b32_e32 v80, 48, v128
	v_lshl_add_u64 v[56:57], s[0:1], 0, v[0:1]
	s_add_u32 s0, s24, s3
	v_lshlrev_b32_e32 v4, 6, v200
	v_mul_u32_u24_e32 v5, 0x90, v200
	v_lshl_add_u32 v81, v67, 2, v6
	v_lshl_add_u32 v82, v78, 1, v6
	v_lshl_add_u32 v83, v79, 1, v6
	v_lshl_add_u32 v84, v80, 1, v6
	v_mul_u32_u24_e32 v6, 0x90, v129
	v_mul_u32_u24_e32 v7, 0x90, v131
	v_mov_b32_e32 v67, v1
	s_addc_u32 s1, s25, 0
	v_lshlrev_b32_e32 v0, 1, v64
	v_lshl_add_u64 v[26:27], v[2:3], 0, v[66:67]
	v_lshl_add_u64 v[58:59], s[0:1], 0, v[0:1]
	v_add_u32_e32 v85, s37, v4
	s_movk_i32 s39, 0x1600
	s_mov_b32 s68, 0xbfb8aa3b
	s_mov_b32 s69, 0x800000
	s_mov_b32 s70, 0x3f317217
	s_mov_b32 s71, 0x7f800000
	s_movk_i32 s72, 0x7fff
	s_mov_b32 s73, 0xffff0000
	v_add_u32_e32 v86, s37, v5
	s_mov_b32 s74, 0x3a000
	s_mov_b32 s75, 0x39000
	s_mov_b32 s76, 0x3b000
	s_mov_b32 s77, 0x3d000
	s_mov_b32 s78, 0x3f000
	s_mov_b32 s79, 0x3e000
	s_mov_b32 s80, 0x41000
	s_mov_b32 s81, 0x42000
	s_mov_b32 s82, 0x45000
	s_mov_b32 s83, 0x44000
	s_mov_b32 s84, 0x46000
	s_mov_b32 s85, 0x48000
	s_mov_b32 s86, 0x4a000
	s_mov_b32 s87, 0x49000
	s_mov_b32 s88, 0x4c000
	s_mov_b32 s89, 0x4d000
	s_mov_b32 s90, 0x50000
	s_mov_b32 s91, 0x4f000
	s_mov_b32 s20, 0x51000
	s_mov_b32 s21, 0x53000
	s_mov_b32 s28, 0x55000
	v_add_u32_e32 v87, v65, v6
	v_add_u32_e32 v88, v65, v7
	v_mov_b32_e32 v89, 0x1600
	v_mov_b32_e32 v90, 0x41b17218
	v_mov_b32_e32 v91, 1
	s_mov_b32 s29, 0x54000
	s_mov_b32 s30, 0x57000
	s_mov_b32 s63, 0
	s_mov_b32 s64, s38

; __device__ __forceinline__ void xcd_barrier(const XcdBarrier& b) {
;     asm volatile("s_waitcnt vmcnt(0)" ::: "memory");
;     __syncthreads();
;     if (threadIdx.x == 0) {
;         unsigned* bar = b.bar;
;         __builtin_amdgcn_s_waitcnt(0);
;         unsigned nloc = b.st[0], nx = b.st[1];
;         if (nloc == 0u) { xcd_barrier_complete(bar, b.x, b.gsz, nloc, nx); b.st[0] = nloc; b.st[1] = nx; }
.LBB0_525:
	s_cmp_gt_i32 s53, 7
	s_cselect_b64 s[4:5], -1, 0
	s_and_b64 s[0:1], s[0:1], s[4:5]
	s_andn2_b64 vcc, exec, s[0:1]
	s_cbranch_vccnz .LBB0_570
	s_waitcnt vmcnt(0)
	s_waitcnt lgkmcnt(0)
	s_barrier
	s_cmp_eq_u32 s97, 0
	s_cbranch_scc1 .Lbpf_skip_5
	v_mov_b32_e32 v232, s95
	v_mul_u32_u24_e32 v232, 7, v232
	v_add_u32_e32 v232, s97, v232
	v_add_u32_e32 v232, -1, v232
	v_lshl_add_u32 v232, v232, 6, v200
	v_lshrrev_b32_e32 v231, 1, v232
	v_min_u32_e32 v231, 0x3ff, v231
	v_mul_u32_u24_e32 v231, 0x800, v231
	v_and_b32_e32 v232, 1, v232
	v_lshlrev_b32_e32 v232, 7, v232
	v_add_u32_e32 v232, v231, v232
	v_add_u32_e32 v232, 0x1e00000, v232
	global_load_dword v231, v232, s[34:35]
.Lbpf_skip_5:
	s_and_saveexec_b64 s[0:1], s[8:9]
	s_cbranch_execz .LBB0_569
	v_mov_b32_e32 v0, s92
	s_waitcnt vmcnt(0) expcnt(0) lgkmcnt(0)
	ds_read_b32 v2, v0
	ds_read_b32 v0, v0 offset:4
	s_waitcnt lgkmcnt(1)
	v_cmp_ne_u32_e32 vcc, 0, v2
	s_cbranch_vccnz .LBB0_540
	s_add_u32 s6, s54, 0x1000
	s_addc_u32 s7, s55, 0
	s_add_u32 s64, s54, 0x1100
	s_addc_u32 s65, s55, 0
	s_add_u32 s66, s54, 0x1200
	s_addc_u32 s67, s55, 0
	s_add_u32 s68, s54, 0x1300
	s_addc_u32 s69, s55, 0
	s_mov_b32 s2, 1
	v_mov_b32_e32 v16, 0
	s_branch .LBB0_530

; __device__ __forceinline__ void xcd_barrier(const XcdBarrier& b) {
;     asm volatile("s_waitcnt vmcnt(0)" ::: "memory");
;     __syncthreads();
;     if (threadIdx.x == 0) {
;         unsigned* bar = b.bar;
;         __builtin_amdgcn_s_waitcnt(0);
;         unsigned nloc = b.st[0], nx = b.st[1];
;         if (nloc == 0u) { xcd_barrier_complete(bar, b.x, b.gsz, nloc, nx); b.st[0] = nloc; b.st[1] = nx; }
.LBB0_605:
	s_cmp_gt_i32 s53, 8
	s_cselect_b64 s[4:5], -1, 0
	s_and_b64 s[0:1], s[0:1], s[4:5]
	s_andn2_b64 vcc, exec, s[0:1]
	s_cbranch_vccnz .LBB0_650
	s_waitcnt vmcnt(0)
	s_waitcnt lgkmcnt(0)
	s_barrier
	s_cmp_eq_u32 s97, 0
	s_cbranch_scc1 .Lbpf_skip_6
	v_mov_b32_e32 v232, s95
	v_mul_u32_u24_e32 v232, 7, v232
	v_add_u32_e32 v232, s97, v232
	v_add_u32_e32 v232, -1, v232
	v_lshl_add_u32 v232, v232, 6, v200
	v_lshrrev_b32_e32 v231, 1, v232
	v_min_u32_e32 v231, 0x15ff, v231
	v_mul_u32_u24_e32 v231, 0x800, v231
	v_and_b32_e32 v232, 1, v232
	v_lshlrev_b32_e32 v232, 7, v232
	v_add_u32_e32 v232, v231, v232
	v_add_u32_e32 v232, 0x2000000, v232
	global_load_dword v231, v232, s[34:35]

; __device__ __forceinline__ unsigned cvt_pk_bf16(float lo, float hi) { unsigned r; asm volatile("v_cvt_pk_bf16_f32 %0, %1, %2" : "=v"(r) : "v"(lo), "v"(hi)); return r; }
; __device__ __forceinline__ float ss_val(u64 v) { return (float)v * (1.0f / 1099511627776.0f); }
;     __device__ __forceinline__ void operator()(const f32x4 (&acc)[2][2][4][2], const Unit& u, const Unit& nxt, bool has_next, int wr, int wc, int fr, int fq) const {
;     ...
;         for (int g = 0; g < 8; ++g) {
;             const int ai = g >> 2, m = g & 3;
;             const float rs = __builtin_amdgcn_rsqf(ss_val(cur[g]) * inv_k + eps), rsn = rs * -1.44269504089f, rs2 = rs * rs;
;             float h[8];
; #pragma unroll
;             for (int n = 0; n < 2; ++n)
; #pragma unroll
;                 for (int jp = 0; jp < 2; ++jp) {
;                     const f32x2v av = {acc[ai][0][m][n][2 * jp], acc[ai][0][m][n][2 * jp + 1]}, gv = {acc[ai][1][m][n][2 * jp], acc[ai][1][m][n][2 * jp + 1]};
;                     const f32x2v t = (av * gv) * rs2, y = gv * rsn;
;                     f32x2v ex; ex.x = __builtin_amdgcn_exp2f(y.x); ex.y = __builtin_amdgcn_exp2f(y.y);
;                     const f32x2v d = ex + 1.0f;
;                     f32x2v r; r.x = __builtin_amdgcn_rcpf(d.x); r.y = __builtin_amdgcn_rcpf(d.y);
;                     const f32x2v o = t * r;
;                     h[4 * n + 2 * jp] = o.x; h[4 * n + 2 * jp + 1] = o.y;
;                 }
;             u32x4 w; w.x = cvt_pk_bf16(h[0], h[1]); w.y = cvt_pk_bf16(h[2], h[3]); w.z = cvt_pk_bf16(h[4], h[5]); w.w = cvt_pk_bf16(h[6], h[7]);
;             *(u32x4*)(O + (size_t)(row0 + ai * HALF + m * 16) * ldc + col0) = w;
;         }
.LBB0_665:
	s_waitcnt vmcnt(0)
	v_pk_mul_f32 v[124:125], v[124:125], v[116:117]
	v_pk_mul_f32 v[120:121], v[120:121], v[112:113]
	v_cvt_f32_u32_e32 v186, v186
	v_cvt_f32_u32_e32 v187, v187
	v_fmamk_f32 v186, v187, 0x4f800000, v186
	v_fmamk_f32 v161, v186, 0x26800000, v193
	v_rsq_f32_e32 v161, v161
	v_pk_mul_f32 v[126:127], v[126:127], v[118:119]
	v_pk_mul_f32 v[122:123], v[122:123], v[114:115]
	v_lshl_or_b32 v186, s86, 7, v189
	v_mul_f32_e32 v194, 0xbfb8aa3b, v161
	v_pk_mul_f32 v[116:117], v[116:117], v[194:195] op_sel_hi:[1,0]
	v_pk_mul_f32 v[112:113], v[112:113], v[194:195] op_sel_hi:[1,0]
	v_exp_f32_e32 v116, v116
	v_exp_f32_e32 v117, v117
	v_pk_mul_f32 v[118:119], v[118:119], v[194:195] op_sel_hi:[1,0]
	v_exp_f32_e32 v112, v112
	v_exp_f32_e32 v113, v113
	v_pk_mul_f32 v[114:115], v[114:115], v[194:195] op_sel_hi:[1,0]
	v_exp_f32_e32 v118, v118
	v_exp_f32_e32 v119, v119
	v_exp_f32_e32 v114, v114
	v_exp_f32_e32 v115, v115
	v_pk_add_f32 v[116:117], v[116:117], 1.0 op_sel_hi:[1,0]
	v_pk_add_f32 v[112:113], v[112:113], 1.0 op_sel_hi:[1,0]
	v_rcp_f32_e32 v116, v116
	v_rcp_f32_e32 v117, v117
	v_pk_add_f32 v[118:119], v[118:119], 1.0 op_sel_hi:[1,0]
	v_rcp_f32_e32 v112, v112
	v_rcp_f32_e32 v113, v113
	v_pk_add_f32 v[114:115], v[114:115], 1.0 op_sel_hi:[1,0]
	v_rcp_f32_e32 v118, v118
	v_rcp_f32_e32 v119, v119
	v_rcp_f32_e32 v114, v114
	v_rcp_f32_e32 v115, v115
	v_mul_f32_e32 v196, v161, v161
	v_pk_mul_f32 v[124:125], v[124:125], v[196:197] op_sel_hi:[1,0]
	v_pk_mul_f32 v[120:121], v[120:121], v[196:197] op_sel_hi:[1,0]
	v_pk_mul_f32 v[116:117], v[124:125], v[116:117]
	v_pk_mul_f32 v[124:125], v[126:127], v[196:197] op_sel_hi:[1,0]
	v_pk_mul_f32 v[112:113], v[120:121], v[112:113]
	v_pk_mul_f32 v[120:121], v[122:123], v[196:197] op_sel_hi:[1,0]
	v_pk_mul_f32 v[118:119], v[124:125], v[118:119]
	v_pk_mul_f32 v[114:115], v[120:121], v[114:115]
	v_cvt_pk_bf16_f32 v116, v116, v117
	v_cvt_pk_bf16_f32 v117, v118, v119
	v_cvt_pk_bf16_f32 v118, v112, v113
	v_ashrrev_i32_e32 v187, 31, v186
	v_cvt_pk_bf16_f32 v119, v114, v115
	v_mov_b64_e32 v[112:113], s[24:25]
	v_mad_i64_i32 v[120:121], s[58:59], v182, s57, v[112:113]
	v_cvt_f32_u32_e32 v184, v184
	v_cvt_f32_u32_e32 v185, v185
	v_fmamk_f32 v184, v185, 0x4f800000, v184
	v_fmamk_f32 v114, v184, 0x26800000, v193
	v_rsq_f32_e32 v122, v114
	v_lshlrev_b64 v[114:115], 1, v[186:187]
	v_lshl_add_u64 v[120:121], v[120:121], 0, v[114:115]
	global_store_dwordx4 v[120:121], v[116:119], off
	v_pk_mul_f32 v[104:105], v[104:105], v[96:97]
	v_pk_mul_f32 v[108:109], v[108:109], v[100:101]
	v_mul_f32_e32 v116, 0xbfb8aa3b, v122
	v_pk_mul_f32 v[96:97], v[96:97], v[116:117] op_sel_hi:[1,0]
	v_pk_mul_f32 v[100:101], v[100:101], v[116:117] op_sel_hi:[1,0]
	v_pk_mul_f32 v[106:107], v[106:107], v[98:99]
	v_exp_f32_e32 v96, v96
	v_exp_f32_e32 v97, v97
	v_pk_mul_f32 v[98:99], v[98:99], v[116:117] op_sel_hi:[1,0]
	v_exp_f32_e32 v100, v100
	v_exp_f32_e32 v101, v101
	v_exp_f32_e32 v98, v98
	v_exp_f32_e32 v99, v99
	v_pk_add_f32 v[96:97], v[96:97], 1.0 op_sel_hi:[1,0]
	v_pk_add_f32 v[100:101], v[100:101], 1.0 op_sel_hi:[1,0]
	v_rcp_f32_e32 v96, v96
	v_rcp_f32_e32 v97, v97
	v_pk_add_f32 v[98:99], v[98:99], 1.0 op_sel_hi:[1,0]
	v_rcp_f32_e32 v100, v100
	v_rcp_f32_e32 v101, v101
	v_rcp_f32_e32 v98, v98
	v_rcp_f32_e32 v99, v99
	v_mul_f32_e32 v118, v122, v122
	v_pk_mul_f32 v[104:105], v[104:105], v[118:119] op_sel_hi:[1,0]
	v_pk_mul_f32 v[108:109], v[108:109], v[118:119] op_sel_hi:[1,0]
	v_pk_mul_f32 v[104:105], v[104:105], v[96:97]
	v_pk_mul_f32 v[96:97], v[106:107], v[118:119] op_sel_hi:[1,0]
	v_pk_mul_f32 v[100:101], v[108:109], v[100:101]
	v_pk_mul_f32 v[106:107], v[96:97], v[98:99]
	v_pk_mul_f32 v[110:111], v[110:111], v[102:103]
	v_pk_mul_f32 v[102:103], v[102:103], v[116:117] op_sel_hi:[1,0]
	v_cvt_pk_bf16_f32 v96, v100, v101
	v_exp_f32_e32 v102, v102
	v_exp_f32_e32 v103, v103
	s_nop 0
	v_pk_add_f32 v[102:103], v[102:103], 1.0 op_sel_hi:[1,0]
	v_rcp_f32_e32 v102, v102
	v_rcp_f32_e32 v103, v103
	v_pk_mul_f32 v[108:109], v[110:111], v[118:119] op_sel_hi:[1,0]
	v_pk_mul_f32 v[102:103], v[108:109], v[102:103]
	v_cvt_f32_u32_e32 v180, v180
	v_cvt_f32_u32_e32 v181, v181
	v_fmamk_f32 v180, v181, 0x4f800000, v180
	v_fmamk_f32 v100, v180, 0x26800000, v193
	v_cvt_pk_bf16_f32 v97, v102, v103
	v_rsq_f32_e32 v102, v100
	v_mad_i64_i32 v[100:101], s[58:59], v178, s57, v[112:113]
	v_lshl_add_u64 v[100:101], v[100:101], 0, v[114:115]
	v_cvt_pk_bf16_f32 v98, v104, v105
	v_cvt_pk_bf16_f32 v99, v106, v107
	global_store_dwordx4 v[100:101], v[96:99], off
	v_pk_mul_f32 v[88:89], v[88:89], v[80:81]
	v_pk_mul_f32 v[92:93], v[92:93], v[84:85]
	v_mul_f32_e32 v96, 0xbfb8aa3b, v102
	v_pk_mul_f32 v[80:81], v[80:81], v[96:97] op_sel_hi:[1,0]
	v_pk_mul_f32 v[84:85], v[84:85], v[96:97] op_sel_hi:[1,0]
	v_pk_mul_f32 v[90:91], v[90:91], v[82:83]
	v_exp_f32_e32 v80, v80
	v_exp_f32_e32 v81, v81
	v_pk_mul_f32 v[82:83], v[82:83], v[96:97] op_sel_hi:[1,0]
	v_exp_f32_e32 v84, v84
	v_exp_f32_e32 v85, v85
	v_exp_f32_e32 v82, v82
	v_exp_f32_e32 v83, v83
	v_pk_add_f32 v[80:81], v[80:81], 1.0 op_sel_hi:[1,0]
	v_pk_add_f32 v[84:85], v[84:85], 1.0 op_sel_hi:[1,0]
	v_rcp_f32_e32 v80, v80
	v_rcp_f32_e32 v81, v81
	v_pk_add_f32 v[82:83], v[82:83], 1.0 op_sel_hi:[1,0]
	v_rcp_f32_e32 v84, v84
	v_rcp_f32_e32 v85, v85
	v_rcp_f32_e32 v82, v82
	v_rcp_f32_e32 v83, v83
	v_mul_f32_e32 v98, v102, v102
	v_pk_mul_f32 v[88:89], v[88:89], v[98:99] op_sel_hi:[1,0]
	v_pk_mul_f32 v[92:93], v[92:93], v[98:99] op_sel_hi:[1,0]
	v_pk_mul_f32 v[88:89], v[88:89], v[80:81]
	v_pk_mul_f32 v[80:81], v[90:91], v[98:99] op_sel_hi:[1,0]
	v_pk_mul_f32 v[84:85], v[92:93], v[84:85]
	v_pk_mul_f32 v[90:91], v[80:81], v[82:83]
; __device__ __forceinline__ unsigned cvt_pk_bf16(float lo, float hi) { unsigned r; asm volatile("v_cvt_pk_bf16_f32 %0, %1, %2" : "=v"(r) : "v"(lo), "v"(hi)); return r; }
; __device__ __forceinline__ float ss_val(u64 v) { return (float)v * (1.0f / 1099511627776.0f); }
;     __device__ __forceinline__ void operator()(const f32x4 (&acc)[2][2][4][2], const Unit& u, const Unit& nxt, bool has_next, int wr, int wc, int fr, int fq) const {
;     ...
;         for (int g = 0; g < 8; ++g) {
;             const int ai = g >> 2, m = g & 3;
;             const float rs = __builtin_amdgcn_rsqf(ss_val(cur[g]) * inv_k + eps), rsn = rs * -1.44269504089f, rs2 = rs * rs;
;             float h[8];
; #pragma unroll
;             for (int n = 0; n < 2; ++n)
; #pragma unroll
;                 for (int jp = 0; jp < 2; ++jp) {
;                     const f32x2v av = {acc[ai][0][m][n][2 * jp], acc[ai][0][m][n][2 * jp + 1]}, gv = {acc[ai][1][m][n][2 * jp], acc[ai][1][m][n][2 * jp + 1]};
;                     const f32x2v t = (av * gv) * rs2, y = gv * rsn;
;                     f32x2v ex; ex.x = __builtin_amdgcn_exp2f(y.x); ex.y = __builtin_amdgcn_exp2f(y.y);
;                     const f32x2v d = ex + 1.0f;
;                     f32x2v r; r.x = __builtin_amdgcn_rcpf(d.x); r.y = __builtin_amdgcn_rcpf(d.y);
;                     const f32x2v o = t * r;
;                     h[4 * n + 2 * jp] = o.x; h[4 * n + 2 * jp + 1] = o.y;
;                 }
;             u32x4 w; w.x = cvt_pk_bf16(h[0], h[1]); w.y = cvt_pk_bf16(h[2], h[3]); w.z = cvt_pk_bf16(h[4], h[5]); w.w = cvt_pk_bf16(h[6], h[7]);
;             *(u32x4*)(O + (size_t)(row0 + ai * HALF + m * 16) * ldc + col0) = w;
;         }
	v_pk_mul_f32 v[94:95], v[94:95], v[86:87]
	v_pk_mul_f32 v[86:87], v[86:87], v[96:97] op_sel_hi:[1,0]
	v_cvt_pk_bf16_f32 v80, v84, v85
	v_exp_f32_e32 v86, v86
	v_exp_f32_e32 v87, v87
	s_nop 0
	v_pk_add_f32 v[86:87], v[86:87], 1.0 op_sel_hi:[1,0]
	v_rcp_f32_e32 v86, v86
	v_rcp_f32_e32 v87, v87
	v_pk_mul_f32 v[92:93], v[94:95], v[98:99] op_sel_hi:[1,0]
	v_pk_mul_f32 v[86:87], v[92:93], v[86:87]
	v_cvt_f32_u32_e32 v176, v176
	v_cvt_f32_u32_e32 v177, v177
	v_fmamk_f32 v176, v177, 0x4f800000, v176
	v_fmamk_f32 v84, v176, 0x26800000, v193
	v_cvt_pk_bf16_f32 v81, v86, v87
	v_rsq_f32_e32 v86, v84
	v_mad_i64_i32 v[84:85], s[58:59], v174, s57, v[112:113]
	v_lshl_add_u64 v[84:85], v[84:85], 0, v[114:115]
	v_cvt_pk_bf16_f32 v82, v88, v89
	v_cvt_pk_bf16_f32 v83, v90, v91
	global_store_dwordx4 v[84:85], v[80:83], off
	v_pk_mul_f32 v[72:73], v[72:73], v[64:65]
	v_pk_mul_f32 v[76:77], v[76:77], v[68:69]
	v_mul_f32_e32 v80, 0xbfb8aa3b, v86
	v_pk_mul_f32 v[64:65], v[64:65], v[80:81] op_sel_hi:[1,0]
	v_pk_mul_f32 v[68:69], v[68:69], v[80:81] op_sel_hi:[1,0]
	v_pk_mul_f32 v[74:75], v[74:75], v[66:67]
	v_exp_f32_e32 v64, v64
	v_exp_f32_e32 v65, v65
	v_pk_mul_f32 v[66:67], v[66:67], v[80:81] op_sel_hi:[1,0]
	v_exp_f32_e32 v68, v68
	v_exp_f32_e32 v69, v69
	v_exp_f32_e32 v66, v66
	v_exp_f32_e32 v67, v67
	v_pk_add_f32 v[64:65], v[64:65], 1.0 op_sel_hi:[1,0]
	v_pk_add_f32 v[68:69], v[68:69], 1.0 op_sel_hi:[1,0]
	v_rcp_f32_e32 v64, v64
	v_rcp_f32_e32 v65, v65
	v_pk_add_f32 v[66:67], v[66:67], 1.0 op_sel_hi:[1,0]
	v_rcp_f32_e32 v68, v68
	v_rcp_f32_e32 v69, v69
	v_rcp_f32_e32 v66, v66
	v_rcp_f32_e32 v67, v67
	v_mul_f32_e32 v82, v86, v86
	v_pk_mul_f32 v[72:73], v[72:73], v[82:83] op_sel_hi:[1,0]
	v_pk_mul_f32 v[76:77], v[76:77], v[82:83] op_sel_hi:[1,0]
	v_pk_mul_f32 v[72:73], v[72:73], v[64:65]
	v_pk_mul_f32 v[64:65], v[74:75], v[82:83] op_sel_hi:[1,0]
	v_pk_mul_f32 v[68:69], v[76:77], v[68:69]
	v_pk_mul_f32 v[74:75], v[64:65], v[66:67]
	v_pk_mul_f32 v[78:79], v[78:79], v[70:71]
	v_pk_mul_f32 v[70:71], v[70:71], v[80:81] op_sel_hi:[1,0]
	v_cvt_pk_bf16_f32 v64, v68, v69
	v_exp_f32_e32 v70, v70
	v_exp_f32_e32 v71, v71
	s_nop 0
	v_pk_add_f32 v[70:71], v[70:71], 1.0 op_sel_hi:[1,0]
	v_rcp_f32_e32 v70, v70
	v_rcp_f32_e32 v71, v71
	v_pk_mul_f32 v[76:77], v[78:79], v[82:83] op_sel_hi:[1,0]
	v_pk_mul_f32 v[70:71], v[76:77], v[70:71]
	v_cvt_f32_u32_e32 v172, v172
	v_cvt_f32_u32_e32 v173, v173
	v_fmamk_f32 v172, v173, 0x4f800000, v172
	v_fmamk_f32 v68, v172, 0x26800000, v193
	v_cvt_pk_bf16_f32 v65, v70, v71
	v_rsq_f32_e32 v70, v68
	v_mad_i64_i32 v[68:69], s[58:59], v170, s57, v[112:113]
	v_lshl_add_u64 v[68:69], v[68:69], 0, v[114:115]
	v_cvt_pk_bf16_f32 v66, v72, v73
	v_cvt_pk_bf16_f32 v67, v74, v75
	global_store_dwordx4 v[68:69], v[64:67], off
	v_pk_mul_f32 v[56:57], v[56:57], v[48:49]
	v_pk_mul_f32 v[60:61], v[60:61], v[52:53]
	v_mul_f32_e32 v64, 0xbfb8aa3b, v70
	v_pk_mul_f32 v[48:49], v[48:49], v[64:65] op_sel_hi:[1,0]
	v_pk_mul_f32 v[52:53], v[52:53], v[64:65] op_sel_hi:[1,0]
	v_pk_mul_f32 v[58:59], v[58:59], v[50:51]
	v_exp_f32_e32 v48, v48
	v_exp_f32_e32 v49, v49
	v_pk_mul_f32 v[50:51], v[50:51], v[64:65] op_sel_hi:[1,0]
	v_exp_f32_e32 v52, v52
	v_exp_f32_e32 v53, v53
	v_exp_f32_e32 v50, v50
	v_exp_f32_e32 v51, v51
	v_pk_add_f32 v[48:49], v[48:49], 1.0 op_sel_hi:[1,0]
	v_pk_add_f32 v[52:53], v[52:53], 1.0 op_sel_hi:[1,0]
	v_rcp_f32_e32 v48, v48
	v_rcp_f32_e32 v49, v49
	v_pk_add_f32 v[50:51], v[50:51], 1.0 op_sel_hi:[1,0]
	v_rcp_f32_e32 v52, v52
	v_rcp_f32_e32 v53, v53
	v_rcp_f32_e32 v50, v50
	v_rcp_f32_e32 v51, v51
	v_mul_f32_e32 v66, v70, v70
	v_pk_mul_f32 v[56:57], v[56:57], v[66:67] op_sel_hi:[1,0]
	v_pk_mul_f32 v[60:61], v[60:61], v[66:67] op_sel_hi:[1,0]
	v_pk_mul_f32 v[56:57], v[56:57], v[48:49]
	v_pk_mul_f32 v[48:49], v[58:59], v[66:67] op_sel_hi:[1,0]
	v_pk_mul_f32 v[52:53], v[60:61], v[52:53]
	v_pk_mul_f32 v[58:59], v[48:49], v[50:51]
	v_pk_mul_f32 v[62:63], v[62:63], v[54:55]
	v_pk_mul_f32 v[54:55], v[54:55], v[64:65] op_sel_hi:[1,0]
	v_cvt_pk_bf16_f32 v48, v52, v53
	v_exp_f32_e32 v54, v54
	v_exp_f32_e32 v55, v55
	s_nop 0
	v_pk_add_f32 v[54:55], v[54:55], 1.0 op_sel_hi:[1,0]
	v_rcp_f32_e32 v54, v54
	v_rcp_f32_e32 v55, v55
	v_pk_mul_f32 v[60:61], v[62:63], v[66:67] op_sel_hi:[1,0]
	v_pk_mul_f32 v[54:55], v[60:61], v[54:55]
	v_cvt_f32_u32_e32 v168, v168
	v_cvt_f32_u32_e32 v169, v169
	v_fmamk_f32 v168, v169, 0x4f800000, v168
	v_fmamk_f32 v52, v168, 0x26800000, v193
	v_cvt_pk_bf16_f32 v49, v54, v55
	v_rsq_f32_e32 v54, v52
	v_add_u32_e32 v141, 0x80, v182
	v_mad_i64_i32 v[52:53], s[58:59], v141, s57, v[112:113]
	v_lshl_add_u64 v[52:53], v[52:53], 0, v[114:115]
	v_cvt_pk_bf16_f32 v50, v56, v57
	v_cvt_pk_bf16_f32 v51, v58, v59
	global_store_dwordx4 v[52:53], v[48:51], off
	v_pk_mul_f32 v[40:41], v[40:41], v[32:33]
	v_pk_mul_f32 v[44:45], v[44:45], v[36:37]
	v_mul_f32_e32 v48, 0xbfb8aa3b, v54
	v_pk_mul_f32 v[32:33], v[32:33], v[48:49] op_sel_hi:[1,0]
	v_pk_mul_f32 v[36:37], v[36:37], v[48:49] op_sel_hi:[1,0]
	v_pk_mul_f32 v[42:43], v[42:43], v[34:35]
	v_exp_f32_e32 v32, v32
	v_exp_f32_e32 v33, v33
	v_pk_mul_f32 v[34:35], v[34:35], v[48:49] op_sel_hi:[1,0]
	v_exp_f32_e32 v36, v36
	v_exp_f32_e32 v37, v37
	v_exp_f32_e32 v34, v34
	v_exp_f32_e32 v35, v35
	v_pk_add_f32 v[32:33], v[32:33], 1.0 op_sel_hi:[1,0]
	v_pk_add_f32 v[36:37], v[36:37], 1.0 op_sel_hi:[1,0]
	v_rcp_f32_e32 v32, v32
; __device__ __forceinline__ unsigned cvt_pk_bf16(float lo, float hi) { unsigned r; asm volatile("v_cvt_pk_bf16_f32 %0, %1, %2" : "=v"(r) : "v"(lo), "v"(hi)); return r; }
; __device__ __forceinline__ float ss_val(u64 v) { return (float)v * (1.0f / 1099511627776.0f); }
;     __device__ __forceinline__ void operator()(const f32x4 (&acc)[2][2][4][2], const Unit& u, const Unit& nxt, bool has_next, int wr, int wc, int fr, int fq) const {
;     ...
;         for (int g = 0; g < 8; ++g) {
;             const int ai = g >> 2, m = g & 3;
;             const float rs = __builtin_amdgcn_rsqf(ss_val(cur[g]) * inv_k + eps), rsn = rs * -1.44269504089f, rs2 = rs * rs;
;             float h[8];
; #pragma unroll
;             for (int n = 0; n < 2; ++n)
; #pragma unroll
;                 for (int jp = 0; jp < 2; ++jp) {
;                     const f32x2v av = {acc[ai][0][m][n][2 * jp], acc[ai][0][m][n][2 * jp + 1]}, gv = {acc[ai][1][m][n][2 * jp], acc[ai][1][m][n][2 * jp + 1]};
;                     const f32x2v t = (av * gv) * rs2, y = gv * rsn;
;                     f32x2v ex; ex.x = __builtin_amdgcn_exp2f(y.x); ex.y = __builtin_amdgcn_exp2f(y.y);
;                     const f32x2v d = ex + 1.0f;
;                     f32x2v r; r.x = __builtin_amdgcn_rcpf(d.x); r.y = __builtin_amdgcn_rcpf(d.y);
;                     const f32x2v o = t * r;
;                     h[4 * n + 2 * jp] = o.x; h[4 * n + 2 * jp + 1] = o.y;
;                 }
;             u32x4 w; w.x = cvt_pk_bf16(h[0], h[1]); w.y = cvt_pk_bf16(h[2], h[3]); w.z = cvt_pk_bf16(h[4], h[5]); w.w = cvt_pk_bf16(h[6], h[7]);
;             *(u32x4*)(O + (size_t)(row0 + ai * HALF + m * 16) * ldc + col0) = w;
;         }
;         if (has_next) { u64 x = 0;
; #pragma unroll
;             for (int g = 0; g < 8; ++g) x |= warm[g];
;             asm volatile("" :: "v"((unsigned)x), "v"((unsigned)(x >> 32))); }
	v_rcp_f32_e32 v33, v33
	v_pk_add_f32 v[34:35], v[34:35], 1.0 op_sel_hi:[1,0]
	v_rcp_f32_e32 v36, v36
	v_rcp_f32_e32 v37, v37
	v_rcp_f32_e32 v34, v34
	v_rcp_f32_e32 v35, v35
	v_mul_f32_e32 v50, v54, v54
	v_pk_mul_f32 v[40:41], v[40:41], v[50:51] op_sel_hi:[1,0]
	v_pk_mul_f32 v[44:45], v[44:45], v[50:51] op_sel_hi:[1,0]
	v_pk_mul_f32 v[40:41], v[40:41], v[32:33]
	v_pk_mul_f32 v[32:33], v[42:43], v[50:51] op_sel_hi:[1,0]
	v_pk_mul_f32 v[36:37], v[44:45], v[36:37]
	v_pk_mul_f32 v[42:43], v[32:33], v[34:35]
	v_pk_mul_f32 v[46:47], v[46:47], v[38:39]
	v_pk_mul_f32 v[38:39], v[38:39], v[48:49] op_sel_hi:[1,0]
	v_cvt_pk_bf16_f32 v32, v36, v37
	v_exp_f32_e32 v38, v38
	v_exp_f32_e32 v39, v39
	s_nop 0
	v_pk_add_f32 v[38:39], v[38:39], 1.0 op_sel_hi:[1,0]
	v_rcp_f32_e32 v38, v38
	v_rcp_f32_e32 v39, v39
	v_pk_mul_f32 v[44:45], v[46:47], v[50:51] op_sel_hi:[1,0]
	v_pk_mul_f32 v[38:39], v[44:45], v[38:39]
	v_cvt_f32_u32_e32 v166, v166
	v_cvt_f32_u32_e32 v167, v167
	v_fmamk_f32 v166, v167, 0x4f800000, v166
	v_fmamk_f32 v36, v166, 0x26800000, v193
	v_cvt_pk_bf16_f32 v33, v38, v39
	v_rsq_f32_e32 v38, v36
	v_mad_i64_i32 v[36:37], s[58:59], v164, s57, v[112:113]
	v_lshl_add_u64 v[36:37], v[36:37], 0, v[114:115]
	v_cvt_pk_bf16_f32 v34, v40, v41
	v_cvt_pk_bf16_f32 v35, v42, v43
	global_store_dwordx4 v[36:37], v[32:35], off
	v_pk_mul_f32 v[24:25], v[24:25], v[16:17]
	v_pk_mul_f32 v[28:29], v[28:29], v[20:21]
	v_mul_f32_e32 v32, 0xbfb8aa3b, v38
	v_pk_mul_f32 v[16:17], v[16:17], v[32:33] op_sel_hi:[1,0]
	v_pk_mul_f32 v[20:21], v[20:21], v[32:33] op_sel_hi:[1,0]
	v_pk_mul_f32 v[26:27], v[26:27], v[18:19]
	v_exp_f32_e32 v16, v16
	v_exp_f32_e32 v17, v17
	v_pk_mul_f32 v[18:19], v[18:19], v[32:33] op_sel_hi:[1,0]
	v_exp_f32_e32 v20, v20
	v_exp_f32_e32 v21, v21
	v_exp_f32_e32 v18, v18
	v_exp_f32_e32 v19, v19
	v_pk_add_f32 v[16:17], v[16:17], 1.0 op_sel_hi:[1,0]
	v_pk_add_f32 v[20:21], v[20:21], 1.0 op_sel_hi:[1,0]
	v_rcp_f32_e32 v16, v16
	v_rcp_f32_e32 v17, v17
	v_pk_add_f32 v[18:19], v[18:19], 1.0 op_sel_hi:[1,0]
	v_rcp_f32_e32 v20, v20
	v_rcp_f32_e32 v21, v21
	v_rcp_f32_e32 v18, v18
	v_rcp_f32_e32 v19, v19
	v_mul_f32_e32 v34, v38, v38
	v_pk_mul_f32 v[24:25], v[24:25], v[34:35] op_sel_hi:[1,0]
	v_pk_mul_f32 v[28:29], v[28:29], v[34:35] op_sel_hi:[1,0]
	v_pk_mul_f32 v[24:25], v[24:25], v[16:17]
	v_pk_mul_f32 v[16:17], v[26:27], v[34:35] op_sel_hi:[1,0]
	v_pk_mul_f32 v[20:21], v[28:29], v[20:21]
	v_pk_mul_f32 v[26:27], v[16:17], v[18:19]
	v_pk_mul_f32 v[30:31], v[30:31], v[22:23]
	v_pk_mul_f32 v[22:23], v[22:23], v[32:33] op_sel_hi:[1,0]
	v_cvt_pk_bf16_f32 v16, v20, v21
	v_exp_f32_e32 v22, v22
	v_exp_f32_e32 v23, v23
	s_nop 0
	v_pk_add_f32 v[22:23], v[22:23], 1.0 op_sel_hi:[1,0]
	v_rcp_f32_e32 v22, v22
	v_rcp_f32_e32 v23, v23
	v_pk_mul_f32 v[28:29], v[30:31], v[34:35] op_sel_hi:[1,0]
	v_pk_mul_f32 v[22:23], v[28:29], v[22:23]
	v_cvt_f32_u32_e32 v162, v162
	v_cvt_f32_u32_e32 v163, v163
	v_fmamk_f32 v162, v163, 0x4f800000, v162
	v_fmamk_f32 v20, v162, 0x26800000, v193
	v_cvt_pk_bf16_f32 v17, v22, v23
	v_rsq_f32_e32 v22, v20
	v_mad_i64_i32 v[20:21], s[58:59], v160, s57, v[112:113]
	v_lshl_add_u64 v[20:21], v[20:21], 0, v[114:115]
	v_cvt_pk_bf16_f32 v18, v24, v25
	v_cvt_pk_bf16_f32 v19, v26, v27
	global_store_dwordx4 v[20:21], v[16:19], off
	v_pk_mul_f32 v[12:13], v[12:13], v[4:5]
	v_pk_mul_f32 v[8:9], v[8:9], v[0:1]
	v_mul_f32_e32 v16, 0xbfb8aa3b, v22
	v_pk_mul_f32 v[4:5], v[4:5], v[16:17] op_sel_hi:[1,0]
	v_pk_mul_f32 v[0:1], v[0:1], v[16:17] op_sel_hi:[1,0]
	v_exp_f32_e32 v4, v4
	v_exp_f32_e32 v5, v5
	v_pk_mul_f32 v[10:11], v[10:11], v[2:3]
	v_exp_f32_e32 v0, v0
	v_exp_f32_e32 v1, v1
	v_pk_mul_f32 v[2:3], v[2:3], v[16:17] op_sel_hi:[1,0]
	v_pk_mul_f32 v[14:15], v[14:15], v[6:7]
	v_exp_f32_e32 v2, v2
	v_exp_f32_e32 v3, v3
	v_pk_mul_f32 v[6:7], v[6:7], v[16:17] op_sel_hi:[1,0]
	v_pk_add_f32 v[4:5], v[4:5], 1.0 op_sel_hi:[1,0]
	v_exp_f32_e32 v6, v6
	v_exp_f32_e32 v7, v7
	v_pk_add_f32 v[0:1], v[0:1], 1.0 op_sel_hi:[1,0]
	v_rcp_f32_e32 v4, v4
	v_rcp_f32_e32 v5, v5
	v_rcp_f32_e32 v0, v0
	v_rcp_f32_e32 v1, v1
	v_pk_add_f32 v[2:3], v[2:3], 1.0 op_sel_hi:[1,0]
	v_mul_f32_e32 v18, v22, v22
	v_rcp_f32_e32 v2, v2
	v_rcp_f32_e32 v3, v3
	v_pk_add_f32 v[6:7], v[6:7], 1.0 op_sel_hi:[1,0]
	v_pk_mul_f32 v[12:13], v[12:13], v[18:19] op_sel_hi:[1,0]
	v_rcp_f32_e32 v6, v6
	v_rcp_f32_e32 v7, v7
	v_pk_mul_f32 v[8:9], v[8:9], v[18:19] op_sel_hi:[1,0]
	v_pk_mul_f32 v[4:5], v[12:13], v[4:5]
	v_pk_mul_f32 v[8:9], v[8:9], v[0:1]
	v_pk_mul_f32 v[0:1], v[10:11], v[18:19] op_sel_hi:[1,0]
	v_pk_mul_f32 v[12:13], v[14:15], v[18:19] op_sel_hi:[1,0]
	v_pk_mul_f32 v[10:11], v[0:1], v[2:3]
	v_cvt_pk_bf16_f32 v0, v4, v5
	v_mad_i64_i32 v[4:5], s[58:59], v140, s57, v[112:113]
	v_lshl_add_u64 v[4:5], v[4:5], 0, v[114:115]
	s_and_b64 vcc, exec, s[4:5]
	s_mov_b64 s[4:5], -1
	v_pk_mul_f32 v[6:7], v[12:13], v[6:7]
	s_nop 0
	v_cvt_pk_bf16_f32 v1, v6, v7
	v_cvt_pk_bf16_f32 v2, v8, v9
	v_cvt_pk_bf16_f32 v3, v10, v11
	global_store_dwordx4 v[4:5], v[0:3], off
	s_cbranch_vccnz .LBB0_656
	s_nop 0
	v_or_b32_e32 v0, v159, v157
	v_or_b32_e32 v1, v158, v156
	v_or3_b32 v0, v0, v153, v155
	v_or3_b32 v1, v1, v152, v154
	v_or3_b32 v0, v0, v149, v151
	v_or3_b32 v1, v1, v148, v150
	s_andn2_b64 vcc, exec, s[6:7]
	v_or3_b32 v0, v0, v143, v147
	v_or3_b32 v1, v1, v142, v146
	s_cbranch_vccnz .LBB0_655
	s_barrier
	s_branch .LBB0_655

; __device__ __forceinline__ void xcd_barrier(const XcdBarrier& b) {
;     asm volatile("s_waitcnt vmcnt(0)" ::: "memory");
;     __syncthreads();
;     if (threadIdx.x == 0) {
;         unsigned* bar = b.bar;
;         __builtin_amdgcn_s_waitcnt(0);
;         unsigned nloc = b.st[0], nx = b.st[1];
;         if (nloc == 0u) { xcd_barrier_complete(bar, b.x, b.gsz, nloc, nx); b.st[0] = nloc; b.st[1] = nx; }
.LBB0_669:
	s_cmp_gt_i32 s53, 9
	s_cselect_b64 s[4:5], -1, 0
	s_and_b64 s[0:1], s[0:1], s[4:5]
	s_andn2_b64 vcc, exec, s[0:1]
	s_cbranch_vccnz .LBB0_714
	s_waitcnt vmcnt(0)
	s_waitcnt lgkmcnt(0)
	s_barrier
	s_cmp_eq_u32 s97, 0
	s_cbranch_scc1 .Lbpf_skip_7
	v_mov_b32_e32 v232, s95
	v_mul_u32_u24_e32 v232, 7, v232
	v_add_u32_e32 v232, s97, v232
	v_add_u32_e32 v232, -1, v232
	v_lshl_add_u32 v232, v232, 6, v200
	v_lshrrev_b32_e32 v231, 1, v232
	v_min_u32_e32 v231, 0x3ff, v231
	v_mul_u32_u24_e32 v231, 0x1600, v231
	v_and_b32_e32 v232, 1, v232
	v_lshlrev_b32_e32 v232, 7, v232
	v_add_u32_e32 v232, v231, v232
	v_add_u32_e32 v232, 0x2b00000, v232
	global_load_dword v231, v232, s[34:35]

; __device__ __forceinline__ void xcd_barrier(const XcdBarrier& b) {
;     asm volatile("s_waitcnt vmcnt(0)" ::: "memory");
;     __syncthreads();
;     if (threadIdx.x == 0) {
;         unsigned* bar = b.bar;
;         __builtin_amdgcn_s_waitcnt(0);
;         unsigned nloc = b.st[0], nx = b.st[1];
;         if (nloc == 0u) { xcd_barrier_complete(bar, b.x, b.gsz, nloc, nx); b.st[0] = nloc; b.st[1] = nx; }
.LBB0_753:
	s_cmp_gt_i32 s53, 10
	s_cselect_b64 s[4:5], -1, 0
	s_and_b64 s[0:1], s[0:1], s[4:5]
	s_andn2_b64 vcc, exec, s[0:1]
	s_cbranch_vccnz .LBB0_798
	s_waitcnt vmcnt(0)
	s_waitcnt lgkmcnt(0)
	s_barrier
	s_cmp_eq_u32 s97, 0
	s_cbranch_scc1 .Lbpf_skip_8
	v_mov_b32_e32 v232, s95
	v_mul_u32_u24_e32 v232, 7, v232
	v_add_u32_e32 v232, s97, v232
	v_add_u32_e32 v232, -1, v232
	v_lshl_add_u32 v232, v232, 6, v200
	v_lshrrev_b32_e32 v231, 1, v232
	v_min_u32_e32 v231, 0x15ff, v231
	v_mul_u32_u24_e32 v231, 0x800, v231
	v_and_b32_e32 v232, 1, v232
	v_lshlrev_b32_e32 v232, 7, v232
	v_add_u32_e32 v232, v231, v232
	v_add_u32_e32 v232, 0x3080000, v232
	global_load_dword v231, v232, s[34:35]

; __device__ __forceinline__ void xcd_barrier(const XcdBarrier& b) {
;     asm volatile("s_waitcnt vmcnt(0)" ::: "memory");
;     __syncthreads();
;     if (threadIdx.x == 0) {
;         unsigned* bar = b.bar;
;         __builtin_amdgcn_s_waitcnt(0);
;         unsigned nloc = b.st[0], nx = b.st[1];
;         if (nloc == 0u) { xcd_barrier_complete(bar, b.x, b.gsz, nloc, nx); b.st[0] = nloc; b.st[1] = nx; }
.LBB0_817:
	s_cmp_gt_i32 s53, 11
	s_cselect_b64 s[4:5], -1, 0
	s_and_b64 s[0:1], s[0:1], s[4:5]
	s_andn2_b64 vcc, exec, s[0:1]
	s_cbranch_vccnz .LBB0_862
	s_waitcnt vmcnt(0)
	s_waitcnt lgkmcnt(0)
	s_barrier
	s_cmp_eq_u32 s97, 0
	s_cbranch_scc1 .Lbpf_skip_9
	v_mov_b32_e32 v232, s95
	v_mul_u32_u24_e32 v232, 7, v232
	v_add_u32_e32 v232, s97, v232
	v_add_u32_e32 v232, -1, v232
	v_lshl_add_u32 v232, v232, 6, v200
	v_lshrrev_b32_e32 v231, 1, v232
	v_min_u32_e32 v231, 0x3ff, v231
	v_mul_u32_u24_e32 v231, 0x1600, v231
	v_and_b32_e32 v232, 1, v232
	v_lshlrev_b32_e32 v232, 7, v232
	v_add_u32_e32 v232, v231, v232
	v_add_u32_e32 v232, 0x3b80000, v232
	global_load_dword v231, v232, s[34:35]

; __device__ __forceinline__ void xcd_barrier(const XcdBarrier& b) {
;     asm volatile("s_waitcnt vmcnt(0)" ::: "memory");
;     __syncthreads();
;     if (threadIdx.x == 0) {
;         unsigned* bar = b.bar;
;         __builtin_amdgcn_s_waitcnt(0);
;         unsigned nloc = b.st[0], nx = b.st[1];
;         if (nloc == 0u) { xcd_barrier_complete(bar, b.x, b.gsz, nloc, nx); b.st[0] = nloc; b.st[1] = nx; }
.LBB0_901:
	s_cmp_gt_i32 s53, 12
	s_cselect_b64 s[4:5], -1, 0
	s_and_b64 s[0:1], s[0:1], s[4:5]
	s_andn2_b64 vcc, exec, s[0:1]
	s_cbranch_vccnz .LBB0_946
	s_waitcnt vmcnt(0)
	s_waitcnt lgkmcnt(0)
	s_barrier
	s_cmp_eq_u32 s97, 0
	s_cbranch_scc1 .Lbpf_skip_10
	v_mov_b32_e32 v232, s95
	v_mul_u32_u24_e32 v232, 7, v232
	v_add_u32_e32 v232, s97, v232
	v_add_u32_e32 v232, -1, v232
	v_lshl_add_u32 v232, v232, 6, v200
	v_lshrrev_b32_e32 v231, 1, v232
	v_min_u32_e32 v231, 0x9ff, v231
	v_mul_u32_u24_e32 v231, 0x800, v231
	v_and_b32_e32 v232, 1, v232
	v_lshlrev_b32_e32 v232, 7, v232
	v_add_u32_e32 v232, v231, v232
	v_add_u32_e32 v232, 0x4100000, v232
	global_load_dword v231, v232, s[34:35]

; __device__ __forceinline__ unsigned cvt_pk_bf16(float lo, float hi) { unsigned r; asm volatile("v_cvt_pk_bf16_f32 %0, %1, %2" : "=v"(r) : "v"(lo), "v"(hi)); return r; }
; __device__ __forceinline__ u64 ss_fix(float s) { return (u64)(s * 1099511627776.0f); }
; __device__ __forceinline__ float ss_val(u64 v) { return (float)v * (1.0f / 1099511627776.0f); }
;     __device__ __forceinline__ void operator()(const f32x4 (&acc)[2][2][4][2], const Unit& u, const Unit&, bool, int wr, int wc, int fr, int fq) const {
;     ...
; #pragma unroll
;         for (int ai = 0; ai < 2; ++ai)
; #pragma unroll
;             for (int m = 0; m < 4; ++m) {
;                 const int row = row0 + ai * HALF + m * 16;
;                 const float rs = __builtin_amdgcn_rsqf(ss_val(cur[ai * 4 + m]) * inv_k + eps);
;                 float ss = 0.f;
; #pragma unroll
;                 for (int bj = 0; bj < 2; ++bj) {
;                     const f32x4 v0 = acc[ai][bj][m][0] * rs, v1 = acc[ai][bj][m][1] * rs;
;                     ss += (v0[0] * v0[0] + v0[1] * v0[1]) + (v0[2] * v0[2] + v0[3] * v0[3]) + (v1[0] * v1[0] + v1[1] * v1[1]) + (v1[2] * v1[2] + v1[3] * v1[3]);
;                     u32x4 w; w.x = cvt_pk_bf16(v0[0], v0[1]); w.y = cvt_pk_bf16(v0[2], v0[3]); w.z = cvt_pk_bf16(v1[0], v1[1]); w.w = cvt_pk_bf16(v1[2], v1[3]);
;                     *(u32x4*)(O + (size_t)row * ldc + col0 + bj * HALF) = w;
;                 }
;                 if (is_va) { ss += __shfl_xor(ss, 16); ss += __shfl_xor(ss, 32); if (fq == 0) atomicAdd(rowss_v + row, ss_fix(ss)); }
;             }
.LBB0_965:
	s_waitcnt lgkmcnt(0)
	v_mov_b64_e32 v[120:121], s[24:25]
	s_andn2_b64 vcc, exec, s[84:85]
	v_cvt_f32_u32_e32 v158, v158
	v_cvt_f32_u32_e32 v159, v159
	v_fmamk_f32 v158, v159, 0x4f800000, v158
	v_fmamk_f32 v112, v158, 0x26800000, v166
	v_rsq_f32_e32 v118, v112
	v_or_b32_e32 v112, 16, v142
	v_mad_i64_i32 v[120:121], s[6:7], v112, s57, v[120:121]
	v_cndmask_b32_e64 v113, 0, 1, s[84:85]
	v_pk_mul_f32 v[110:111], v[110:111], v[118:119] op_sel_hi:[1,0]
	v_pk_mul_f32 v[108:109], v[108:109], v[118:119] op_sel_hi:[1,0]
	v_pk_mul_f32 v[106:107], v[106:107], v[118:119] op_sel_hi:[1,0]
	v_pk_mul_f32 v[104:105], v[104:105], v[118:119] op_sel_hi:[1,0]
	v_cvt_pk_bf16_f32 v114, v108, v109
	v_cvt_pk_bf16_f32 v115, v110, v111
	v_lshl_add_u64 v[120:121], v[140:141], 1, v[120:121]
	v_cvt_pk_bf16_f32 v116, v104, v105
	v_cvt_pk_bf16_f32 v117, v106, v107
	v_pk_mul_f32 v[102:103], v[102:103], v[118:119] op_sel_hi:[1,0]
	v_pk_mul_f32 v[100:101], v[100:101], v[118:119] op_sel_hi:[1,0]
	v_pk_mul_f32 v[98:99], v[98:99], v[118:119] op_sel_hi:[1,0]
	v_pk_mul_f32 v[96:97], v[96:97], v[118:119] op_sel_hi:[1,0]
	v_cmp_ne_u32_e64 s[6:7], 1, v113
	global_store_dwordx4 v[120:121], v[114:117], off
	s_nop 1
	v_cvt_pk_bf16_f32 v114, v100, v101
	v_cvt_pk_bf16_f32 v115, v102, v103
	v_cvt_pk_bf16_f32 v116, v96, v97
	v_cvt_pk_bf16_f32 v117, v98, v99
	global_store_dwordx4 v[120:121], v[114:117], off offset:256
	s_cbranch_vccnz .LBB0_969
	v_mul_f32_e32 v99, v99, v99
	v_fmac_f32_e32 v99, v98, v98
	v_mul_f32_e32 v98, v101, v101
	v_mul_f32_e32 v107, v107, v107
	v_fmac_f32_e32 v98, v100, v100
	v_mul_f32_e32 v100, v103, v103
	v_fmac_f32_e32 v107, v106, v106
	v_mul_f32_e32 v106, v109, v109
	v_fmac_f32_e32 v100, v102, v102
	v_mul_f32_e32 v97, v97, v97
	v_fmac_f32_e32 v106, v108, v108
	v_mul_f32_e32 v108, v111, v111
	v_add_f32_e32 v98, v98, v100
	v_fmac_f32_e32 v97, v96, v96
	v_fmac_f32_e32 v108, v110, v110
	v_mul_f32_e32 v105, v105, v105
	v_add_f32_e32 v96, v97, v98
	v_and_b32_e32 v98, 64, v167
	v_add_f32_e32 v106, v106, v108
	v_fmac_f32_e32 v105, v104, v104
	v_xor_b32_e32 v97, 16, v167
	v_add_u32_e32 v98, 64, v98
	v_add_f32_e32 v104, v105, v106
	v_cmp_lt_i32_e32 vcc, v97, v98
	v_add_f32_e32 v104, v107, v104
	v_add_f32_e32 v96, v99, v96
	v_cndmask_b32_e32 v97, v167, v97, vcc
	v_add_f32_e32 v96, v104, v96
	v_lshlrev_b32_e32 v97, 2, v97
	ds_bpermute_b32 v97, v97, v96
	s_waitcnt lgkmcnt(0)
	v_add_f32_e32 v96, v96, v97
	v_xor_b32_e32 v97, 32, v167
	v_cmp_lt_i32_e32 vcc, v97, v98
	s_nop 1
	v_cndmask_b32_e32 v97, v167, v97, vcc
	v_lshlrev_b32_e32 v97, 2, v97
	ds_bpermute_b32 v97, v97, v96
	s_and_saveexec_b64 s[84:85], s[4:5]
	s_cbranch_execz .LBB0_968
	s_waitcnt lgkmcnt(0)
	v_add_f32_e32 v96, v96, v97
	v_mul_f32_e32 v96, 0x53800000, v96
	v_trunc_f32_e32 v96, v96
	v_mul_f32_e32 v97, 0x2f800000, v96
	v_floor_f32_e32 v97, v97
	v_fmac_f32_e32 v96, 0xcf800000, v97
	v_cvt_u32_f32_e32 v96, v96
	v_cvt_u32_f32_e32 v97, v97
	v_ashrrev_i32_e32 v113, 31, v112
	v_lshl_add_u64 v[98:99], v[112:113], 3, s[68:69]
	global_atomic_add_x2 v[98:99], v[96:97], off

; __device__ __forceinline__ unsigned cvt_pk_bf16(float lo, float hi) { unsigned r; asm volatile("v_cvt_pk_bf16_f32 %0, %1, %2" : "=v"(r) : "v"(lo), "v"(hi)); return r; }
; __device__ __forceinline__ u64 ss_fix(float s) { return (u64)(s * 1099511627776.0f); }
; __device__ __forceinline__ float ss_val(u64 v) { return (float)v * (1.0f / 1099511627776.0f); }
;     __device__ __forceinline__ void operator()(const f32x4 (&acc)[2][2][4][2], const Unit& u, const Unit&, bool, int wr, int wc, int fr, int fq) const {
;     ...
; #pragma unroll
;         for (int ai = 0; ai < 2; ++ai)
; #pragma unroll
;             for (int m = 0; m < 4; ++m) {
;                 const int row = row0 + ai * HALF + m * 16;
;                 const float rs = __builtin_amdgcn_rsqf(ss_val(cur[ai * 4 + m]) * inv_k + eps);
;                 float ss = 0.f;
; #pragma unroll
;                 for (int bj = 0; bj < 2; ++bj) {
;                     const f32x4 v0 = acc[ai][bj][m][0] * rs, v1 = acc[ai][bj][m][1] * rs;
;                     ss += (v0[0] * v0[0] + v0[1] * v0[1]) + (v0[2] * v0[2] + v0[3] * v0[3]) + (v1[0] * v1[0] + v1[1] * v1[1]) + (v1[2] * v1[2] + v1[3] * v1[3]);
;                     u32x4 w; w.x = cvt_pk_bf16(v0[0], v0[1]); w.y = cvt_pk_bf16(v0[2], v0[3]); w.z = cvt_pk_bf16(v1[0], v1[1]); w.w = cvt_pk_bf16(v1[2], v1[3]);
;                     *(u32x4*)(O + (size_t)row * ldc + col0 + bj * HALF) = w;
;                 }
;                 if (is_va) { ss += __shfl_xor(ss, 16); ss += __shfl_xor(ss, 32); if (fq == 0) atomicAdd(rowss_v + row, ss_fix(ss)); }
;             }
.LBB0_969:
	s_waitcnt lgkmcnt(0)
	v_mov_b64_e32 v[104:105], s[24:25]
	s_and_b64 vcc, exec, s[6:7]
	v_cvt_f32_u32_e32 v156, v156
	v_cvt_f32_u32_e32 v157, v157
	v_fmamk_f32 v156, v157, 0x4f800000, v156
	v_fmamk_f32 v96, v156, 0x26800000, v166
	v_rsq_f32_e32 v102, v96
	v_or_b32_e32 v96, 32, v142
	v_mad_i64_i32 v[104:105], s[58:59], v96, s57, v[104:105]
	v_pk_mul_f32 v[94:95], v[94:95], v[102:103] op_sel_hi:[1,0]
	v_pk_mul_f32 v[92:93], v[92:93], v[102:103] op_sel_hi:[1,0]
	v_pk_mul_f32 v[90:91], v[90:91], v[102:103] op_sel_hi:[1,0]
	v_pk_mul_f32 v[88:89], v[88:89], v[102:103] op_sel_hi:[1,0]
	v_cvt_pk_bf16_f32 v98, v92, v93
	v_cvt_pk_bf16_f32 v99, v94, v95
	v_lshl_add_u64 v[104:105], v[140:141], 1, v[104:105]
	v_cvt_pk_bf16_f32 v100, v88, v89
	v_cvt_pk_bf16_f32 v101, v90, v91
	v_pk_mul_f32 v[86:87], v[86:87], v[102:103] op_sel_hi:[1,0]
	v_pk_mul_f32 v[84:85], v[84:85], v[102:103] op_sel_hi:[1,0]
	v_pk_mul_f32 v[82:83], v[82:83], v[102:103] op_sel_hi:[1,0]
	v_pk_mul_f32 v[80:81], v[80:81], v[102:103] op_sel_hi:[1,0]
	global_store_dwordx4 v[104:105], v[98:101], off
	s_nop 1
	v_cvt_pk_bf16_f32 v98, v84, v85
	v_cvt_pk_bf16_f32 v99, v86, v87
	v_cvt_pk_bf16_f32 v100, v80, v81
	v_cvt_pk_bf16_f32 v101, v82, v83
	global_store_dwordx4 v[104:105], v[98:101], off offset:256
	s_cbranch_vccnz .LBB0_973
	v_mul_f32_e32 v83, v83, v83
	v_fmac_f32_e32 v83, v82, v82
	v_mul_f32_e32 v82, v85, v85
	v_mul_f32_e32 v91, v91, v91
	v_fmac_f32_e32 v82, v84, v84
	v_mul_f32_e32 v84, v87, v87
	v_fmac_f32_e32 v91, v90, v90
	v_mul_f32_e32 v90, v93, v93
	v_fmac_f32_e32 v84, v86, v86
	v_mul_f32_e32 v81, v81, v81
	v_fmac_f32_e32 v90, v92, v92
	v_mul_f32_e32 v92, v95, v95
	v_add_f32_e32 v82, v82, v84
	v_fmac_f32_e32 v81, v80, v80
	v_fmac_f32_e32 v92, v94, v94
	v_mul_f32_e32 v89, v89, v89
	v_add_f32_e32 v80, v81, v82
	v_and_b32_e32 v82, 64, v167
	v_add_f32_e32 v90, v90, v92
	v_fmac_f32_e32 v89, v88, v88
	v_xor_b32_e32 v81, 16, v167
	v_add_u32_e32 v82, 64, v82
	v_add_f32_e32 v88, v89, v90
	v_cmp_lt_i32_e32 vcc, v81, v82
	v_add_f32_e32 v88, v91, v88
	v_add_f32_e32 v80, v83, v80
	v_cndmask_b32_e32 v81, v167, v81, vcc
	v_add_f32_e32 v80, v88, v80
	v_lshlrev_b32_e32 v81, 2, v81
	ds_bpermute_b32 v81, v81, v80
	s_waitcnt lgkmcnt(0)
	v_add_f32_e32 v80, v80, v81
	v_xor_b32_e32 v81, 32, v167
	v_cmp_lt_i32_e32 vcc, v81, v82
	s_nop 1
	v_cndmask_b32_e32 v81, v167, v81, vcc
	v_lshlrev_b32_e32 v81, 2, v81
	ds_bpermute_b32 v81, v81, v80
	s_and_saveexec_b64 s[84:85], s[4:5]
	s_cbranch_execz .LBB0_972
	s_waitcnt lgkmcnt(0)
	v_add_f32_e32 v80, v80, v81
	v_mul_f32_e32 v80, 0x53800000, v80
	v_trunc_f32_e32 v80, v80
	v_mul_f32_e32 v81, 0x2f800000, v80
	v_floor_f32_e32 v81, v81
	v_fmac_f32_e32 v80, 0xcf800000, v81
	v_cvt_u32_f32_e32 v80, v80
	v_cvt_u32_f32_e32 v81, v81
	v_ashrrev_i32_e32 v97, 31, v96
	v_lshl_add_u64 v[82:83], v[96:97], 3, s[68:69]
	global_atomic_add_x2 v[82:83], v[80:81], off

; __device__ __forceinline__ unsigned cvt_pk_bf16(float lo, float hi) { unsigned r; asm volatile("v_cvt_pk_bf16_f32 %0, %1, %2" : "=v"(r) : "v"(lo), "v"(hi)); return r; }
; __device__ __forceinline__ u64 ss_fix(float s) { return (u64)(s * 1099511627776.0f); }
; __device__ __forceinline__ float ss_val(u64 v) { return (float)v * (1.0f / 1099511627776.0f); }
;     __device__ __forceinline__ void operator()(const f32x4 (&acc)[2][2][4][2], const Unit& u, const Unit&, bool, int wr, int wc, int fr, int fq) const {
;     ...
; #pragma unroll
;         for (int ai = 0; ai < 2; ++ai)
; #pragma unroll
;             for (int m = 0; m < 4; ++m) {
;                 const int row = row0 + ai * HALF + m * 16;
;                 const float rs = __builtin_amdgcn_rsqf(ss_val(cur[ai * 4 + m]) * inv_k + eps);
;                 float ss = 0.f;
; #pragma unroll
;                 for (int bj = 0; bj < 2; ++bj) {
;                     const f32x4 v0 = acc[ai][bj][m][0] * rs, v1 = acc[ai][bj][m][1] * rs;
;                     ss += (v0[0] * v0[0] + v0[1] * v0[1]) + (v0[2] * v0[2] + v0[3] * v0[3]) + (v1[0] * v1[0] + v1[1] * v1[1]) + (v1[2] * v1[2] + v1[3] * v1[3]);
;                     u32x4 w; w.x = cvt_pk_bf16(v0[0], v0[1]); w.y = cvt_pk_bf16(v0[2], v0[3]); w.z = cvt_pk_bf16(v1[0], v1[1]); w.w = cvt_pk_bf16(v1[2], v1[3]);
;                     *(u32x4*)(O + (size_t)row * ldc + col0 + bj * HALF) = w;
;                 }
;                 if (is_va) { ss += __shfl_xor(ss, 16); ss += __shfl_xor(ss, 32); if (fq == 0) atomicAdd(rowss_v + row, ss_fix(ss)); }
;             }
.LBB0_973:
	s_waitcnt lgkmcnt(0)
	v_mov_b64_e32 v[88:89], s[24:25]
	s_and_b64 vcc, exec, s[6:7]
	v_cvt_f32_u32_e32 v154, v154
	v_cvt_f32_u32_e32 v155, v155
	v_fmamk_f32 v154, v155, 0x4f800000, v154
	v_fmamk_f32 v80, v154, 0x26800000, v166
	v_rsq_f32_e32 v86, v80
	v_or_b32_e32 v80, 48, v142
	v_mad_i64_i32 v[88:89], s[58:59], v80, s57, v[88:89]
	v_pk_mul_f32 v[78:79], v[78:79], v[86:87] op_sel_hi:[1,0]
	v_pk_mul_f32 v[76:77], v[76:77], v[86:87] op_sel_hi:[1,0]
	v_pk_mul_f32 v[74:75], v[74:75], v[86:87] op_sel_hi:[1,0]
	v_pk_mul_f32 v[72:73], v[72:73], v[86:87] op_sel_hi:[1,0]
	v_cvt_pk_bf16_f32 v82, v76, v77
	v_cvt_pk_bf16_f32 v83, v78, v79
	v_lshl_add_u64 v[88:89], v[140:141], 1, v[88:89]
	v_cvt_pk_bf16_f32 v84, v72, v73
	v_cvt_pk_bf16_f32 v85, v74, v75
	v_pk_mul_f32 v[70:71], v[70:71], v[86:87] op_sel_hi:[1,0]
	v_pk_mul_f32 v[68:69], v[68:69], v[86:87] op_sel_hi:[1,0]
	v_pk_mul_f32 v[66:67], v[66:67], v[86:87] op_sel_hi:[1,0]
	v_pk_mul_f32 v[64:65], v[64:65], v[86:87] op_sel_hi:[1,0]
	global_store_dwordx4 v[88:89], v[82:85], off
	s_nop 1
	v_cvt_pk_bf16_f32 v82, v68, v69
	v_cvt_pk_bf16_f32 v83, v70, v71
	v_cvt_pk_bf16_f32 v84, v64, v65
	v_cvt_pk_bf16_f32 v85, v66, v67
	global_store_dwordx4 v[88:89], v[82:85], off offset:256
	s_cbranch_vccnz .LBB0_977
	v_mul_f32_e32 v67, v67, v67
	v_fmac_f32_e32 v67, v66, v66
	v_mul_f32_e32 v66, v69, v69
	v_mul_f32_e32 v75, v75, v75
	v_fmac_f32_e32 v66, v68, v68
	v_mul_f32_e32 v68, v71, v71
	v_fmac_f32_e32 v75, v74, v74
	v_mul_f32_e32 v74, v77, v77
	v_fmac_f32_e32 v68, v70, v70
	v_mul_f32_e32 v65, v65, v65
	v_fmac_f32_e32 v74, v76, v76
	v_mul_f32_e32 v76, v79, v79
	v_add_f32_e32 v66, v66, v68
	v_fmac_f32_e32 v65, v64, v64
	v_fmac_f32_e32 v76, v78, v78
	v_mul_f32_e32 v73, v73, v73
	v_add_f32_e32 v64, v65, v66
	v_and_b32_e32 v66, 64, v167
	v_add_f32_e32 v74, v74, v76
	v_fmac_f32_e32 v73, v72, v72
	v_xor_b32_e32 v65, 16, v167
	v_add_u32_e32 v66, 64, v66
	v_add_f32_e32 v72, v73, v74
	v_cmp_lt_i32_e32 vcc, v65, v66
	v_add_f32_e32 v72, v75, v72
	v_add_f32_e32 v64, v67, v64
	v_cndmask_b32_e32 v65, v167, v65, vcc
	v_add_f32_e32 v64, v72, v64
	v_lshlrev_b32_e32 v65, 2, v65
	ds_bpermute_b32 v65, v65, v64
	s_waitcnt lgkmcnt(0)
	v_add_f32_e32 v64, v64, v65
	v_xor_b32_e32 v65, 32, v167
	v_cmp_lt_i32_e32 vcc, v65, v66
	s_nop 1
	v_cndmask_b32_e32 v65, v167, v65, vcc
	v_lshlrev_b32_e32 v65, 2, v65
	ds_bpermute_b32 v65, v65, v64
	s_and_saveexec_b64 s[84:85], s[4:5]
	s_cbranch_execz .LBB0_976
	s_waitcnt lgkmcnt(0)
	v_add_f32_e32 v64, v64, v65
	v_mul_f32_e32 v64, 0x53800000, v64
	v_trunc_f32_e32 v64, v64
	v_mul_f32_e32 v65, 0x2f800000, v64
	v_floor_f32_e32 v65, v65
	v_fmac_f32_e32 v64, 0xcf800000, v65
	v_cvt_u32_f32_e32 v64, v64
	v_cvt_u32_f32_e32 v65, v65
	v_ashrrev_i32_e32 v81, 31, v80
	v_lshl_add_u64 v[66:67], v[80:81], 3, s[68:69]
	global_atomic_add_x2 v[66:67], v[64:65], off

; __device__ __forceinline__ unsigned cvt_pk_bf16(float lo, float hi) { unsigned r; asm volatile("v_cvt_pk_bf16_f32 %0, %1, %2" : "=v"(r) : "v"(lo), "v"(hi)); return r; }
; __device__ __forceinline__ u64 ss_fix(float s) { return (u64)(s * 1099511627776.0f); }
; __device__ __forceinline__ float ss_val(u64 v) { return (float)v * (1.0f / 1099511627776.0f); }
;     __device__ __forceinline__ void operator()(const f32x4 (&acc)[2][2][4][2], const Unit& u, const Unit&, bool, int wr, int wc, int fr, int fq) const {
;     ...
; #pragma unroll
;         for (int ai = 0; ai < 2; ++ai)
; #pragma unroll
;             for (int m = 0; m < 4; ++m) {
;                 const int row = row0 + ai * HALF + m * 16;
;                 const float rs = __builtin_amdgcn_rsqf(ss_val(cur[ai * 4 + m]) * inv_k + eps);
;                 float ss = 0.f;
; #pragma unroll
;                 for (int bj = 0; bj < 2; ++bj) {
;                     const f32x4 v0 = acc[ai][bj][m][0] * rs, v1 = acc[ai][bj][m][1] * rs;
;                     ss += (v0[0] * v0[0] + v0[1] * v0[1]) + (v0[2] * v0[2] + v0[3] * v0[3]) + (v1[0] * v1[0] + v1[1] * v1[1]) + (v1[2] * v1[2] + v1[3] * v1[3]);
;                     u32x4 w; w.x = cvt_pk_bf16(v0[0], v0[1]); w.y = cvt_pk_bf16(v0[2], v0[3]); w.z = cvt_pk_bf16(v1[0], v1[1]); w.w = cvt_pk_bf16(v1[2], v1[3]);
;                     *(u32x4*)(O + (size_t)row * ldc + col0 + bj * HALF) = w;
;                 }
;                 if (is_va) { ss += __shfl_xor(ss, 16); ss += __shfl_xor(ss, 32); if (fq == 0) atomicAdd(rowss_v + row, ss_fix(ss)); }
;             }
.LBB0_977:
	s_waitcnt lgkmcnt(0)
	v_mov_b64_e32 v[72:73], s[24:25]
	s_and_b64 vcc, exec, s[6:7]
	v_cvt_f32_u32_e32 v152, v152
	v_cvt_f32_u32_e32 v153, v153
	v_fmamk_f32 v152, v153, 0x4f800000, v152
	v_fmamk_f32 v64, v152, 0x26800000, v166
	v_rsq_f32_e32 v70, v64
	v_add_u32_e32 v64, 0x80, v142
	v_mad_i64_i32 v[72:73], s[58:59], v64, s57, v[72:73]
	v_pk_mul_f32 v[62:63], v[62:63], v[70:71] op_sel_hi:[1,0]
	v_pk_mul_f32 v[60:61], v[60:61], v[70:71] op_sel_hi:[1,0]
	v_pk_mul_f32 v[58:59], v[58:59], v[70:71] op_sel_hi:[1,0]
	v_pk_mul_f32 v[56:57], v[56:57], v[70:71] op_sel_hi:[1,0]
	v_cvt_pk_bf16_f32 v66, v60, v61
	v_cvt_pk_bf16_f32 v67, v62, v63
	v_lshl_add_u64 v[72:73], v[140:141], 1, v[72:73]
	v_cvt_pk_bf16_f32 v68, v56, v57
	v_cvt_pk_bf16_f32 v69, v58, v59
	v_pk_mul_f32 v[54:55], v[54:55], v[70:71] op_sel_hi:[1,0]
	v_pk_mul_f32 v[52:53], v[52:53], v[70:71] op_sel_hi:[1,0]
	v_pk_mul_f32 v[50:51], v[50:51], v[70:71] op_sel_hi:[1,0]
	v_pk_mul_f32 v[48:49], v[48:49], v[70:71] op_sel_hi:[1,0]
	global_store_dwordx4 v[72:73], v[66:69], off
	s_nop 1
	v_cvt_pk_bf16_f32 v66, v52, v53
	v_cvt_pk_bf16_f32 v67, v54, v55
	v_cvt_pk_bf16_f32 v68, v48, v49
	v_cvt_pk_bf16_f32 v69, v50, v51
	global_store_dwordx4 v[72:73], v[66:69], off offset:256
	s_cbranch_vccnz .LBB0_981
	v_mul_f32_e32 v51, v51, v51
	v_fmac_f32_e32 v51, v50, v50
	v_mul_f32_e32 v50, v53, v53
	v_mul_f32_e32 v59, v59, v59
	v_fmac_f32_e32 v50, v52, v52
	v_mul_f32_e32 v52, v55, v55
	v_fmac_f32_e32 v59, v58, v58
	v_mul_f32_e32 v58, v61, v61
	v_fmac_f32_e32 v52, v54, v54
	v_mul_f32_e32 v49, v49, v49
	v_fmac_f32_e32 v58, v60, v60
	v_mul_f32_e32 v60, v63, v63
	v_add_f32_e32 v50, v50, v52
	v_fmac_f32_e32 v49, v48, v48
	v_fmac_f32_e32 v60, v62, v62
	v_mul_f32_e32 v57, v57, v57
	v_add_f32_e32 v48, v49, v50
	v_and_b32_e32 v50, 64, v167
	v_add_f32_e32 v58, v58, v60
	v_fmac_f32_e32 v57, v56, v56
	v_xor_b32_e32 v49, 16, v167
	v_add_u32_e32 v50, 64, v50
	v_add_f32_e32 v56, v57, v58
	v_cmp_lt_i32_e32 vcc, v49, v50
	v_add_f32_e32 v56, v59, v56
	v_add_f32_e32 v48, v51, v48
	v_cndmask_b32_e32 v49, v167, v49, vcc
	v_add_f32_e32 v48, v56, v48
	v_lshlrev_b32_e32 v49, 2, v49
	ds_bpermute_b32 v49, v49, v48
	s_waitcnt lgkmcnt(0)
	v_add_f32_e32 v48, v48, v49
	v_xor_b32_e32 v49, 32, v167
	v_cmp_lt_i32_e32 vcc, v49, v50
	s_nop 1
	v_cndmask_b32_e32 v49, v167, v49, vcc
	v_lshlrev_b32_e32 v49, 2, v49
	ds_bpermute_b32 v49, v49, v48
	s_and_saveexec_b64 s[84:85], s[4:5]
	s_cbranch_execz .LBB0_980
	s_waitcnt lgkmcnt(0)
	v_add_f32_e32 v48, v48, v49
	v_mul_f32_e32 v48, 0x53800000, v48
	v_trunc_f32_e32 v48, v48
	v_mul_f32_e32 v49, 0x2f800000, v48
	v_floor_f32_e32 v49, v49
	v_fmac_f32_e32 v48, 0xcf800000, v49
	v_cvt_u32_f32_e32 v48, v48
	v_cvt_u32_f32_e32 v49, v49
	v_ashrrev_i32_e32 v65, 31, v64
	v_lshl_add_u64 v[50:51], v[64:65], 3, s[68:69]
	global_atomic_add_x2 v[50:51], v[48:49], off

; __device__ __forceinline__ unsigned cvt_pk_bf16(float lo, float hi) { unsigned r; asm volatile("v_cvt_pk_bf16_f32 %0, %1, %2" : "=v"(r) : "v"(lo), "v"(hi)); return r; }
; __device__ __forceinline__ u64 ss_fix(float s) { return (u64)(s * 1099511627776.0f); }
; __device__ __forceinline__ float ss_val(u64 v) { return (float)v * (1.0f / 1099511627776.0f); }
;     __device__ __forceinline__ void operator()(const f32x4 (&acc)[2][2][4][2], const Unit& u, const Unit&, bool, int wr, int wc, int fr, int fq) const {
;     ...
; #pragma unroll
;         for (int ai = 0; ai < 2; ++ai)
; #pragma unroll
;             for (int m = 0; m < 4; ++m) {
;                 const int row = row0 + ai * HALF + m * 16;
;                 const float rs = __builtin_amdgcn_rsqf(ss_val(cur[ai * 4 + m]) * inv_k + eps);
;                 float ss = 0.f;
; #pragma unroll
;                 for (int bj = 0; bj < 2; ++bj) {
;                     const f32x4 v0 = acc[ai][bj][m][0] * rs, v1 = acc[ai][bj][m][1] * rs;
;                     ss += (v0[0] * v0[0] + v0[1] * v0[1]) + (v0[2] * v0[2] + v0[3] * v0[3]) + (v1[0] * v1[0] + v1[1] * v1[1]) + (v1[2] * v1[2] + v1[3] * v1[3]);
;                     u32x4 w; w.x = cvt_pk_bf16(v0[0], v0[1]); w.y = cvt_pk_bf16(v0[2], v0[3]); w.z = cvt_pk_bf16(v1[0], v1[1]); w.w = cvt_pk_bf16(v1[2], v1[3]);
;                     *(u32x4*)(O + (size_t)row * ldc + col0 + bj * HALF) = w;
;                 }
;                 if (is_va) { ss += __shfl_xor(ss, 16); ss += __shfl_xor(ss, 32); if (fq == 0) atomicAdd(rowss_v + row, ss_fix(ss)); }
;             }
.LBB0_981:
	s_waitcnt lgkmcnt(0)
	v_mov_b64_e32 v[56:57], s[24:25]
	s_and_b64 vcc, exec, s[6:7]
	v_cvt_f32_u32_e32 v150, v150
	v_cvt_f32_u32_e32 v151, v151
	v_fmamk_f32 v150, v151, 0x4f800000, v150
	v_fmamk_f32 v48, v150, 0x26800000, v166
	v_rsq_f32_e32 v54, v48
	v_add_u32_e32 v48, 0x90, v142
	v_mad_i64_i32 v[56:57], s[58:59], v48, s57, v[56:57]
	v_pk_mul_f32 v[46:47], v[46:47], v[54:55] op_sel_hi:[1,0]
	v_pk_mul_f32 v[44:45], v[44:45], v[54:55] op_sel_hi:[1,0]
	v_pk_mul_f32 v[42:43], v[42:43], v[54:55] op_sel_hi:[1,0]
	v_pk_mul_f32 v[40:41], v[40:41], v[54:55] op_sel_hi:[1,0]
	v_cvt_pk_bf16_f32 v50, v44, v45
	v_cvt_pk_bf16_f32 v51, v46, v47
	v_lshl_add_u64 v[56:57], v[140:141], 1, v[56:57]
	v_cvt_pk_bf16_f32 v52, v40, v41
	v_cvt_pk_bf16_f32 v53, v42, v43
	v_pk_mul_f32 v[38:39], v[38:39], v[54:55] op_sel_hi:[1,0]
	v_pk_mul_f32 v[36:37], v[36:37], v[54:55] op_sel_hi:[1,0]
	v_pk_mul_f32 v[34:35], v[34:35], v[54:55] op_sel_hi:[1,0]
	v_pk_mul_f32 v[32:33], v[32:33], v[54:55] op_sel_hi:[1,0]
	global_store_dwordx4 v[56:57], v[50:53], off
	s_nop 1
	v_cvt_pk_bf16_f32 v50, v36, v37
	v_cvt_pk_bf16_f32 v51, v38, v39
	v_cvt_pk_bf16_f32 v52, v32, v33
	v_cvt_pk_bf16_f32 v53, v34, v35
	global_store_dwordx4 v[56:57], v[50:53], off offset:256
	s_cbranch_vccnz .LBB0_985
	v_mul_f32_e32 v35, v35, v35
	v_fmac_f32_e32 v35, v34, v34
	v_mul_f32_e32 v34, v37, v37
	v_mul_f32_e32 v43, v43, v43
	v_fmac_f32_e32 v34, v36, v36
	v_mul_f32_e32 v36, v39, v39
	v_fmac_f32_e32 v43, v42, v42
	v_mul_f32_e32 v42, v45, v45
	v_fmac_f32_e32 v36, v38, v38
	v_mul_f32_e32 v33, v33, v33
	v_fmac_f32_e32 v42, v44, v44
	v_mul_f32_e32 v44, v47, v47
	v_add_f32_e32 v34, v34, v36
	v_fmac_f32_e32 v33, v32, v32
	v_fmac_f32_e32 v44, v46, v46
	v_mul_f32_e32 v41, v41, v41
	v_add_f32_e32 v32, v33, v34
	v_and_b32_e32 v34, 64, v167
	v_add_f32_e32 v42, v42, v44
	v_fmac_f32_e32 v41, v40, v40
	v_xor_b32_e32 v33, 16, v167
	v_add_u32_e32 v34, 64, v34
	v_add_f32_e32 v40, v41, v42
	v_cmp_lt_i32_e32 vcc, v33, v34
	v_add_f32_e32 v40, v43, v40
	v_add_f32_e32 v32, v35, v32
	v_cndmask_b32_e32 v33, v167, v33, vcc
	v_add_f32_e32 v32, v40, v32
	v_lshlrev_b32_e32 v33, 2, v33
	ds_bpermute_b32 v33, v33, v32
	s_waitcnt lgkmcnt(0)
	v_add_f32_e32 v32, v32, v33
	v_xor_b32_e32 v33, 32, v167
	v_cmp_lt_i32_e32 vcc, v33, v34
	s_nop 1
	v_cndmask_b32_e32 v33, v167, v33, vcc
	v_lshlrev_b32_e32 v33, 2, v33
	ds_bpermute_b32 v33, v33, v32
	s_and_saveexec_b64 s[84:85], s[4:5]
	s_cbranch_execz .LBB0_984
	s_waitcnt lgkmcnt(0)
	v_add_f32_e32 v32, v32, v33
	v_mul_f32_e32 v32, 0x53800000, v32
	v_trunc_f32_e32 v32, v32
	v_mul_f32_e32 v33, 0x2f800000, v32
	v_floor_f32_e32 v33, v33
	v_fmac_f32_e32 v32, 0xcf800000, v33
	v_cvt_u32_f32_e32 v32, v32
	v_cvt_u32_f32_e32 v33, v33
	v_ashrrev_i32_e32 v49, 31, v48
	v_lshl_add_u64 v[34:35], v[48:49], 3, s[68:69]
	global_atomic_add_x2 v[34:35], v[32:33], off

; __device__ __forceinline__ unsigned cvt_pk_bf16(float lo, float hi) { unsigned r; asm volatile("v_cvt_pk_bf16_f32 %0, %1, %2" : "=v"(r) : "v"(lo), "v"(hi)); return r; }
; __device__ __forceinline__ u64 ss_fix(float s) { return (u64)(s * 1099511627776.0f); }
; __device__ __forceinline__ float ss_val(u64 v) { return (float)v * (1.0f / 1099511627776.0f); }
;     __device__ __forceinline__ void operator()(const f32x4 (&acc)[2][2][4][2], const Unit& u, const Unit&, bool, int wr, int wc, int fr, int fq) const {
;     ...
; #pragma unroll
;         for (int ai = 0; ai < 2; ++ai)
; #pragma unroll
;             for (int m = 0; m < 4; ++m) {
;                 const int row = row0 + ai * HALF + m * 16;
;                 const float rs = __builtin_amdgcn_rsqf(ss_val(cur[ai * 4 + m]) * inv_k + eps);
;                 float ss = 0.f;
; #pragma unroll
;                 for (int bj = 0; bj < 2; ++bj) {
;                     const f32x4 v0 = acc[ai][bj][m][0] * rs, v1 = acc[ai][bj][m][1] * rs;
;                     ss += (v0[0] * v0[0] + v0[1] * v0[1]) + (v0[2] * v0[2] + v0[3] * v0[3]) + (v1[0] * v1[0] + v1[1] * v1[1]) + (v1[2] * v1[2] + v1[3] * v1[3]);
;                     u32x4 w; w.x = cvt_pk_bf16(v0[0], v0[1]); w.y = cvt_pk_bf16(v0[2], v0[3]); w.z = cvt_pk_bf16(v1[0], v1[1]); w.w = cvt_pk_bf16(v1[2], v1[3]);
;                     *(u32x4*)(O + (size_t)row * ldc + col0 + bj * HALF) = w;
;                 }
;                 if (is_va) { ss += __shfl_xor(ss, 16); ss += __shfl_xor(ss, 32); if (fq == 0) atomicAdd(rowss_v + row, ss_fix(ss)); }
;             }
.LBB0_985:
	s_waitcnt lgkmcnt(0)
	v_mov_b64_e32 v[40:41], s[24:25]
	s_and_b64 vcc, exec, s[6:7]
	v_cvt_f32_u32_e32 v148, v148
	v_cvt_f32_u32_e32 v149, v149
	v_fmamk_f32 v148, v149, 0x4f800000, v148
	v_fmamk_f32 v32, v148, 0x26800000, v166
	v_rsq_f32_e32 v38, v32
	v_add_u32_e32 v32, 0xa0, v142
	v_mad_i64_i32 v[40:41], s[58:59], v32, s57, v[40:41]
	v_pk_mul_f32 v[30:31], v[30:31], v[38:39] op_sel_hi:[1,0]
	v_pk_mul_f32 v[28:29], v[28:29], v[38:39] op_sel_hi:[1,0]
	v_pk_mul_f32 v[26:27], v[26:27], v[38:39] op_sel_hi:[1,0]
	v_pk_mul_f32 v[24:25], v[24:25], v[38:39] op_sel_hi:[1,0]
	v_cvt_pk_bf16_f32 v34, v28, v29
	v_cvt_pk_bf16_f32 v35, v30, v31
	v_lshl_add_u64 v[40:41], v[140:141], 1, v[40:41]
	v_cvt_pk_bf16_f32 v36, v24, v25
	v_cvt_pk_bf16_f32 v37, v26, v27
	v_pk_mul_f32 v[22:23], v[22:23], v[38:39] op_sel_hi:[1,0]
	v_pk_mul_f32 v[20:21], v[20:21], v[38:39] op_sel_hi:[1,0]
	v_pk_mul_f32 v[18:19], v[18:19], v[38:39] op_sel_hi:[1,0]
	v_pk_mul_f32 v[16:17], v[16:17], v[38:39] op_sel_hi:[1,0]
	global_store_dwordx4 v[40:41], v[34:37], off
	s_nop 1
	v_cvt_pk_bf16_f32 v34, v20, v21
	v_cvt_pk_bf16_f32 v35, v22, v23
	v_cvt_pk_bf16_f32 v36, v16, v17
	v_cvt_pk_bf16_f32 v37, v18, v19
	global_store_dwordx4 v[40:41], v[34:37], off offset:256
	s_cbranch_vccnz .LBB0_989
	v_mul_f32_e32 v19, v19, v19
	v_fmac_f32_e32 v19, v18, v18
	v_mul_f32_e32 v18, v21, v21
	v_mul_f32_e32 v27, v27, v27
	v_fmac_f32_e32 v18, v20, v20
	v_mul_f32_e32 v20, v23, v23
	v_fmac_f32_e32 v27, v26, v26
	v_mul_f32_e32 v26, v29, v29
	v_fmac_f32_e32 v20, v22, v22
	v_mul_f32_e32 v17, v17, v17
	v_fmac_f32_e32 v26, v28, v28
	v_mul_f32_e32 v28, v31, v31
	v_add_f32_e32 v18, v18, v20
	v_fmac_f32_e32 v17, v16, v16
	v_fmac_f32_e32 v28, v30, v30
	v_mul_f32_e32 v25, v25, v25
	v_add_f32_e32 v16, v17, v18
	v_and_b32_e32 v18, 64, v167
	v_add_f32_e32 v26, v26, v28
	v_fmac_f32_e32 v25, v24, v24
	v_xor_b32_e32 v17, 16, v167
	v_add_u32_e32 v18, 64, v18
	v_add_f32_e32 v24, v25, v26
	v_cmp_lt_i32_e32 vcc, v17, v18
	v_add_f32_e32 v24, v27, v24
	v_add_f32_e32 v16, v19, v16
	v_cndmask_b32_e32 v17, v167, v17, vcc
	v_add_f32_e32 v16, v24, v16
	v_lshlrev_b32_e32 v17, 2, v17
	ds_bpermute_b32 v17, v17, v16
	s_waitcnt lgkmcnt(0)
	v_add_f32_e32 v16, v16, v17
	v_xor_b32_e32 v17, 32, v167
	v_cmp_lt_i32_e32 vcc, v17, v18
	s_nop 1
	v_cndmask_b32_e32 v17, v167, v17, vcc
	v_lshlrev_b32_e32 v17, 2, v17
	ds_bpermute_b32 v17, v17, v16
	s_and_saveexec_b64 s[84:85], s[4:5]
	s_cbranch_execz .LBB0_988
	s_waitcnt lgkmcnt(0)
	v_add_f32_e32 v16, v16, v17
	v_mul_f32_e32 v16, 0x53800000, v16
	v_trunc_f32_e32 v16, v16
	v_mul_f32_e32 v17, 0x2f800000, v16
	v_floor_f32_e32 v17, v17
	v_fmac_f32_e32 v16, 0xcf800000, v17
	v_cvt_u32_f32_e32 v16, v16
	v_cvt_u32_f32_e32 v17, v17
	v_ashrrev_i32_e32 v33, 31, v32
	v_lshl_add_u64 v[18:19], v[32:33], 3, s[68:69]
	global_atomic_add_x2 v[18:19], v[16:17], off

; __device__ __forceinline__ unsigned cvt_pk_bf16(float lo, float hi) { unsigned r; asm volatile("v_cvt_pk_bf16_f32 %0, %1, %2" : "=v"(r) : "v"(lo), "v"(hi)); return r; }
; __device__ __forceinline__ u64 ss_fix(float s) { return (u64)(s * 1099511627776.0f); }
; __device__ __forceinline__ float ss_val(u64 v) { return (float)v * (1.0f / 1099511627776.0f); }
;     __device__ __forceinline__ void operator()(const f32x4 (&acc)[2][2][4][2], const Unit& u, const Unit&, bool, int wr, int wc, int fr, int fq) const {
;     ...
; #pragma unroll
;         for (int ai = 0; ai < 2; ++ai)
; #pragma unroll
;             for (int m = 0; m < 4; ++m) {
;                 const int row = row0 + ai * HALF + m * 16;
;                 const float rs = __builtin_amdgcn_rsqf(ss_val(cur[ai * 4 + m]) * inv_k + eps);
;                 float ss = 0.f;
; #pragma unroll
;                 for (int bj = 0; bj < 2; ++bj) {
;                     const f32x4 v0 = acc[ai][bj][m][0] * rs, v1 = acc[ai][bj][m][1] * rs;
;                     ss += (v0[0] * v0[0] + v0[1] * v0[1]) + (v0[2] * v0[2] + v0[3] * v0[3]) + (v1[0] * v1[0] + v1[1] * v1[1]) + (v1[2] * v1[2] + v1[3] * v1[3]);
;                     u32x4 w; w.x = cvt_pk_bf16(v0[0], v0[1]); w.y = cvt_pk_bf16(v0[2], v0[3]); w.z = cvt_pk_bf16(v1[0], v1[1]); w.w = cvt_pk_bf16(v1[2], v1[3]);
;                     *(u32x4*)(O + (size_t)row * ldc + col0 + bj * HALF) = w;
;                 }
;                 if (is_va) { ss += __shfl_xor(ss, 16); ss += __shfl_xor(ss, 32); if (fq == 0) atomicAdd(rowss_v + row, ss_fix(ss)); }
;             }
.LBB0_989:
	s_waitcnt lgkmcnt(0)
	v_mov_b64_e32 v[24:25], s[24:25]
	s_and_b64 vcc, exec, s[6:7]
	v_cvt_f32_u32_e32 v146, v146
	v_cvt_f32_u32_e32 v147, v147
	v_fmamk_f32 v146, v147, 0x4f800000, v146
	v_fmamk_f32 v16, v146, 0x26800000, v166
	v_rsq_f32_e32 v22, v16
	v_add_u32_e32 v16, 0xb0, v142
	v_mad_i64_i32 v[24:25], s[58:59], v16, s57, v[24:25]
	v_pk_mul_f32 v[14:15], v[14:15], v[22:23] op_sel_hi:[1,0]
	v_pk_mul_f32 v[12:13], v[12:13], v[22:23] op_sel_hi:[1,0]
	v_pk_mul_f32 v[10:11], v[10:11], v[22:23] op_sel_hi:[1,0]
	v_pk_mul_f32 v[8:9], v[8:9], v[22:23] op_sel_hi:[1,0]
	v_cvt_pk_bf16_f32 v18, v12, v13
	v_cvt_pk_bf16_f32 v19, v14, v15
	v_lshl_add_u64 v[24:25], v[140:141], 1, v[24:25]
	v_cvt_pk_bf16_f32 v20, v8, v9
	v_cvt_pk_bf16_f32 v21, v10, v11
	v_pk_mul_f32 v[6:7], v[6:7], v[22:23] op_sel_hi:[1,0]
	v_pk_mul_f32 v[4:5], v[4:5], v[22:23] op_sel_hi:[1,0]
	v_pk_mul_f32 v[2:3], v[2:3], v[22:23] op_sel_hi:[1,0]
	v_pk_mul_f32 v[0:1], v[0:1], v[22:23] op_sel_hi:[1,0]
	global_store_dwordx4 v[24:25], v[18:21], off
	s_nop 1
	v_cvt_pk_bf16_f32 v18, v4, v5
	v_cvt_pk_bf16_f32 v19, v6, v7
	v_cvt_pk_bf16_f32 v20, v0, v1
	v_cvt_pk_bf16_f32 v21, v2, v3
	global_store_dwordx4 v[24:25], v[18:21], off offset:256
	s_cbranch_vccnz .LBB0_993
	v_mul_f32_e32 v3, v3, v3
	v_fmac_f32_e32 v3, v2, v2
	v_mul_f32_e32 v2, v5, v5
	v_mul_f32_e32 v11, v11, v11
	v_fmac_f32_e32 v2, v4, v4
	v_mul_f32_e32 v4, v7, v7
	v_fmac_f32_e32 v11, v10, v10
	v_mul_f32_e32 v10, v13, v13
	v_fmac_f32_e32 v4, v6, v6
	v_mul_f32_e32 v1, v1, v1
	v_fmac_f32_e32 v10, v12, v12
	v_mul_f32_e32 v12, v15, v15
	v_add_f32_e32 v2, v2, v4
	v_fmac_f32_e32 v1, v0, v0
	v_fmac_f32_e32 v12, v14, v14
	v_mul_f32_e32 v9, v9, v9
	v_add_f32_e32 v0, v1, v2
	v_and_b32_e32 v2, 64, v167
	v_add_f32_e32 v10, v10, v12
	v_fmac_f32_e32 v9, v8, v8
	v_xor_b32_e32 v1, 16, v167
	v_add_u32_e32 v2, 64, v2
	v_add_f32_e32 v8, v9, v10
	v_cmp_lt_i32_e32 vcc, v1, v2
	v_add_f32_e32 v8, v11, v8
	v_add_f32_e32 v0, v3, v0
	v_cndmask_b32_e32 v1, v167, v1, vcc
	v_add_f32_e32 v0, v8, v0
	v_lshlrev_b32_e32 v1, 2, v1
	ds_bpermute_b32 v1, v1, v0
	s_waitcnt lgkmcnt(0)
	v_add_f32_e32 v0, v0, v1
	v_xor_b32_e32 v1, 32, v167
	v_cmp_lt_i32_e32 vcc, v1, v2
	s_nop 1
	v_cndmask_b32_e32 v1, v167, v1, vcc
	v_lshlrev_b32_e32 v1, 2, v1
	ds_bpermute_b32 v1, v1, v0
	s_and_saveexec_b64 s[6:7], s[4:5]
	s_cbranch_execz .LBB0_992
	s_waitcnt lgkmcnt(0)
	v_add_f32_e32 v0, v0, v1
	v_mul_f32_e32 v0, 0x53800000, v0
	v_trunc_f32_e32 v0, v0
	v_mul_f32_e32 v1, 0x2f800000, v0
	v_floor_f32_e32 v1, v1
	v_fmac_f32_e32 v0, 0xcf800000, v1
	v_cvt_u32_f32_e32 v0, v0
	v_cvt_u32_f32_e32 v1, v1
	v_ashrrev_i32_e32 v17, 31, v16
	v_lshl_add_u64 v[2:3], v[16:17], 3, s[68:69]
	global_atomic_add_x2 v[2:3], v[0:1], off

; __device__ __forceinline__ float ss_val(u64 v) { return (float)v * (1.0f / 1099511627776.0f); }
; __device__ __forceinline__ void rank_unit(const bf16* XN, const bf16* WrT, const u64* rowss, float* R, int m0, int lane) {
;     ...
;     for (int ki = 0; ki < 32; ki += 2) {
;         const bf16x8 a0 = *(const bf16x8*)(ap + 32 * ki), b0 = *(const bf16x8*)(bp + 32 * ki), a1 = *(const bf16x8*)(ap + 32 * ki + 32), b1 = *(const bf16x8*)(bp + 32 * ki + 32);
;         acc0 = __builtin_amdgcn_mfma_f32_16x16x32_bf16(b0, a0, acc0, 0, 0, 0);
;         acc1 = __builtin_amdgcn_mfma_f32_16x16x32_bf16(b1, a1, acc1, 0, 0, 0);
;     }
;     { const int row = m0 + fr; const float rs = __builtin_amdgcn_rsqf(ss_val(rowss[row]) * (1.f / D) + EPS); *(f32x4*)(R + (size_t)row * 16 + 4 * fq) = (acc0 + acc1) * rs; }
.LBB0_1000:
	v_lshl_add_u64 v[78:79], v[18:19], 0, v[8:9]
	v_add_co_u32_e32 v92, vcc, s3, v78
	v_lshl_add_u64 v[90:91], v[16:17], 0, v[8:9]
	s_nop 0
	v_addc_co_u32_e32 v93, vcc, 0, v79, vcc
	global_load_dwordx4 v[22:25], v[90:91], off offset:-512
	global_load_dwordx4 v[26:29], v[90:91], off offset:-448
	global_load_dwordx4 v[30:33], v[90:91], off offset:-384
	global_load_dwordx4 v[34:37], v[90:91], off offset:-320
	global_load_dwordx4 v[38:41], v[90:91], off offset:-256
	global_load_dwordx4 v[42:45], v[90:91], off offset:-192
	global_load_dwordx4 v[46:49], v[90:91], off offset:-128
	global_load_dwordx4 v[50:53], v[90:91], off offset:-64
	global_load_dwordx4 v[54:57], v[90:91], off
	global_load_dwordx4 v[58:61], v[90:91], off offset:64
	global_load_dwordx4 v[62:65], v[90:91], off offset:128
	global_load_dwordx4 v[66:69], v[90:91], off offset:192
	global_load_dwordx4 v[70:73], v[90:91], off offset:256
	global_load_dwordx4 v[74:77], v[90:91], off offset:320
	global_load_dwordx4 v[78:81], v[92:93], off
	global_load_dwordx4 v[82:85], v[92:93], off offset:64
	global_load_dwordx4 v[86:89], v[92:93], off offset:128
	s_add_i32 s20, s20, 16
	v_lshl_add_u64 v[18:19], v[18:19], 0, s[6:7]
	s_cmp_lt_u32 s20, 30
	v_lshl_add_u64 v[16:17], v[16:17], 0, s[6:7]
	s_waitcnt vmcnt(2)
	v_mfma_f32_16x16x32_bf16 v[0:3], v[78:81], v[22:25], v[0:3]
	global_load_dwordx4 v[22:25], v[92:93], off offset:192
	s_waitcnt vmcnt(2)
	v_mfma_f32_16x16x32_bf16 v[4:7], v[82:85], v[26:29], v[4:7]
	global_load_dwordx4 v[26:29], v[92:93], off offset:256
	s_waitcnt vmcnt(2)
	v_mfma_f32_16x16x32_bf16 v[0:3], v[86:89], v[30:33], v[0:3]
	global_load_dwordx4 v[30:33], v[92:93], off offset:320
	s_waitcnt vmcnt(2)
	v_mfma_f32_16x16x32_bf16 v[4:7], v[22:25], v[34:37], v[4:7]
	global_load_dwordx4 v[22:25], v[92:93], off offset:384
	s_waitcnt vmcnt(2)
	v_mfma_f32_16x16x32_bf16 v[0:3], v[26:29], v[38:41], v[0:3]
	global_load_dwordx4 v[26:29], v[92:93], off offset:448
	s_waitcnt vmcnt(2)
	v_mfma_f32_16x16x32_bf16 v[4:7], v[30:33], v[42:45], v[4:7]
	global_load_dwordx4 v[30:33], v[92:93], off offset:512
	s_waitcnt vmcnt(2)
	v_mfma_f32_16x16x32_bf16 v[0:3], v[22:25], v[46:49], v[0:3]
	global_load_dwordx4 v[22:25], v[92:93], off offset:576
	s_waitcnt vmcnt(2)
	v_mfma_f32_16x16x32_bf16 v[4:7], v[26:29], v[50:53], v[4:7]
	global_load_dwordx4 v[26:29], v[92:93], off offset:640
	s_waitcnt vmcnt(2)
	v_mfma_f32_16x16x32_bf16 v[0:3], v[30:33], v[54:57], v[0:3]
	global_load_dwordx4 v[30:33], v[92:93], off offset:704
	s_waitcnt vmcnt(2)
	v_mfma_f32_16x16x32_bf16 v[4:7], v[22:25], v[58:61], v[4:7]
	global_load_dwordx4 v[22:25], v[92:93], off offset:768
	s_waitcnt vmcnt(2)
	v_mfma_f32_16x16x32_bf16 v[0:3], v[26:29], v[62:65], v[0:3]
	global_load_dwordx4 v[26:29], v[92:93], off offset:832
	s_waitcnt vmcnt(2)
	v_mfma_f32_16x16x32_bf16 v[4:7], v[30:33], v[66:69], v[4:7]
	global_load_dwordx4 v[30:33], v[92:93], off offset:896
	global_load_dwordx4 v[34:37], v[92:93], off offset:960
	s_waitcnt vmcnt(3)
	v_mfma_f32_16x16x32_bf16 v[0:3], v[22:25], v[70:73], v[0:3]
	global_load_dwordx4 v[22:25], v[90:91], off offset:384
	s_waitcnt vmcnt(3)
	v_mfma_f32_16x16x32_bf16 v[4:7], v[26:29], v[74:77], v[4:7]
	global_load_dwordx4 v[26:29], v[90:91], off offset:448
	s_waitcnt vmcnt(1)
	v_mfma_f32_16x16x32_bf16 v[0:3], v[30:33], v[22:25], v[0:3]
	s_waitcnt vmcnt(0)
	v_mfma_f32_16x16x32_bf16 v[4:7], v[34:37], v[26:29], v[4:7]
	s_cbranch_scc1 .LBB0_1000
	v_lshl_or_b32 v16, s11, 4, v160
	v_ashrrev_i32_e32 v17, 31, v16
	v_lshl_add_u64 v[18:19], v[16:17], 3, s[64:65]
	global_load_dwordx2 v[18:19], v[18:19], off
	s_nop 2
	v_pk_add_f32 v[2:3], v[2:3], v[6:7]
	v_pk_add_f32 v[0:1], v[0:1], v[4:5]
	s_add_i32 s11, s11, s36
	s_cmpk_lt_i32 s11, 0x100
	v_add_u32_e32 v14, s2, v14
	s_waitcnt vmcnt(0)
	v_cvt_f32_u32_e32 v18, v18
	v_cvt_f32_u32_e32 v19, v19
	v_fmamk_f32 v18, v19, 0x4f800000, v18
	v_fmamk_f32 v4, v18, 0x26800000, v20
	v_rsq_f32_e32 v4, v4
	v_lshlrev_b64 v[6:7], 6, v[16:17]
	v_lshl_add_u64 v[6:7], v[10:11], 0, v[6:7]
	v_pk_mul_f32 v[2:3], v[2:3], v[4:5] op_sel_hi:[1,0]
	v_pk_mul_f32 v[0:1], v[0:1], v[4:5] op_sel_hi:[1,0]
	global_store_dwordx4 v[6:7], v[0:3], off
	s_cbranch_scc1 .LBB0_999

; __device__ __forceinline__ float ss_val(u64 v) { return (float)v * (1.0f / 1099511627776.0f); }
; __device__ __forceinline__ unsigned pk2(float lo, float hi) { return f2bf(lo) | (f2bf(hi) << 16); }
; __device__ __forceinline__ void gmlp_unit(LAS unsigned char* wl, const bf16* PROJ, const u64* rowss_v, const bf16* wsb, const float* norm_v, const float* b_s, bf16* Y, int nb, int g, int lane) {
;     ...
;     for (int it = 0; it < 8; ++it) {
;         const int s0 = it * 16 + 2 * sp;
;         const float r0 = __builtin_amdgcn_rsqf(ss_val(rowss_v[tok0 + s0]) * (1.f / 512.f) + EPS), r1 = __builtin_amdgcn_rsqf(ss_val(rowss_v[tok0 + s0 + 1]) * (1.f / 512.f) + EPS);
;         const u32x4 va = *(const u32x4*)(PROJ + (size_t)(tok0 + s0) * NPROJ + 512 + g * 64 + 8 * cc);
;         const u32x4 vb = *(const u32x4*)(PROJ + (size_t)(tok0 + s0 + 1) * NPROJ + 512 + g * 64 + 8 * cc);
; #pragma unroll
;         for (int i = 0; i < 4; ++i) {
;             VT32[(8 * cc + 2 * i) * (VS / 2) + (s0 >> 1)] = pk2(bf_lo(va[i]) * r0, bf_lo(vb[i]) * r1);
;             VT32[(8 * cc + 2 * i + 1) * (VS / 2) + (s0 >> 1)] = pk2(bf_hi(va[i]) * r0, bf_hi(vb[i]) * r1);
;         }
.LBB0_1051:
	v_add_u32_e32 v0, s11, v2
	v_ashrrev_i32_e32 v1, 31, v0
	v_add_u32_e32 v8, 1, v0
	v_add_u32_e32 v40, 16, v0
	v_add_u32_e32 v9, 17, v0
	v_add_u32_e32 v42, 32, v0
	v_add_u32_e32 v10, 33, v0
	v_add_u32_e32 v44, 48, v0
	v_add_u32_e32 v11, 49, v0
	v_mad_i64_i32 v[12:13], s[12:13], v0, s4, v[136:137]
	v_lshl_add_u64 v[0:1], v[0:1], 3, s[0:1]
	v_mad_i64_i32 v[16:17], s[12:13], v8, s4, v[136:137]
	v_ashrrev_i32_e32 v41, 31, v40
	v_mad_i64_i32 v[20:21], s[12:13], v40, s4, v[136:137]
	v_mad_i64_i32 v[24:25], s[12:13], v9, s4, v[136:137]
	v_ashrrev_i32_e32 v43, 31, v42
	v_mad_i64_i32 v[28:29], s[12:13], v10, s4, v[136:137]
	v_ashrrev_i32_e32 v45, 31, v44
	v_mad_i64_i32 v[32:33], s[12:13], v44, s4, v[136:137]
	v_mad_i64_i32 v[36:37], s[12:13], v11, s4, v[136:137]
	v_mad_i64_i32 v[48:49], s[12:13], v42, s4, v[136:137]
	global_load_dwordx4 v[8:11], v[0:1], off
	s_nop 0
	global_load_dwordx4 v[12:15], v[12:13], off offset:1024
	s_nop 0
	global_load_dwordx4 v[16:19], v[16:17], off offset:1024
	s_nop 0
	global_load_dwordx4 v[20:23], v[20:21], off offset:1024
	s_nop 0
	global_load_dwordx4 v[24:27], v[24:25], off offset:1024
	s_nop 0
	global_load_dwordx4 v[28:31], v[28:29], off offset:1024
	s_nop 0
	global_load_dwordx4 v[32:35], v[32:33], off offset:1024
	s_nop 0
	global_load_dwordx4 v[36:39], v[36:37], off offset:1024
	v_lshl_add_u64 v[0:1], v[40:41], 3, s[0:1]
	v_lshl_add_u64 v[46:47], v[42:43], 3, s[0:1]
	v_lshl_add_u64 v[52:53], v[44:45], 3, s[0:1]
	global_load_dwordx4 v[40:43], v[0:1], off
	s_nop 0
	global_load_dwordx4 v[44:47], v[46:47], off
	s_nop 0
	global_load_dwordx4 v[48:51], v[48:49], off offset:1024
	s_nop 0
	global_load_dwordx4 v[52:55], v[52:53], off
	v_add_u32_e32 v4, v3, v152
	s_add_i32 s11, s11, 64
	v_add_u32_e32 v5, v3, v151
	v_add_u32_e32 v6, v3, v150
	v_add_u32_e32 v7, v3, v149
	v_add_u32_e32 v3, 0x80, v3
	v_add_u32_e32 v56, 0x400, v4
	s_cmpk_lg_i32 s11, 0x80
	v_add_u32_e32 v57, 0x400, v5
	v_add_u32_e32 v58, 0x400, v6
	v_add_u32_e32 v59, 0x400, v7
	s_waitcnt vmcnt(11)
	v_ffbh_u32_e32 v0, v9
	v_ffbh_u32_e32 v1, v11
	s_waitcnt vmcnt(10)
	v_lshlrev_b32_e32 v60, 16, v12
	v_and_b32_e32 v62, 0xffff0000, v12
	v_lshlrev_b32_e32 v155, 16, v13
	v_and_b32_e32 v157, 0xffff0000, v13
	v_lshlrev_b32_e32 v159, 16, v14
	v_and_b32_e32 v161, 0xffff0000, v14
	v_min_u32_e32 v12, 32, v0
	v_min_u32_e32 v13, 32, v1
	s_waitcnt vmcnt(3)
	v_ffbh_u32_e32 v14, v41
	v_lshlrev_b32_e32 v61, 16, v16
	v_and_b32_e32 v63, 0xffff0000, v16
	v_lshlrev_b32_e32 v156, 16, v17
	v_and_b32_e32 v158, 0xffff0000, v17
	v_lshlrev_b32_e32 v160, 16, v18
	v_and_b32_e32 v162, 0xffff0000, v18
	v_lshlrev_b32_e32 v163, 16, v15
	v_and_b32_e32 v165, 0xffff0000, v15
	v_ffbh_u32_e32 v15, v43
	s_waitcnt vmcnt(2)
	v_ffbh_u32_e32 v16, v45
	v_ffbh_u32_e32 v17, v47
	s_waitcnt vmcnt(0)
	v_ffbh_u32_e32 v18, v53
	v_lshlrev_b64 v[0:1], v12, v[8:9]
	v_sub_u32_e32 v193, 32, v12
	v_lshlrev_b64 v[8:9], v13, v[10:11]
	v_min_u32_e32 v12, 32, v14
	v_lshlrev_b32_e32 v164, 16, v19
	v_and_b32_e32 v166, 0xffff0000, v19
	v_lshlrev_b32_e32 v167, 16, v20
	v_and_b32_e32 v169, 0xffff0000, v20
	v_lshlrev_b32_e32 v170, 16, v21
	v_and_b32_e32 v172, 0xffff0000, v21
	v_min_u32_e32 v14, 32, v15
	v_min_u32_e32 v16, 32, v16
	v_min_u32_e32 v20, 32, v17
	v_min_u32_e32 v21, 32, v18
	v_min_u32_e32 v0, 1, v0
	v_min_u32_e32 v8, 1, v8
	v_lshlrev_b64 v[10:11], v12, v[40:41]
	v_sub_u32_e32 v194, 32, v13
	v_sub_u32_e32 v40, 32, v12
	v_lshlrev_b64 v[12:13], v14, v[42:43]
	v_sub_u32_e32 v41, 32, v14
	v_lshlrev_b64 v[14:15], v16, v[44:45]
	v_sub_u32_e32 v42, 32, v16
	v_lshlrev_b64 v[16:17], v20, v[46:47]
	v_lshlrev_b64 v[18:19], v21, v[52:53]
	v_or_b32_e32 v0, v1, v0
	v_or_b32_e32 v1, v9, v8
	v_min_u32_e32 v8, 1, v10
	v_sub_u32_e32 v43, 32, v20
	v_sub_u32_e32 v44, 32, v21
	v_min_u32_e32 v9, 1, v12
	v_min_u32_e32 v10, 1, v14
	v_min_u32_e32 v12, 1, v16
	v_min_u32_e32 v14, 1, v18
	v_cvt_f32_u32_e32 v0, v0
	v_or_b32_e32 v8, v11, v8
	v_cvt_f32_u32_e32 v1, v1
	v_or_b32_e32 v9, v13, v9
	v_or_b32_e32 v10, v15, v10
	v_or_b32_e32 v11, v17, v12
	v_or_b32_e32 v12, v19, v14
	v_cvt_f32_u32_e32 v8, v8
	v_cvt_f32_u32_e32 v9, v9
	v_cvt_f32_u32_e32 v10, v10
	v_cvt_f32_u32_e32 v11, v11
	v_cvt_f32_u32_e32 v12, v12
	v_ldexp_f32 v0, v0, v193
	v_ldexp_f32 v1, v1, v194
	v_mul_f32_e32 v0, 0x2b800000, v0
	v_ldexp_f32 v8, v8, v40
	v_mul_f32_e32 v1, 0x2b800000, v1
	v_ldexp_f32 v9, v9, v41
	v_ldexp_f32 v10, v10, v42
	v_ldexp_f32 v11, v11, v43
	v_ldexp_f32 v12, v12, v44
	v_fmamk_f32 v0, v0, 0x3b000000, v153
	v_mul_f32_e32 v8, 0x2b800000, v8
	v_fmamk_f32 v1, v1, 0x3b000000, v153
	v_mul_f32_e32 v9, 0x2b800000, v9
	v_mul_f32_e32 v10, 0x2b800000, v10
	v_mul_f32_e32 v11, 0x2b800000, v11
	v_mul_f32_e32 v12, 0x2b800000, v12
	v_rsq_f32_e32 v0, v0
	v_fmamk_f32 v8, v8, 0x3b000000, v153
	v_rsq_f32_e32 v1, v1
	v_fmamk_f32 v9, v9, 0x3b000000, v153
	v_fmamk_f32 v10, v10, 0x3b000000, v153
	v_fmamk_f32 v11, v11, 0x3b000000, v153
	v_fmamk_f32 v12, v12, 0x3b000000, v153
	v_rsq_f32_e32 v8, v8
	v_cvt_f32_u32_e32 v54, v54
	v_cvt_f32_u32_e32 v55, v55
	v_fmamk_f32 v54, v55, 0x4f800000, v54
	v_fmamk_f32 v13, v54, 0x27000000, v153
	v_rsq_f32_e32 v9, v9
	v_rsq_f32_e32 v10, v10
	v_rsq_f32_e32 v11, v11
	v_rsq_f32_e32 v12, v12
	v_rsq_f32_e32 v13, v13
	v_mul_f32_e32 v14, v0, v60
	v_mul_f32_e32 v16, v0, v62
	v_mul_f32_e32 v18, v0, v155
	v_mul_f32_e32 v20, v0, v157
	v_mul_f32_e32 v40, v0, v159
	v_mul_f32_e32 v42, v0, v161
	v_mul_f32_e32 v44, v0, v163
	v_mul_f32_e32 v0, v0, v165
	v_lshlrev_b32_e32 v168, 16, v24
	v_and_b32_e32 v24, 0xffff0000, v24
	v_lshlrev_b32_e32 v171, 16, v25
	v_and_b32_e32 v25, 0xffff0000, v25
	v_lshlrev_b32_e32 v173, 16, v22
	v_lshlrev_b32_e32 v174, 16, v26
; __device__ __forceinline__ float ss_val(u64 v) { return (float)v * (1.0f / 1099511627776.0f); }
; __device__ __forceinline__ unsigned pk2(float lo, float hi) { return f2bf(lo) | (f2bf(hi) << 16); }
; __device__ __forceinline__ void gmlp_unit(LAS unsigned char* wl, const bf16* PROJ, const u64* rowss_v, const bf16* wsb, const float* norm_v, const float* b_s, bf16* Y, int nb, int g, int lane) {
;     ...
;     for (int it = 0; it < 8; ++it) {
;         const int s0 = it * 16 + 2 * sp;
;         const float r0 = __builtin_amdgcn_rsqf(ss_val(rowss_v[tok0 + s0]) * (1.f / 512.f) + EPS), r1 = __builtin_amdgcn_rsqf(ss_val(rowss_v[tok0 + s0 + 1]) * (1.f / 512.f) + EPS);
;         const u32x4 va = *(const u32x4*)(PROJ + (size_t)(tok0 + s0) * NPROJ + 512 + g * 64 + 8 * cc);
;         const u32x4 vb = *(const u32x4*)(PROJ + (size_t)(tok0 + s0 + 1) * NPROJ + 512 + g * 64 + 8 * cc);
; #pragma unroll
;         for (int i = 0; i < 4; ++i) {
;             VT32[(8 * cc + 2 * i) * (VS / 2) + (s0 >> 1)] = pk2(bf_lo(va[i]) * r0, bf_lo(vb[i]) * r1);
;             VT32[(8 * cc + 2 * i + 1) * (VS / 2) + (s0 >> 1)] = pk2(bf_hi(va[i]) * r0, bf_hi(vb[i]) * r1);
;         }
	v_and_b32_e32 v22, 0xffff0000, v22
	v_and_b32_e32 v26, 0xffff0000, v26
	v_lshlrev_b32_e32 v175, 16, v23
	v_lshlrev_b32_e32 v176, 16, v27
	v_and_b32_e32 v23, 0xffff0000, v23
	v_and_b32_e32 v27, 0xffff0000, v27
	v_lshlrev_b32_e32 v177, 16, v28
	v_and_b32_e32 v28, 0xffff0000, v28
	v_lshlrev_b32_e32 v178, 16, v29
	v_and_b32_e32 v29, 0xffff0000, v29
	v_lshlrev_b32_e32 v179, 16, v30
	v_and_b32_e32 v30, 0xffff0000, v30
	v_lshlrev_b32_e32 v180, 16, v31
	v_and_b32_e32 v31, 0xffff0000, v31
	v_lshlrev_b32_e32 v181, 16, v32
	v_and_b32_e32 v32, 0xffff0000, v32
	v_lshlrev_b32_e32 v183, 16, v33
	v_and_b32_e32 v33, 0xffff0000, v33
	v_lshlrev_b32_e32 v185, 16, v34
	v_and_b32_e32 v34, 0xffff0000, v34
	v_lshlrev_b32_e32 v187, 16, v35
	v_and_b32_e32 v35, 0xffff0000, v35
	v_lshlrev_b32_e32 v189, 16, v48
	v_and_b32_e32 v48, 0xffff0000, v48
	v_lshlrev_b32_e32 v190, 16, v49
	v_and_b32_e32 v49, 0xffff0000, v49
	v_lshlrev_b32_e32 v191, 16, v50
	v_and_b32_e32 v50, 0xffff0000, v50
	v_lshlrev_b32_e32 v192, 16, v51
	v_and_b32_e32 v51, 0xffff0000, v51
	v_mul_f32_e32 v15, v1, v61
	v_mul_f32_e32 v17, v1, v63
	v_mul_f32_e32 v19, v1, v156
	v_mul_f32_e32 v21, v1, v158
	v_mul_f32_e32 v41, v1, v160
	v_mul_f32_e32 v43, v1, v162
	v_mul_f32_e32 v45, v1, v164
	v_mul_f32_e32 v1, v1, v166
	v_bfe_u32 v46, v14, 16, 1
	v_bfe_u32 v52, v16, 16, 1
	v_bfe_u32 v60, v20, 16, 1
	v_bfe_u32 v62, v40, 16, 1
	v_bfe_u32 v155, v42, 16, 1
	v_bfe_u32 v157, v44, 16, 1
	v_bfe_u32 v159, v0, 16, 1
	v_mul_f32_e32 v161, v8, v167
	v_mul_f32_e32 v163, v8, v169
	v_lshlrev_b32_e32 v182, 16, v36
	v_and_b32_e32 v36, 0xffff0000, v36
	v_lshlrev_b32_e32 v184, 16, v37
	v_and_b32_e32 v37, 0xffff0000, v37
	v_lshlrev_b32_e32 v186, 16, v38
	v_and_b32_e32 v38, 0xffff0000, v38
	v_lshlrev_b32_e32 v188, 16, v39
	v_and_b32_e32 v39, 0xffff0000, v39
	v_bfe_u32 v47, v15, 16, 1
	v_bfe_u32 v53, v17, 16, 1
	v_bfe_u32 v54, v18, 16, 1
	v_bfe_u32 v61, v21, 16, 1
	v_bfe_u32 v63, v41, 16, 1
	v_bfe_u32 v156, v43, 16, 1
	v_bfe_u32 v158, v45, 16, 1
	v_bfe_u32 v160, v1, 16, 1
	v_mul_f32_e32 v162, v9, v168
	v_mul_f32_e32 v24, v9, v24
	v_mul_f32_e32 v164, v8, v170
	v_mul_f32_e32 v165, v9, v171
	v_mul_f32_e32 v166, v8, v172
	v_mul_f32_e32 v25, v9, v25
	v_mul_f32_e32 v167, v8, v173
	v_mul_f32_e32 v168, v9, v174
	v_mul_f32_e32 v22, v8, v22
	v_mul_f32_e32 v26, v9, v26
	v_mul_f32_e32 v169, v8, v175
	v_mul_f32_e32 v170, v9, v176
	v_mul_f32_e32 v8, v8, v23
	v_mul_f32_e32 v9, v9, v27
	v_mul_f32_e32 v23, v10, v189
	v_mul_f32_e32 v27, v11, v177
	v_mul_f32_e32 v48, v10, v48
	v_mul_f32_e32 v28, v11, v28
	v_mul_f32_e32 v171, v10, v190
	v_mul_f32_e32 v172, v11, v178
	v_mul_f32_e32 v49, v10, v49
	v_mul_f32_e32 v29, v11, v29
	v_mul_f32_e32 v173, v10, v191
	v_mul_f32_e32 v174, v11, v179
	v_mul_f32_e32 v50, v10, v50
	v_mul_f32_e32 v30, v11, v30
	v_mul_f32_e32 v175, v10, v192
	v_mul_f32_e32 v176, v11, v180
	v_mul_f32_e32 v10, v10, v51
	v_mul_f32_e32 v11, v11, v31
	v_mul_f32_e32 v31, v12, v181
	v_mul_f32_e32 v32, v12, v32
	v_mul_f32_e32 v177, v12, v183
	v_mul_f32_e32 v33, v12, v33
	v_mul_f32_e32 v179, v12, v185
	v_mul_f32_e32 v34, v12, v34
	v_mul_f32_e32 v181, v12, v187
	v_mul_f32_e32 v12, v12, v35
	v_add3_u32 v14, v14, v46, s5
	v_add3_u32 v16, v16, v52, s5
	v_add3_u32 v20, v20, v60, s5
	v_add3_u32 v35, v40, v62, s5
	v_add3_u32 v40, v42, v155, s5
	v_add3_u32 v42, v44, v157, s5
	v_add3_u32 v0, v0, v159, s5
	v_bfe_u32 v44, v161, 16, 1
	v_bfe_u32 v46, v163, 16, 1
	v_bfe_u32 v55, v19, 16, 1
	v_mul_f32_e32 v51, v13, v182
	v_mul_f32_e32 v36, v13, v36
	v_mul_f32_e32 v178, v13, v184
	v_mul_f32_e32 v37, v13, v37
	v_mul_f32_e32 v180, v13, v186
	v_mul_f32_e32 v38, v13, v38
	v_mul_f32_e32 v182, v13, v188
	v_mul_f32_e32 v13, v13, v39
	v_add3_u32 v15, v15, v47, s5
	v_add3_u32 v17, v17, v53, s5
	v_add3_u32 v18, v18, v54, s5
	v_add3_u32 v21, v21, v61, s5
	v_add3_u32 v39, v41, v63, s5
	v_add3_u32 v41, v43, v156, s5
	v_add3_u32 v43, v45, v158, s5
	v_add3_u32 v1, v1, v160, s5
	v_bfe_u32 v45, v162, 16, 1
	v_bfe_u32 v47, v24, 16, 1
	v_bfe_u32 v52, v164, 16, 1
	v_bfe_u32 v53, v165, 16, 1
	v_bfe_u32 v54, v166, 16, 1
	v_bfe_u32 v60, v167, 16, 1
	v_bfe_u32 v62, v22, 16, 1
	v_bfe_u32 v155, v169, 16, 1
	v_bfe_u32 v157, v8, 16, 1
	v_bfe_u32 v159, v23, 16, 1
	v_bfe_u32 v183, v48, 16, 1
	v_bfe_u32 v185, v171, 16, 1
	v_bfe_u32 v187, v49, 16, 1
	v_bfe_u32 v189, v173, 16, 1
	v_bfe_u32 v191, v50, 16, 1
	v_bfe_u32 v193, v175, 16, 1
	v_bfe_u32 v195, v10, 16, 1
	v_bfe_u32 v197, v31, 16, 1
	v_bfe_u32 v199, v32, 16, 1
	v_bfe_u32 v206, v177, 16, 1
	v_bfe_u32 v208, v33, 16, 1
	v_bfe_u32 v210, v179, 16, 1
	v_bfe_u32 v212, v34, 16, 1
	v_bfe_u32 v214, v181, 16, 1
	v_bfe_u32 v216, v12, 16, 1
	v_lshrrev_b32_e32 v14, 16, v14
	v_lshrrev_b32_e32 v16, 16, v16
	v_lshrrev_b32_e32 v20, 16, v20
	v_lshrrev_b32_e32 v0, 16, v0
	v_add3_u32 v44, v161, v44, s5
	v_add3_u32 v46, v163, v46, s5
	v_add3_u32 v19, v19, v55, s5
	v_bfe_u32 v55, v25, 16, 1
	v_bfe_u32 v61, v168, 16, 1
	v_bfe_u32 v63, v26, 16, 1
	v_bfe_u32 v156, v170, 16, 1
	v_bfe_u32 v158, v9, 16, 1
	v_bfe_u32 v160, v27, 16, 1
	v_bfe_u32 v184, v28, 16, 1
	v_bfe_u32 v186, v172, 16, 1
	v_bfe_u32 v188, v29, 16, 1
	v_bfe_u32 v190, v174, 16, 1
	v_bfe_u32 v192, v30, 16, 1
	v_bfe_u32 v194, v176, 16, 1
	v_bfe_u32 v196, v11, 16, 1
	v_bfe_u32 v198, v51, 16, 1
	v_bfe_u32 v205, v36, 16, 1
	v_bfe_u32 v207, v178, 16, 1
	v_bfe_u32 v209, v37, 16, 1
	v_bfe_u32 v211, v180, 16, 1
	v_bfe_u32 v213, v38, 16, 1
	v_bfe_u32 v215, v182, 16, 1
	v_bfe_u32 v217, v13, 16, 1
	v_lshrrev_b32_e32 v18, 16, v18
	v_lshrrev_b32_e32 v35, 16, v35
	v_lshrrev_b32_e32 v40, 16, v40
	v_lshrrev_b32_e32 v42, 16, v42
	v_add3_u32 v45, v162, v45, s5
	v_add3_u32 v24, v24, v47, s5
	v_add3_u32 v47, v164, v52, s5
; #define LAS __attribute__((address_space(3)))
; __device__ __forceinline__ unsigned pk2(float lo, float hi) { return f2bf(lo) | (f2bf(hi) << 16); }
; template <int HF>
; __device__ __forceinline__ void gmlp_half(LAS unsigned char* wl, const bf16* PROJ, const bf16* wsg, const float* norm_v, const float* b_s, bf16* Y, int tok0, int g, int fr, int fq) {
;     ...
; #pragma unroll
;     for (int ki = 0; ki < NK; ++ki)
; #pragma unroll
;         for (int nt = 0; nt < 4; ++nt) bw[ki][nt] = *(const bf16x8*)(wsg + (size_t)(64 * HF + 16 * nt + fr) * 128 + 32 * ki + 8 * fq);
;     f32x4 acc[4][4];
; #pragma unroll
;     for (int i = 0; i < 4; ++i)
; #pragma unroll
;         for (int j = 0; j < 4; ++j) acc[i][j] = (f32x4){0.f, 0.f, 0.f, 0.f};
; #pragma unroll
;     for (int ki = 0; ki < NK; ++ki) {
;         bf16x8 av[4];
; #pragma unroll
;         for (int mi = 0; mi < 4; ++mi) av[mi] = *(const LAS bf16x8*)(wl + ((32 * (mi >> 1) + 8 * (fr >> 2) + 4 * (mi & 1) + (fr & 3)) * VS + 32 * ki + 8 * fq) * 2);
; #pragma unroll
;         for (int nt = 0; nt < 4; ++nt)
; #pragma unroll
;             for (int mi = 0; mi < 4; ++mi) acc[mi][nt] = __builtin_amdgcn_mfma_f32_16x16x32_bf16(av[mi], bw[ki][nt], acc[mi][nt], 0, 0, 0);
;     }
; __device__ __forceinline__ void gmlp_unit(LAS unsigned char* wl, const bf16* PROJ, const u64* rowss_v, const bf16* wsb, const float* norm_v, const float* b_s, bf16* Y, int nb, int g, int lane) {
;     ...
;         for (int i = 0; i < 4; ++i) {
;             VT32[(8 * cc + 2 * i) * (VS / 2) + (s0 >> 1)] = pk2(bf_lo(va[i]) * r0, bf_lo(vb[i]) * r1);
;             VT32[(8 * cc + 2 * i + 1) * (VS / 2) + (s0 >> 1)] = pk2(bf_hi(va[i]) * r0, bf_hi(vb[i]) * r1);
;         }
	v_add3_u32 v52, v165, v53, s5
	v_add3_u32 v53, v166, v54, s5
	v_add3_u32 v54, v167, v60, s5
	v_add3_u32 v22, v22, v62, s5
	v_add3_u32 v60, v169, v155, s5
	v_add3_u32 v8, v8, v157, s5
	v_add3_u32 v23, v23, v159, s5
	v_add3_u32 v48, v48, v183, s5
	v_add3_u32 v62, v171, v185, s5
	v_add3_u32 v49, v49, v187, s5
	v_add3_u32 v155, v173, v189, s5
	v_add3_u32 v50, v50, v191, s5
	v_add3_u32 v157, v175, v193, s5
	v_add3_u32 v10, v10, v195, s5
	v_add3_u32 v31, v31, v197, s5
	v_add3_u32 v32, v32, v199, s5
	v_add3_u32 v159, v177, v206, s5
	v_add3_u32 v33, v33, v208, s5
	v_add3_u32 v161, v179, v210, s5
	v_add3_u32 v34, v34, v212, s5
	v_add3_u32 v163, v181, v214, s5
	v_add3_u32 v12, v12, v216, s5
	v_and_or_b32 v14, v15, s6, v14
	v_and_or_b32 v15, v17, s6, v16
	v_and_or_b32 v17, v21, s6, v20
	v_and_or_b32 v0, v1, s6, v0
	v_lshrrev_b32_e32 v1, 16, v44
	v_lshrrev_b32_e32 v21, 16, v46
	v_add3_u32 v25, v25, v55, s5
	v_add3_u32 v55, v168, v61, s5
	v_add3_u32 v26, v26, v63, s5
	v_add3_u32 v61, v170, v156, s5
	v_add3_u32 v9, v9, v158, s5
	v_add3_u32 v27, v27, v160, s5
	v_add3_u32 v28, v28, v184, s5
	v_add3_u32 v63, v172, v186, s5
	v_add3_u32 v29, v29, v188, s5
	v_add3_u32 v156, v174, v190, s5
	v_add3_u32 v30, v30, v192, s5
	v_add3_u32 v158, v176, v194, s5
	v_add3_u32 v11, v11, v196, s5
	v_add3_u32 v51, v51, v198, s5
	v_add3_u32 v36, v36, v205, s5
	v_add3_u32 v160, v178, v207, s5
	v_add3_u32 v37, v37, v209, s5
	v_add3_u32 v162, v180, v211, s5
	v_add3_u32 v38, v38, v213, s5
	v_add3_u32 v164, v182, v215, s5
	v_add3_u32 v13, v13, v217, s5
	v_and_or_b32 v16, v19, s6, v18
	v_and_or_b32 v18, v39, s6, v35
	v_and_or_b32 v19, v41, s6, v40
	v_and_or_b32 v20, v43, s6, v42
	v_lshrrev_b32_e32 v35, 16, v47
	v_lshrrev_b32_e32 v39, 16, v53
	v_lshrrev_b32_e32 v40, 16, v54
	v_lshrrev_b32_e32 v22, 16, v22
	v_lshrrev_b32_e32 v41, 16, v60
	v_lshrrev_b32_e32 v8, 16, v8
	v_lshrrev_b32_e32 v23, 16, v23
	v_lshrrev_b32_e32 v42, 16, v48
	v_lshrrev_b32_e32 v43, 16, v62
	v_lshrrev_b32_e32 v44, 16, v49
	v_lshrrev_b32_e32 v46, 16, v155
	v_lshrrev_b32_e32 v47, 16, v50
	v_lshrrev_b32_e32 v48, 16, v157
	v_lshrrev_b32_e32 v10, 16, v10
	v_lshrrev_b32_e32 v31, 16, v31
	v_lshrrev_b32_e32 v32, 16, v32
	v_lshrrev_b32_e32 v49, 16, v159
	v_lshrrev_b32_e32 v33, 16, v33
	v_lshrrev_b32_e32 v50, 16, v161
	v_lshrrev_b32_e32 v34, 16, v34
	v_lshrrev_b32_e32 v53, 16, v163
	v_lshrrev_b32_e32 v12, 16, v12
	ds_write2_b32 v4, v14, v15 offset1:68
	ds_write2_b32 v4, v16, v17 offset0:136 offset1:204
	ds_write2_b32 v56, v18, v19 offset0:16 offset1:84
	ds_write2_b32 v56, v20, v0 offset0:152 offset1:220
	v_and_or_b32 v0, v45, s6, v1
	v_and_or_b32 v1, v24, s6, v21
	v_and_or_b32 v4, v52, s6, v35
	v_and_or_b32 v14, v25, s6, v39
	v_and_or_b32 v15, v55, s6, v40
	v_and_or_b32 v16, v26, s6, v22
	v_and_or_b32 v17, v61, s6, v41
	v_and_or_b32 v8, v9, s6, v8
	v_and_or_b32 v9, v27, s6, v23
	v_and_or_b32 v18, v28, s6, v42
	v_and_or_b32 v19, v63, s6, v43
	v_and_or_b32 v20, v29, s6, v44
	v_and_or_b32 v21, v156, s6, v46
	v_and_or_b32 v22, v30, s6, v47
	v_and_or_b32 v23, v158, s6, v48
	v_and_or_b32 v10, v11, s6, v10
	v_and_or_b32 v11, v51, s6, v31
	v_and_or_b32 v24, v36, s6, v32
	v_and_or_b32 v25, v160, s6, v49
	v_and_or_b32 v26, v37, s6, v33
	v_and_or_b32 v27, v162, s6, v50
	v_and_or_b32 v28, v38, s6, v34
	v_and_or_b32 v29, v164, s6, v53
	v_and_or_b32 v12, v13, s6, v12
	ds_write2_b32 v5, v0, v1 offset1:68
	ds_write2_b32 v5, v4, v14 offset0:136 offset1:204
	ds_write2_b32 v57, v15, v16 offset0:16 offset1:84
	ds_write2_b32 v57, v17, v8 offset0:152 offset1:220
	ds_write2_b32 v6, v9, v18 offset1:68
	ds_write2_b32 v6, v19, v20 offset0:136 offset1:204
	ds_write2_b32 v58, v21, v22 offset0:16 offset1:84
	ds_write2_b32 v58, v23, v10 offset0:152 offset1:220
	ds_write2_b32 v7, v11, v24 offset1:68
	ds_write2_b32 v7, v25, v26 offset0:136 offset1:204
	ds_write2_b32 v59, v27, v28 offset0:16 offset1:84
	ds_write2_b32 v59, v29, v12 offset0:152 offset1:220
	s_cbranch_scc1 .LBB0_1051
	s_waitcnt lgkmcnt(0)
	global_load_dwordx4 v[4:7], v[68:69], off
	ds_read_b128 v[20:23], v154
	ds_read_b128 v[28:31], v154 offset:1088
	global_load_dwordx4 v[156:159], v[68:69], off offset:64
	ds_read_b128 v[48:51], v154 offset:64
	ds_read_b128 v[12:15], v154 offset:8704
	ds_read_b128 v[32:35], v154 offset:1152
	global_load_dwordx4 v[24:27], v[70:71], off
	ds_read_b128 v[8:11], v154 offset:8768
	ds_read_b128 v[16:19], v154 offset:9792
	ds_read_b128 v[0:3], v154 offset:9856
	s_lshl_b32 s11, s7, 4
	s_and_b32 s12, s11, 0xffffff80
	v_or_b32_e32 v222, s12, v139
	global_load_dwordx4 v[206:209], v[76:77], off
	v_ashrrev_i32_e32 v223, 31, v222
	s_add_i32 s7, s7, s36
	s_add_i32 s2, s2, s3
	s_cmpk_gt_i32 s7, 0xff
	s_waitcnt vmcnt(3) lgkmcnt(7)
	v_mfma_f32_16x16x32_bf16 v[36:39], v[20:23], v[4:7], 0
	s_waitcnt lgkmcnt(6)
	v_mfma_f32_16x16x32_bf16 v[160:163], v[28:31], v[4:7], 0
	s_waitcnt lgkmcnt(4)
	v_mfma_f32_16x16x32_bf16 v[164:167], v[12:15], v[4:7], 0
	s_waitcnt lgkmcnt(1)
	v_mfma_f32_16x16x32_bf16 v[168:171], v[16:19], v[4:7], 0
	global_load_dwordx4 v[4:7], v[72:73], off
	s_waitcnt vmcnt(2)
	v_mfma_f32_16x16x32_bf16 v[172:175], v[20:23], v[24:27], 0
	v_mfma_f32_16x16x32_bf16 v[176:179], v[28:31], v[24:27], 0
	v_mfma_f32_16x16x32_bf16 v[180:183], v[12:15], v[24:27], 0
	v_mfma_f32_16x16x32_bf16 v[184:187], v[16:19], v[24:27], 0
	global_load_dwordx4 v[24:27], v[74:75], off
	v_mfma_f32_16x16x32_bf16 v[210:213], v[48:51], v[156:159], v[36:39]
	v_mfma_f32_16x16x32_bf16 v[160:163], v[32:35], v[156:159], v[160:163]
	v_mfma_f32_16x16x32_bf16 v[164:167], v[8:11], v[156:159], v[164:167]
	s_waitcnt lgkmcnt(0)
	v_mfma_f32_16x16x32_bf16 v[156:159], v[0:3], v[156:159], v[168:171]
	s_waitcnt vmcnt(2)
; __device__ __forceinline__ unsigned pk2(float lo, float hi) { return f2bf(lo) | (f2bf(hi) << 16); }
; template <int HF>
; __device__ __forceinline__ void gmlp_half(LAS unsigned char* wl, const bf16* PROJ, const bf16* wsg, const float* norm_v, const float* b_s, bf16* Y, int tok0, int g, int fr, int fq) {
;     ...
;             for (int mi = 0; mi < 4; ++mi) acc[mi][nt] = __builtin_amdgcn_mfma_f32_16x16x32_bf16(av[mi], bw[ki][nt], acc[mi][nt], 0, 0, 0);
;     }
;     asm volatile("" ::: "memory");
;     f32x4 nv[2][2];
; #pragma unroll
;     for (int p = 0; p < 2; ++p) { nv[p][0] = *(const f32x4*)(norm_v + g * 64 + 32 * p + 8 * fq); nv[p][1] = *(const f32x4*)(norm_v + g * 64 + 32 * p + 8 * fq + 4); }
; #pragma unroll
;     for (int nt = 0; nt < 4; ++nt) {
;         const int t = 64 * HF + 16 * nt + fr; const size_t tok = (size_t)(tok0 + t); const float bs = b_s[g * 128 + t];
;         u32x4 uu[2];
; #pragma unroll
;         for (int p = 0; p < 2; ++p) uu[p] = *(const u32x4*)(PROJ + tok * NPROJ + g * 64 + 32 * p + 8 * fq);
; #pragma unroll
;         for (int p = 0; p < 2; ++p) {
;             u32x4 w;
; #pragma unroll
;             for (int e2 = 0; e2 < 2; ++e2) {
;                 const f32x4 z = nv[p][e2] * acc[2 * p + e2][nt] + bs;
;                 const unsigned u0 = uu[p][2 * e2], u1 = uu[p][2 * e2 + 1];
;                 w[2 * e2] = pk2(bf_lo(u0) * z[0], bf_hi(u0) * z[1]); w[2 * e2 + 1] = pk2(bf_lo(u1) * z[2], bf_hi(u1) * z[3]);
;             }
;             *(u32x4*)(Y + tok * D + g * 64 + 32 * p + 8 * fq) = w;
;         }
	v_mfma_f32_16x16x32_bf16 v[168:171], v[48:51], v[206:209], v[172:175]
	v_mfma_f32_16x16x32_bf16 v[172:175], v[32:35], v[206:209], v[176:179]
	v_mfma_f32_16x16x32_bf16 v[176:179], v[8:11], v[206:209], v[180:183]
	v_mfma_f32_16x16x32_bf16 v[180:183], v[0:3], v[206:209], v[184:187]
	s_waitcnt vmcnt(1)
	v_mfma_f32_16x16x32_bf16 v[188:191], v[20:23], v[4:7], 0
	v_mfma_f32_16x16x32_bf16 v[192:195], v[28:31], v[4:7], 0
	v_mfma_f32_16x16x32_bf16 v[196:199], v[12:15], v[4:7], 0
	v_mfma_f32_16x16x32_bf16 v[52:55], v[16:19], v[4:7], 0
	global_load_dwordx4 v[60:63], v[78:79], off
	global_load_dwordx4 v[4:7], v[80:81], off
	s_waitcnt vmcnt(2)
	v_mfma_f32_16x16x32_bf16 v[56:59], v[20:23], v[24:27], 0
	v_mad_i64_i32 v[20:21], s[20:21], v222, s4, v[82:83]
	global_load_dwordx4 v[214:217], v[20:21], off
	global_load_dwordx4 v[44:47], v[118:119], off offset:2048
	global_load_dword v224, v[120:121], off
	v_mfma_f32_16x16x32_bf16 v[40:43], v[28:31], v[24:27], 0
	global_load_dwordx4 v[36:39], v[118:119], off offset:2064
	global_load_dwordx4 v[28:31], v[118:119], off offset:2176
	global_load_dwordx4 v[218:221], v[20:21], off offset:64
	v_lshlrev_b64 v[222:223], 11, v[222:223]
	global_load_dwordx4 v[20:23], v[118:119], off offset:2192
	v_lshl_add_u64 v[222:223], v[84:85], 0, v[222:223]
	v_mfma_f32_16x16x32_bf16 v[12:15], v[12:15], v[24:27], 0
	s_waitcnt vmcnt(6)
	v_lshlrev_b32_e32 v227, 16, v215
	v_lshlrev_b32_e32 v226, 16, v214
	s_waitcnt vmcnt(4)
	v_pk_fma_f32 v[184:185], v[212:213], v[46:47], v[224:225] op_sel_hi:[1,1,0]
	v_pk_fma_f32 v[186:187], v[210:211], v[44:45], v[224:225] op_sel_hi:[1,1,0]
	s_waitcnt vmcnt(3)
	v_pk_fma_f32 v[162:163], v[162:163], v[38:39], v[224:225] op_sel_hi:[1,1,0]
	v_pk_fma_f32 v[160:161], v[160:161], v[36:37], v[224:225] op_sel_hi:[1,1,0]
	v_lshlrev_b32_e32 v229, 16, v217
	v_lshlrev_b32_e32 v228, 16, v216
	v_and_b32_e32 v217, 0xffff0000, v217
	v_and_b32_e32 v216, 0xffff0000, v216
	v_mov_b32_e32 v206, v186
	v_mov_b32_e32 v207, v184
	v_mov_b32_e32 v184, v187
	v_mov_b32_e32 v186, v160
	v_mov_b32_e32 v187, v162
	v_mov_b32_e32 v162, v161
	v_and_b32_e32 v215, 0xffff0000, v215
	v_and_b32_e32 v214, 0xffff0000, v214
	v_pk_mul_f32 v[160:161], v[206:207], v[226:227]
	v_pk_mul_f32 v[186:187], v[186:187], v[228:229]
	v_pk_mul_f32 v[162:163], v[162:163], v[216:217]
	v_pk_mul_f32 v[184:185], v[184:185], v[214:215]
	v_bfe_u32 v155, v163, 16, 1
	v_bfe_u32 v208, v160, 16, 1
	v_bfe_u32 v209, v161, 16, 1
	v_bfe_u32 v210, v186, 16, 1
	v_bfe_u32 v211, v187, 16, 1
	v_bfe_u32 v205, v162, 16, 1
	v_bfe_u32 v206, v185, 16, 1
	v_bfe_u32 v207, v184, 16, 1
	v_add3_u32 v155, v163, v155, s5
	v_add3_u32 v163, v187, v211, s5
	v_add3_u32 v186, v186, v210, s5
	v_add3_u32 v161, v161, v209, s5
	v_add3_u32 v160, v160, v208, s5
	v_add3_u32 v184, v184, v207, s5
	v_add3_u32 v185, v185, v206, s5
	v_add3_u32 v162, v162, v205, s5
	v_lshrrev_b32_e32 v160, 16, v160
	v_lshrrev_b32_e32 v161, 16, v161
	v_lshrrev_b32_e32 v186, 16, v186
	v_lshrrev_b32_e32 v163, 16, v163
	v_and_or_b32 v163, v155, s6, v163
	v_and_or_b32 v162, v162, s6, v186
	v_and_or_b32 v161, v185, s6, v161
	v_and_or_b32 v160, v184, s6, v160
	global_store_dwordx4 v[222:223], v[160:163], off
	s_waitcnt vmcnt(1)
	v_pk_fma_f32 v[158:159], v[158:159], v[22:23], v[224:225] op_sel_hi:[1,1,0]
	v_pk_fma_f32 v[156:157], v[156:157], v[20:21], v[224:225] op_sel_hi:[1,1,0]
	v_pk_fma_f32 v[160:161], v[166:167], v[30:31], v[224:225] op_sel_hi:[1,1,0]
	v_pk_fma_f32 v[162:163], v[164:165], v[28:29], v[224:225] op_sel_hi:[1,1,0]
	v_lshlrev_b32_e32 v165, 16, v219
	v_lshlrev_b32_e32 v164, 16, v218
	v_mov_b32_e32 v166, v162
	v_mov_b32_e32 v167, v160
	v_pk_mul_f32 v[164:165], v[166:167], v[164:165]
	v_and_b32_e32 v167, 0xffff0000, v219
	v_and_b32_e32 v166, 0xffff0000, v218
	v_mov_b32_e32 v160, v163
	v_pk_mul_f32 v[160:161], v[160:161], v[166:167]
	v_lshlrev_b32_e32 v163, 16, v221
	v_lshlrev_b32_e32 v162, 16, v220
	v_mov_b32_e32 v166, v156
	v_mov_b32_e32 v167, v158
	v_pk_mul_f32 v[162:163], v[166:167], v[162:163]
	v_and_b32_e32 v167, 0xffff0000, v221
	v_and_b32_e32 v166, 0xffff0000, v220
	v_mov_b32_e32 v158, v157
	v_pk_mul_f32 v[156:157], v[158:159], v[166:167]
	v_bfe_u32 v159, v161, 16, 1
	v_bfe_u32 v155, v157, 16, 1
	v_bfe_u32 v158, v156, 16, 1
	v_bfe_u32 v166, v160, 16, 1
	v_add3_u32 v160, v160, v166, s5
	v_add3_u32 v161, v161, v159, s5
	v_add3_u32 v156, v156, v158, s5
	v_add3_u32 v155, v157, v155, s5
	v_bfe_u32 v157, v164, 16, 1
	v_bfe_u32 v158, v165, 16, 1
	v_bfe_u32 v159, v162, 16, 1
	v_bfe_u32 v166, v163, 16, 1
	v_add3_u32 v163, v163, v166, s5
	v_add3_u32 v159, v162, v159, s5
	v_add3_u32 v158, v165, v158, s5
	v_add3_u32 v157, v164, v157, s5
	v_lshrrev_b32_e32 v162, 16, v157
	v_lshrrev_b32_e32 v157, 16, v158
	v_lshrrev_b32_e32 v158, 16, v159
	v_lshrrev_b32_e32 v159, 16, v163
	v_and_or_b32 v159, v155, s6, v159
	v_and_or_b32 v158, v156, s6, v158
	v_and_or_b32 v157, v161, s6, v157
	v_and_or_b32 v156, v160, s6, v162
	global_store_dwordx4 v[222:223], v[156:159], off offset:64
	v_or_b32_e32 v206, s12, v142
	global_load_dword v208, v[122:123], off
	v_mad_i64_i32 v[164:165], s[20:21], v206, s4, v[82:83]
	global_load_dwordx4 v[156:159], v[164:165], off
	v_ashrrev_i32_e32 v207, 31, v206
	global_load_dwordx4 v[164:167], v[164:165], off offset:64
	v_mfma_f32_16x16x32_bf16 v[160:163], v[48:51], v[60:63], v[188:191]
	v_or_b32_e32 v218, s12, v145
	v_ashrrev_i32_e32 v219, 31, v218
	s_waitcnt vmcnt(2)
; __device__ __forceinline__ unsigned pk2(float lo, float hi) { return f2bf(lo) | (f2bf(hi) << 16); }
; template <int HF>
; __device__ __forceinline__ void gmlp_half(LAS unsigned char* wl, const bf16* PROJ, const bf16* wsg, const float* norm_v, const float* b_s, bf16* Y, int tok0, int g, int fr, int fq) {
;     ...
;     for (int nt = 0; nt < 4; ++nt) {
;         const int t = 64 * HF + 16 * nt + fr; const size_t tok = (size_t)(tok0 + t); const float bs = b_s[g * 128 + t];
;         u32x4 uu[2];
; #pragma unroll
;         for (int p = 0; p < 2; ++p) uu[p] = *(const u32x4*)(PROJ + tok * NPROJ + g * 64 + 32 * p + 8 * fq);
; #pragma unroll
;         for (int p = 0; p < 2; ++p) {
;             u32x4 w;
; #pragma unroll
;             for (int e2 = 0; e2 < 2; ++e2) {
;                 const f32x4 z = nv[p][e2] * acc[2 * p + e2][nt] + bs;
;                 const unsigned u0 = uu[p][2 * e2], u1 = uu[p][2 * e2 + 1];
;                 w[2 * e2] = pk2(bf_lo(u0) * z[0], bf_hi(u0) * z[1]); w[2 * e2 + 1] = pk2(bf_lo(u1) * z[2], bf_hi(u1) * z[3]);
;             }
;             *(u32x4*)(Y + tok * D + g * 64 + 32 * p + 8 * fq) = w;
;         }
	v_pk_fma_f32 v[170:171], v[170:171], v[46:47], v[208:209] op_sel_hi:[1,1,0]
	v_lshlrev_b64 v[188:189], 11, v[206:207]
	v_pk_fma_f32 v[168:169], v[168:169], v[44:45], v[208:209] op_sel_hi:[1,1,0]
	v_pk_fma_f32 v[174:175], v[174:175], v[38:39], v[208:209] op_sel_hi:[1,1,0]
	v_pk_fma_f32 v[172:173], v[172:173], v[36:37], v[208:209] op_sel_hi:[1,1,0]
	v_mfma_f32_16x16x32_bf16 v[184:187], v[32:35], v[60:63], v[192:195]
	s_nop 2
	v_lshl_add_u64 v[192:193], v[84:85], 0, v[188:189]
	v_mfma_f32_16x16x32_bf16 v[188:191], v[8:11], v[60:63], v[196:199]
	s_waitcnt vmcnt(1)
	v_lshlrev_b32_e32 v195, 16, v157
	v_lshlrev_b32_e32 v194, 16, v156
	v_and_b32_e32 v157, 0xffff0000, v157
	v_and_b32_e32 v156, 0xffff0000, v156
	v_lshlrev_b32_e32 v197, 16, v159
	v_lshlrev_b32_e32 v196, 16, v158
	v_and_b32_e32 v159, 0xffff0000, v159
	v_mov_b32_e32 v199, v170
	v_mov_b32_e32 v170, v169
	v_mov_b32_e32 v169, v174
	v_and_b32_e32 v158, 0xffff0000, v158
	v_mov_b32_e32 v174, v173
	v_mov_b32_e32 v198, v168
	v_mov_b32_e32 v168, v172
	v_pk_mul_f32 v[156:157], v[170:171], v[156:157]
	v_pk_mul_f32 v[158:159], v[174:175], v[158:159]
	v_pk_mul_f32 v[194:195], v[198:199], v[194:195]
	v_pk_mul_f32 v[168:169], v[168:169], v[196:197]
	v_bfe_u32 v155, v159, 16, 1
	v_bfe_u32 v170, v158, 16, 1
	v_bfe_u32 v171, v157, 16, 1
	v_bfe_u32 v172, v156, 16, 1
	v_add3_u32 v156, v156, v172, s5
	v_add3_u32 v157, v157, v171, s5
	v_add3_u32 v158, v158, v170, s5
	v_add3_u32 v155, v159, v155, s5
	v_bfe_u32 v159, v194, 16, 1
	v_bfe_u32 v170, v195, 16, 1
	v_bfe_u32 v171, v168, 16, 1
	v_bfe_u32 v172, v169, 16, 1
	v_add3_u32 v169, v169, v172, s5
	v_add3_u32 v168, v168, v171, s5
	v_add3_u32 v170, v195, v170, s5
	v_add3_u32 v159, v194, v159, s5
	v_lshrrev_b32_e32 v171, 16, v159
	v_lshrrev_b32_e32 v170, 16, v170
	v_lshrrev_b32_e32 v168, 16, v168
	v_lshrrev_b32_e32 v159, 16, v169
	v_and_or_b32 v159, v155, s6, v159
	v_and_or_b32 v158, v158, s6, v168
	v_and_or_b32 v157, v157, s6, v170
	v_and_or_b32 v156, v156, s6, v171
	global_store_dwordx4 v[192:193], v[156:159], off
	s_waitcnt vmcnt(1)
	v_lshlrev_b32_e32 v169, 16, v165
	v_lshlrev_b32_e32 v168, 16, v164
	v_pk_fma_f32 v[156:157], v[178:179], v[30:31], v[208:209] op_sel_hi:[1,1,0]
	v_pk_fma_f32 v[158:159], v[176:177], v[28:29], v[208:209] op_sel_hi:[1,1,0]
	v_mov_b32_e32 v171, v156
	v_and_b32_e32 v165, 0xffff0000, v165
	v_and_b32_e32 v164, 0xffff0000, v164
	v_mov_b32_e32 v156, v159
	v_mov_b32_e32 v170, v158
	v_pk_mul_f32 v[156:157], v[156:157], v[164:165]
	v_pk_fma_f32 v[158:159], v[182:183], v[22:23], v[208:209] op_sel_hi:[1,1,0]
	v_pk_fma_f32 v[164:165], v[180:181], v[20:21], v[208:209] op_sel_hi:[1,1,0]
	v_pk_mul_f32 v[168:169], v[170:171], v[168:169]
	v_lshlrev_b32_e32 v171, 16, v167
	v_lshlrev_b32_e32 v170, 16, v166
	v_mov_b32_e32 v173, v158
	v_and_b32_e32 v167, 0xffff0000, v167
	v_and_b32_e32 v166, 0xffff0000, v166
	v_mov_b32_e32 v158, v165
	v_mov_b32_e32 v172, v164
	v_pk_mul_f32 v[158:159], v[158:159], v[166:167]
	v_pk_mul_f32 v[170:171], v[172:173], v[170:171]
	v_bfe_u32 v155, v159, 16, 1
	v_bfe_u32 v164, v158, 16, 1
	v_bfe_u32 v165, v157, 16, 1
	v_bfe_u32 v166, v156, 16, 1
	v_add3_u32 v156, v156, v166, s5
	v_add3_u32 v157, v157, v165, s5
	v_add3_u32 v158, v158, v164, s5
	v_add3_u32 v155, v159, v155, s5
	v_bfe_u32 v159, v168, 16, 1
	v_bfe_u32 v164, v169, 16, 1
	v_bfe_u32 v165, v170, 16, 1
	v_bfe_u32 v166, v171, 16, 1
	v_add3_u32 v166, v171, v166, s5
	v_add3_u32 v165, v170, v165, s5
	v_add3_u32 v164, v169, v164, s5
	v_add3_u32 v159, v168, v159, s5
	v_lshrrev_b32_e32 v167, 16, v159
	v_lshrrev_b32_e32 v164, 16, v164
	v_lshrrev_b32_e32 v165, 16, v165
	v_lshrrev_b32_e32 v159, 16, v166
	v_and_or_b32 v159, v155, s6, v159
	v_and_or_b32 v158, v158, s6, v165
	v_and_or_b32 v157, v157, s6, v164
	v_and_or_b32 v156, v156, s6, v167
	global_store_dwordx4 v[192:193], v[156:159], off offset:64
	v_or_b32_e32 v164, s12, v143
	global_load_dword v166, v[124:125], off
	v_mad_i64_i32 v[168:169], s[20:21], v164, s4, v[82:83]
	global_load_dwordx4 v[156:159], v[168:169], off
	v_mfma_f32_16x16x32_bf16 v[52:55], v[0:3], v[60:63], v[52:55]
	global_load_dwordx4 v[60:63], v[168:169], off offset:64
	v_ashrrev_i32_e32 v165, 31, v164
	v_mfma_f32_16x16x32_bf16 v[48:51], v[48:51], v[4:7], v[56:59]
	s_nop 2
	v_lshlrev_b64 v[56:57], 11, v[164:165]
	v_lshl_add_u64 v[164:165], v[84:85], 0, v[56:57]
	v_mfma_f32_16x16x32_bf16 v[32:35], v[32:35], v[4:7], v[40:43]
	s_waitcnt vmcnt(2)
	v_pk_fma_f32 v[56:57], v[162:163], v[46:47], v[166:167] op_sel_hi:[1,1,0]
	v_pk_fma_f32 v[58:59], v[160:161], v[44:45], v[166:167] op_sel_hi:[1,1,0]
	v_mov_b32_e32 v163, v56
	s_waitcnt vmcnt(1)
	v_lshlrev_b32_e32 v161, 16, v157
	v_lshlrev_b32_e32 v160, 16, v156
	v_and_b32_e32 v157, 0xffff0000, v157
	v_and_b32_e32 v156, 0xffff0000, v156
	v_mov_b32_e32 v56, v59
	v_mov_b32_e32 v162, v58
	v_pk_mul_f32 v[56:57], v[56:57], v[156:157]
	v_pk_fma_f32 v[58:59], v[186:187], v[38:39], v[166:167] op_sel_hi:[1,1,0]
	v_pk_fma_f32 v[156:157], v[184:185], v[36:37], v[166:167] op_sel_hi:[1,1,0]
	v_pk_mul_f32 v[160:161], v[162:163], v[160:161]
	v_lshlrev_b32_e32 v163, 16, v159
	v_lshlrev_b32_e32 v162, 16, v158
	v_mov_b32_e32 v169, v58
	v_and_b32_e32 v159, 0xffff0000, v159
	v_and_b32_e32 v158, 0xffff0000, v158
	v_mov_b32_e32 v58, v157
	v_mov_b32_e32 v168, v156
	v_pk_mul_f32 v[58:59], v[58:59], v[158:159]
	v_pk_mul_f32 v[162:163], v[168:169], v[162:163]
	v_bfe_u32 v155, v59, 16, 1
	v_bfe_u32 v156, v58, 16, 1
	v_bfe_u32 v157, v57, 16, 1
	v_bfe_u32 v158, v56, 16, 1
	v_add3_u32 v56, v56, v158, s5
	v_add3_u32 v57, v57, v157, s5
	v_add3_u32 v58, v58, v156, s5
	v_add3_u32 v59, v59, v155, s5
	v_bfe_u32 v155, v160, 16, 1
	v_bfe_u32 v156, v161, 16, 1
	v_bfe_u32 v157, v162, 16, 1
	v_bfe_u32 v158, v163, 16, 1
	v_add3_u32 v158, v163, v158, s5
	v_add3_u32 v157, v162, v157, s5
	v_add3_u32 v156, v161, v156, s5
	v_add3_u32 v155, v160, v155, s5
	v_lshrrev_b32_e32 v155, 16, v155
	v_lshrrev_b32_e32 v156, 16, v156
	v_lshrrev_b32_e32 v157, 16, v157
	v_lshrrev_b32_e32 v158, 16, v158
	v_and_or_b32 v59, v59, s6, v158
	v_and_or_b32 v58, v58, s6, v157
	v_and_or_b32 v57, v57, s6, v156
	v_and_or_b32 v56, v56, s6, v155
	global_store_dwordx4 v[164:165], v[56:59], off
	s_waitcnt vmcnt(1)
; #define LAS __attribute__((address_space(3)))
; __device__ __forceinline__ unsigned pk2(float lo, float hi) { return f2bf(lo) | (f2bf(hi) << 16); }
; template <int HF>
; __device__ __forceinline__ void gmlp_half(LAS unsigned char* wl, const bf16* PROJ, const bf16* wsg, const float* norm_v, const float* b_s, bf16* Y, int tok0, int g, int fr, int fq) {
;     ...
; #pragma unroll
;     for (int ki = 0; ki < NK; ++ki)
; #pragma unroll
;         for (int nt = 0; nt < 4; ++nt) bw[ki][nt] = *(const bf16x8*)(wsg + (size_t)(64 * HF + 16 * nt + fr) * 128 + 32 * ki + 8 * fq);
;     f32x4 acc[4][4];
; #pragma unroll
;     for (int i = 0; i < 4; ++i)
; #pragma unroll
;         for (int j = 0; j < 4; ++j) acc[i][j] = (f32x4){0.f, 0.f, 0.f, 0.f};
; #pragma unroll
;     for (int ki = 0; ki < NK; ++ki) {
;         bf16x8 av[4];
; #pragma unroll
;         for (int mi = 0; mi < 4; ++mi) av[mi] = *(const LAS bf16x8*)(wl + ((32 * (mi >> 1) + 8 * (fr >> 2) + 4 * (mi & 1) + (fr & 3)) * VS + 32 * ki + 8 * fq) * 2);
;     ...
;     for (int nt = 0; nt < 4; ++nt) {
;         const int t = 64 * HF + 16 * nt + fr; const size_t tok = (size_t)(tok0 + t); const float bs = b_s[g * 128 + t];
;         u32x4 uu[2];
; #pragma unroll
;         for (int p = 0; p < 2; ++p) uu[p] = *(const u32x4*)(PROJ + tok * NPROJ + g * 64 + 32 * p + 8 * fq);
; #pragma unroll
;         for (int p = 0; p < 2; ++p) {
;             u32x4 w;
; #pragma unroll
;             for (int e2 = 0; e2 < 2; ++e2) {
;                 const f32x4 z = nv[p][e2] * acc[2 * p + e2][nt] + bs;
;                 const unsigned u0 = uu[p][2 * e2], u1 = uu[p][2 * e2 + 1];
;                 w[2 * e2] = pk2(bf_lo(u0) * z[0], bf_hi(u0) * z[1]); w[2 * e2 + 1] = pk2(bf_lo(u1) * z[2], bf_hi(u1) * z[3]);
;             }
;             *(u32x4*)(Y + tok * D + g * 64 + 32 * p + 8 * fq) = w;
;         }
	v_lshlrev_b32_e32 v157, 16, v61
	v_lshlrev_b32_e32 v156, 16, v60
	v_pk_fma_f32 v[56:57], v[190:191], v[30:31], v[166:167] op_sel_hi:[1,1,0]
	v_pk_fma_f32 v[58:59], v[188:189], v[28:29], v[166:167] op_sel_hi:[1,1,0]
	v_mov_b32_e32 v159, v56
	v_and_b32_e32 v61, 0xffff0000, v61
	v_and_b32_e32 v60, 0xffff0000, v60
	v_mov_b32_e32 v56, v59
	v_pk_fma_f32 v[54:55], v[54:55], v[22:23], v[166:167] op_sel_hi:[1,1,0]
	v_pk_fma_f32 v[52:53], v[52:53], v[20:21], v[166:167] op_sel_hi:[1,1,0]
	v_mov_b32_e32 v158, v58
	v_pk_mul_f32 v[56:57], v[56:57], v[60:61]
	v_lshlrev_b32_e32 v59, 16, v63
	v_lshlrev_b32_e32 v58, 16, v62
	v_mov_b32_e32 v60, v52
	v_mov_b32_e32 v61, v54
	v_pk_mul_f32 v[58:59], v[60:61], v[58:59]
	v_and_b32_e32 v61, 0xffff0000, v63
	v_and_b32_e32 v60, 0xffff0000, v62
	v_mov_b32_e32 v54, v53
	v_pk_mul_f32 v[52:53], v[54:55], v[60:61]
	v_pk_mul_f32 v[156:157], v[158:159], v[156:157]
	v_bfe_u32 v54, v53, 16, 1
	v_bfe_u32 v55, v52, 16, 1
	v_bfe_u32 v60, v57, 16, 1
	v_bfe_u32 v61, v56, 16, 1
	v_add3_u32 v56, v56, v61, s5
	v_add3_u32 v57, v57, v60, s5
	v_add3_u32 v52, v52, v55, s5
	v_add3_u32 v53, v53, v54, s5
	v_bfe_u32 v54, v156, 16, 1
	v_bfe_u32 v55, v157, 16, 1
	v_bfe_u32 v60, v58, 16, 1
	v_bfe_u32 v61, v59, 16, 1
	v_add3_u32 v59, v59, v61, s5
	v_add3_u32 v58, v58, v60, s5
	v_add3_u32 v55, v157, v55, s5
	v_add3_u32 v54, v156, v54, s5
	v_lshrrev_b32_e32 v60, 16, v54
	v_lshrrev_b32_e32 v61, 16, v55
	v_lshrrev_b32_e32 v54, 16, v58
	v_lshrrev_b32_e32 v55, 16, v59
	v_and_or_b32 v55, v53, s6, v55
	v_and_or_b32 v54, v52, s6, v54
	v_and_or_b32 v53, v57, s6, v61
	v_and_or_b32 v52, v56, s6, v60
	global_store_dwordx4 v[164:165], v[52:55], off offset:64
	v_or_b32_e32 v56, s12, v202
	global_load_dword v160, v[126:127], off
	v_mad_i64_i32 v[58:59], s[20:21], v56, s4, v[82:83]
	global_load_dwordx4 v[52:55], v[58:59], off
	global_load_dwordx4 v[40:43], v[58:59], off offset:64
	v_ashrrev_i32_e32 v57, 31, v56
	v_lshlrev_b64 v[56:57], 11, v[56:57]
	v_lshl_add_u64 v[180:181], v[84:85], 0, v[56:57]
	v_mfma_f32_16x16x32_bf16 v[16:19], v[16:19], v[24:27], 0
	s_waitcnt vmcnt(2)
	v_pk_fma_f32 v[46:47], v[50:51], v[46:47], v[160:161] op_sel_hi:[1,1,0]
	v_pk_fma_f32 v[44:45], v[48:49], v[44:45], v[160:161] op_sel_hi:[1,1,0]
	v_pk_fma_f32 v[34:35], v[34:35], v[38:39], v[160:161] op_sel_hi:[1,1,0]
	v_pk_fma_f32 v[32:33], v[32:33], v[36:37], v[160:161] op_sel_hi:[1,1,0]
	s_waitcnt vmcnt(1)
	v_lshlrev_b32_e32 v49, 16, v53
	v_lshlrev_b32_e32 v48, 16, v52
	v_mov_b32_e32 v50, v44
	v_mov_b32_e32 v51, v46
	v_lshlrev_b32_e32 v37, 16, v55
	v_lshlrev_b32_e32 v36, 16, v54
	v_mov_b32_e32 v38, v32
	v_mov_b32_e32 v39, v34
	v_pk_mul_f32 v[48:49], v[50:51], v[48:49]
	v_and_b32_e32 v51, 0xffff0000, v53
	v_and_b32_e32 v50, 0xffff0000, v52
	v_mov_b32_e32 v46, v45
	v_pk_mul_f32 v[36:37], v[38:39], v[36:37]
	v_and_b32_e32 v39, 0xffff0000, v55
	v_and_b32_e32 v38, 0xffff0000, v54
	v_mov_b32_e32 v34, v33
	v_pk_mul_f32 v[44:45], v[46:47], v[50:51]
	v_pk_mul_f32 v[32:33], v[34:35], v[38:39]
	v_bfe_u32 v38, v45, 16, 1
	v_bfe_u32 v34, v33, 16, 1
	v_bfe_u32 v35, v32, 16, 1
	v_bfe_u32 v39, v44, 16, 1
	v_add3_u32 v39, v44, v39, s5
	v_add3_u32 v38, v45, v38, s5
	v_add3_u32 v32, v32, v35, s5
	v_add3_u32 v33, v33, v34, s5
	v_bfe_u32 v34, v48, 16, 1
	v_bfe_u32 v35, v49, 16, 1
	v_bfe_u32 v44, v36, 16, 1
	v_bfe_u32 v45, v37, 16, 1
	v_add3_u32 v37, v37, v45, s5
	v_add3_u32 v36, v36, v44, s5
	v_add3_u32 v35, v49, v35, s5
	v_add3_u32 v34, v48, v34, s5
	v_lshrrev_b32_e32 v44, 16, v34
	v_lshrrev_b32_e32 v45, 16, v35
	v_lshrrev_b32_e32 v34, 16, v36
	v_lshrrev_b32_e32 v35, 16, v37
	v_and_or_b32 v35, v33, s6, v35
	v_and_or_b32 v34, v32, s6, v34
	v_and_or_b32 v33, v38, s6, v45
	v_and_or_b32 v32, v39, s6, v44
	global_store_dwordx4 v[180:181], v[32:35], off
	global_load_dwordx4 v[32:35], v[86:87], off
	s_nop 0
	global_load_dwordx4 v[36:39], v[88:89], off
	global_load_dwordx4 v[44:47], v[90:91], off
	global_load_dwordx4 v[24:27], v[92:93], off
	v_mfma_f32_16x16x32_bf16 v[8:11], v[8:11], v[4:7], v[12:15]
	ds_read_b128 v[48:51], v154 offset:8704
	ds_read_b128 v[52:55], v154 offset:9792
	s_nop 0
	ds_read_b128 v[12:15], v154
	ds_read_b128 v[56:59], v154 offset:64
	ds_read_b128 v[60:63], v154 offset:1088
	ds_read_b128 v[156:159], v154 offset:1152
	s_nop 0
	v_pk_fma_f32 v[8:9], v[8:9], v[28:29], v[160:161] op_sel_hi:[1,1,0]
	v_mfma_f32_16x16x32_bf16 v[0:3], v[0:3], v[4:7], v[16:19]
	v_mov_b32_e32 v28, v8
	s_nop 1
	v_pk_fma_f32 v[16:17], v[10:11], v[30:31], v[160:161] op_sel_hi:[1,1,0]
	s_waitcnt vmcnt(5)
	v_lshlrev_b32_e32 v11, 16, v41
	s_nop 1
	v_pk_fma_f32 v[162:163], v[2:3], v[22:23], v[160:161] op_sel_hi:[1,1,0]
	v_pk_fma_f32 v[160:161], v[0:1], v[20:21], v[160:161] op_sel_hi:[1,1,0]
	v_lshlrev_b32_e32 v10, 16, v40
	v_and_b32_e32 v19, 0xffff0000, v41
	v_and_b32_e32 v18, 0xffff0000, v40
	v_mov_b32_e32 v29, v16
	v_lshlrev_b32_e32 v41, 16, v43
	v_lshlrev_b32_e32 v40, 16, v42
	v_mov_b32_e32 v166, v160
	v_mov_b32_e32 v167, v162
	v_mov_b32_e32 v16, v9
	v_pk_mul_f32 v[176:177], v[28:29], v[10:11]
	v_pk_mul_f32 v[178:179], v[166:167], v[40:41]
	v_and_b32_e32 v167, 0xffff0000, v43
	v_and_b32_e32 v166, 0xffff0000, v42
	v_mov_b32_e32 v162, v161
	v_pk_mul_f32 v[164:165], v[16:17], v[18:19]
	v_pk_mul_f32 v[168:169], v[162:163], v[166:167]
	v_bfe_u32 v185, v176, 16, 1
	v_bfe_u32 v186, v177, 16, 1
	v_bfe_u32 v187, v178, 16, 1
	v_bfe_u32 v172, v179, 16, 1
	v_bfe_u32 v155, v169, 16, 1
	v_bfe_u32 v166, v168, 16, 1
	v_bfe_u32 v167, v165, 16, 1
	v_bfe_u32 v170, v164, 16, 1
	v_add3_u32 v179, v179, v172, s5
	v_add3_u32 v178, v178, v187, s5
	v_add3_u32 v177, v177, v186, s5
	v_add3_u32 v176, v176, v185, s5
	v_add3_u32 v182, v164, v170, s5
	v_add3_u32 v183, v165, v167, s5
	v_add3_u32 v184, v168, v166, s5
	v_add3_u32 v155, v169, v155, s5
	v_lshrrev_b32_e32 v176, 16, v176
	v_lshrrev_b32_e32 v177, 16, v177
	v_lshrrev_b32_e32 v178, 16, v178
	v_lshrrev_b32_e32 v179, 16, v179
	v_and_or_b32 v179, v155, s6, v179
	v_and_or_b32 v178, v184, s6, v178
	v_and_or_b32 v177, v183, s6, v177
	v_and_or_b32 v176, v182, s6, v176
	global_store_dwordx4 v[180:181], v[176:179], off offset:64
	s_waitcnt vmcnt(4) lgkmcnt(3)
; #define LAS __attribute__((address_space(3)))
; template <int HF>
; __device__ __forceinline__ void gmlp_half(LAS unsigned char* wl, const bf16* PROJ, const bf16* wsg, const float* norm_v, const float* b_s, bf16* Y, int tok0, int g, int fr, int fq) {
;     ...
; #pragma unroll
;     for (int ki = 0; ki < NK; ++ki)
; #pragma unroll
;         for (int nt = 0; nt < 4; ++nt) bw[ki][nt] = *(const bf16x8*)(wsg + (size_t)(64 * HF + 16 * nt + fr) * 128 + 32 * ki + 8 * fq);
;     f32x4 acc[4][4];
; #pragma unroll
;     for (int i = 0; i < 4; ++i)
; #pragma unroll
;         for (int j = 0; j < 4; ++j) acc[i][j] = (f32x4){0.f, 0.f, 0.f, 0.f};
; #pragma unroll
;     for (int ki = 0; ki < NK; ++ki) {
;         bf16x8 av[4];
; #pragma unroll
;         for (int mi = 0; mi < 4; ++mi) av[mi] = *(const LAS bf16x8*)(wl + ((32 * (mi >> 1) + 8 * (fr >> 2) + 4 * (mi & 1) + (fr & 3)) * VS + 32 * ki + 8 * fq) * 2);
; #pragma unroll
;         for (int nt = 0; nt < 4; ++nt)
; #pragma unroll
;             for (int mi = 0; mi < 4; ++mi) acc[mi][nt] = __builtin_amdgcn_mfma_f32_16x16x32_bf16(av[mi], bw[ki][nt], acc[mi][nt], 0, 0, 0);
;     }
;     asm volatile("" ::: "memory");
;     f32x4 nv[2][2];
; #pragma unroll
;     for (int p = 0; p < 2; ++p) { nv[p][0] = *(const f32x4*)(norm_v + g * 64 + 32 * p + 8 * fq); nv[p][1] = *(const f32x4*)(norm_v + g * 64 + 32 * p + 8 * fq + 4); }
	v_mfma_f32_16x16x32_bf16 v[4:7], v[12:15], v[32:35], 0
	global_load_dwordx4 v[176:179], v[94:95], off
	ds_read_b128 v[16:19], v154 offset:8768
	ds_read_b128 v[0:3], v154 offset:9856
	s_waitcnt lgkmcnt(3)
	v_mfma_f32_16x16x32_bf16 v[8:11], v[60:63], v[32:35], 0
	v_mfma_f32_16x16x32_bf16 v[28:31], v[48:51], v[32:35], 0
	v_mfma_f32_16x16x32_bf16 v[20:23], v[52:55], v[32:35], 0
	s_waitcnt vmcnt(4)
	v_mfma_f32_16x16x32_bf16 v[32:35], v[12:15], v[36:39], 0
	v_mfma_f32_16x16x32_bf16 v[40:43], v[60:63], v[36:39], 0
	v_mfma_f32_16x16x32_bf16 v[160:163], v[48:51], v[36:39], 0
	v_mfma_f32_16x16x32_bf16 v[36:39], v[52:55], v[36:39], 0
	s_waitcnt vmcnt(3)
	v_mfma_f32_16x16x32_bf16 v[164:167], v[12:15], v[44:47], 0
	v_mfma_f32_16x16x32_bf16 v[168:171], v[60:63], v[44:47], 0
	v_mfma_f32_16x16x32_bf16 v[172:175], v[48:51], v[44:47], 0
	v_mfma_f32_16x16x32_bf16 v[44:47], v[52:55], v[44:47], 0
	s_waitcnt vmcnt(2)
	v_mfma_f32_16x16x32_bf16 v[12:15], v[12:15], v[24:27], 0
	v_mfma_f32_16x16x32_bf16 v[60:63], v[60:63], v[24:27], 0
	v_mfma_f32_16x16x32_bf16 v[48:51], v[48:51], v[24:27], 0
	v_mfma_f32_16x16x32_bf16 v[24:27], v[52:55], v[24:27], 0
	global_load_dwordx4 v[52:55], v[96:97], off
	s_waitcnt vmcnt(1)
	v_mfma_f32_16x16x32_bf16 v[4:7], v[56:59], v[176:179], v[4:7]
	s_waitcnt lgkmcnt(2)
	v_mfma_f32_16x16x32_bf16 v[8:11], v[156:159], v[176:179], v[8:11]
	s_waitcnt lgkmcnt(1)
	v_mfma_f32_16x16x32_bf16 v[28:31], v[16:19], v[176:179], v[28:31]
	s_waitcnt lgkmcnt(0)
	v_mfma_f32_16x16x32_bf16 v[20:23], v[0:3], v[176:179], v[20:23]
	s_waitcnt vmcnt(0)
	v_mfma_f32_16x16x32_bf16 v[32:35], v[56:59], v[52:55], v[32:35]
	v_mfma_f32_16x16x32_bf16 v[176:179], v[156:159], v[52:55], v[40:43]
	v_mfma_f32_16x16x32_bf16 v[160:163], v[16:19], v[52:55], v[160:163]
	s_nop 1
	global_load_dwordx4 v[40:43], v[98:99], off
	v_mfma_f32_16x16x32_bf16 v[52:55], v[0:3], v[52:55], v[36:39]
	s_nop 2
	global_load_dwordx4 v[36:39], v[100:101], off
	s_waitcnt vmcnt(1)
	v_mfma_f32_16x16x32_bf16 v[168:171], v[156:159], v[40:43], v[168:171]
	s_waitcnt vmcnt(0)
	v_mfma_f32_16x16x32_bf16 v[60:63], v[156:159], v[36:39], v[60:63]
	global_load_dwordx4 v[156:159], v[102:103], off
	v_mfma_f32_16x16x32_bf16 v[164:167], v[56:59], v[40:43], v[164:167]
	v_mfma_f32_16x16x32_bf16 v[172:175], v[16:19], v[40:43], v[172:175]
	v_mfma_f32_16x16x32_bf16 v[44:47], v[0:3], v[40:43], v[44:47]
	v_mfma_f32_16x16x32_bf16 v[56:59], v[56:59], v[36:39], v[12:15]
	v_mfma_f32_16x16x32_bf16 v[16:19], v[16:19], v[36:39], v[48:51]
	s_nop 2
	global_load_dwordx4 v[48:51], v[104:105], off
	v_mfma_f32_16x16x32_bf16 v[0:3], v[0:3], v[36:39], v[24:27]
	s_nop 2
	ds_read_b128 v[24:27], v154 offset:128
	ds_read_b128 v[36:39], v154 offset:192
	ds_read_b128 v[180:183], v154 offset:1216
	ds_read_b128 v[40:43], v154 offset:1280
	s_waitcnt vmcnt(1) lgkmcnt(1)
	v_mfma_f32_16x16x32_bf16 v[184:187], v[180:183], v[156:159], v[8:11]
	ds_read_b128 v[188:191], v154 offset:8832
	s_nop 1
	ds_read_b128 v[8:11], v154 offset:8896
	ds_read_b128 v[192:195], v154 offset:9920
	ds_read_b128 v[12:15], v154 offset:9984
	global_load_dwordx4 v[196:199], v[108:109], off
	v_mfma_f32_16x16x32_bf16 v[4:7], v[24:27], v[156:159], v[4:7]
	s_waitcnt lgkmcnt(3)
	v_mfma_f32_16x16x32_bf16 v[28:31], v[188:191], v[156:159], v[28:31]
	s_waitcnt lgkmcnt(1)
	v_mfma_f32_16x16x32_bf16 v[156:159], v[192:195], v[156:159], v[20:23]
	s_nop 2
	global_load_dwordx4 v[20:23], v[106:107], off
	s_waitcnt vmcnt(2)
	v_mfma_f32_16x16x32_bf16 v[32:35], v[24:27], v[48:51], v[32:35]
	v_mfma_f32_16x16x32_bf16 v[176:179], v[180:183], v[48:51], v[176:179]
	v_mfma_f32_16x16x32_bf16 v[160:163], v[188:191], v[48:51], v[160:163]
	v_mfma_f32_16x16x32_bf16 v[52:55], v[192:195], v[48:51], v[52:55]
	s_waitcnt vmcnt(0)
	v_mfma_f32_16x16x32_bf16 v[164:167], v[24:27], v[20:23], v[164:167]
	v_mfma_f32_16x16x32_bf16 v[48:51], v[24:27], v[196:199], v[56:59]
	global_load_dwordx4 v[24:27], v[110:111], off
	v_mfma_f32_16x16x32_bf16 v[168:171], v[180:183], v[20:23], v[168:171]
	s_nop 0
	v_mad_i64_i32 v[56:57], s[20:21], v218, s4, v[82:83]
	v_mfma_f32_16x16x32_bf16 v[172:175], v[188:191], v[20:23], v[172:175]
	v_mfma_f32_16x16x32_bf16 v[206:209], v[192:195], v[20:23], v[44:47]
	v_mfma_f32_16x16x32_bf16 v[20:23], v[192:195], v[196:199], v[0:3]
	s_nop 2
	global_load_dwordx4 v[0:3], v[112:113], off
	v_mfma_f32_16x16x32_bf16 v[44:47], v[180:183], v[196:199], v[60:63]
	v_mfma_f32_16x16x32_bf16 v[16:19], v[188:191], v[196:199], v[16:19]
	s_waitcnt vmcnt(1)
	v_mfma_f32_16x16x32_bf16 v[188:191], v[8:11], v[24:27], v[28:31]
	global_load_dwordx4 v[196:199], v[114:115], off
	s_nop 1
	global_load_dwordx4 v[28:31], v[116:117], off
	global_load_dword v220, v[128:129], off
	s_waitcnt vmcnt(3)
	v_mfma_f32_16x16x32_bf16 v[192:195], v[36:39], v[0:3], v[32:35]
	s_nop 2
	global_load_dwordx4 v[32:35], v[118:119], off offset:2048
	global_load_dwordx4 v[210:213], v[56:57], off
	v_mfma_f32_16x16x32_bf16 v[180:183], v[36:39], v[24:27], v[4:7]
	v_mfma_f32_16x16x32_bf16 v[184:187], v[40:43], v[24:27], v[184:187]
	s_waitcnt lgkmcnt(0)
	v_mfma_f32_16x16x32_bf16 v[156:159], v[12:15], v[24:27], v[156:159]
	global_load_dwordx4 v[24:27], v[118:119], off offset:2064
	global_load_dwordx4 v[4:7], v[118:119], off offset:2176
	global_load_dwordx4 v[214:217], v[56:57], off offset:64
	v_mfma_f32_16x16x32_bf16 v[176:179], v[40:43], v[0:3], v[176:179]
	v_mfma_f32_16x16x32_bf16 v[160:163], v[8:11], v[0:3], v[160:163]
	v_mfma_f32_16x16x32_bf16 v[60:63], v[12:15], v[0:3], v[52:55]
	global_load_dwordx4 v[0:3], v[118:119], off offset:2192
	s_waitcnt vmcnt(0)
; __device__ __forceinline__ unsigned pk2(float lo, float hi) { return f2bf(lo) | (f2bf(hi) << 16); }
; template <int HF>
; __device__ __forceinline__ void gmlp_half(LAS unsigned char* wl, const bf16* PROJ, const bf16* wsg, const float* norm_v, const float* b_s, bf16* Y, int tok0, int g, int fr, int fq) {
;     ...
;         for (int nt = 0; nt < 4; ++nt)
; #pragma unroll
;             for (int mi = 0; mi < 4; ++mi) acc[mi][nt] = __builtin_amdgcn_mfma_f32_16x16x32_bf16(av[mi], bw[ki][nt], acc[mi][nt], 0, 0, 0);
;     }
;     asm volatile("" ::: "memory");
;     f32x4 nv[2][2];
; #pragma unroll
;     for (int p = 0; p < 2; ++p) { nv[p][0] = *(const f32x4*)(norm_v + g * 64 + 32 * p + 8 * fq); nv[p][1] = *(const f32x4*)(norm_v + g * 64 + 32 * p + 8 * fq + 4); }
; #pragma unroll
;     for (int nt = 0; nt < 4; ++nt) {
;         const int t = 64 * HF + 16 * nt + fr; const size_t tok = (size_t)(tok0 + t); const float bs = b_s[g * 128 + t];
;         u32x4 uu[2];
; #pragma unroll
;         for (int p = 0; p < 2; ++p) uu[p] = *(const u32x4*)(PROJ + tok * NPROJ + g * 64 + 32 * p + 8 * fq);
; #pragma unroll
;         for (int p = 0; p < 2; ++p) {
;             u32x4 w;
; #pragma unroll
;             for (int e2 = 0; e2 < 2; ++e2) {
;                 const f32x4 z = nv[p][e2] * acc[2 * p + e2][nt] + bs;
;                 const unsigned u0 = uu[p][2 * e2], u1 = uu[p][2 * e2 + 1];
;                 w[2 * e2] = pk2(bf_lo(u0) * z[0], bf_hi(u0) * z[1]); w[2 * e2 + 1] = pk2(bf_lo(u1) * z[2], bf_hi(u1) * z[3]);
;             }
;             *(u32x4*)(Y + tok * D + g * 64 + 32 * p + 8 * fq) = w;
;         }
	v_pk_fma_f32 v[158:159], v[158:159], v[2:3], v[220:221] op_sel_hi:[1,1,0]
	v_mfma_f32_16x16x32_bf16 v[56:59], v[36:39], v[196:199], v[164:167]
	v_fma_f32 v156, v156, v0, v220
	v_fma_f32 v157, v157, v1, v220
	s_nop 0
	v_lshlrev_b64 v[164:165], 11, v[218:219]
	v_mfma_f32_16x16x32_bf16 v[52:55], v[40:43], v[196:199], v[168:171]
	v_fma_f32 v166, v180, v32, v220
	v_fma_f32 v167, v181, v33, v220
	v_mov_b32_e32 v180, v166
	v_lshl_add_u64 v[168:169], v[84:85], 0, v[164:165]
	v_pk_fma_f32 v[164:165], v[182:183], v[34:35], v[220:221] op_sel_hi:[1,1,0]
	v_lshlrev_b32_e32 v171, 16, v211
	v_lshlrev_b32_e32 v170, 16, v210
	v_mov_b32_e32 v181, v164
	v_pk_mul_f32 v[170:171], v[180:181], v[170:171]
	v_and_b32_e32 v181, 0xffff0000, v211
	v_and_b32_e32 v180, 0xffff0000, v210
	v_mov_b32_e32 v164, v167
	v_pk_mul_f32 v[164:165], v[164:165], v[180:181]
	v_pk_fma_f32 v[166:167], v[186:187], v[26:27], v[220:221] op_sel_hi:[1,1,0]
	v_pk_fma_f32 v[180:181], v[184:185], v[24:25], v[220:221] op_sel_hi:[1,1,0]
	v_lshlrev_b32_e32 v183, 16, v213
	v_lshlrev_b32_e32 v182, 16, v212
	v_mov_b32_e32 v184, v180
	v_mov_b32_e32 v185, v166
	v_pk_mul_f32 v[182:183], v[184:185], v[182:183]
	v_and_b32_e32 v185, 0xffff0000, v213
	v_and_b32_e32 v184, 0xffff0000, v212
	v_mov_b32_e32 v166, v181
	v_pk_mul_f32 v[166:167], v[166:167], v[184:185]
	v_bfe_u32 v181, v165, 16, 1
	v_bfe_u32 v155, v167, 16, 1
	v_bfe_u32 v180, v166, 16, 1
	v_bfe_u32 v184, v164, 16, 1
	v_add3_u32 v164, v164, v184, s5
	v_add3_u32 v165, v165, v181, s5
	v_add3_u32 v166, v166, v180, s5
	v_add3_u32 v155, v167, v155, s5
	v_bfe_u32 v167, v170, 16, 1
	v_bfe_u32 v180, v171, 16, 1
	v_bfe_u32 v181, v182, 16, 1
	v_bfe_u32 v184, v183, 16, 1
	v_add3_u32 v183, v183, v184, s5
	v_add3_u32 v181, v182, v181, s5
	v_add3_u32 v171, v171, v180, s5
	v_add3_u32 v167, v170, v167, s5
	v_lshrrev_b32_e32 v170, 16, v167
	v_lshrrev_b32_e32 v171, 16, v171
	v_lshrrev_b32_e32 v180, 16, v181
	v_lshrrev_b32_e32 v167, 16, v183
	v_and_or_b32 v167, v155, s6, v167
	v_and_or_b32 v166, v166, s6, v180
	v_and_or_b32 v165, v165, s6, v171
	v_and_or_b32 v164, v164, s6, v170
	global_store_dwordx4 v[168:169], v[164:167], off
	v_lshlrev_b32_e32 v171, 16, v215
	v_lshlrev_b32_e32 v170, 16, v214
	v_pk_fma_f32 v[164:165], v[190:191], v[6:7], v[220:221] op_sel_hi:[1,1,0]
	v_pk_fma_f32 v[166:167], v[188:189], v[4:5], v[220:221] op_sel_hi:[1,1,0]
	v_mov_b32_e32 v181, v164
	v_mov_b32_e32 v180, v166
	v_pk_mul_f32 v[170:171], v[180:181], v[170:171]
	v_and_b32_e32 v181, 0xffff0000, v215
	v_and_b32_e32 v180, 0xffff0000, v214
	v_mov_b32_e32 v164, v167
	v_pk_mul_f32 v[164:165], v[164:165], v[180:181]
	v_lshlrev_b32_e32 v167, 16, v217
	v_lshlrev_b32_e32 v166, 16, v216
	v_mov_b32_e32 v180, v156
	v_mov_b32_e32 v181, v158
	v_pk_mul_f32 v[166:167], v[180:181], v[166:167]
	v_and_b32_e32 v181, 0xffff0000, v217
	v_and_b32_e32 v180, 0xffff0000, v216
	v_mov_b32_e32 v158, v157
	v_pk_mul_f32 v[156:157], v[158:159], v[180:181]
	v_bfe_u32 v159, v165, 16, 1
	v_bfe_u32 v155, v157, 16, 1
	v_bfe_u32 v158, v156, 16, 1
	v_bfe_u32 v180, v164, 16, 1
	v_add3_u32 v164, v164, v180, s5
	v_add3_u32 v165, v165, v159, s5
	v_add3_u32 v156, v156, v158, s5
	v_add3_u32 v155, v157, v155, s5
	v_bfe_u32 v157, v170, 16, 1
	v_bfe_u32 v158, v171, 16, 1
	v_bfe_u32 v159, v166, 16, 1
	v_bfe_u32 v180, v167, 16, 1
	v_add3_u32 v167, v167, v180, s5
	v_add3_u32 v159, v166, v159, s5
	v_add3_u32 v158, v171, v158, s5
	v_add3_u32 v157, v170, v157, s5
	v_lshrrev_b32_e32 v166, 16, v157
	v_lshrrev_b32_e32 v157, 16, v158
	v_lshrrev_b32_e32 v158, 16, v159
	v_lshrrev_b32_e32 v159, 16, v167
	v_and_or_b32 v159, v155, s6, v159
	v_and_or_b32 v158, v156, s6, v158
	v_and_or_b32 v157, v165, s6, v157
	v_and_or_b32 v156, v164, s6, v166
	global_store_dwordx4 v[168:169], v[156:159], off offset:64
	v_or_b32_e32 v180, s12, v146
	global_load_dword v182, v[130:131], off
	v_mad_i64_i32 v[168:169], s[20:21], v180, s4, v[82:83]
	global_load_dwordx4 v[156:159], v[168:169], off
	v_ashrrev_i32_e32 v181, 31, v180
	global_load_dwordx4 v[168:171], v[168:169], off offset:64
	v_lshlrev_b64 v[180:181], 11, v[180:181]
	v_lshl_add_u64 v[180:181], v[84:85], 0, v[180:181]
	v_mfma_f32_16x16x32_bf16 v[36:39], v[36:39], v[28:31], v[48:51]
	s_waitcnt vmcnt(2)
	v_pk_fma_f32 v[184:185], v[194:195], v[34:35], v[182:183] op_sel_hi:[1,1,0]
	v_pk_fma_f32 v[186:187], v[192:193], v[32:33], v[182:183] op_sel_hi:[1,1,0]
	v_mov_b32_e32 v191, v184
	s_waitcnt vmcnt(1)
	v_lshlrev_b32_e32 v189, 16, v157
	v_lshlrev_b32_e32 v188, 16, v156
	v_and_b32_e32 v157, 0xffff0000, v157
	v_and_b32_e32 v156, 0xffff0000, v156
	v_mov_b32_e32 v184, v187
	v_pk_fma_f32 v[178:179], v[178:179], v[26:27], v[182:183] op_sel_hi:[1,1,0]
	v_pk_fma_f32 v[176:177], v[176:177], v[24:25], v[182:183] op_sel_hi:[1,1,0]
	v_pk_mul_f32 v[156:157], v[184:185], v[156:157]
	v_lshlrev_b32_e32 v185, 16, v159
	v_lshlrev_b32_e32 v184, 16, v158
	v_mov_b32_e32 v187, v178
	v_and_b32_e32 v159, 0xffff0000, v159
	v_and_b32_e32 v158, 0xffff0000, v158
	v_mov_b32_e32 v178, v177
	v_mov_b32_e32 v190, v186
	v_mov_b32_e32 v186, v176
	v_pk_mul_f32 v[158:159], v[178:179], v[158:159]
	v_pk_mul_f32 v[188:189], v[190:191], v[188:189]
	v_pk_mul_f32 v[184:185], v[186:187], v[184:185]
	v_bfe_u32 v155, v159, 16, 1
	v_bfe_u32 v176, v158, 16, 1
	v_bfe_u32 v177, v157, 16, 1
	v_bfe_u32 v178, v156, 16, 1
	v_add3_u32 v156, v156, v178, s5
	v_add3_u32 v157, v157, v177, s5
	v_add3_u32 v158, v158, v176, s5
	v_add3_u32 v155, v159, v155, s5
	v_bfe_u32 v159, v188, 16, 1
	v_bfe_u32 v176, v189, 16, 1
	v_bfe_u32 v177, v184, 16, 1
	v_bfe_u32 v178, v185, 16, 1
	v_add3_u32 v178, v185, v178, s5
	v_add3_u32 v177, v184, v177, s5
	v_add3_u32 v176, v189, v176, s5
	v_add3_u32 v159, v188, v159, s5
	v_lshrrev_b32_e32 v179, 16, v159
	v_lshrrev_b32_e32 v176, 16, v176
	v_lshrrev_b32_e32 v177, 16, v177
	v_lshrrev_b32_e32 v159, 16, v178
	v_and_or_b32 v159, v155, s6, v159
	v_and_or_b32 v158, v158, s6, v177
	v_and_or_b32 v157, v157, s6, v176
	v_and_or_b32 v156, v156, s6, v179
	global_store_dwordx4 v[180:181], v[156:159], off
	v_pk_fma_f32 v[62:63], v[62:63], v[2:3], v[182:183] op_sel_hi:[1,1,0]
	v_pk_fma_f32 v[60:61], v[60:61], v[0:1], v[182:183] op_sel_hi:[1,1,0]
	v_pk_fma_f32 v[156:157], v[162:163], v[6:7], v[182:183] op_sel_hi:[1,1,0]
	v_pk_fma_f32 v[158:159], v[160:161], v[4:5], v[182:183] op_sel_hi:[1,1,0]
	s_waitcnt vmcnt(1)
; __device__ __forceinline__ unsigned pk2(float lo, float hi) { return f2bf(lo) | (f2bf(hi) << 16); }
; template <int HF>
; __device__ __forceinline__ void gmlp_half(LAS unsigned char* wl, const bf16* PROJ, const bf16* wsg, const float* norm_v, const float* b_s, bf16* Y, int tok0, int g, int fr, int fq) {
;     ...
;     for (int nt = 0; nt < 4; ++nt) {
;         const int t = 64 * HF + 16 * nt + fr; const size_t tok = (size_t)(tok0 + t); const float bs = b_s[g * 128 + t];
;         u32x4 uu[2];
; #pragma unroll
;         for (int p = 0; p < 2; ++p) uu[p] = *(const u32x4*)(PROJ + tok * NPROJ + g * 64 + 32 * p + 8 * fq);
; #pragma unroll
;         for (int p = 0; p < 2; ++p) {
;             u32x4 w;
; #pragma unroll
;             for (int e2 = 0; e2 < 2; ++e2) {
;                 const f32x4 z = nv[p][e2] * acc[2 * p + e2][nt] + bs;
;                 const unsigned u0 = uu[p][2 * e2], u1 = uu[p][2 * e2 + 1];
;                 w[2 * e2] = pk2(bf_lo(u0) * z[0], bf_hi(u0) * z[1]); w[2 * e2 + 1] = pk2(bf_lo(u1) * z[2], bf_hi(u1) * z[3]);
;             }
;             *(u32x4*)(Y + tok * D + g * 64 + 32 * p + 8 * fq) = w;
;         }
	v_lshlrev_b32_e32 v161, 16, v169
	v_lshlrev_b32_e32 v160, 16, v168
	v_mov_b32_e32 v162, v158
	v_mov_b32_e32 v163, v156
	v_pk_mul_f32 v[160:161], v[162:163], v[160:161]
	v_and_b32_e32 v163, 0xffff0000, v169
	v_and_b32_e32 v162, 0xffff0000, v168
	v_mov_b32_e32 v156, v159
	v_pk_mul_f32 v[156:157], v[156:157], v[162:163]
	v_lshlrev_b32_e32 v159, 16, v171
	v_lshlrev_b32_e32 v158, 16, v170
	v_mov_b32_e32 v162, v60
	v_mov_b32_e32 v163, v62
	v_pk_mul_f32 v[158:159], v[162:163], v[158:159]
	v_and_b32_e32 v163, 0xffff0000, v171
	v_and_b32_e32 v162, 0xffff0000, v170
	v_mov_b32_e32 v62, v61
	v_pk_mul_f32 v[60:61], v[62:63], v[162:163]
	v_bfe_u32 v155, v157, 16, 1
	v_bfe_u32 v62, v61, 16, 1
	v_bfe_u32 v63, v60, 16, 1
	v_bfe_u32 v162, v156, 16, 1
	v_add3_u32 v156, v156, v162, s5
	v_add3_u32 v155, v157, v155, s5
	v_add3_u32 v60, v60, v63, s5
	v_add3_u32 v61, v61, v62, s5
	v_bfe_u32 v62, v160, 16, 1
	v_bfe_u32 v63, v161, 16, 1
	v_bfe_u32 v157, v158, 16, 1
	v_bfe_u32 v162, v159, 16, 1
	v_add3_u32 v159, v159, v162, s5
	v_add3_u32 v157, v158, v157, s5
	v_add3_u32 v63, v161, v63, s5
	v_add3_u32 v62, v160, v62, s5
	v_lshrrev_b32_e32 v158, 16, v62
	v_lshrrev_b32_e32 v160, 16, v63
	v_lshrrev_b32_e32 v62, 16, v157
	v_lshrrev_b32_e32 v63, 16, v159
	v_and_or_b32 v63, v61, s6, v63
	v_and_or_b32 v62, v60, s6, v62
	v_and_or_b32 v61, v155, s6, v160
	v_and_or_b32 v60, v156, s6, v158
	global_store_dwordx4 v[180:181], v[60:63], off offset:64
	v_or_b32_e32 v156, s12, v147
	global_load_dword v158, v[132:133], off
	v_mad_i64_i32 v[160:161], s[12:13], v156, s4, v[82:83]
	global_load_dwordx4 v[60:63], v[160:161], off
	global_load_dwordx4 v[48:51], v[160:161], off offset:64
	v_ashrrev_i32_e32 v157, 31, v156
	v_mfma_f32_16x16x32_bf16 v[40:43], v[40:43], v[28:31], v[44:47]
	s_waitcnt vmcnt(2)
	v_pk_fma_f32 v[52:53], v[52:53], v[24:25], v[158:159] op_sel_hi:[1,1,0]
	s_nop 0
	v_lshlrev_b64 v[44:45], 11, v[156:157]
	v_lshl_add_u64 v[156:157], v[84:85], 0, v[44:45]
	v_pk_fma_f32 v[44:45], v[58:59], v[34:35], v[158:159] op_sel_hi:[1,1,0]
	v_pk_fma_f32 v[46:47], v[56:57], v[32:33], v[158:159] op_sel_hi:[1,1,0]
	s_waitcnt vmcnt(1)
	v_lshlrev_b32_e32 v57, 16, v61
	v_lshlrev_b32_e32 v56, 16, v60
	v_mov_b32_e32 v58, v46
	v_mov_b32_e32 v59, v44
	v_pk_mul_f32 v[56:57], v[58:59], v[56:57]
	v_and_b32_e32 v59, 0xffff0000, v61
	v_and_b32_e32 v58, 0xffff0000, v60
	v_mov_b32_e32 v44, v47
	v_pk_fma_f32 v[46:47], v[54:55], v[26:27], v[158:159] op_sel_hi:[1,1,0]
	v_pk_mul_f32 v[44:45], v[44:45], v[58:59]
	v_lshlrev_b32_e32 v55, 16, v63
	v_lshlrev_b32_e32 v54, 16, v62
	v_mov_b32_e32 v58, v52
	v_mov_b32_e32 v59, v46
	v_pk_mul_f32 v[54:55], v[58:59], v[54:55]
	v_and_b32_e32 v59, 0xffff0000, v63
	v_and_b32_e32 v58, 0xffff0000, v62
	v_mov_b32_e32 v46, v53
	v_pk_mul_f32 v[46:47], v[46:47], v[58:59]
	v_bfe_u32 v58, v45, 16, 1
	v_bfe_u32 v52, v47, 16, 1
	v_bfe_u32 v53, v46, 16, 1
	v_bfe_u32 v59, v44, 16, 1
	v_mfma_f32_16x16x32_bf16 v[164:167], v[8:11], v[196:199], v[172:175]
	v_add3_u32 v44, v44, v59, s5
	v_add3_u32 v45, v45, v58, s5
	v_add3_u32 v46, v46, v53, s5
	v_add3_u32 v47, v47, v52, s5
	v_bfe_u32 v52, v56, 16, 1
	v_bfe_u32 v53, v57, 16, 1
	v_bfe_u32 v58, v54, 16, 1
	v_bfe_u32 v59, v55, 16, 1
	v_add3_u32 v55, v55, v59, s5
	v_add3_u32 v54, v54, v58, s5
	v_add3_u32 v53, v57, v53, s5
	v_add3_u32 v52, v56, v52, s5
	v_mfma_f32_16x16x32_bf16 v[172:175], v[12:15], v[196:199], v[206:209]
	v_lshrrev_b32_e32 v52, 16, v52
	v_lshrrev_b32_e32 v53, 16, v53
	v_lshrrev_b32_e32 v54, 16, v54
	v_lshrrev_b32_e32 v55, 16, v55
	v_and_or_b32 v47, v47, s6, v55
	v_and_or_b32 v46, v46, s6, v54
	v_and_or_b32 v45, v45, s6, v53
	v_and_or_b32 v44, v44, s6, v52
	global_store_dwordx4 v[156:157], v[44:47], off
	s_waitcnt vmcnt(1)
	v_lshlrev_b32_e32 v53, 16, v49
	v_lshlrev_b32_e32 v52, 16, v48
	v_pk_fma_f32 v[44:45], v[166:167], v[6:7], v[158:159] op_sel_hi:[1,1,0]
	v_pk_fma_f32 v[46:47], v[164:165], v[4:5], v[158:159] op_sel_hi:[1,1,0]
	v_mov_b32_e32 v55, v44
	v_and_b32_e32 v49, 0xffff0000, v49
	v_and_b32_e32 v48, 0xffff0000, v48
	v_mov_b32_e32 v44, v47
	v_mov_b32_e32 v54, v46
	v_pk_mul_f32 v[44:45], v[44:45], v[48:49]
	v_pk_fma_f32 v[46:47], v[174:175], v[2:3], v[158:159] op_sel_hi:[1,1,0]
	v_pk_fma_f32 v[48:49], v[172:173], v[0:1], v[158:159] op_sel_hi:[1,1,0]
	v_pk_mul_f32 v[52:53], v[54:55], v[52:53]
	v_lshlrev_b32_e32 v55, 16, v51
	v_lshlrev_b32_e32 v54, 16, v50
	v_mov_b32_e32 v57, v46
	v_and_b32_e32 v51, 0xffff0000, v51
	v_and_b32_e32 v50, 0xffff0000, v50
	v_mov_b32_e32 v46, v49
	v_mov_b32_e32 v56, v48
	v_pk_mul_f32 v[46:47], v[46:47], v[50:51]
	v_pk_mul_f32 v[54:55], v[56:57], v[54:55]
	v_bfe_u32 v48, v47, 16, 1
	v_bfe_u32 v49, v46, 16, 1
	v_bfe_u32 v50, v45, 16, 1
	v_bfe_u32 v51, v44, 16, 1
	v_add3_u32 v44, v44, v51, s5
	v_add3_u32 v45, v45, v50, s5
	v_add3_u32 v46, v46, v49, s5
	v_add3_u32 v47, v47, v48, s5
	v_bfe_u32 v48, v52, 16, 1
	v_bfe_u32 v49, v53, 16, 1
	v_bfe_u32 v50, v54, 16, 1
	v_bfe_u32 v51, v55, 16, 1
	v_add3_u32 v51, v55, v51, s5
	v_add3_u32 v50, v54, v50, s5
	v_add3_u32 v49, v53, v49, s5
	v_add3_u32 v48, v52, v48, s5
	v_lshrrev_b32_e32 v48, 16, v48
	v_lshrrev_b32_e32 v49, 16, v49
	v_lshrrev_b32_e32 v50, 16, v50
	v_lshrrev_b32_e32 v51, 16, v51
	v_and_or_b32 v47, v47, s6, v51
	v_and_or_b32 v46, v46, s6, v50
	v_and_or_b32 v45, v45, s6, v49
	v_and_or_b32 v44, v44, s6, v48
	global_store_dwordx4 v[156:157], v[44:47], off offset:64
	v_or_b32_e32 v48, s11, v148
	global_load_dword v50, v[134:135], off
	v_mad_i64_i32 v[52:53], s[12:13], v48, s4, v[82:83]
	global_load_dwordx4 v[44:47], v[52:53], off
	v_mfma_f32_16x16x32_bf16 v[8:11], v[8:11], v[28:31], v[16:19]
	v_ashrrev_i32_e32 v49, 31, v48
	s_waitcnt vmcnt(1)
; #define LAS __attribute__((address_space(3)))
; __device__ __forceinline__ unsigned pk2(float lo, float hi) { return f2bf(lo) | (f2bf(hi) << 16); }
; template <int HF>
; __device__ __forceinline__ void gmlp_half(LAS unsigned char* wl, const bf16* PROJ, const bf16* wsg, const float* norm_v, const float* b_s, bf16* Y, int tok0, int g, int fr, int fq) {
;     ...
;         for (int p = 0; p < 2; ++p) uu[p] = *(const u32x4*)(PROJ + tok * NPROJ + g * 64 + 32 * p + 8 * fq);
; #pragma unroll
;         for (int p = 0; p < 2; ++p) {
;             u32x4 w;
; #pragma unroll
;             for (int e2 = 0; e2 < 2; ++e2) {
;                 const f32x4 z = nv[p][e2] * acc[2 * p + e2][nt] + bs;
;                 const unsigned u0 = uu[p][2 * e2], u1 = uu[p][2 * e2 + 1];
;                 w[2 * e2] = pk2(bf_lo(u0) * z[0], bf_hi(u0) * z[1]); w[2 * e2 + 1] = pk2(bf_lo(u1) * z[2], bf_hi(u1) * z[3]);
;             }
;             *(u32x4*)(Y + tok * D + g * 64 + 32 * p + 8 * fq) = w;
;         }
; __device__ __forceinline__ void gla_upd_unit(LAS unsigned char* wl, const bf16* PROJ, const float* R, const float* w_gk2, const float* b_gk, float* UPD, float* DEC, int unit, int lane) {
;     constexpr int KS = 72;
;     LAS unsigned* KD32 = (LAS unsigned*)wl; LAS unsigned* VB32 = (LAS unsigned*)(wl + 9216);
;     const int h = unit & 3, tok0 = (unit >> 2) * 64, kk = lane;
;     { const f32x4* rp = (const f32x4*)(R + (size_t)(tok0 + lane) * 16); LAS f32x4* rl = (LAS f32x4*)(wl + 9216) + lane * 4;
;       const f32x4 r0 = rp[0], r1 = rp[1], r2 = rp[2], r3 = rp[3]; rl[0] = r0; rl[1] = r1; rl[2] = r2; rl[3] = r3; }
;     const bf16* kp = PROJ + (size_t)tok0 * NPROJ + 1280 + h * 64 + kk;
;     unsigned short kv0[32], kv1[32];
; #pragma unroll
;     for (int t = 0; t < 32; ++t) kv0[t] = kp[(size_t)t * NPROJ];
;     float w[16];
; #pragma unroll
;     for (int j = 0; j < 16; ++j) w[j] = w_gk2[j * 256 + h * 64 + kk];
;     const float bias = b_gk[h * 64 + kk];
	v_pk_fma_f32 v[24:25], v[40:41], v[24:25], v[50:51] op_sel_hi:[1,1,0]
	global_load_dwordx4 v[16:19], v[52:53], off offset:64
	v_mfma_f32_16x16x32_bf16 v[12:15], v[12:15], v[28:31], v[20:23]
	s_nop 2
	v_fma_f32 v6, v10, v6, v50
	v_fma_f32 v7, v11, v7, v50
	v_pk_fma_f32 v[4:5], v[8:9], v[4:5], v[50:51] op_sel_hi:[1,1,0]
	s_waitcnt vmcnt(1)
	v_lshlrev_b32_e32 v31, 16, v45
	v_lshlrev_b64 v[20:21], 11, v[48:49]
	v_lshl_add_u64 v[28:29], v[84:85], 0, v[20:21]
	v_pk_fma_f32 v[20:21], v[38:39], v[34:35], v[50:51] op_sel_hi:[1,1,0]
	v_pk_fma_f32 v[22:23], v[36:37], v[32:33], v[50:51] op_sel_hi:[1,1,0]
	v_lshlrev_b32_e32 v30, 16, v44
	v_mov_b32_e32 v32, v22
	v_mov_b32_e32 v33, v20
	v_mov_b32_e32 v10, v4
	v_mov_b32_e32 v11, v6
	v_pk_mul_f32 v[30:31], v[32:33], v[30:31]
	v_and_b32_e32 v33, 0xffff0000, v45
	v_and_b32_e32 v32, 0xffff0000, v44
	v_mov_b32_e32 v20, v23
	v_pk_fma_f32 v[22:23], v[42:43], v[26:27], v[50:51] op_sel_hi:[1,1,0]
	v_mov_b32_e32 v6, v5
	v_pk_fma_f32 v[2:3], v[14:15], v[2:3], v[50:51] op_sel_hi:[1,1,0]
	v_pk_fma_f32 v[0:1], v[12:13], v[0:1], v[50:51] op_sel_hi:[1,1,0]
	v_pk_mul_f32 v[20:21], v[20:21], v[32:33]
	v_lshlrev_b32_e32 v27, 16, v47
	v_lshlrev_b32_e32 v26, 16, v46
	v_mov_b32_e32 v32, v24
	v_mov_b32_e32 v33, v22
	v_pk_mul_f32 v[26:27], v[32:33], v[26:27]
	v_and_b32_e32 v33, 0xffff0000, v47
	v_and_b32_e32 v32, 0xffff0000, v46
	v_mov_b32_e32 v22, v25
	v_pk_mul_f32 v[22:23], v[22:23], v[32:33]
	v_bfe_u32 v32, v21, 16, 1
	v_bfe_u32 v24, v23, 16, 1
	v_bfe_u32 v25, v22, 16, 1
	v_bfe_u32 v33, v20, 16, 1
	v_add3_u32 v20, v20, v33, s5
	v_add3_u32 v21, v21, v32, s5
	v_add3_u32 v22, v22, v25, s5
	v_add3_u32 v23, v23, v24, s5
	v_bfe_u32 v24, v30, 16, 1
	v_bfe_u32 v25, v31, 16, 1
	v_bfe_u32 v32, v26, 16, 1
	v_bfe_u32 v33, v27, 16, 1
	v_add3_u32 v27, v27, v33, s5
	v_add3_u32 v26, v26, v32, s5
	v_add3_u32 v25, v31, v25, s5
	v_add3_u32 v24, v30, v24, s5
	v_lshrrev_b32_e32 v24, 16, v24
	v_lshrrev_b32_e32 v25, 16, v25
	v_lshrrev_b32_e32 v26, 16, v26
	v_lshrrev_b32_e32 v27, 16, v27
	v_and_or_b32 v23, v23, s6, v27
	v_and_or_b32 v22, v22, s6, v26
	v_and_or_b32 v21, v21, s6, v25
	v_and_or_b32 v20, v20, s6, v24
	global_store_dwordx4 v[28:29], v[20:23], off
	s_waitcnt vmcnt(1)
	v_lshlrev_b32_e32 v9, 16, v17
	v_lshlrev_b32_e32 v8, 16, v16
	v_pk_mul_f32 v[8:9], v[10:11], v[8:9]
	v_and_b32_e32 v11, 0xffff0000, v17
	v_and_b32_e32 v10, 0xffff0000, v16
	v_pk_mul_f32 v[4:5], v[6:7], v[10:11]
	v_lshlrev_b32_e32 v7, 16, v19
	v_lshlrev_b32_e32 v6, 16, v18
	v_mov_b32_e32 v10, v0
	v_mov_b32_e32 v11, v2
	v_pk_mul_f32 v[6:7], v[10:11], v[6:7]
	v_and_b32_e32 v11, 0xffff0000, v19
	v_and_b32_e32 v10, 0xffff0000, v18
	v_mov_b32_e32 v2, v1
	v_pk_mul_f32 v[0:1], v[2:3], v[10:11]
	v_bfe_u32 v10, v5, 16, 1
	v_bfe_u32 v2, v1, 16, 1
	v_bfe_u32 v3, v0, 16, 1
	v_bfe_u32 v11, v4, 16, 1
	v_add3_u32 v4, v4, v11, s5
	v_add3_u32 v5, v5, v10, s5
	v_add3_u32 v0, v0, v3, s5
	v_add3_u32 v1, v1, v2, s5
	v_bfe_u32 v2, v8, 16, 1
	v_bfe_u32 v3, v9, 16, 1
	v_bfe_u32 v10, v6, 16, 1
	v_bfe_u32 v11, v7, 16, 1
	v_add3_u32 v7, v7, v11, s5
	v_add3_u32 v6, v6, v10, s5
	v_add3_u32 v3, v9, v3, s5
	v_add3_u32 v2, v8, v2, s5
	v_lshrrev_b32_e32 v8, 16, v2
	v_lshrrev_b32_e32 v9, 16, v3
	v_lshrrev_b32_e32 v2, 16, v6
	v_lshrrev_b32_e32 v3, 16, v7
	v_and_or_b32 v3, v1, s6, v3
	v_and_or_b32 v2, v0, s6, v2
	v_and_or_b32 v1, v5, s6, v9
	v_and_or_b32 v0, v4, s6, v8
	global_store_dwordx4 v[28:29], v[0:3], off offset:64
	s_waitcnt lgkmcnt(0)
	s_cbranch_scc0 .LBB0_1050
	v_readlane_b32 s0, v230, 10
	v_lshlrev_b32_e32 v0, 2, v200
	v_mov_b32_e32 v1, 0
	v_readlane_b32 s1, v230, 11
	v_and_b32_e32 v2, 12, v140
	v_readlane_b32 s2, v230, 8
	v_lshl_add_u64 v[24:25], s[0:1], 0, v[0:1]
	s_movk_i32 s0, 0x90
	v_mov_b32_e32 v6, s37
	v_lshlrev_b32_e32 v2, 2, v2
	v_mov_b32_e32 v3, v1
	v_readlane_b32 s3, v230, 9
	v_mad_u32_u24 v6, v64, s0, v6
	v_readlane_b32 s0, v230, 4
	v_lshl_add_u64 v[2:3], s[2:3], 0, v[2:3]
	s_bfe_u32 s2, s0, 0x20006
	s_lshl_b32 s3, s2, 8
	v_lshl_add_u32 v81, v67, 2, v6
	v_mov_b32_e32 v67, v1
	v_or_b32_e32 v0, s3, v0
	v_lshl_add_u64 v[26:27], v[2:3], 0, v[66:67]
	v_lshl_add_u64 v[2:3], s[14:15], 0, v[0:1]
	s_mov_b64 s[0:1], 0x4000
	v_lshl_add_u64 v[28:29], v[2:3], 0, s[0:1]
	s_mov_b64 s[0:1], 0x5000
	v_lshl_add_u64 v[30:31], v[2:3], 0, s[0:1]
	s_mov_b64 s[0:1], 0x5400
	v_lshl_add_u64 v[32:33], v[2:3], 0, s[0:1]
	s_mov_b64 s[0:1], 0x5800
	v_lshl_add_u64 v[34:35], v[2:3], 0, s[0:1]
	s_mov_b64 s[0:1], 0x5c00
	v_lshl_add_u64 v[36:37], v[2:3], 0, s[0:1]
	s_mov_b64 s[0:1], 0x6000
	v_lshl_add_u64 v[38:39], v[2:3], 0, s[0:1]
	s_mov_b64 s[0:1], 0x6400
	v_lshl_add_u64 v[40:41], v[2:3], 0, s[0:1]
	s_mov_b64 s[0:1], 0x6800
	v_lshl_add_u64 v[42:43], v[2:3], 0, s[0:1]
	s_mov_b64 s[0:1], 0x6c00
	v_lshl_add_u64 v[44:45], v[2:3], 0, s[0:1]
	s_mov_b64 s[0:1], 0x7000
	v_lshl_add_u64 v[46:47], v[2:3], 0, s[0:1]
	s_mov_b64 s[0:1], 0x7400
	v_lshl_add_u64 v[48:49], v[2:3], 0, s[0:1]
	s_mov_b64 s[0:1], 0x7800
	v_lshl_add_u64 v[50:51], v[2:3], 0, s[0:1]
	s_mov_b64 s[0:1], 0x7c00
	v_lshl_add_u64 v[52:53], v[2:3], 0, s[0:1]
	s_lshl_b32 s0, s2, 7
	s_add_u32 s0, s24, s0
	v_lshl_add_u64 v[54:55], s[16:17], 0, v[0:1]
	s_addc_u32 s1, s25, 0
	v_lshlrev_b32_e32 v0, 1, v200
	v_or_b32_e32 v78, 16, v138
	v_or_b32_e32 v79, 32, v138
	v_or_b32_e32 v80, 48, v138
	v_lshl_add_u64 v[56:57], s[0:1], 0, v[0:1]
	s_add_u32 s0, s24, s3
	v_lshlrev_b32_e32 v4, 6, v200
	v_mul_u32_u24_e32 v5, 0x90, v200
	v_lshl_add_u32 v82, v78, 1, v6
	v_lshl_add_u32 v83, v79, 1, v6
	v_lshl_add_u32 v84, v80, 1, v6
	v_mul_u32_u24_e32 v6, 0x90, v139
	v_mul_u32_u24_e32 v7, 0x90, v202
	s_addc_u32 s1, s25, 0
	v_lshlrev_b32_e32 v0, 1, v64
	v_lshl_add_u64 v[58:59], s[0:1], 0, v[0:1]
	v_add_u32_e32 v85, s37, v4
	s_movk_i32 s39, 0x1600
	s_mov_b32 s48, 0xbfb8aa3b
	s_mov_b32 s49, 0x800000
	s_mov_b32 s56, 0x3f317217
	s_mov_b32 s57, 0x7f800000
	s_movk_i32 s58, 0x7fff
	s_mov_b32 s59, 0xffff0000
	v_add_u32_e32 v86, s37, v5
	s_mov_b32 s66, 0x2c000
	s_mov_b32 s67, 0x2f000
	s_mov_b32 s68, 0x2e000
	s_mov_b32 s69, 0x30000
	s_mov_b32 s70, 0x32000
	s_mov_b32 s71, 0x34000
	s_mov_b32 s72, 0x33000
	s_mov_b32 s20, 0x36000
	s_mov_b32 s21, 0x37000
	s_mov_b32 s28, 0x3a000
	s_mov_b32 s29, 0x39000
	s_mov_b32 s30, 0x3b000
	s_mov_b32 s31, 0x3d000
	s_mov_b32 s73, 0x3f000
	s_mov_b32 s74, 0x3e000
	s_mov_b32 s75, 0x41000
	s_mov_b32 s76, 0x42000
	s_mov_b32 s77, 0x45000
	s_mov_b32 s78, 0x44000
	s_mov_b32 s79, 0x46000
	s_mov_b32 s80, 0x48000
	s_mov_b32 s81, 0x4a000
	s_mov_b32 s82, 0x49000
	s_mov_b32 s83, 0x4c000
	s_mov_b32 s84, 0x4d000
	s_mov_b32 s85, 0x50000
	s_mov_b32 s86, 0x4f000
	v_add_u32_e32 v87, v65, v6
	v_add_u32_e32 v88, v65, v7
	v_mov_b32_e32 v89, 0x1600
	v_mov_b32_e32 v90, 0x41b17218
	v_mov_b32_e32 v91, 1
	s_mov_b32 s87, 0x51000
	s_mov_b32 s88, 0x53000
	s_mov_b32 s89, 0x55000
	s_mov_b32 s90, 0x54000
	s_mov_b32 s91, 0x57000
	s_mov_b32 s13, 0
	s_mov_b32 s14, s38

; __device__ __forceinline__ void xcd_barrier(const XcdBarrier& b) {
;     asm volatile("s_waitcnt vmcnt(0)" ::: "memory");
;     __syncthreads();
;     if (threadIdx.x == 0) {
;         unsigned* bar = b.bar;
;         __builtin_amdgcn_s_waitcnt(0);
;         unsigned nloc = b.st[0], nx = b.st[1];
; template <int L>
; __device__ __forceinline__ void layer(const Args& a, LAS unsigned char* lds, const XcdBarrier& bar, int lo, int hi, int wave, int lane, int b, int r, int GS) {
;     ...
;         pg8::Gemm g{YB, (const bf16*)(wl + WOUT_OFF), SEQ, D, D}; pg8::GroupOrder S; S.init(SEQ, D, GS, r);
;         pg8::EpiResid E{nullptr, XN, rowss + (size_t)(3 * L + 2) * M, 1.0f, D};
;         pg8::gemm_phase<pg8::EpiResid, pg8::GroupOrder, true, true>(lds, g, S, E);
.LBB0_1158:
	s_cmp_gt_i32 s53, 16
	s_cselect_b64 s[2:3], -1, 0
	s_and_b64 s[0:1], s[0:1], s[2:3]
	s_andn2_b64 vcc, exec, s[0:1]
	s_cbranch_vccnz .LBB0_1203
	s_waitcnt vmcnt(0)
	s_waitcnt lgkmcnt(0)
	s_barrier
	s_cmp_eq_u32 s97, 0
	s_cbranch_scc1 .Lbpf_skip_14
	v_mov_b32_e32 v232, s95
	v_mul_u32_u24_e32 v232, 7, v232
	v_add_u32_e32 v232, s97, v232
	v_add_u32_e32 v232, -1, v232
	v_lshl_add_u32 v232, v232, 6, v200
	v_lshrrev_b32_e32 v231, 1, v232
	v_min_u32_e32 v231, 0x3ff, v231
	v_mul_u32_u24_e32 v231, 0x800, v231
	v_and_b32_e32 v232, 1, v232
	v_lshlrev_b32_e32 v232, 7, v232
	v_add_u32_e32 v232, v231, v232
	v_add_u32_e32 v232, 0x4680000, v232
	global_load_dword v231, v232, s[34:35]
.Lbpf_skip_14:
	s_and_saveexec_b64 s[0:1], s[8:9]
	s_cbranch_execz .LBB0_1202
	v_mov_b32_e32 v0, s92
	s_waitcnt vmcnt(0) expcnt(0) lgkmcnt(0)
	ds_read_b32 v2, v0
	ds_read_b32 v0, v0 offset:4
	s_waitcnt lgkmcnt(1)
	v_cmp_ne_u32_e32 vcc, 0, v2
	s_cbranch_vccnz .LBB0_1173
	s_add_u32 s4, s54, 0x1000
	s_addc_u32 s5, s55, 0
	s_add_u32 s6, s54, 0x1100
	s_addc_u32 s7, s55, 0
	s_add_u32 s12, s54, 0x1200
	s_addc_u32 s13, s55, 0
	s_add_u32 s14, s54, 0x1300
	s_addc_u32 s15, s55, 0
	s_mov_b32 s11, 1
	v_mov_b32_e32 v16, 0
	s_branch .LBB0_1163

; __device__ __forceinline__ void xcd_barrier(const XcdBarrier& b) {
;     asm volatile("s_waitcnt vmcnt(0)" ::: "memory");
;     __syncthreads();
;     if (threadIdx.x == 0) {
;         unsigned* bar = b.bar;
;         __builtin_amdgcn_s_waitcnt(0);
;         unsigned nloc = b.st[0], nx = b.st[1];
; template <int L>
; __device__ __forceinline__ void layer(const Args& a, LAS unsigned char* lds, const XcdBarrier& bar, int lo, int hi, int wave, int lane, int b, int r, int GS) {
;     ...
;         pg8::Gemm g{XN, (const bf16*)(wl + W3_OFF), SEQ, NFF, D}; pg8::GroupOrder S; S.init(SEQ, NFF, GS, r);
;         pg8::EpiSwiglu E{HB, DFF, rowss + (size_t)(3 * L + 2) * M, 1.f / D, EPS};
;         pg8::gemm_phase<pg8::EpiSwiglu, pg8::GroupOrder, true, true>(lds, g, S, E);
.LBB0_1238:
	s_cmp_gt_i32 s53, 17
	s_cselect_b64 s[2:3], -1, 0
	s_and_b64 s[0:1], s[0:1], s[2:3]
	s_andn2_b64 vcc, exec, s[0:1]
	s_cbranch_vccnz .LBB0_1283
	s_waitcnt vmcnt(0)
	s_waitcnt lgkmcnt(0)
	s_barrier
	s_cmp_eq_u32 s97, 0
	s_cbranch_scc1 .Lbpf_skip_15
	v_mov_b32_e32 v232, s95
	v_mul_u32_u24_e32 v232, 7, v232
	v_add_u32_e32 v232, s97, v232
	v_add_u32_e32 v232, -1, v232
	v_lshl_add_u32 v232, v232, 6, v200
	v_lshrrev_b32_e32 v231, 1, v232
	v_min_u32_e32 v231, 0x15ff, v231
	v_mul_u32_u24_e32 v231, 0x800, v231
	v_and_b32_e32 v232, 1, v232
	v_lshlrev_b32_e32 v232, 7, v232
	v_add_u32_e32 v232, v231, v232
	v_add_u32_e32 v232, 0x4880000, v232
	global_load_dword v231, v232, s[34:35]

; __device__ __forceinline__ unsigned cvt_pk_bf16(float lo, float hi) { unsigned r; asm volatile("v_cvt_pk_bf16_f32 %0, %1, %2" : "=v"(r) : "v"(lo), "v"(hi)); return r; }
; __device__ __forceinline__ float ss_val(u64 v) { return (float)v * (1.0f / 1099511627776.0f); }
;     __device__ __forceinline__ void operator()(const f32x4 (&acc)[2][2][4][2], const Unit& u, const Unit& nxt, bool has_next, int wr, int wc, int fr, int fq) const {
;     ...
;         for (int g = 0; g < 8; ++g) {
;             const int ai = g >> 2, m = g & 3;
;             const float rs = __builtin_amdgcn_rsqf(ss_val(cur[g]) * inv_k + eps), rsn = rs * -1.44269504089f, rs2 = rs * rs;
;             float h[8];
; #pragma unroll
;             for (int n = 0; n < 2; ++n)
; #pragma unroll
;                 for (int jp = 0; jp < 2; ++jp) {
;                     const f32x2v av = {acc[ai][0][m][n][2 * jp], acc[ai][0][m][n][2 * jp + 1]}, gv = {acc[ai][1][m][n][2 * jp], acc[ai][1][m][n][2 * jp + 1]};
;                     const f32x2v t = (av * gv) * rs2, y = gv * rsn;
;                     f32x2v ex; ex.x = __builtin_amdgcn_exp2f(y.x); ex.y = __builtin_amdgcn_exp2f(y.y);
;                     const f32x2v d = ex + 1.0f;
;                     f32x2v r; r.x = __builtin_amdgcn_rcpf(d.x); r.y = __builtin_amdgcn_rcpf(d.y);
;                     const f32x2v o = t * r;
;                     h[4 * n + 2 * jp] = o.x; h[4 * n + 2 * jp + 1] = o.y;
;                 }
;             u32x4 w; w.x = cvt_pk_bf16(h[0], h[1]); w.y = cvt_pk_bf16(h[2], h[3]); w.z = cvt_pk_bf16(h[4], h[5]); w.w = cvt_pk_bf16(h[6], h[7]);
;             *(u32x4*)(O + (size_t)(row0 + ai * HALF + m * 16) * ldc + col0) = w;
.LBB0_1298:
	s_waitcnt vmcnt(0)
	v_pk_mul_f32 v[124:125], v[124:125], v[116:117]
	v_pk_mul_f32 v[120:121], v[120:121], v[112:113]
	v_cvt_f32_u32_e32 v184, v184
	v_cvt_f32_u32_e32 v185, v185
	v_fmamk_f32 v184, v185, 0x4f800000, v184
	v_fmamk_f32 v159, v184, 0x26800000, v192
	v_rsq_f32_e32 v159, v159
	v_pk_mul_f32 v[126:127], v[126:127], v[118:119]
	v_pk_mul_f32 v[122:123], v[122:123], v[114:115]
	v_lshl_or_b32 v184, s62, 7, v188
	v_mul_f32_e32 v194, 0xbfb8aa3b, v159
	v_pk_mul_f32 v[116:117], v[116:117], v[194:195] op_sel_hi:[1,0]
	v_pk_mul_f32 v[112:113], v[112:113], v[194:195] op_sel_hi:[1,0]
	v_exp_f32_e32 v116, v116
	v_exp_f32_e32 v117, v117
	v_pk_mul_f32 v[118:119], v[118:119], v[194:195] op_sel_hi:[1,0]
	v_exp_f32_e32 v112, v112
	v_exp_f32_e32 v113, v113
	v_pk_mul_f32 v[114:115], v[114:115], v[194:195] op_sel_hi:[1,0]
	v_exp_f32_e32 v118, v118
	v_exp_f32_e32 v119, v119
	v_exp_f32_e32 v114, v114
	v_exp_f32_e32 v115, v115
	v_pk_add_f32 v[116:117], v[116:117], 1.0 op_sel_hi:[1,0]
	v_pk_add_f32 v[112:113], v[112:113], 1.0 op_sel_hi:[1,0]
	v_rcp_f32_e32 v116, v116
	v_rcp_f32_e32 v117, v117
	v_pk_add_f32 v[118:119], v[118:119], 1.0 op_sel_hi:[1,0]
	v_rcp_f32_e32 v112, v112
	v_rcp_f32_e32 v113, v113
	v_pk_add_f32 v[114:115], v[114:115], 1.0 op_sel_hi:[1,0]
	v_rcp_f32_e32 v118, v118
	v_rcp_f32_e32 v119, v119
	v_rcp_f32_e32 v114, v114
	v_rcp_f32_e32 v115, v115
	v_mul_f32_e32 v196, v159, v159
	v_pk_mul_f32 v[124:125], v[124:125], v[196:197] op_sel_hi:[1,0]
	v_pk_mul_f32 v[120:121], v[120:121], v[196:197] op_sel_hi:[1,0]
	v_pk_mul_f32 v[116:117], v[124:125], v[116:117]
	v_pk_mul_f32 v[124:125], v[126:127], v[196:197] op_sel_hi:[1,0]
	v_pk_mul_f32 v[112:113], v[120:121], v[112:113]
	v_pk_mul_f32 v[120:121], v[122:123], v[196:197] op_sel_hi:[1,0]
	v_pk_mul_f32 v[118:119], v[124:125], v[118:119]
	v_pk_mul_f32 v[114:115], v[120:121], v[114:115]
	v_cvt_pk_bf16_f32 v116, v116, v117
	v_cvt_pk_bf16_f32 v117, v118, v119
	v_cvt_pk_bf16_f32 v118, v112, v113
	v_ashrrev_i32_e32 v185, 31, v184
	v_cvt_pk_bf16_f32 v119, v114, v115
	v_mov_b64_e32 v[112:113], s[24:25]
	v_mad_i64_i32 v[120:121], s[46:47], v180, s61, v[112:113]
	v_cvt_f32_u32_e32 v182, v182
	v_cvt_f32_u32_e32 v183, v183
	v_fmamk_f32 v182, v183, 0x4f800000, v182
	v_fmamk_f32 v114, v182, 0x26800000, v192
	v_rsq_f32_e32 v122, v114
	v_lshlrev_b64 v[114:115], 1, v[184:185]
	v_lshl_add_u64 v[120:121], v[120:121], 0, v[114:115]
	global_store_dwordx4 v[120:121], v[116:119], off
	v_pk_mul_f32 v[104:105], v[104:105], v[96:97]
	v_pk_mul_f32 v[108:109], v[108:109], v[100:101]
	v_mul_f32_e32 v116, 0xbfb8aa3b, v122
	v_pk_mul_f32 v[96:97], v[96:97], v[116:117] op_sel_hi:[1,0]
	v_pk_mul_f32 v[100:101], v[100:101], v[116:117] op_sel_hi:[1,0]
	v_pk_mul_f32 v[106:107], v[106:107], v[98:99]
	v_exp_f32_e32 v96, v96
	v_exp_f32_e32 v97, v97
	v_pk_mul_f32 v[98:99], v[98:99], v[116:117] op_sel_hi:[1,0]
	v_exp_f32_e32 v100, v100
	v_exp_f32_e32 v101, v101
	v_exp_f32_e32 v98, v98
	v_exp_f32_e32 v99, v99
	v_pk_add_f32 v[96:97], v[96:97], 1.0 op_sel_hi:[1,0]
	v_pk_add_f32 v[100:101], v[100:101], 1.0 op_sel_hi:[1,0]
	v_rcp_f32_e32 v96, v96
	v_rcp_f32_e32 v97, v97
	v_pk_add_f32 v[98:99], v[98:99], 1.0 op_sel_hi:[1,0]
	v_rcp_f32_e32 v100, v100
	v_rcp_f32_e32 v101, v101
	v_rcp_f32_e32 v98, v98
	v_rcp_f32_e32 v99, v99
	v_mul_f32_e32 v118, v122, v122
	v_pk_mul_f32 v[104:105], v[104:105], v[118:119] op_sel_hi:[1,0]
	v_pk_mul_f32 v[108:109], v[108:109], v[118:119] op_sel_hi:[1,0]
	v_pk_mul_f32 v[104:105], v[104:105], v[96:97]
	v_pk_mul_f32 v[96:97], v[106:107], v[118:119] op_sel_hi:[1,0]
	v_pk_mul_f32 v[100:101], v[108:109], v[100:101]
	v_pk_mul_f32 v[106:107], v[96:97], v[98:99]
	v_pk_mul_f32 v[110:111], v[110:111], v[102:103]
	v_pk_mul_f32 v[102:103], v[102:103], v[116:117] op_sel_hi:[1,0]
	v_cvt_pk_bf16_f32 v96, v100, v101
	v_exp_f32_e32 v102, v102
	v_exp_f32_e32 v103, v103
	s_nop 0
	v_pk_add_f32 v[102:103], v[102:103], 1.0 op_sel_hi:[1,0]
	v_rcp_f32_e32 v102, v102
	v_rcp_f32_e32 v103, v103
	v_pk_mul_f32 v[108:109], v[110:111], v[118:119] op_sel_hi:[1,0]
	v_pk_mul_f32 v[102:103], v[108:109], v[102:103]
	v_cvt_f32_u32_e32 v178, v178
	v_cvt_f32_u32_e32 v179, v179
	v_fmamk_f32 v178, v179, 0x4f800000, v178
	v_fmamk_f32 v100, v178, 0x26800000, v192
	v_cvt_pk_bf16_f32 v97, v102, v103
	v_rsq_f32_e32 v102, v100
	v_mad_i64_i32 v[100:101], s[46:47], v176, s61, v[112:113]
	v_lshl_add_u64 v[100:101], v[100:101], 0, v[114:115]
	v_cvt_pk_bf16_f32 v98, v104, v105
	v_cvt_pk_bf16_f32 v99, v106, v107
	global_store_dwordx4 v[100:101], v[96:99], off
	v_pk_mul_f32 v[88:89], v[88:89], v[80:81]
	v_pk_mul_f32 v[92:93], v[92:93], v[84:85]
	v_mul_f32_e32 v96, 0xbfb8aa3b, v102
	v_pk_mul_f32 v[80:81], v[80:81], v[96:97] op_sel_hi:[1,0]
	v_pk_mul_f32 v[84:85], v[84:85], v[96:97] op_sel_hi:[1,0]
	v_pk_mul_f32 v[90:91], v[90:91], v[82:83]
	v_exp_f32_e32 v80, v80
	v_exp_f32_e32 v81, v81
	v_pk_mul_f32 v[82:83], v[82:83], v[96:97] op_sel_hi:[1,0]
	v_exp_f32_e32 v84, v84
	v_exp_f32_e32 v85, v85
	v_exp_f32_e32 v82, v82
	v_exp_f32_e32 v83, v83
	v_pk_add_f32 v[80:81], v[80:81], 1.0 op_sel_hi:[1,0]
	v_pk_add_f32 v[84:85], v[84:85], 1.0 op_sel_hi:[1,0]
	v_rcp_f32_e32 v80, v80
	v_rcp_f32_e32 v81, v81
	v_pk_add_f32 v[82:83], v[82:83], 1.0 op_sel_hi:[1,0]
	v_rcp_f32_e32 v84, v84
	v_rcp_f32_e32 v85, v85
	v_rcp_f32_e32 v82, v82
	v_rcp_f32_e32 v83, v83
	v_mul_f32_e32 v98, v102, v102
	v_pk_mul_f32 v[88:89], v[88:89], v[98:99] op_sel_hi:[1,0]
	v_pk_mul_f32 v[92:93], v[92:93], v[98:99] op_sel_hi:[1,0]
	v_pk_mul_f32 v[88:89], v[88:89], v[80:81]
	v_pk_mul_f32 v[80:81], v[90:91], v[98:99] op_sel_hi:[1,0]
	v_pk_mul_f32 v[84:85], v[92:93], v[84:85]
	v_pk_mul_f32 v[90:91], v[80:81], v[82:83]
; __device__ __forceinline__ unsigned cvt_pk_bf16(float lo, float hi) { unsigned r; asm volatile("v_cvt_pk_bf16_f32 %0, %1, %2" : "=v"(r) : "v"(lo), "v"(hi)); return r; }
; __device__ __forceinline__ float ss_val(u64 v) { return (float)v * (1.0f / 1099511627776.0f); }
;     __device__ __forceinline__ void operator()(const f32x4 (&acc)[2][2][4][2], const Unit& u, const Unit& nxt, bool has_next, int wr, int wc, int fr, int fq) const {
;     ...
;         for (int g = 0; g < 8; ++g) {
;             const int ai = g >> 2, m = g & 3;
;             const float rs = __builtin_amdgcn_rsqf(ss_val(cur[g]) * inv_k + eps), rsn = rs * -1.44269504089f, rs2 = rs * rs;
;             float h[8];
; #pragma unroll
;             for (int n = 0; n < 2; ++n)
; #pragma unroll
;                 for (int jp = 0; jp < 2; ++jp) {
;                     const f32x2v av = {acc[ai][0][m][n][2 * jp], acc[ai][0][m][n][2 * jp + 1]}, gv = {acc[ai][1][m][n][2 * jp], acc[ai][1][m][n][2 * jp + 1]};
;                     const f32x2v t = (av * gv) * rs2, y = gv * rsn;
;                     f32x2v ex; ex.x = __builtin_amdgcn_exp2f(y.x); ex.y = __builtin_amdgcn_exp2f(y.y);
;                     const f32x2v d = ex + 1.0f;
;                     f32x2v r; r.x = __builtin_amdgcn_rcpf(d.x); r.y = __builtin_amdgcn_rcpf(d.y);
;                     const f32x2v o = t * r;
;                     h[4 * n + 2 * jp] = o.x; h[4 * n + 2 * jp + 1] = o.y;
;                 }
;             u32x4 w; w.x = cvt_pk_bf16(h[0], h[1]); w.y = cvt_pk_bf16(h[2], h[3]); w.z = cvt_pk_bf16(h[4], h[5]); w.w = cvt_pk_bf16(h[6], h[7]);
;             *(u32x4*)(O + (size_t)(row0 + ai * HALF + m * 16) * ldc + col0) = w;
	v_pk_mul_f32 v[94:95], v[94:95], v[86:87]
	v_pk_mul_f32 v[86:87], v[86:87], v[96:97] op_sel_hi:[1,0]
	v_cvt_pk_bf16_f32 v80, v84, v85
	v_exp_f32_e32 v86, v86
	v_exp_f32_e32 v87, v87
	s_nop 0
	v_pk_add_f32 v[86:87], v[86:87], 1.0 op_sel_hi:[1,0]
	v_rcp_f32_e32 v86, v86
	v_rcp_f32_e32 v87, v87
	v_pk_mul_f32 v[92:93], v[94:95], v[98:99] op_sel_hi:[1,0]
	v_pk_mul_f32 v[86:87], v[92:93], v[86:87]
	v_cvt_f32_u32_e32 v174, v174
	v_cvt_f32_u32_e32 v175, v175
	v_fmamk_f32 v174, v175, 0x4f800000, v174
	v_fmamk_f32 v84, v174, 0x26800000, v192
	v_cvt_pk_bf16_f32 v81, v86, v87
	v_rsq_f32_e32 v86, v84
	v_mad_i64_i32 v[84:85], s[46:47], v172, s61, v[112:113]
	v_lshl_add_u64 v[84:85], v[84:85], 0, v[114:115]
	v_cvt_pk_bf16_f32 v82, v88, v89
	v_cvt_pk_bf16_f32 v83, v90, v91
	global_store_dwordx4 v[84:85], v[80:83], off
	v_pk_mul_f32 v[72:73], v[72:73], v[64:65]
	v_pk_mul_f32 v[76:77], v[76:77], v[68:69]
	v_mul_f32_e32 v80, 0xbfb8aa3b, v86
	v_pk_mul_f32 v[64:65], v[64:65], v[80:81] op_sel_hi:[1,0]
	v_pk_mul_f32 v[68:69], v[68:69], v[80:81] op_sel_hi:[1,0]
	v_pk_mul_f32 v[74:75], v[74:75], v[66:67]
	v_exp_f32_e32 v64, v64
	v_exp_f32_e32 v65, v65
	v_pk_mul_f32 v[66:67], v[66:67], v[80:81] op_sel_hi:[1,0]
	v_exp_f32_e32 v68, v68
	v_exp_f32_e32 v69, v69
	v_exp_f32_e32 v66, v66
	v_exp_f32_e32 v67, v67
	v_pk_add_f32 v[64:65], v[64:65], 1.0 op_sel_hi:[1,0]
	v_pk_add_f32 v[68:69], v[68:69], 1.0 op_sel_hi:[1,0]
	v_rcp_f32_e32 v64, v64
	v_rcp_f32_e32 v65, v65
	v_pk_add_f32 v[66:67], v[66:67], 1.0 op_sel_hi:[1,0]
	v_rcp_f32_e32 v68, v68
	v_rcp_f32_e32 v69, v69
	v_rcp_f32_e32 v66, v66
	v_rcp_f32_e32 v67, v67
	v_mul_f32_e32 v82, v86, v86
	v_pk_mul_f32 v[72:73], v[72:73], v[82:83] op_sel_hi:[1,0]
	v_pk_mul_f32 v[76:77], v[76:77], v[82:83] op_sel_hi:[1,0]
	v_pk_mul_f32 v[72:73], v[72:73], v[64:65]
	v_pk_mul_f32 v[64:65], v[74:75], v[82:83] op_sel_hi:[1,0]
	v_pk_mul_f32 v[68:69], v[76:77], v[68:69]
	v_pk_mul_f32 v[74:75], v[64:65], v[66:67]
	v_pk_mul_f32 v[78:79], v[78:79], v[70:71]
	v_pk_mul_f32 v[70:71], v[70:71], v[80:81] op_sel_hi:[1,0]
	v_cvt_pk_bf16_f32 v64, v68, v69
	v_exp_f32_e32 v70, v70
	v_exp_f32_e32 v71, v71
	s_nop 0
	v_pk_add_f32 v[70:71], v[70:71], 1.0 op_sel_hi:[1,0]
	v_rcp_f32_e32 v70, v70
	v_rcp_f32_e32 v71, v71
	v_pk_mul_f32 v[76:77], v[78:79], v[82:83] op_sel_hi:[1,0]
	v_pk_mul_f32 v[70:71], v[76:77], v[70:71]
	v_cvt_f32_u32_e32 v170, v170
	v_cvt_f32_u32_e32 v171, v171
	v_fmamk_f32 v170, v171, 0x4f800000, v170
	v_fmamk_f32 v68, v170, 0x26800000, v192
	v_cvt_pk_bf16_f32 v65, v70, v71
	v_rsq_f32_e32 v70, v68
	v_mad_i64_i32 v[68:69], s[46:47], v168, s61, v[112:113]
	v_lshl_add_u64 v[68:69], v[68:69], 0, v[114:115]
	v_cvt_pk_bf16_f32 v66, v72, v73
	v_cvt_pk_bf16_f32 v67, v74, v75
	global_store_dwordx4 v[68:69], v[64:67], off
	v_pk_mul_f32 v[56:57], v[56:57], v[48:49]
	v_pk_mul_f32 v[60:61], v[60:61], v[52:53]
	v_mul_f32_e32 v64, 0xbfb8aa3b, v70
	v_pk_mul_f32 v[48:49], v[48:49], v[64:65] op_sel_hi:[1,0]
	v_pk_mul_f32 v[52:53], v[52:53], v[64:65] op_sel_hi:[1,0]
	v_pk_mul_f32 v[58:59], v[58:59], v[50:51]
	v_exp_f32_e32 v48, v48
	v_exp_f32_e32 v49, v49
	v_pk_mul_f32 v[50:51], v[50:51], v[64:65] op_sel_hi:[1,0]
	v_exp_f32_e32 v52, v52
	v_exp_f32_e32 v53, v53
	v_exp_f32_e32 v50, v50
	v_exp_f32_e32 v51, v51
	v_pk_add_f32 v[48:49], v[48:49], 1.0 op_sel_hi:[1,0]
	v_pk_add_f32 v[52:53], v[52:53], 1.0 op_sel_hi:[1,0]
	v_rcp_f32_e32 v48, v48
	v_rcp_f32_e32 v49, v49
	v_pk_add_f32 v[50:51], v[50:51], 1.0 op_sel_hi:[1,0]
	v_rcp_f32_e32 v52, v52
	v_rcp_f32_e32 v53, v53
	v_rcp_f32_e32 v50, v50
	v_rcp_f32_e32 v51, v51
	v_mul_f32_e32 v66, v70, v70
	v_pk_mul_f32 v[56:57], v[56:57], v[66:67] op_sel_hi:[1,0]
	v_pk_mul_f32 v[60:61], v[60:61], v[66:67] op_sel_hi:[1,0]
	v_pk_mul_f32 v[56:57], v[56:57], v[48:49]
	v_pk_mul_f32 v[48:49], v[58:59], v[66:67] op_sel_hi:[1,0]
	v_pk_mul_f32 v[52:53], v[60:61], v[52:53]
	v_pk_mul_f32 v[58:59], v[48:49], v[50:51]
	v_pk_mul_f32 v[62:63], v[62:63], v[54:55]
	v_pk_mul_f32 v[54:55], v[54:55], v[64:65] op_sel_hi:[1,0]
	v_cvt_pk_bf16_f32 v48, v52, v53
	v_exp_f32_e32 v54, v54
	v_exp_f32_e32 v55, v55
	s_nop 0
	v_pk_add_f32 v[54:55], v[54:55], 1.0 op_sel_hi:[1,0]
	v_rcp_f32_e32 v54, v54
	v_rcp_f32_e32 v55, v55
	v_pk_mul_f32 v[60:61], v[62:63], v[66:67] op_sel_hi:[1,0]
	v_pk_mul_f32 v[54:55], v[60:61], v[54:55]
	v_cvt_f32_u32_e32 v166, v166
	v_cvt_f32_u32_e32 v167, v167
	v_fmamk_f32 v166, v167, 0x4f800000, v166
	v_fmamk_f32 v52, v166, 0x26800000, v192
	v_cvt_pk_bf16_f32 v49, v54, v55
	v_rsq_f32_e32 v54, v52
	v_add_u32_e32 v141, 0x80, v180
	v_mad_i64_i32 v[52:53], s[46:47], v141, s61, v[112:113]
	v_lshl_add_u64 v[52:53], v[52:53], 0, v[114:115]
	v_cvt_pk_bf16_f32 v50, v56, v57
	v_cvt_pk_bf16_f32 v51, v58, v59
	global_store_dwordx4 v[52:53], v[48:51], off
	v_pk_mul_f32 v[40:41], v[40:41], v[32:33]
	v_pk_mul_f32 v[44:45], v[44:45], v[36:37]
	v_mul_f32_e32 v48, 0xbfb8aa3b, v54
	v_pk_mul_f32 v[32:33], v[32:33], v[48:49] op_sel_hi:[1,0]
	v_pk_mul_f32 v[36:37], v[36:37], v[48:49] op_sel_hi:[1,0]
	v_pk_mul_f32 v[42:43], v[42:43], v[34:35]
	v_exp_f32_e32 v32, v32
	v_exp_f32_e32 v33, v33
	v_pk_mul_f32 v[34:35], v[34:35], v[48:49] op_sel_hi:[1,0]
	v_exp_f32_e32 v36, v36
	v_exp_f32_e32 v37, v37
	v_exp_f32_e32 v34, v34
	v_exp_f32_e32 v35, v35
	v_pk_add_f32 v[32:33], v[32:33], 1.0 op_sel_hi:[1,0]
	v_pk_add_f32 v[36:37], v[36:37], 1.0 op_sel_hi:[1,0]
	v_rcp_f32_e32 v32, v32
; __device__ __forceinline__ unsigned cvt_pk_bf16(float lo, float hi) { unsigned r; asm volatile("v_cvt_pk_bf16_f32 %0, %1, %2" : "=v"(r) : "v"(lo), "v"(hi)); return r; }
; __device__ __forceinline__ float ss_val(u64 v) { return (float)v * (1.0f / 1099511627776.0f); }
;     __device__ __forceinline__ void operator()(const f32x4 (&acc)[2][2][4][2], const Unit& u, const Unit& nxt, bool has_next, int wr, int wc, int fr, int fq) const {
;     ...
;         for (int g = 0; g < 8; ++g) {
;             const int ai = g >> 2, m = g & 3;
;             const float rs = __builtin_amdgcn_rsqf(ss_val(cur[g]) * inv_k + eps), rsn = rs * -1.44269504089f, rs2 = rs * rs;
;             float h[8];
; #pragma unroll
;             for (int n = 0; n < 2; ++n)
; #pragma unroll
;                 for (int jp = 0; jp < 2; ++jp) {
;                     const f32x2v av = {acc[ai][0][m][n][2 * jp], acc[ai][0][m][n][2 * jp + 1]}, gv = {acc[ai][1][m][n][2 * jp], acc[ai][1][m][n][2 * jp + 1]};
;                     const f32x2v t = (av * gv) * rs2, y = gv * rsn;
;                     f32x2v ex; ex.x = __builtin_amdgcn_exp2f(y.x); ex.y = __builtin_amdgcn_exp2f(y.y);
;                     const f32x2v d = ex + 1.0f;
;                     f32x2v r; r.x = __builtin_amdgcn_rcpf(d.x); r.y = __builtin_amdgcn_rcpf(d.y);
;                     const f32x2v o = t * r;
;                     h[4 * n + 2 * jp] = o.x; h[4 * n + 2 * jp + 1] = o.y;
;                 }
;             u32x4 w; w.x = cvt_pk_bf16(h[0], h[1]); w.y = cvt_pk_bf16(h[2], h[3]); w.z = cvt_pk_bf16(h[4], h[5]); w.w = cvt_pk_bf16(h[6], h[7]);
;             *(u32x4*)(O + (size_t)(row0 + ai * HALF + m * 16) * ldc + col0) = w;
;         }
;         if (has_next) { u64 x = 0;
; #pragma unroll
;             for (int g = 0; g < 8; ++g) x |= warm[g];
;             asm volatile("" :: "v"((unsigned)x), "v"((unsigned)(x >> 32))); }
	v_rcp_f32_e32 v33, v33
	v_pk_add_f32 v[34:35], v[34:35], 1.0 op_sel_hi:[1,0]
	v_rcp_f32_e32 v36, v36
	v_rcp_f32_e32 v37, v37
	v_rcp_f32_e32 v34, v34
	v_rcp_f32_e32 v35, v35
	v_mul_f32_e32 v50, v54, v54
	v_pk_mul_f32 v[40:41], v[40:41], v[50:51] op_sel_hi:[1,0]
	v_pk_mul_f32 v[44:45], v[44:45], v[50:51] op_sel_hi:[1,0]
	v_pk_mul_f32 v[40:41], v[40:41], v[32:33]
	v_pk_mul_f32 v[32:33], v[42:43], v[50:51] op_sel_hi:[1,0]
	v_pk_mul_f32 v[36:37], v[44:45], v[36:37]
	v_pk_mul_f32 v[42:43], v[32:33], v[34:35]
	v_pk_mul_f32 v[46:47], v[46:47], v[38:39]
	v_pk_mul_f32 v[38:39], v[38:39], v[48:49] op_sel_hi:[1,0]
	v_cvt_pk_bf16_f32 v32, v36, v37
	v_exp_f32_e32 v38, v38
	v_exp_f32_e32 v39, v39
	s_nop 0
	v_pk_add_f32 v[38:39], v[38:39], 1.0 op_sel_hi:[1,0]
	v_rcp_f32_e32 v38, v38
	v_rcp_f32_e32 v39, v39
	v_pk_mul_f32 v[44:45], v[46:47], v[50:51] op_sel_hi:[1,0]
	v_pk_mul_f32 v[38:39], v[44:45], v[38:39]
	v_cvt_f32_u32_e32 v164, v164
	v_cvt_f32_u32_e32 v165, v165
	v_fmamk_f32 v164, v165, 0x4f800000, v164
	v_fmamk_f32 v36, v164, 0x26800000, v192
	v_cvt_pk_bf16_f32 v33, v38, v39
	v_rsq_f32_e32 v38, v36
	v_mad_i64_i32 v[36:37], s[46:47], v162, s61, v[112:113]
	v_lshl_add_u64 v[36:37], v[36:37], 0, v[114:115]
	v_cvt_pk_bf16_f32 v34, v40, v41
	v_cvt_pk_bf16_f32 v35, v42, v43
	global_store_dwordx4 v[36:37], v[32:35], off
	v_pk_mul_f32 v[24:25], v[24:25], v[16:17]
	v_pk_mul_f32 v[28:29], v[28:29], v[20:21]
	v_mul_f32_e32 v32, 0xbfb8aa3b, v38
	v_pk_mul_f32 v[16:17], v[16:17], v[32:33] op_sel_hi:[1,0]
	v_pk_mul_f32 v[20:21], v[20:21], v[32:33] op_sel_hi:[1,0]
	v_pk_mul_f32 v[26:27], v[26:27], v[18:19]
	v_exp_f32_e32 v16, v16
	v_exp_f32_e32 v17, v17
	v_pk_mul_f32 v[18:19], v[18:19], v[32:33] op_sel_hi:[1,0]
	v_exp_f32_e32 v20, v20
	v_exp_f32_e32 v21, v21
	v_exp_f32_e32 v18, v18
	v_exp_f32_e32 v19, v19
	v_pk_add_f32 v[16:17], v[16:17], 1.0 op_sel_hi:[1,0]
	v_pk_add_f32 v[20:21], v[20:21], 1.0 op_sel_hi:[1,0]
	v_rcp_f32_e32 v16, v16
	v_rcp_f32_e32 v17, v17
	v_pk_add_f32 v[18:19], v[18:19], 1.0 op_sel_hi:[1,0]
	v_rcp_f32_e32 v20, v20
	v_rcp_f32_e32 v21, v21
	v_rcp_f32_e32 v18, v18
	v_rcp_f32_e32 v19, v19
	v_mul_f32_e32 v34, v38, v38
	v_pk_mul_f32 v[24:25], v[24:25], v[34:35] op_sel_hi:[1,0]
	v_pk_mul_f32 v[28:29], v[28:29], v[34:35] op_sel_hi:[1,0]
	v_pk_mul_f32 v[24:25], v[24:25], v[16:17]
	v_pk_mul_f32 v[16:17], v[26:27], v[34:35] op_sel_hi:[1,0]
	v_pk_mul_f32 v[20:21], v[28:29], v[20:21]
	v_pk_mul_f32 v[26:27], v[16:17], v[18:19]
	v_pk_mul_f32 v[30:31], v[30:31], v[22:23]
	v_pk_mul_f32 v[22:23], v[22:23], v[32:33] op_sel_hi:[1,0]
	v_cvt_pk_bf16_f32 v16, v20, v21
	v_exp_f32_e32 v22, v22
	v_exp_f32_e32 v23, v23
	s_nop 0
	v_pk_add_f32 v[22:23], v[22:23], 1.0 op_sel_hi:[1,0]
	v_rcp_f32_e32 v22, v22
	v_rcp_f32_e32 v23, v23
	v_pk_mul_f32 v[28:29], v[30:31], v[34:35] op_sel_hi:[1,0]
	v_pk_mul_f32 v[22:23], v[28:29], v[22:23]
	v_cvt_f32_u32_e32 v160, v160
	v_cvt_f32_u32_e32 v161, v161
	v_fmamk_f32 v160, v161, 0x4f800000, v160
	v_fmamk_f32 v20, v160, 0x26800000, v192
	v_cvt_pk_bf16_f32 v17, v22, v23
	v_rsq_f32_e32 v22, v20
	v_mad_i64_i32 v[20:21], s[46:47], v158, s61, v[112:113]
	v_lshl_add_u64 v[20:21], v[20:21], 0, v[114:115]
	v_cvt_pk_bf16_f32 v18, v24, v25
	v_cvt_pk_bf16_f32 v19, v26, v27
	global_store_dwordx4 v[20:21], v[16:19], off
	v_pk_mul_f32 v[12:13], v[12:13], v[4:5]
	v_pk_mul_f32 v[8:9], v[8:9], v[0:1]
	v_mul_f32_e32 v16, 0xbfb8aa3b, v22
	v_pk_mul_f32 v[4:5], v[4:5], v[16:17] op_sel_hi:[1,0]
	v_pk_mul_f32 v[0:1], v[0:1], v[16:17] op_sel_hi:[1,0]
	v_exp_f32_e32 v4, v4
	v_exp_f32_e32 v5, v5
	v_pk_mul_f32 v[10:11], v[10:11], v[2:3]
	v_exp_f32_e32 v0, v0
	v_exp_f32_e32 v1, v1
	v_pk_mul_f32 v[2:3], v[2:3], v[16:17] op_sel_hi:[1,0]
	v_pk_mul_f32 v[14:15], v[14:15], v[6:7]
	v_exp_f32_e32 v2, v2
	v_exp_f32_e32 v3, v3
	v_pk_mul_f32 v[6:7], v[6:7], v[16:17] op_sel_hi:[1,0]
	v_pk_add_f32 v[4:5], v[4:5], 1.0 op_sel_hi:[1,0]
	v_exp_f32_e32 v6, v6
	v_exp_f32_e32 v7, v7
	v_pk_add_f32 v[0:1], v[0:1], 1.0 op_sel_hi:[1,0]
	v_rcp_f32_e32 v4, v4
	v_rcp_f32_e32 v5, v5
	v_rcp_f32_e32 v0, v0
	v_rcp_f32_e32 v1, v1
	v_pk_add_f32 v[2:3], v[2:3], 1.0 op_sel_hi:[1,0]
	v_mul_f32_e32 v18, v22, v22
	v_rcp_f32_e32 v2, v2
	v_rcp_f32_e32 v3, v3
	v_pk_add_f32 v[6:7], v[6:7], 1.0 op_sel_hi:[1,0]
	v_pk_mul_f32 v[12:13], v[12:13], v[18:19] op_sel_hi:[1,0]
	v_rcp_f32_e32 v6, v6
	v_rcp_f32_e32 v7, v7
	v_pk_mul_f32 v[8:9], v[8:9], v[18:19] op_sel_hi:[1,0]
	v_pk_mul_f32 v[4:5], v[12:13], v[4:5]
	v_pk_mul_f32 v[8:9], v[8:9], v[0:1]
	v_pk_mul_f32 v[0:1], v[10:11], v[18:19] op_sel_hi:[1,0]
	v_pk_mul_f32 v[12:13], v[14:15], v[18:19] op_sel_hi:[1,0]
	v_pk_mul_f32 v[10:11], v[0:1], v[2:3]
	v_cvt_pk_bf16_f32 v0, v4, v5
	v_mad_i64_i32 v[4:5], s[46:47], v140, s61, v[112:113]
	v_lshl_add_u64 v[4:5], v[4:5], 0, v[114:115]
	s_and_b64 vcc, exec, s[2:3]
	s_mov_b64 s[2:3], -1
	v_pk_mul_f32 v[6:7], v[12:13], v[6:7]
	s_nop 0
	v_cvt_pk_bf16_f32 v1, v6, v7
	v_cvt_pk_bf16_f32 v2, v8, v9
	v_cvt_pk_bf16_f32 v3, v10, v11
	global_store_dwordx4 v[4:5], v[0:3], off
	s_cbranch_vccnz .LBB0_1289
	s_nop 0
	v_or_b32_e32 v0, v157, v155
	v_or_b32_e32 v1, v156, v154
	v_or3_b32 v0, v0, v151, v153
	v_or3_b32 v1, v1, v150, v152
	v_or3_b32 v0, v0, v147, v149
	v_or3_b32 v1, v1, v146, v148
	s_andn2_b64 vcc, exec, s[4:5]
	v_or3_b32 v0, v0, v143, v145
	v_or3_b32 v1, v1, v142, v144
	s_cbranch_vccnz .LBB0_1288
	s_barrier
	s_branch .LBB0_1288

; __device__ __forceinline__ void xcd_barrier(const XcdBarrier& b) {
;     asm volatile("s_waitcnt vmcnt(0)" ::: "memory");
;     __syncthreads();
;     if (threadIdx.x == 0) {
;         unsigned* bar = b.bar;
;         __builtin_amdgcn_s_waitcnt(0);
;         unsigned nloc = b.st[0], nx = b.st[1];
; template <int L>
; __device__ __forceinline__ void layer(const Args& a, LAS unsigned char* lds, const XcdBarrier& bar, int lo, int hi, int wave, int lane, int b, int r, int GS) {
;     ...
;         pg8::Gemm g{HB, (const bf16*)(wl + W4_OFF), SEQ, D, DFF}; pg8::GroupOrder S; S.init(SEQ, D, GS, r);
;         pg8::EpiResid E{nullptr, XN, rowss + (size_t)(3 * L + 3) * M, 0.5f, D};
;         pg8::gemm_phase<pg8::EpiResid, pg8::GroupOrder, true, true>(lds, g, S, E);
.LBB0_1302:
	s_cmp_gt_i32 s53, 18
	s_cselect_b64 s[2:3], -1, 0
	s_and_b64 s[0:1], s[0:1], s[2:3]
	s_andn2_b64 vcc, exec, s[0:1]
	s_cbranch_vccnz .LBB0_1347
	s_waitcnt vmcnt(0)
	s_waitcnt lgkmcnt(0)
	s_barrier
	s_cmp_eq_u32 s97, 0
	s_cbranch_scc1 .Lbpf_skip_16
	v_mov_b32_e32 v232, s95
	v_mul_u32_u24_e32 v232, 7, v232
	v_add_u32_e32 v232, s97, v232
	v_add_u32_e32 v232, -1, v232
	v_lshl_add_u32 v232, v232, 6, v200
	v_lshrrev_b32_e32 v231, 1, v232
	v_min_u32_e32 v231, 0x3ff, v231
	v_mul_u32_u24_e32 v231, 0x1600, v231
	v_and_b32_e32 v232, 1, v232
	v_lshlrev_b32_e32 v232, 7, v232
	v_add_u32_e32 v232, v231, v232
	v_add_u32_e32 v232, 0x5380000, v232
	global_load_dword v231, v232, s[34:35]

; __device__ __forceinline__ float ss_val(u64 v) { return (float)v * (1.0f / 1099511627776.0f); }
; __global__ void __launch_bounds__(NTHREADS, 2) fwd(Args a) {
;     ...
;         for (int m = gw; m < SEQ; m += 2 * NGW) {
;             const int m1 = m + NGW; const bool two = m1 < SEQ;
;             u32x4 xv[2][2]; u64 sv[2];
;             sv[0] = rs6[m]; sv[1] = two ? rs6[m1] : sv[0];
; #pragma unroll
;             for (int j = 0; j < 2; ++j) { xv[0][j] = *((const u32x4*)(XN + (size_t)m * D) + lane + 64 * j); xv[1][j] = two ? *((const u32x4*)(XN + (size_t)m1 * D) + lane + 64 * j) : xv[0][j]; }
;             asm volatile("" : "+v"(xv[0][0]), "+v"(xv[0][1]), "+v"(xv[1][0]), "+v"(xv[1][1]), "+v"(sv[0]), "+v"(sv[1]) :: "memory");
; #pragma unroll
;             for (int r2 = 0; r2 < 2; ++r2) {
;                 if (r2 == 1 && !two) break;
;                 const float rs = __builtin_amdgcn_rsqf(ss_val(sv[r2]) * (1.f / D) + EPS);
;                 f32x4* orow = (f32x4*)(outb + (size_t)(r2 ? m1 : m) * D);
; #pragma unroll
;                 for (int j = 0; j < 2; ++j) {
;                     const u32x4 x4 = xv[r2][j]; const f32x4 w0 = wv[j][0], w1 = wv[j][1];
;                     f32x4 o0, o1;
;                     o0[0] = bf_lo(x4[0]) * rs * w0[0]; o0[1] = bf_hi(x4[0]) * rs * w0[1]; o0[2] = bf_lo(x4[1]) * rs * w0[2]; o0[3] = bf_hi(x4[1]) * rs * w0[3];
;                     o1[0] = bf_lo(x4[2]) * rs * w1[0]; o1[1] = bf_hi(x4[2]) * rs * w1[1]; o1[2] = bf_lo(x4[3]) * rs * w1[2]; o1[3] = bf_hi(x4[3]) * rs * w1[3];
;                     orow[2 * (lane + 64 * j)] = o0; orow[2 * (lane + 64 * j) + 1] = o1;
;                 }
;             }
.LBB0_1443:
	s_waitcnt vmcnt(0)
	s_lshl_b64 s[8:9], s[38:39], 12
	v_ffbh_u32_e32 v42, v41
	v_min_u32_e32 v42, 32, v42
	v_lshlrev_b64 v[40:41], v42, v[40:41]
	v_min_u32_e32 v40, 1, v40
	v_or_b32_e32 v40, v41, v40
	v_cvt_f32_u32_e32 v43, v40
	v_lshlrev_b32_e32 v40, 16, v28
	v_and_b32_e32 v41, 0xffff0000, v28
	v_sub_u32_e32 v28, 32, v42
	v_ldexp_f32 v28, v43, v28
	v_mul_f32_e32 v28, 0x2b800000, v28
	v_fmamk_f32 v28, v28, 0x3a800000, v32
	v_rsq_f32_e32 v44, v28
	v_lshlrev_b32_e32 v28, 16, v29
	v_and_b32_e32 v29, 0xffff0000, v29
	v_lshlrev_b32_e32 v46, 16, v30
	v_pk_mul_f32 v[28:29], v[44:45], v[28:29] op_sel_hi:[0,1]
	v_and_b32_e32 v47, 0xffff0000, v30
	v_pk_mul_f32 v[40:41], v[44:45], v[40:41] op_sel_hi:[0,1]
	v_pk_mul_f32 v[42:43], v[10:11], v[28:29]
	v_pk_mul_f32 v[28:29], v[44:45], v[46:47] op_sel_hi:[0,1]
	v_lshlrev_b32_e32 v30, 16, v31
	v_and_b32_e32 v31, 0xffff0000, v31
	v_pk_mul_f32 v[40:41], v[8:9], v[40:41]
	v_pk_mul_f32 v[28:29], v[12:13], v[28:29]
	v_pk_mul_f32 v[30:31], v[44:45], v[30:31] op_sel_hi:[0,1]
	v_lshl_add_u64 v[46:47], v[36:37], 0, s[8:9]
	v_pk_mul_f32 v[30:31], v[14:15], v[30:31]
	global_store_dwordx4 v[46:47], v[40:43], off
	global_store_dwordx4 v[46:47], v[28:31], off offset:16
	s_and_b64 vcc, exec, s[0:1]
	s_nop 0
	v_lshlrev_b32_e32 v28, 16, v24
	v_and_b32_e32 v29, 0xffff0000, v24
	v_lshlrev_b32_e32 v24, 16, v25
	v_and_b32_e32 v25, 0xffff0000, v25
	v_pk_mul_f32 v[24:25], v[44:45], v[24:25] op_sel_hi:[0,1]
	v_pk_mul_f32 v[30:31], v[2:3], v[24:25]
	v_lshlrev_b32_e32 v24, 16, v26
	v_and_b32_e32 v25, 0xffff0000, v26
	v_lshlrev_b32_e32 v26, 16, v27
	v_and_b32_e32 v27, 0xffff0000, v27
	v_pk_mul_f32 v[28:29], v[44:45], v[28:29] op_sel_hi:[0,1]
	v_pk_mul_f32 v[24:25], v[44:45], v[24:25] op_sel_hi:[0,1]
	v_pk_mul_f32 v[26:27], v[44:45], v[26:27] op_sel_hi:[0,1]
	v_pk_mul_f32 v[28:29], v[0:1], v[28:29]
	v_pk_mul_f32 v[24:25], v[4:5], v[24:25]
	v_pk_mul_f32 v[26:27], v[6:7], v[26:27]
	global_store_dwordx4 v[46:47], v[28:31], off offset:2048
	global_store_dwordx4 v[46:47], v[24:27], off offset:2064
	s_cbranch_vccnz .LBB0_1434
	s_nop 0
	v_lshlrev_b32_e32 v24, 16, v20
	s_lshl_b64 s[0:1], s[6:7], 12
	v_cvt_f32_u32_e32 v38, v38
	v_cvt_f32_u32_e32 v39, v39
	v_fmamk_f32 v38, v39, 0x4f800000, v38
	v_fmamk_f32 v25, v38, 0x26800000, v32
	v_rsq_f32_e32 v28, v25
	v_and_b32_e32 v25, 0xffff0000, v20
	v_lshlrev_b32_e32 v20, 16, v21
	v_and_b32_e32 v21, 0xffff0000, v21
	v_pk_mul_f32 v[20:21], v[28:29], v[20:21] op_sel_hi:[0,1]
	v_pk_mul_f32 v[26:27], v[10:11], v[20:21]
	v_lshlrev_b32_e32 v20, 16, v22
	v_and_b32_e32 v21, 0xffff0000, v22
	v_pk_mul_f32 v[24:25], v[28:29], v[24:25] op_sel_hi:[0,1]
	v_pk_mul_f32 v[20:21], v[28:29], v[20:21] op_sel_hi:[0,1]
	v_lshlrev_b32_e32 v22, 16, v23
	v_and_b32_e32 v23, 0xffff0000, v23
	v_pk_mul_f32 v[24:25], v[8:9], v[24:25]
	v_pk_mul_f32 v[20:21], v[12:13], v[20:21]
	v_pk_mul_f32 v[22:23], v[28:29], v[22:23] op_sel_hi:[0,1]
	v_lshl_add_u64 v[30:31], v[36:37], 0, s[0:1]
	v_pk_mul_f32 v[22:23], v[14:15], v[22:23]
	global_store_dwordx4 v[30:31], v[24:27], off
	global_store_dwordx4 v[30:31], v[20:23], off offset:16
	s_nop 1
	v_lshlrev_b32_e32 v20, 16, v16
	v_and_b32_e32 v21, 0xffff0000, v16
	v_lshlrev_b32_e32 v16, 16, v17
	v_and_b32_e32 v17, 0xffff0000, v17
	v_pk_mul_f32 v[16:17], v[28:29], v[16:17] op_sel_hi:[0,1]
	v_pk_mul_f32 v[20:21], v[28:29], v[20:21] op_sel_hi:[0,1]
	v_pk_mul_f32 v[22:23], v[2:3], v[16:17]
	v_lshlrev_b32_e32 v16, 16, v18
	v_and_b32_e32 v17, 0xffff0000, v18
	v_lshlrev_b32_e32 v18, 16, v19
	v_and_b32_e32 v19, 0xffff0000, v19
	v_pk_mul_f32 v[20:21], v[0:1], v[20:21]
	v_pk_mul_f32 v[16:17], v[28:29], v[16:17] op_sel_hi:[0,1]
	v_pk_mul_f32 v[18:19], v[28:29], v[18:19] op_sel_hi:[0,1]
	v_pk_mul_f32 v[16:17], v[4:5], v[16:17]
	v_pk_mul_f32 v[18:19], v[6:7], v[18:19]
	global_store_dwordx4 v[30:31], v[20:23], off offset:2048
	global_store_dwordx4 v[30:31], v[16:19], off offset:2064
	s_branch .LBB0_1434

; #define LAS __attribute__((address_space(3)))
; __global__ void __launch_bounds__(NTHREADS, 2) fwd(Args a) {
;     extern __shared__ __attribute__((aligned(16))) unsigned char lds_raw[];
;     LAS unsigned char* lds = (LAS unsigned char*)lds_raw;
;     const int tid = threadIdx.x, lane = tid & 63, wave = __builtin_amdgcn_readfirstlane(tid >> 6);
	.amdhsa_kernel _Z3fwd4Args
		.amdhsa_group_segment_fixed_size 0
		.amdhsa_private_segment_fixed_size 0
		.amdhsa_kernarg_size 416
		.amdhsa_user_sgpr_count 2
		.amdhsa_user_sgpr_dispatch_ptr 0
		.amdhsa_user_sgpr_queue_ptr 0
		.amdhsa_user_sgpr_kernarg_segment_ptr 1
		.amdhsa_user_sgpr_dispatch_id 0
		.amdhsa_user_sgpr_kernarg_preload_length 0
		.amdhsa_user_sgpr_kernarg_preload_offset 0
		.amdhsa_user_sgpr_private_segment_size 0
		.amdhsa_uses_dynamic_stack 0
		.amdhsa_enable_private_segment 0
		.amdhsa_system_sgpr_workgroup_id_x 1
		.amdhsa_system_sgpr_workgroup_id_y 0
		.amdhsa_system_sgpr_workgroup_id_z 0
		.amdhsa_system_sgpr_workgroup_info 0
		.amdhsa_system_vgpr_workitem_id 2
		.amdhsa_next_free_vgpr 236
		.amdhsa_next_free_sgpr 102
		.amdhsa_accum_offset 236
		.amdhsa_reserve_vcc 1
		.amdhsa_float_round_mode_32 0
		.amdhsa_float_round_mode_16_64 0
		.amdhsa_float_denorm_mode_32 3
		.amdhsa_float_denorm_mode_16_64 3
		.amdhsa_dx10_clamp 1
		.amdhsa_ieee_mode 1
		.amdhsa_fp16_overflow 0
		.amdhsa_tg_split 0
		.amdhsa_exception_fp_ieee_invalid_op 0
		.amdhsa_exception_fp_denorm_src 0
		.amdhsa_exception_fp_ieee_div_zero 0
		.amdhsa_exception_fp_ieee_overflow 0
		.amdhsa_exception_fp_ieee_underflow 0
		.amdhsa_exception_fp_ieee_inexact 0
		.amdhsa_exception_int_div_zero 0
	.end_amdhsa_kernel

; #define LAS __attribute__((address_space(3)))
; __global__ void __launch_bounds__(NTHREADS, 2) fwd(Args a) {
;     extern __shared__ __attribute__((aligned(16))) unsigned char lds_raw[];
;     LAS unsigned char* lds = (LAS unsigned char*)lds_raw;
;     const int tid = threadIdx.x, lane = tid & 63, wave = __builtin_amdgcn_readfirstlane(tid >> 6);
amdhsa.kernels:
  - .agpr_count:     0
    .args:
      - .offset:         0
        .size:           160
        .value_kind:     by_value
      - .offset:         160
        .size:           4
        .value_kind:     hidden_block_count_x
      - .offset:         164
        .size:           4
        .value_kind:     hidden_block_count_y
      - .offset:         168
        .size:           4
        .value_kind:     hidden_block_count_z
      - .offset:         172
        .size:           2
        .value_kind:     hidden_group_size_x
      - .offset:         174
        .size:           2
        .value_kind:     hidden_group_size_y
      - .offset:         176
        .size:           2
        .value_kind:     hidden_group_size_z
      - .offset:         178
        .size:           2
        .value_kind:     hidden_remainder_x
      - .offset:         180
        .size:           2
        .value_kind:     hidden_remainder_y
      - .offset:         182
        .size:           2
        .value_kind:     hidden_remainder_z
      - .offset:         200
        .size:           8
        .value_kind:     hidden_global_offset_x
      - .offset:         208
        .size:           8
        .value_kind:     hidden_global_offset_y
      - .offset:         216
        .size:           8
        .value_kind:     hidden_global_offset_z
      - .offset:         224
        .size:           2
        .value_kind:     hidden_grid_dims
      - .offset:         248
        .size:           8
        .value_kind:     hidden_multigrid_sync_arg
      - .offset:         280
        .size:           4
        .value_kind:     hidden_dynamic_lds_size
    .group_segment_fixed_size: 0
    .kernarg_segment_align: 8
    .kernarg_segment_size: 416
    .language:       OpenCL C
    .language_version:
      - 2
      - 0
    .max_flat_workgroup_size: 512
    .name:           _Z3fwd4Args
    .private_segment_fixed_size: 0
    .sgpr_count:     108
    .sgpr_spill_count: 16
    .symbol:         _Z3fwd4Args.kd
    .uniform_work_group_size: 1
    .uses_dynamic_stack: false
    .vgpr_count:     236
    .vgpr_spill_count: 0
    .wavefront_size: 64
